# stack f + per-segment s_setprio flips removed from the gemm loops (A/B of the flips)
# baseline (speedup 1.0000x reference)
; #define PG8_STAGE(bufoff, gbase, voff) do { _Pragma("unroll") for (int _i = 0; _i < 2; ++_i) \
;         __builtin_amdgcn_global_load_lds((const unsigned*)((const char*)(gbase) + (voff)[_i]), (LAS unsigned*)(lds + (bufoff) + ldsw + _i * 8192), 16, 0, 0); } while (0)
; #define PG8_LDA(dst, b, h) do { _Pragma("unroll") for (int m = 0; m < 4; ++m) _Pragma("unroll") for (int k = 0; k < 2; ++k) dst[m][k] = *(const LAS bf16x8*)(lds + PG8_SA(b, h) + aoff + m * 2048 + k * 1024); } while (0)
; #define PG8_LDB(dst, b, h) do { _Pragma("unroll") for (int n = 0; n < 2; ++n) _Pragma("unroll") for (int k = 0; k < 2; ++k) dst[n][k] = *(const LAS bf16x8*)(lds + PG8_SB(b, h) + boff + n * 2048 + k * 1024); } while (0)
; #define PG8_MMA(ai, bj, At, Bt) do { __builtin_amdgcn_s_setprio(1); _Pragma("unroll") for (int m = 0; m < 4; ++m) _Pragma("unroll") for (int n = 0; n < 2; ++n) _Pragma("unroll") for (int k = 0; k < 2; ++k) \
;         acc[ai][bj][m][n] = __builtin_amdgcn_mfma_f32_16x16x32_bf16(Bt[n][k], At[m][k], acc[ai][bj][m][n], 0, 0, 0); __builtin_amdgcn_s_setprio(0); } while (0)
; template <class Epi>
; __device__ __forceinline__ void gemm_phase(LAS unsigned char* lds, const Gemm g, const StaticOrder S, const Epi E) {
;     ...
;         const bool has_next = S.next(ui + 1, nxt);
;         const char* nA = has_next ? (const char*)g.A + (size_t)nxt.pm * tstep + (size_t)nxt.k0 * kstep : cA; const char* nB = has_next ? (const char*)g.Bt + (size_t)nxt.pn * tstep + (size_t)nxt.k0 * kstep : cB;
;         const int nt = cur.nk;
;         for (int t = 0; t < nt; t += 2) {
;             const bool last = (t == nt - 2);
;             const char* a1 = cA + (size_t)(t + 1) * kstep;
;             const char* a2 = last ? nA : cA + (size_t)(t + 2) * kstep; const char* b2 = last ? nB : cB + (size_t)(t + 2) * kstep;
;             const char* a3 = a2 + kstep; const char* b3 = b2 + kstep;
;             PG8_LDB(B0, 0, 0); PG8_SCHED; PG8_LDA(At, 0, 0); PG8_STAGE(PG8_SA(1, 1), a1 + hstep, voffA);
;             PG8_WAIT_L(8); PG8_BAR; PG8_WAIT_L(0); PG8_MMA(0, 0, At, B0); PG8_BAR; PG8_SCHED;
;             PG8_LDB(B1, 0, 1); PG8_STAGE(PG8_SB(0, 0), b2, voffA);
;             PG8_BAR; PG8_WAIT_L(0); PG8_MMA(0, 1, At, B1); PG8_BAR;
;             PG8_LDA(At, 0, 1); PG8_STAGE(PG8_SA(0, 0), a2, voffA);
;             PG8_BAR; PG8_WAIT_L(0); PG8_MMA(1, 0, At, B0); PG8_BAR; PG8_SCHED;
.LBB0_2218:
	s_ashr_i32 s11, s10, 31
	s_lshl_b64 s[28:29], s[10:11], 20
	v_readlane_b32 s3, v255, 1
	v_cmp_lt_i64_e32 vcc, s[40:41], v[180:181]
	s_add_u32 s40, s3, s28
	v_readlane_b32 s3, v255, 2
	s_addc_u32 s41, s3, s29
	s_and_b64 s[28:29], vcc, exec
	s_cselect_b32 s11, s41, s45
	s_cselect_b32 s28, s40, s44
	s_ashr_i32 s3, s2, 31
	s_lshl_b64 s[30:31], s[2:3], 20
	s_add_u32 s42, s6, s30
	s_addc_u32 s43, s7, s31
	s_and_b64 s[30:31], vcc, exec
	s_cselect_b32 s3, s43, s47
	s_cselect_b32 s29, s42, s46
	s_add_u32 s44, s44, 0x80080
	s_addc_u32 s45, s45, 0
	s_add_u32 s54, s46, 0x100
	s_addc_u32 s55, s47, 0
	s_mov_b32 s56, -2
	s_add_u32 s30, s44, 0xfff80080
	s_addc_u32 s31, s45, -1
	s_add_i32 s57, 0, 0x10000
	v_add_u32_e32 v134, s57, v137
	ds_read_b128 v[140:143], v134
	ds_read_b128 v[144:147], v134 offset:1024
	ds_read_b128 v[148:151], v134 offset:2048
	ds_read_b128 v[152:155], v134 offset:3072
	s_cmp_eq_u32 s56, 28
	s_cselect_b32 s49, s11, s31
	s_cselect_b32 s48, s28, s30
	s_cselect_b32 s47, s3, s55
	s_cselect_b32 s46, s29, s54
	v_lshl_add_u64 v[134:135], s[44:45], 0, v[130:131]
	s_add_i32 m0, s23, 0xc000
	ds_read_b128 v[156:159], v139
	ds_read_b128 v[160:163], v139 offset:1024
	ds_read_b128 v[164:167], v139 offset:2048
	ds_read_b128 v[168:171], v139 offset:3072
	ds_read_b128 v[172:175], v139 offset:4096
	ds_read_b128 v[194:197], v139 offset:5120
	ds_read_b128 v[198:201], v139 offset:6144
	ds_read_b128 v[202:205], v139 offset:7168
	global_load_lds_dwordx4 v[134:135], off
	v_lshl_add_u64 v[134:135], s[44:45], 0, v[132:133]
	s_add_i32 m0, s23, 0xe000
	s_nop 0
	global_load_lds_dwordx4 v[134:135], off
	s_waitcnt lgkmcnt(8)
	s_barrier
	s_waitcnt lgkmcnt(0)
	v_mfma_f32_16x16x32_bf16 v[120:123], v[140:143], v[156:159], 0
	v_mfma_f32_16x16x32_bf16 v[124:127], v[148:151], v[156:159], 0
	v_mfma_f32_16x16x32_bf16 v[104:107], v[140:143], v[164:167], 0
	v_mfma_f32_16x16x32_bf16 v[108:111], v[148:151], v[164:167], 0
	v_mfma_f32_16x16x32_bf16 v[88:91], v[140:143], v[172:175], 0
	v_mfma_f32_16x16x32_bf16 v[92:95], v[148:151], v[172:175], 0
	v_mfma_f32_16x16x32_bf16 v[72:75], v[140:143], v[198:201], 0
	v_mfma_f32_16x16x32_bf16 v[76:79], v[148:151], v[198:201], 0
	v_mfma_f32_16x16x32_bf16 v[120:123], v[144:147], v[160:163], v[120:123]
	v_mfma_f32_16x16x32_bf16 v[124:127], v[152:155], v[160:163], v[124:127]
	v_mfma_f32_16x16x32_bf16 v[104:107], v[144:147], v[168:171], v[104:107]
	v_mfma_f32_16x16x32_bf16 v[108:111], v[152:155], v[168:171], v[108:111]
	v_mfma_f32_16x16x32_bf16 v[88:91], v[144:147], v[194:197], v[88:91]
	v_mfma_f32_16x16x32_bf16 v[92:95], v[152:155], v[194:197], v[92:95]
	v_mfma_f32_16x16x32_bf16 v[72:75], v[144:147], v[202:205], v[72:75]
	v_mfma_f32_16x16x32_bf16 v[76:79], v[152:155], v[202:205], v[76:79]
	s_barrier
	s_add_i32 s58, 0, 0x14000
	v_add_u32_e32 v134, s58, v137
	s_add_i32 s30, s57, s22
	ds_read_b128 v[206:209], v134
	ds_read_b128 v[228:231], v134 offset:1024
	ds_read_b128 v[232:235], v134 offset:2048
	ds_read_b128 v[236:239], v134 offset:3072
	v_lshl_add_u64 v[134:135], s[46:47], 0, v[178:179]
	s_mov_b32 m0, s30
	v_lshl_add_u64 v[210:211], s[46:47], 0, v[128:129]
	global_load_lds_dwordx4 v[134:135], off
	s_add_i32 m0, s30, 0x2000
	s_nop 0
	global_load_lds_dwordx4 v[210:211], off
	s_barrier
	s_waitcnt lgkmcnt(0)
	v_mfma_f32_16x16x32_bf16 v[112:115], v[206:209], v[156:159], 0
	v_mfma_f32_16x16x32_bf16 v[116:119], v[232:235], v[156:159], 0
	v_mfma_f32_16x16x32_bf16 v[96:99], v[206:209], v[164:167], 0
	v_mfma_f32_16x16x32_bf16 v[100:103], v[232:235], v[164:167], 0
	v_mfma_f32_16x16x32_bf16 v[80:83], v[206:209], v[172:175], 0
	v_mfma_f32_16x16x32_bf16 v[84:87], v[232:235], v[172:175], 0
	v_mfma_f32_16x16x32_bf16 v[64:67], v[206:209], v[198:201], 0
	v_mfma_f32_16x16x32_bf16 v[68:71], v[232:235], v[198:201], 0
	v_mfma_f32_16x16x32_bf16 v[112:115], v[228:231], v[160:163], v[112:115]
	v_mfma_f32_16x16x32_bf16 v[116:119], v[236:239], v[160:163], v[116:119]
	v_mfma_f32_16x16x32_bf16 v[96:99], v[228:231], v[168:171], v[96:99]
	v_mfma_f32_16x16x32_bf16 v[100:103], v[236:239], v[168:171], v[100:103]
	v_mfma_f32_16x16x32_bf16 v[80:83], v[228:231], v[194:197], v[80:83]
	v_mfma_f32_16x16x32_bf16 v[84:87], v[236:239], v[194:197], v[84:87]
	v_mfma_f32_16x16x32_bf16 v[64:67], v[228:231], v[202:205], v[64:67]
	v_mfma_f32_16x16x32_bf16 v[68:71], v[236:239], v[202:205], v[68:71]
	s_barrier
	s_mov_b32 m0, s23
	v_lshl_add_u64 v[220:221], s[48:49], 0, v[178:179]
	ds_read_b128 v[156:159], v139 offset:16384
	ds_read_b128 v[160:163], v139 offset:17408
	ds_read_b128 v[164:167], v139 offset:18432
	ds_read_b128 v[168:171], v139 offset:19456
	ds_read_b128 v[172:175], v139 offset:20480
	ds_read_b128 v[194:197], v139 offset:21504
	ds_read_b128 v[198:201], v139 offset:22528
	ds_read_b128 v[202:205], v139 offset:23552
	global_load_lds_dwordx4 v[220:221], off
	v_lshl_add_u64 v[222:223], s[48:49], 0, v[128:129]
	s_mov_b32 m0, s24
	s_nop 0
	global_load_lds_dwordx4 v[222:223], off
	s_barrier
	s_waitcnt lgkmcnt(0)
	v_mfma_f32_16x16x32_bf16 v[56:59], v[140:143], v[156:159], 0
	v_mfma_f32_16x16x32_bf16 v[60:63], v[148:151], v[156:159], 0
	v_mfma_f32_16x16x32_bf16 v[40:43], v[140:143], v[164:167], 0
	v_mfma_f32_16x16x32_bf16 v[44:47], v[148:151], v[164:167], 0
	v_mfma_f32_16x16x32_bf16 v[24:27], v[140:143], v[172:175], 0
	v_mfma_f32_16x16x32_bf16 v[28:31], v[148:151], v[172:175], 0
	v_mfma_f32_16x16x32_bf16 v[8:11], v[140:143], v[198:201], 0
	v_mfma_f32_16x16x32_bf16 v[12:15], v[148:151], v[198:201], 0
	v_mfma_f32_16x16x32_bf16 v[56:59], v[144:147], v[160:163], v[56:59]
	v_mfma_f32_16x16x32_bf16 v[60:63], v[152:155], v[160:163], v[60:63]
	v_mfma_f32_16x16x32_bf16 v[40:43], v[144:147], v[168:171], v[40:43]
	v_mfma_f32_16x16x32_bf16 v[44:47], v[152:155], v[168:171], v[44:47]
	v_mfma_f32_16x16x32_bf16 v[24:27], v[144:147], v[194:197], v[24:27]
	v_mfma_f32_16x16x32_bf16 v[28:31], v[152:155], v[194:197], v[28:31]
	v_mfma_f32_16x16x32_bf16 v[8:11], v[144:147], v[202:205], v[8:11]
	v_mfma_f32_16x16x32_bf16 v[12:15], v[152:155], v[202:205], v[12:15]
	s_barrier
; #define PG8_STAGE(bufoff, gbase, voff) do { _Pragma("unroll") for (int _i = 0; _i < 2; ++_i) \
;         __builtin_amdgcn_global_load_lds((const unsigned*)((const char*)(gbase) + (voff)[_i]), (LAS unsigned*)(lds + (bufoff) + ldsw + _i * 8192), 16, 0, 0); } while (0)
; #define PG8_LDA(dst, b, h) do { _Pragma("unroll") for (int m = 0; m < 4; ++m) _Pragma("unroll") for (int k = 0; k < 2; ++k) dst[m][k] = *(const LAS bf16x8*)(lds + PG8_SA(b, h) + aoff + m * 2048 + k * 1024); } while (0)
; #define PG8_LDB(dst, b, h) do { _Pragma("unroll") for (int n = 0; n < 2; ++n) _Pragma("unroll") for (int k = 0; k < 2; ++k) dst[n][k] = *(const LAS bf16x8*)(lds + PG8_SB(b, h) + boff + n * 2048 + k * 1024); } while (0)
; #define PG8_MMA(ai, bj, At, Bt) do { __builtin_amdgcn_s_setprio(1); _Pragma("unroll") for (int m = 0; m < 4; ++m) _Pragma("unroll") for (int n = 0; n < 2; ++n) _Pragma("unroll") for (int k = 0; k < 2; ++k) \
;         acc[ai][bj][m][n] = __builtin_amdgcn_mfma_f32_16x16x32_bf16(Bt[n][k], At[m][k], acc[ai][bj][m][n], 0, 0, 0); __builtin_amdgcn_s_setprio(0); } while (0)
; #define PG8_WAIT_V(n) asm volatile("s_waitcnt vmcnt(" #n ")" ::: "memory")
; #define PG8_WAIT_L(n) asm volatile("s_waitcnt lgkmcnt(" #n ")" ::: "memory")
; #define PG8_BAR __builtin_amdgcn_s_barrier()
; #define PG8_SCHED __builtin_amdgcn_sched_barrier(0)
; template <class Epi>
; __device__ __forceinline__ void gemm_phase(LAS unsigned char* lds, const Gemm g, const StaticOrder S, const Epi E) {
;     ...
;             PG8_STAGE(PG8_SB(0, 1), b2 + hstep, voffA);
;             PG8_WAIT_V(6); PG8_BAR; PG8_MMA(1, 1, At, B1); PG8_BAR;
;             PG8_LDB(B0, 1, 0); PG8_SCHED; PG8_LDA(At, 1, 0); PG8_STAGE(PG8_SA(0, 1), a2 + hstep, voffA);
;             PG8_WAIT_L(8); PG8_BAR; PG8_WAIT_L(0); PG8_MMA(0, 0, At, B0); PG8_BAR; PG8_SCHED;
;             PG8_LDB(B1, 1, 1); PG8_STAGE(PG8_SB(1, 0), b3, voffA);
;             PG8_BAR; PG8_WAIT_L(0); PG8_MMA(0, 1, At, B1); PG8_BAR;
;             PG8_LDA(At, 1, 1); PG8_STAGE(PG8_SA(1, 0), a3, voffA);
	s_add_u32 s30, s46, 0x80000
	s_addc_u32 s31, s47, 0
	s_add_i32 s57, s58, s22
	v_lshl_add_u64 v[140:141], s[30:31], 0, v[178:179]
	s_mov_b32 m0, s57
	s_nop 0
	global_load_lds_dwordx4 v[140:141], off
	v_lshl_add_u64 v[140:141], s[30:31], 0, v[128:129]
	s_add_i32 m0, s57, 0x2000
	s_nop 0
	global_load_lds_dwordx4 v[140:141], off
	s_waitcnt vmcnt(6)
	s_barrier
	v_mfma_f32_16x16x32_bf16 v[48:51], v[206:209], v[156:159], 0
	v_mfma_f32_16x16x32_bf16 v[52:55], v[232:235], v[156:159], 0
	v_mfma_f32_16x16x32_bf16 v[32:35], v[206:209], v[164:167], 0
	v_mfma_f32_16x16x32_bf16 v[36:39], v[232:235], v[164:167], 0
	v_mfma_f32_16x16x32_bf16 v[16:19], v[206:209], v[172:175], 0
	v_mfma_f32_16x16x32_bf16 v[20:23], v[232:235], v[172:175], 0
	v_mfma_f32_16x16x32_bf16 v[0:3], v[206:209], v[198:201], 0
	v_mfma_f32_16x16x32_bf16 v[4:7], v[232:235], v[198:201], 0
	v_mfma_f32_16x16x32_bf16 v[48:51], v[228:231], v[160:163], v[48:51]
	v_mfma_f32_16x16x32_bf16 v[52:55], v[236:239], v[160:163], v[52:55]
	v_mfma_f32_16x16x32_bf16 v[32:35], v[228:231], v[168:171], v[32:35]
	v_mfma_f32_16x16x32_bf16 v[36:39], v[236:239], v[168:171], v[36:39]
	v_mfma_f32_16x16x32_bf16 v[16:19], v[228:231], v[194:197], v[16:19]
	v_mfma_f32_16x16x32_bf16 v[20:23], v[236:239], v[194:197], v[20:23]
	v_mfma_f32_16x16x32_bf16 v[0:3], v[228:231], v[202:205], v[0:3]
	v_mfma_f32_16x16x32_bf16 v[4:7], v[236:239], v[202:205], v[4:7]
	s_barrier
	s_add_i32 s57, 0, 0x18000
	v_add_u32_e32 v152, s57, v137
	ds_read_b128 v[140:143], v152
	ds_read_b128 v[144:147], v152 offset:1024
	ds_read_b128 v[148:151], v152 offset:2048
	ds_read_b128 v[152:155], v152 offset:3072
	s_add_u32 s30, s48, 0x80000
	s_addc_u32 s31, s49, 0
	s_mov_b32 m0, s25
	v_lshl_add_u64 v[206:207], s[30:31], 0, v[178:179]
	ds_read_b128 v[156:159], v139 offset:32768
	ds_read_b128 v[160:163], v139 offset:33792
	ds_read_b128 v[164:167], v139 offset:34816
	ds_read_b128 v[168:171], v139 offset:35840
	ds_read_b128 v[172:175], v139 offset:36864
	ds_read_b128 v[194:197], v139 offset:37888
	ds_read_b128 v[198:201], v139 offset:38912
	ds_read_b128 v[202:205], v139 offset:39936
	global_load_lds_dwordx4 v[206:207], off
	v_lshl_add_u64 v[206:207], s[30:31], 0, v[128:129]
	s_mov_b32 m0, s50
	s_nop 0
	global_load_lds_dwordx4 v[206:207], off
	s_waitcnt lgkmcnt(8)
	s_barrier
	s_waitcnt lgkmcnt(0)
	v_mfma_f32_16x16x32_bf16 v[120:123], v[140:143], v[156:159], v[120:123]
	v_mfma_f32_16x16x32_bf16 v[124:127], v[148:151], v[156:159], v[124:127]
	v_mfma_f32_16x16x32_bf16 v[104:107], v[140:143], v[164:167], v[104:107]
	v_mfma_f32_16x16x32_bf16 v[108:111], v[148:151], v[164:167], v[108:111]
	v_mfma_f32_16x16x32_bf16 v[88:91], v[140:143], v[172:175], v[88:91]
	v_mfma_f32_16x16x32_bf16 v[92:95], v[148:151], v[172:175], v[92:95]
	v_mfma_f32_16x16x32_bf16 v[72:75], v[140:143], v[198:201], v[72:75]
	v_mfma_f32_16x16x32_bf16 v[76:79], v[148:151], v[198:201], v[76:79]
	v_mfma_f32_16x16x32_bf16 v[120:123], v[144:147], v[160:163], v[120:123]
	v_mfma_f32_16x16x32_bf16 v[124:127], v[152:155], v[160:163], v[124:127]
	v_mfma_f32_16x16x32_bf16 v[104:107], v[144:147], v[168:171], v[104:107]
	v_mfma_f32_16x16x32_bf16 v[108:111], v[152:155], v[168:171], v[108:111]
	v_mfma_f32_16x16x32_bf16 v[88:91], v[144:147], v[194:197], v[88:91]
	v_mfma_f32_16x16x32_bf16 v[92:95], v[152:155], v[194:197], v[92:95]
	v_mfma_f32_16x16x32_bf16 v[72:75], v[144:147], v[202:205], v[72:75]
	v_mfma_f32_16x16x32_bf16 v[76:79], v[152:155], v[202:205], v[76:79]
	s_barrier
	s_add_i32 s48, 0, 0x1c000
	s_add_i32 s30, s57, s22
	v_add_u32_e32 v227, s48, v137
	v_lshl_add_u64 v[134:135], v[134:135], 0, s[34:35]
	s_mov_b32 m0, s30
	ds_read_b128 v[206:209], v227
	ds_read_b128 v[228:231], v227 offset:1024
	ds_read_b128 v[232:235], v227 offset:2048
	ds_read_b128 v[236:239], v227 offset:3072
	global_load_lds_dwordx4 v[134:135], off
	v_lshl_add_u64 v[134:135], v[210:211], 0, s[34:35]
	s_add_i32 m0, s30, 0x2000
	s_nop 0
	global_load_lds_dwordx4 v[134:135], off
	s_barrier
	s_waitcnt lgkmcnt(0)
	v_mfma_f32_16x16x32_bf16 v[112:115], v[206:209], v[156:159], v[112:115]
	v_mfma_f32_16x16x32_bf16 v[116:119], v[232:235], v[156:159], v[116:119]
	v_mfma_f32_16x16x32_bf16 v[96:99], v[206:209], v[164:167], v[96:99]
	v_mfma_f32_16x16x32_bf16 v[100:103], v[232:235], v[164:167], v[100:103]
	v_mfma_f32_16x16x32_bf16 v[80:83], v[206:209], v[172:175], v[80:83]
	v_mfma_f32_16x16x32_bf16 v[84:87], v[232:235], v[172:175], v[84:87]
	v_mfma_f32_16x16x32_bf16 v[64:67], v[206:209], v[198:201], v[64:67]
	v_mfma_f32_16x16x32_bf16 v[68:71], v[232:235], v[198:201], v[68:71]
	v_mfma_f32_16x16x32_bf16 v[112:115], v[228:231], v[160:163], v[112:115]
	v_mfma_f32_16x16x32_bf16 v[116:119], v[236:239], v[160:163], v[116:119]
	v_mfma_f32_16x16x32_bf16 v[96:99], v[228:231], v[168:171], v[96:99]
	v_mfma_f32_16x16x32_bf16 v[100:103], v[236:239], v[168:171], v[100:103]
	v_mfma_f32_16x16x32_bf16 v[80:83], v[228:231], v[194:197], v[80:83]
	v_mfma_f32_16x16x32_bf16 v[84:87], v[236:239], v[194:197], v[84:87]
	v_mfma_f32_16x16x32_bf16 v[64:67], v[228:231], v[202:205], v[64:67]
	v_mfma_f32_16x16x32_bf16 v[68:71], v[236:239], v[202:205], v[68:71]
	s_barrier
	s_mov_b32 m0, s51
	v_lshl_add_u64 v[134:135], v[220:221], 0, s[34:35]
	ds_read_b128 v[156:159], v139 offset:49152
	ds_read_b128 v[160:163], v139 offset:50176
	ds_read_b128 v[164:167], v139 offset:51200
	ds_read_b128 v[168:171], v139 offset:52224
	ds_read_b128 v[172:175], v139 offset:53248
	ds_read_b128 v[194:197], v139 offset:54272
	ds_read_b128 v[198:201], v139 offset:55296
	ds_read_b128 v[202:205], v139 offset:56320
	global_load_lds_dwordx4 v[134:135], off
	v_lshl_add_u64 v[134:135], v[222:223], 0, s[34:35]
	s_mov_b32 m0, s52
	s_nop 0
	global_load_lds_dwordx4 v[134:135], off
	s_barrier
; #define PG8_STAGE(bufoff, gbase, voff) do { _Pragma("unroll") for (int _i = 0; _i < 2; ++_i) \
;         __builtin_amdgcn_global_load_lds((const unsigned*)((const char*)(gbase) + (voff)[_i]), (LAS unsigned*)(lds + (bufoff) + ldsw + _i * 8192), 16, 0, 0); } while (0)
; #define PG8_LDA(dst, b, h) do { _Pragma("unroll") for (int m = 0; m < 4; ++m) _Pragma("unroll") for (int k = 0; k < 2; ++k) dst[m][k] = *(const LAS bf16x8*)(lds + PG8_SA(b, h) + aoff + m * 2048 + k * 1024); } while (0)
; #define PG8_LDB(dst, b, h) do { _Pragma("unroll") for (int n = 0; n < 2; ++n) _Pragma("unroll") for (int k = 0; k < 2; ++k) dst[n][k] = *(const LAS bf16x8*)(lds + PG8_SB(b, h) + boff + n * 2048 + k * 1024); } while (0)
; #define PG8_MMA(ai, bj, At, Bt) do { __builtin_amdgcn_s_setprio(1); _Pragma("unroll") for (int m = 0; m < 4; ++m) _Pragma("unroll") for (int n = 0; n < 2; ++n) _Pragma("unroll") for (int k = 0; k < 2; ++k) \
;         acc[ai][bj][m][n] = __builtin_amdgcn_mfma_f32_16x16x32_bf16(Bt[n][k], At[m][k], acc[ai][bj][m][n], 0, 0, 0); __builtin_amdgcn_s_setprio(0); } while (0)
; #define PG8_WAIT_V(n) asm volatile("s_waitcnt vmcnt(" #n ")" ::: "memory")
; #define PG8_WAIT_L(n) asm volatile("s_waitcnt lgkmcnt(" #n ")" ::: "memory")
; #define PG8_BAR __builtin_amdgcn_s_barrier()
; #define PG8_SCHED __builtin_amdgcn_sched_barrier(0)
; template <class Epi>
; __device__ __forceinline__ void gemm_phase(LAS unsigned char* lds, const Gemm g, const StaticOrder S, const Epi E) {
;     ...
;         for (int t = 0; t < nt; t += 2) {
;             const bool last = (t == nt - 2);
;             const char* a1 = cA + (size_t)(t + 1) * kstep;
;             const char* a2 = last ? nA : cA + (size_t)(t + 2) * kstep; const char* b2 = last ? nB : cB + (size_t)(t + 2) * kstep;
;             const char* a3 = a2 + kstep; const char* b3 = b2 + kstep;
;             PG8_LDB(B0, 0, 0); PG8_SCHED; PG8_LDA(At, 0, 0); PG8_STAGE(PG8_SA(1, 1), a1 + hstep, voffA);
;             PG8_WAIT_L(8); PG8_BAR; PG8_WAIT_L(0); PG8_MMA(0, 0, At, B0); PG8_BAR; PG8_SCHED;
;             PG8_LDB(B1, 0, 1); PG8_STAGE(PG8_SB(0, 0), b2, voffA);
;     ...
;             PG8_BAR; PG8_WAIT_L(0); PG8_MMA(1, 0, At, B0); PG8_BAR; PG8_SCHED;
;             PG8_STAGE(PG8_SB(1, 1), b3 + hstep, voffA);
;             PG8_WAIT_V(6); PG8_BAR; PG8_MMA(1, 1, At, B1); PG8_BAR;
	s_waitcnt lgkmcnt(0)
	v_mfma_f32_16x16x32_bf16 v[56:59], v[140:143], v[156:159], v[56:59]
	v_mfma_f32_16x16x32_bf16 v[60:63], v[148:151], v[156:159], v[60:63]
	v_mfma_f32_16x16x32_bf16 v[40:43], v[140:143], v[164:167], v[40:43]
	v_mfma_f32_16x16x32_bf16 v[44:47], v[148:151], v[164:167], v[44:47]
	v_mfma_f32_16x16x32_bf16 v[24:27], v[140:143], v[172:175], v[24:27]
	v_mfma_f32_16x16x32_bf16 v[28:31], v[148:151], v[172:175], v[28:31]
	v_mfma_f32_16x16x32_bf16 v[8:11], v[140:143], v[198:201], v[8:11]
	v_mfma_f32_16x16x32_bf16 v[12:15], v[148:151], v[198:201], v[12:15]
	v_mfma_f32_16x16x32_bf16 v[56:59], v[144:147], v[160:163], v[56:59]
	v_mfma_f32_16x16x32_bf16 v[60:63], v[152:155], v[160:163], v[60:63]
	v_mfma_f32_16x16x32_bf16 v[40:43], v[144:147], v[168:171], v[40:43]
	v_mfma_f32_16x16x32_bf16 v[44:47], v[152:155], v[168:171], v[44:47]
	v_mfma_f32_16x16x32_bf16 v[24:27], v[144:147], v[194:197], v[24:27]
	v_mfma_f32_16x16x32_bf16 v[28:31], v[152:155], v[194:197], v[28:31]
	v_mfma_f32_16x16x32_bf16 v[8:11], v[144:147], v[202:205], v[8:11]
	v_mfma_f32_16x16x32_bf16 v[12:15], v[152:155], v[202:205], v[12:15]
	s_barrier
	s_add_u32 s30, s46, 0x80080
	s_addc_u32 s31, s47, 0
	s_add_i32 s46, s48, s22
	v_lshl_add_u64 v[134:135], s[30:31], 0, v[178:179]
	s_mov_b32 m0, s46
	s_nop 0
	global_load_lds_dwordx4 v[134:135], off
	v_lshl_add_u64 v[134:135], s[30:31], 0, v[128:129]
	s_add_i32 m0, s46, 0x2000
	s_nop 0
	global_load_lds_dwordx4 v[134:135], off
	s_waitcnt vmcnt(6)
	s_barrier
	v_mfma_f32_16x16x32_bf16 v[48:51], v[206:209], v[156:159], v[48:51]
	v_mfma_f32_16x16x32_bf16 v[52:55], v[232:235], v[156:159], v[52:55]
	v_mfma_f32_16x16x32_bf16 v[32:35], v[206:209], v[164:167], v[32:35]
	v_mfma_f32_16x16x32_bf16 v[36:39], v[232:235], v[164:167], v[36:39]
	v_mfma_f32_16x16x32_bf16 v[16:19], v[206:209], v[172:175], v[16:19]
	v_mfma_f32_16x16x32_bf16 v[20:23], v[232:235], v[172:175], v[20:23]
	v_mfma_f32_16x16x32_bf16 v[0:3], v[206:209], v[198:201], v[0:3]
	v_mfma_f32_16x16x32_bf16 v[4:7], v[232:235], v[198:201], v[4:7]
	v_mfma_f32_16x16x32_bf16 v[48:51], v[228:231], v[160:163], v[48:51]
	v_mfma_f32_16x16x32_bf16 v[52:55], v[236:239], v[160:163], v[52:55]
	v_mfma_f32_16x16x32_bf16 v[32:35], v[228:231], v[168:171], v[32:35]
	v_mfma_f32_16x16x32_bf16 v[36:39], v[236:239], v[168:171], v[36:39]
	v_mfma_f32_16x16x32_bf16 v[16:19], v[228:231], v[194:197], v[16:19]
	v_mfma_f32_16x16x32_bf16 v[20:23], v[236:239], v[194:197], v[20:23]
	v_mfma_f32_16x16x32_bf16 v[0:3], v[228:231], v[202:205], v[0:3]
	v_mfma_f32_16x16x32_bf16 v[4:7], v[236:239], v[202:205], v[4:7]
	s_barrier
	s_add_i32 s56, s56, 2
	s_add_u32 s44, s44, 0x100
	s_addc_u32 s45, s45, 0
	s_add_u32 s54, s54, 0x100
	s_addc_u32 s55, s55, 0
	s_cmp_gt_u32 s56, 29
	s_cbranch_scc0 .LBB0_2219
	s_branch .Lpeel_exit_0
.LBB0_2219:
	s_add_u32 s30, s44, 0xfff80080
	s_addc_u32 s31, s45, -1
	s_add_i32 s57, 0, 0x10000
	v_add_u32_e32 v134, s57, v137
	ds_read_b128 v[140:143], v134
	ds_read_b128 v[144:147], v134 offset:1024
	ds_read_b128 v[148:151], v134 offset:2048
	ds_read_b128 v[152:155], v134 offset:3072
	s_cmp_eq_u32 s56, 28
	s_cselect_b32 s49, s11, s31
	s_cselect_b32 s48, s28, s30
	s_cselect_b32 s47, s3, s55
	s_cselect_b32 s46, s29, s54
	v_lshl_add_u64 v[134:135], s[44:45], 0, v[130:131]
	s_add_i32 m0, s23, 0xc000
	ds_read_b128 v[156:159], v139
	ds_read_b128 v[160:163], v139 offset:1024
	ds_read_b128 v[164:167], v139 offset:2048
	ds_read_b128 v[168:171], v139 offset:3072
	ds_read_b128 v[172:175], v139 offset:4096
	ds_read_b128 v[194:197], v139 offset:5120
	ds_read_b128 v[198:201], v139 offset:6144
	ds_read_b128 v[202:205], v139 offset:7168
	global_load_lds_dwordx4 v[134:135], off
	v_lshl_add_u64 v[134:135], s[44:45], 0, v[132:133]
	s_add_i32 m0, s23, 0xe000
	s_nop 0
	global_load_lds_dwordx4 v[134:135], off
	s_waitcnt lgkmcnt(8)
	s_barrier
	s_waitcnt lgkmcnt(0)
	v_mfma_f32_16x16x32_bf16 v[120:123], v[140:143], v[156:159], v[120:123]
	v_mfma_f32_16x16x32_bf16 v[124:127], v[148:151], v[156:159], v[124:127]
	v_mfma_f32_16x16x32_bf16 v[104:107], v[140:143], v[164:167], v[104:107]
	v_mfma_f32_16x16x32_bf16 v[108:111], v[148:151], v[164:167], v[108:111]
	v_mfma_f32_16x16x32_bf16 v[88:91], v[140:143], v[172:175], v[88:91]
	v_mfma_f32_16x16x32_bf16 v[92:95], v[148:151], v[172:175], v[92:95]
	v_mfma_f32_16x16x32_bf16 v[72:75], v[140:143], v[198:201], v[72:75]
	v_mfma_f32_16x16x32_bf16 v[76:79], v[148:151], v[198:201], v[76:79]
	v_mfma_f32_16x16x32_bf16 v[120:123], v[144:147], v[160:163], v[120:123]
	v_mfma_f32_16x16x32_bf16 v[124:127], v[152:155], v[160:163], v[124:127]
	v_mfma_f32_16x16x32_bf16 v[104:107], v[144:147], v[168:171], v[104:107]
	v_mfma_f32_16x16x32_bf16 v[108:111], v[152:155], v[168:171], v[108:111]
	v_mfma_f32_16x16x32_bf16 v[88:91], v[144:147], v[194:197], v[88:91]
	v_mfma_f32_16x16x32_bf16 v[92:95], v[152:155], v[194:197], v[92:95]
	v_mfma_f32_16x16x32_bf16 v[72:75], v[144:147], v[202:205], v[72:75]
	v_mfma_f32_16x16x32_bf16 v[76:79], v[152:155], v[202:205], v[76:79]
	s_barrier
	s_add_i32 s58, 0, 0x14000
	v_add_u32_e32 v134, s58, v137
	s_add_i32 s30, s57, s22
	ds_read_b128 v[206:209], v134
	ds_read_b128 v[228:231], v134 offset:1024
	ds_read_b128 v[232:235], v134 offset:2048
	ds_read_b128 v[236:239], v134 offset:3072
	v_lshl_add_u64 v[134:135], s[46:47], 0, v[178:179]
	s_mov_b32 m0, s30
	v_lshl_add_u64 v[210:211], s[46:47], 0, v[128:129]
	global_load_lds_dwordx4 v[134:135], off
	s_add_i32 m0, s30, 0x2000
	s_nop 0
	global_load_lds_dwordx4 v[210:211], off
	s_barrier
; #define PG8_STAGE(bufoff, gbase, voff) do { _Pragma("unroll") for (int _i = 0; _i < 2; ++_i) \
;         __builtin_amdgcn_global_load_lds((const unsigned*)((const char*)(gbase) + (voff)[_i]), (LAS unsigned*)(lds + (bufoff) + ldsw + _i * 8192), 16, 0, 0); } while (0)
; #define PG8_LDA(dst, b, h) do { _Pragma("unroll") for (int m = 0; m < 4; ++m) _Pragma("unroll") for (int k = 0; k < 2; ++k) dst[m][k] = *(const LAS bf16x8*)(lds + PG8_SA(b, h) + aoff + m * 2048 + k * 1024); } while (0)
; #define PG8_LDB(dst, b, h) do { _Pragma("unroll") for (int n = 0; n < 2; ++n) _Pragma("unroll") for (int k = 0; k < 2; ++k) dst[n][k] = *(const LAS bf16x8*)(lds + PG8_SB(b, h) + boff + n * 2048 + k * 1024); } while (0)
; #define PG8_MMA(ai, bj, At, Bt) do { __builtin_amdgcn_s_setprio(1); _Pragma("unroll") for (int m = 0; m < 4; ++m) _Pragma("unroll") for (int n = 0; n < 2; ++n) _Pragma("unroll") for (int k = 0; k < 2; ++k) \
;         acc[ai][bj][m][n] = __builtin_amdgcn_mfma_f32_16x16x32_bf16(Bt[n][k], At[m][k], acc[ai][bj][m][n], 0, 0, 0); __builtin_amdgcn_s_setprio(0); } while (0)
; #define PG8_WAIT_V(n) asm volatile("s_waitcnt vmcnt(" #n ")" ::: "memory")
; #define PG8_WAIT_L(n) asm volatile("s_waitcnt lgkmcnt(" #n ")" ::: "memory")
; #define PG8_BAR __builtin_amdgcn_s_barrier()
; #define PG8_SCHED __builtin_amdgcn_sched_barrier(0)
; template <class Epi>
; __device__ __forceinline__ void gemm_phase(LAS unsigned char* lds, const Gemm g, const StaticOrder S, const Epi E) {
;     ...
;             PG8_BAR; PG8_WAIT_L(0); PG8_MMA(0, 1, At, B1); PG8_BAR;
;             PG8_LDA(At, 0, 1); PG8_STAGE(PG8_SA(0, 0), a2, voffA);
;             PG8_BAR; PG8_WAIT_L(0); PG8_MMA(1, 0, At, B0); PG8_BAR; PG8_SCHED;
;             PG8_STAGE(PG8_SB(0, 1), b2 + hstep, voffA);
;             PG8_WAIT_V(6); PG8_BAR; PG8_MMA(1, 1, At, B1); PG8_BAR;
;             PG8_LDB(B0, 1, 0); PG8_SCHED; PG8_LDA(At, 1, 0); PG8_STAGE(PG8_SA(0, 1), a2 + hstep, voffA);
;             PG8_WAIT_L(8); PG8_BAR; PG8_WAIT_L(0); PG8_MMA(0, 0, At, B0); PG8_BAR; PG8_SCHED;
	s_waitcnt lgkmcnt(0)
	v_mfma_f32_16x16x32_bf16 v[112:115], v[206:209], v[156:159], v[112:115]
	v_mfma_f32_16x16x32_bf16 v[116:119], v[232:235], v[156:159], v[116:119]
	v_mfma_f32_16x16x32_bf16 v[96:99], v[206:209], v[164:167], v[96:99]
	v_mfma_f32_16x16x32_bf16 v[100:103], v[232:235], v[164:167], v[100:103]
	v_mfma_f32_16x16x32_bf16 v[80:83], v[206:209], v[172:175], v[80:83]
	v_mfma_f32_16x16x32_bf16 v[84:87], v[232:235], v[172:175], v[84:87]
	v_mfma_f32_16x16x32_bf16 v[64:67], v[206:209], v[198:201], v[64:67]
	v_mfma_f32_16x16x32_bf16 v[68:71], v[232:235], v[198:201], v[68:71]
	v_mfma_f32_16x16x32_bf16 v[112:115], v[228:231], v[160:163], v[112:115]
	v_mfma_f32_16x16x32_bf16 v[116:119], v[236:239], v[160:163], v[116:119]
	v_mfma_f32_16x16x32_bf16 v[96:99], v[228:231], v[168:171], v[96:99]
	v_mfma_f32_16x16x32_bf16 v[100:103], v[236:239], v[168:171], v[100:103]
	v_mfma_f32_16x16x32_bf16 v[80:83], v[228:231], v[194:197], v[80:83]
	v_mfma_f32_16x16x32_bf16 v[84:87], v[236:239], v[194:197], v[84:87]
	v_mfma_f32_16x16x32_bf16 v[64:67], v[228:231], v[202:205], v[64:67]
	v_mfma_f32_16x16x32_bf16 v[68:71], v[236:239], v[202:205], v[68:71]
	s_barrier
	s_mov_b32 m0, s23
	v_lshl_add_u64 v[220:221], s[48:49], 0, v[178:179]
	ds_read_b128 v[156:159], v139 offset:16384
	ds_read_b128 v[160:163], v139 offset:17408
	ds_read_b128 v[164:167], v139 offset:18432
	ds_read_b128 v[168:171], v139 offset:19456
	ds_read_b128 v[172:175], v139 offset:20480
	ds_read_b128 v[194:197], v139 offset:21504
	ds_read_b128 v[198:201], v139 offset:22528
	ds_read_b128 v[202:205], v139 offset:23552
	global_load_lds_dwordx4 v[220:221], off
	v_lshl_add_u64 v[222:223], s[48:49], 0, v[128:129]
	s_mov_b32 m0, s24
	s_nop 0
	global_load_lds_dwordx4 v[222:223], off
	s_barrier
	s_waitcnt lgkmcnt(0)
	v_mfma_f32_16x16x32_bf16 v[56:59], v[140:143], v[156:159], v[56:59]
	v_mfma_f32_16x16x32_bf16 v[60:63], v[148:151], v[156:159], v[60:63]
	v_mfma_f32_16x16x32_bf16 v[40:43], v[140:143], v[164:167], v[40:43]
	v_mfma_f32_16x16x32_bf16 v[44:47], v[148:151], v[164:167], v[44:47]
	v_mfma_f32_16x16x32_bf16 v[24:27], v[140:143], v[172:175], v[24:27]
	v_mfma_f32_16x16x32_bf16 v[28:31], v[148:151], v[172:175], v[28:31]
	v_mfma_f32_16x16x32_bf16 v[8:11], v[140:143], v[198:201], v[8:11]
	v_mfma_f32_16x16x32_bf16 v[12:15], v[148:151], v[198:201], v[12:15]
	v_mfma_f32_16x16x32_bf16 v[56:59], v[144:147], v[160:163], v[56:59]
	v_mfma_f32_16x16x32_bf16 v[60:63], v[152:155], v[160:163], v[60:63]
	v_mfma_f32_16x16x32_bf16 v[40:43], v[144:147], v[168:171], v[40:43]
	v_mfma_f32_16x16x32_bf16 v[44:47], v[152:155], v[168:171], v[44:47]
	v_mfma_f32_16x16x32_bf16 v[24:27], v[144:147], v[194:197], v[24:27]
	v_mfma_f32_16x16x32_bf16 v[28:31], v[152:155], v[194:197], v[28:31]
	v_mfma_f32_16x16x32_bf16 v[8:11], v[144:147], v[202:205], v[8:11]
	v_mfma_f32_16x16x32_bf16 v[12:15], v[152:155], v[202:205], v[12:15]
	s_barrier
	s_add_u32 s30, s46, 0x80000
	s_addc_u32 s31, s47, 0
	s_add_i32 s57, s58, s22
	v_lshl_add_u64 v[140:141], s[30:31], 0, v[178:179]
	s_mov_b32 m0, s57
	s_nop 0
	global_load_lds_dwordx4 v[140:141], off
	v_lshl_add_u64 v[140:141], s[30:31], 0, v[128:129]
	s_add_i32 m0, s57, 0x2000
	s_nop 0
	global_load_lds_dwordx4 v[140:141], off
	s_waitcnt vmcnt(6)
	s_barrier
	v_mfma_f32_16x16x32_bf16 v[48:51], v[206:209], v[156:159], v[48:51]
	v_mfma_f32_16x16x32_bf16 v[52:55], v[232:235], v[156:159], v[52:55]
	v_mfma_f32_16x16x32_bf16 v[32:35], v[206:209], v[164:167], v[32:35]
	v_mfma_f32_16x16x32_bf16 v[36:39], v[232:235], v[164:167], v[36:39]
	v_mfma_f32_16x16x32_bf16 v[16:19], v[206:209], v[172:175], v[16:19]
	v_mfma_f32_16x16x32_bf16 v[20:23], v[232:235], v[172:175], v[20:23]
	v_mfma_f32_16x16x32_bf16 v[0:3], v[206:209], v[198:201], v[0:3]
	v_mfma_f32_16x16x32_bf16 v[4:7], v[232:235], v[198:201], v[4:7]
	v_mfma_f32_16x16x32_bf16 v[48:51], v[228:231], v[160:163], v[48:51]
	v_mfma_f32_16x16x32_bf16 v[52:55], v[236:239], v[160:163], v[52:55]
	v_mfma_f32_16x16x32_bf16 v[32:35], v[228:231], v[168:171], v[32:35]
	v_mfma_f32_16x16x32_bf16 v[36:39], v[236:239], v[168:171], v[36:39]
	v_mfma_f32_16x16x32_bf16 v[16:19], v[228:231], v[194:197], v[16:19]
	v_mfma_f32_16x16x32_bf16 v[20:23], v[236:239], v[194:197], v[20:23]
	v_mfma_f32_16x16x32_bf16 v[0:3], v[228:231], v[202:205], v[0:3]
	v_mfma_f32_16x16x32_bf16 v[4:7], v[236:239], v[202:205], v[4:7]
	s_barrier
	s_add_i32 s57, 0, 0x18000
	v_add_u32_e32 v152, s57, v137
	ds_read_b128 v[140:143], v152
	ds_read_b128 v[144:147], v152 offset:1024
	ds_read_b128 v[148:151], v152 offset:2048
	ds_read_b128 v[152:155], v152 offset:3072
	s_add_u32 s30, s48, 0x80000
	s_addc_u32 s31, s49, 0
	s_mov_b32 m0, s25
	v_lshl_add_u64 v[206:207], s[30:31], 0, v[178:179]
	ds_read_b128 v[156:159], v139 offset:32768
	ds_read_b128 v[160:163], v139 offset:33792
	ds_read_b128 v[164:167], v139 offset:34816
	ds_read_b128 v[168:171], v139 offset:35840
	ds_read_b128 v[172:175], v139 offset:36864
	ds_read_b128 v[194:197], v139 offset:37888
	ds_read_b128 v[198:201], v139 offset:38912
	ds_read_b128 v[202:205], v139 offset:39936
	global_load_lds_dwordx4 v[206:207], off
	v_lshl_add_u64 v[206:207], s[30:31], 0, v[128:129]
	s_mov_b32 m0, s50
	s_nop 0
	global_load_lds_dwordx4 v[206:207], off
	s_waitcnt lgkmcnt(8)
	s_barrier
; #define PG8_STAGE(bufoff, gbase, voff) do { _Pragma("unroll") for (int _i = 0; _i < 2; ++_i) \
;         __builtin_amdgcn_global_load_lds((const unsigned*)((const char*)(gbase) + (voff)[_i]), (LAS unsigned*)(lds + (bufoff) + ldsw + _i * 8192), 16, 0, 0); } while (0)
; #define PG8_LDA(dst, b, h) do { _Pragma("unroll") for (int m = 0; m < 4; ++m) _Pragma("unroll") for (int k = 0; k < 2; ++k) dst[m][k] = *(const LAS bf16x8*)(lds + PG8_SA(b, h) + aoff + m * 2048 + k * 1024); } while (0)
; #define PG8_LDB(dst, b, h) do { _Pragma("unroll") for (int n = 0; n < 2; ++n) _Pragma("unroll") for (int k = 0; k < 2; ++k) dst[n][k] = *(const LAS bf16x8*)(lds + PG8_SB(b, h) + boff + n * 2048 + k * 1024); } while (0)
; #define PG8_MMA(ai, bj, At, Bt) do { __builtin_amdgcn_s_setprio(1); _Pragma("unroll") for (int m = 0; m < 4; ++m) _Pragma("unroll") for (int n = 0; n < 2; ++n) _Pragma("unroll") for (int k = 0; k < 2; ++k) \
;         acc[ai][bj][m][n] = __builtin_amdgcn_mfma_f32_16x16x32_bf16(Bt[n][k], At[m][k], acc[ai][bj][m][n], 0, 0, 0); __builtin_amdgcn_s_setprio(0); } while (0)
; #define PG8_WAIT_V(n) asm volatile("s_waitcnt vmcnt(" #n ")" ::: "memory")
; #define PG8_WAIT_L(n) asm volatile("s_waitcnt lgkmcnt(" #n ")" ::: "memory")
; #define PG8_BAR __builtin_amdgcn_s_barrier()
; #define PG8_SCHED __builtin_amdgcn_sched_barrier(0)
; template <class Epi>
; __device__ __forceinline__ void gemm_phase(LAS unsigned char* lds, const Gemm g, const StaticOrder S, const Epi E) {
;     ...
;             PG8_WAIT_L(8); PG8_BAR; PG8_WAIT_L(0); PG8_MMA(0, 0, At, B0); PG8_BAR; PG8_SCHED;
;             PG8_LDB(B1, 1, 1); PG8_STAGE(PG8_SB(1, 0), b3, voffA);
;             PG8_BAR; PG8_WAIT_L(0); PG8_MMA(0, 1, At, B1); PG8_BAR;
;             PG8_LDA(At, 1, 1); PG8_STAGE(PG8_SA(1, 0), a3, voffA);
;             PG8_BAR; PG8_WAIT_L(0); PG8_MMA(1, 0, At, B0); PG8_BAR; PG8_SCHED;
;             PG8_STAGE(PG8_SB(1, 1), b3 + hstep, voffA);
;             PG8_WAIT_V(6); PG8_BAR; PG8_MMA(1, 1, At, B1); PG8_BAR;
;         }
	s_waitcnt lgkmcnt(0)
	v_mfma_f32_16x16x32_bf16 v[120:123], v[140:143], v[156:159], v[120:123]
	v_mfma_f32_16x16x32_bf16 v[124:127], v[148:151], v[156:159], v[124:127]
	v_mfma_f32_16x16x32_bf16 v[104:107], v[140:143], v[164:167], v[104:107]
	v_mfma_f32_16x16x32_bf16 v[108:111], v[148:151], v[164:167], v[108:111]
	v_mfma_f32_16x16x32_bf16 v[88:91], v[140:143], v[172:175], v[88:91]
	v_mfma_f32_16x16x32_bf16 v[92:95], v[148:151], v[172:175], v[92:95]
	v_mfma_f32_16x16x32_bf16 v[72:75], v[140:143], v[198:201], v[72:75]
	v_mfma_f32_16x16x32_bf16 v[76:79], v[148:151], v[198:201], v[76:79]
	v_mfma_f32_16x16x32_bf16 v[120:123], v[144:147], v[160:163], v[120:123]
	v_mfma_f32_16x16x32_bf16 v[124:127], v[152:155], v[160:163], v[124:127]
	v_mfma_f32_16x16x32_bf16 v[104:107], v[144:147], v[168:171], v[104:107]
	v_mfma_f32_16x16x32_bf16 v[108:111], v[152:155], v[168:171], v[108:111]
	v_mfma_f32_16x16x32_bf16 v[88:91], v[144:147], v[194:197], v[88:91]
	v_mfma_f32_16x16x32_bf16 v[92:95], v[152:155], v[194:197], v[92:95]
	v_mfma_f32_16x16x32_bf16 v[72:75], v[144:147], v[202:205], v[72:75]
	v_mfma_f32_16x16x32_bf16 v[76:79], v[152:155], v[202:205], v[76:79]
	s_barrier
	s_add_i32 s48, 0, 0x1c000
	s_add_i32 s30, s57, s22
	v_add_u32_e32 v227, s48, v137
	v_lshl_add_u64 v[134:135], v[134:135], 0, s[34:35]
	s_mov_b32 m0, s30
	ds_read_b128 v[206:209], v227
	ds_read_b128 v[228:231], v227 offset:1024
	ds_read_b128 v[232:235], v227 offset:2048
	ds_read_b128 v[236:239], v227 offset:3072
	global_load_lds_dwordx4 v[134:135], off
	v_lshl_add_u64 v[134:135], v[210:211], 0, s[34:35]
	s_add_i32 m0, s30, 0x2000
	s_nop 0
	global_load_lds_dwordx4 v[134:135], off
	s_barrier
	s_waitcnt lgkmcnt(0)
	v_mfma_f32_16x16x32_bf16 v[112:115], v[206:209], v[156:159], v[112:115]
	v_mfma_f32_16x16x32_bf16 v[116:119], v[232:235], v[156:159], v[116:119]
	v_mfma_f32_16x16x32_bf16 v[96:99], v[206:209], v[164:167], v[96:99]
	v_mfma_f32_16x16x32_bf16 v[100:103], v[232:235], v[164:167], v[100:103]
	v_mfma_f32_16x16x32_bf16 v[80:83], v[206:209], v[172:175], v[80:83]
	v_mfma_f32_16x16x32_bf16 v[84:87], v[232:235], v[172:175], v[84:87]
	v_mfma_f32_16x16x32_bf16 v[64:67], v[206:209], v[198:201], v[64:67]
	v_mfma_f32_16x16x32_bf16 v[68:71], v[232:235], v[198:201], v[68:71]
	v_mfma_f32_16x16x32_bf16 v[112:115], v[228:231], v[160:163], v[112:115]
	v_mfma_f32_16x16x32_bf16 v[116:119], v[236:239], v[160:163], v[116:119]
	v_mfma_f32_16x16x32_bf16 v[96:99], v[228:231], v[168:171], v[96:99]
	v_mfma_f32_16x16x32_bf16 v[100:103], v[236:239], v[168:171], v[100:103]
	v_mfma_f32_16x16x32_bf16 v[80:83], v[228:231], v[194:197], v[80:83]
	v_mfma_f32_16x16x32_bf16 v[84:87], v[236:239], v[194:197], v[84:87]
	v_mfma_f32_16x16x32_bf16 v[64:67], v[228:231], v[202:205], v[64:67]
	v_mfma_f32_16x16x32_bf16 v[68:71], v[236:239], v[202:205], v[68:71]
	s_barrier
	s_mov_b32 m0, s51
	v_lshl_add_u64 v[134:135], v[220:221], 0, s[34:35]
	ds_read_b128 v[156:159], v139 offset:49152
	ds_read_b128 v[160:163], v139 offset:50176
	ds_read_b128 v[164:167], v139 offset:51200
	ds_read_b128 v[168:171], v139 offset:52224
	ds_read_b128 v[172:175], v139 offset:53248
	ds_read_b128 v[194:197], v139 offset:54272
	ds_read_b128 v[198:201], v139 offset:55296
	ds_read_b128 v[202:205], v139 offset:56320
	global_load_lds_dwordx4 v[134:135], off
	v_lshl_add_u64 v[134:135], v[222:223], 0, s[34:35]
	s_mov_b32 m0, s52
	s_nop 0
	global_load_lds_dwordx4 v[134:135], off
	s_barrier
	s_waitcnt lgkmcnt(0)
	v_mfma_f32_16x16x32_bf16 v[56:59], v[140:143], v[156:159], v[56:59]
	v_mfma_f32_16x16x32_bf16 v[60:63], v[148:151], v[156:159], v[60:63]
	v_mfma_f32_16x16x32_bf16 v[40:43], v[140:143], v[164:167], v[40:43]
	v_mfma_f32_16x16x32_bf16 v[44:47], v[148:151], v[164:167], v[44:47]
	v_mfma_f32_16x16x32_bf16 v[24:27], v[140:143], v[172:175], v[24:27]
	v_mfma_f32_16x16x32_bf16 v[28:31], v[148:151], v[172:175], v[28:31]
	v_mfma_f32_16x16x32_bf16 v[8:11], v[140:143], v[198:201], v[8:11]
	v_mfma_f32_16x16x32_bf16 v[12:15], v[148:151], v[198:201], v[12:15]
	v_mfma_f32_16x16x32_bf16 v[56:59], v[144:147], v[160:163], v[56:59]
	v_mfma_f32_16x16x32_bf16 v[60:63], v[152:155], v[160:163], v[60:63]
	v_mfma_f32_16x16x32_bf16 v[40:43], v[144:147], v[168:171], v[40:43]
	v_mfma_f32_16x16x32_bf16 v[44:47], v[152:155], v[168:171], v[44:47]
	v_mfma_f32_16x16x32_bf16 v[24:27], v[144:147], v[194:197], v[24:27]
	v_mfma_f32_16x16x32_bf16 v[28:31], v[152:155], v[194:197], v[28:31]
	v_mfma_f32_16x16x32_bf16 v[8:11], v[144:147], v[202:205], v[8:11]
	v_mfma_f32_16x16x32_bf16 v[12:15], v[152:155], v[202:205], v[12:15]
	s_barrier
	s_add_u32 s30, s46, 0x80080
	s_addc_u32 s31, s47, 0
	s_add_i32 s46, s48, s22
	v_lshl_add_u64 v[134:135], s[30:31], 0, v[178:179]
	s_mov_b32 m0, s46
	s_nop 0
	global_load_lds_dwordx4 v[134:135], off
	v_lshl_add_u64 v[134:135], s[30:31], 0, v[128:129]
	s_add_i32 m0, s46, 0x2000
	s_nop 0
	global_load_lds_dwordx4 v[134:135], off
	s_waitcnt vmcnt(6)
	s_barrier
	v_mfma_f32_16x16x32_bf16 v[48:51], v[206:209], v[156:159], v[48:51]
	v_mfma_f32_16x16x32_bf16 v[52:55], v[232:235], v[156:159], v[52:55]
	v_mfma_f32_16x16x32_bf16 v[32:35], v[206:209], v[164:167], v[32:35]
	v_mfma_f32_16x16x32_bf16 v[36:39], v[232:235], v[164:167], v[36:39]
	v_mfma_f32_16x16x32_bf16 v[16:19], v[206:209], v[172:175], v[16:19]
	v_mfma_f32_16x16x32_bf16 v[20:23], v[232:235], v[172:175], v[20:23]
	v_mfma_f32_16x16x32_bf16 v[0:3], v[206:209], v[198:201], v[0:3]
	v_mfma_f32_16x16x32_bf16 v[4:7], v[232:235], v[198:201], v[4:7]
	v_mfma_f32_16x16x32_bf16 v[48:51], v[228:231], v[160:163], v[48:51]
	v_mfma_f32_16x16x32_bf16 v[52:55], v[236:239], v[160:163], v[52:55]
	v_mfma_f32_16x16x32_bf16 v[32:35], v[228:231], v[168:171], v[32:35]
	v_mfma_f32_16x16x32_bf16 v[36:39], v[236:239], v[168:171], v[36:39]
	v_mfma_f32_16x16x32_bf16 v[16:19], v[228:231], v[194:197], v[16:19]
	v_mfma_f32_16x16x32_bf16 v[20:23], v[236:239], v[194:197], v[20:23]
	v_mfma_f32_16x16x32_bf16 v[0:3], v[228:231], v[202:205], v[0:3]
	v_mfma_f32_16x16x32_bf16 v[4:7], v[236:239], v[202:205], v[4:7]
	s_barrier
	s_add_i32 s56, s56, 2
	s_add_u32 s44, s44, 0x100
	s_addc_u32 s45, s45, 0
	s_add_u32 s54, s54, 0x100
	s_addc_u32 s55, s55, 0
	s_cmp_gt_u32 s56, 29
	s_cbranch_scc0 .LBB0_2219

; #define PG8_STAGE(bufoff, gbase, voff) do { _Pragma("unroll") for (int _i = 0; _i < 2; ++_i) \
;         __builtin_amdgcn_global_load_lds((const unsigned*)((const char*)(gbase) + (voff)[_i]), (LAS unsigned*)(lds + (bufoff) + ldsw + _i * 8192), 16, 0, 0); } while (0)
; #define PG8_LDA(dst, b, h) do { _Pragma("unroll") for (int m = 0; m < 4; ++m) _Pragma("unroll") for (int k = 0; k < 2; ++k) dst[m][k] = *(const LAS bf16x8*)(lds + PG8_SA(b, h) + aoff + m * 2048 + k * 1024); } while (0)
; #define PG8_LDB(dst, b, h) do { _Pragma("unroll") for (int n = 0; n < 2; ++n) _Pragma("unroll") for (int k = 0; k < 2; ++k) dst[n][k] = *(const LAS bf16x8*)(lds + PG8_SB(b, h) + boff + n * 2048 + k * 1024); } while (0)
; #define PG8_MMA(ai, bj, At, Bt) do { __builtin_amdgcn_s_setprio(1); _Pragma("unroll") for (int m = 0; m < 4; ++m) _Pragma("unroll") for (int n = 0; n < 2; ++n) _Pragma("unroll") for (int k = 0; k < 2; ++k) \
;         acc[ai][bj][m][n] = __builtin_amdgcn_mfma_f32_16x16x32_bf16(Bt[n][k], At[m][k], acc[ai][bj][m][n], 0, 0, 0); __builtin_amdgcn_s_setprio(0); } while (0)
; template <class Epi>
; __device__ __forceinline__ void gemm_phase(LAS unsigned char* lds, const Gemm g, const StaticOrder S, const Epi E) {
;     ...
;         const bool has_next = S.next(ui + 1, nxt);
;         const char* nA = has_next ? (const char*)g.A + (size_t)nxt.pm * tstep + (size_t)nxt.k0 * kstep : cA; const char* nB = has_next ? (const char*)g.Bt + (size_t)nxt.pn * tstep + (size_t)nxt.k0 * kstep : cB;
;         const int nt = cur.nk;
;         for (int t = 0; t < nt; t += 2) {
;             const bool last = (t == nt - 2);
;             const char* a1 = cA + (size_t)(t + 1) * kstep;
;             const char* a2 = last ? nA : cA + (size_t)(t + 2) * kstep; const char* b2 = last ? nB : cB + (size_t)(t + 2) * kstep;
;             const char* a3 = a2 + kstep; const char* b3 = b2 + kstep;
;             PG8_LDB(B0, 0, 0); PG8_SCHED; PG8_LDA(At, 0, 0); PG8_STAGE(PG8_SA(1, 1), a1 + hstep, voffA);
;             PG8_WAIT_L(8); PG8_BAR; PG8_WAIT_L(0); PG8_MMA(0, 0, At, B0); PG8_BAR; PG8_SCHED;
;             PG8_LDB(B1, 0, 1); PG8_STAGE(PG8_SB(0, 0), b2, voffA);
;             PG8_BAR; PG8_WAIT_L(0); PG8_MMA(0, 1, At, B1); PG8_BAR;
;             PG8_LDA(At, 0, 1); PG8_STAGE(PG8_SA(0, 0), a2, voffA);
;             PG8_BAR; PG8_WAIT_L(0); PG8_MMA(1, 0, At, B0); PG8_BAR; PG8_SCHED;
.LBB0_2572:
	s_add_i32 s11, s63, -2
	s_add_u32 s64, s64, 0x100
	s_addc_u32 s65, s65, 0
	s_mov_b32 s50, 0
	s_add_i32 s66, s50, 2
	s_add_u32 s48, s38, 0x100
	s_addc_u32 s49, s39, 0
	s_add_i32 s30, 0, 0x10000
	v_add_u32_e32 v140, s30, v228
	ds_read_b128 v[128:131], v140
	ds_read_b128 v[132:135], v140 offset:1024
	ds_read_b128 v[136:139], v140 offset:2048
	ds_read_b128 v[140:143], v140 offset:3072
	s_cmp_eq_u32 s11, s50
	s_cselect_b32 s50, s46, s64
	s_cselect_b32 s53, s43, s49
	s_cselect_b32 s52, s42, s48
	s_cselect_b32 s51, s47, s65
	v_lshl_add_u64 v[200:201], s[38:39], 0, v[196:197]
	s_add_i32 m0, s23, 0xc000
	ds_read_b128 v[144:147], v230
	ds_read_b128 v[148:151], v230 offset:1024
	ds_read_b128 v[152:155], v230 offset:2048
	ds_read_b128 v[156:159], v230 offset:3072
	ds_read_b128 v[160:163], v230 offset:4096
	ds_read_b128 v[164:167], v230 offset:5120
	ds_read_b128 v[168:171], v230 offset:6144
	ds_read_b128 v[172:175], v230 offset:7168
	global_load_lds_dwordx4 v[200:201], off
	v_lshl_add_u64 v[200:201], s[38:39], 0, v[198:199]
	s_add_i32 m0, s23, 0xe000
	s_nop 0
	global_load_lds_dwordx4 v[200:201], off
	s_waitcnt lgkmcnt(8)
	s_barrier
	s_waitcnt lgkmcnt(0)
	v_mfma_f32_16x16x32_bf16 v[124:127], v[128:131], v[144:147], 0
	v_mfma_f32_16x16x32_bf16 v[120:123], v[136:139], v[144:147], 0
	v_mfma_f32_16x16x32_bf16 v[112:115], v[128:131], v[152:155], 0
	v_mfma_f32_16x16x32_bf16 v[104:107], v[136:139], v[152:155], 0
	v_mfma_f32_16x16x32_bf16 v[92:95], v[128:131], v[160:163], 0
	v_mfma_f32_16x16x32_bf16 v[88:91], v[136:139], v[160:163], 0
	v_mfma_f32_16x16x32_bf16 v[80:83], v[128:131], v[168:171], 0
	v_mfma_f32_16x16x32_bf16 v[72:75], v[136:139], v[168:171], 0
	v_mfma_f32_16x16x32_bf16 v[124:127], v[132:135], v[148:151], v[124:127]
	v_mfma_f32_16x16x32_bf16 v[120:123], v[140:143], v[148:151], v[120:123]
	v_mfma_f32_16x16x32_bf16 v[112:115], v[132:135], v[156:159], v[112:115]
	v_mfma_f32_16x16x32_bf16 v[104:107], v[140:143], v[156:159], v[104:107]
	v_mfma_f32_16x16x32_bf16 v[92:95], v[132:135], v[164:167], v[92:95]
	v_mfma_f32_16x16x32_bf16 v[88:91], v[140:143], v[164:167], v[88:91]
	v_mfma_f32_16x16x32_bf16 v[80:83], v[132:135], v[172:175], v[80:83]
	v_mfma_f32_16x16x32_bf16 v[72:75], v[140:143], v[172:175], v[72:75]
	s_barrier
	s_add_i32 s38, 0, 0x14000
	v_add_u32_e32 v220, s38, v228
	s_add_i32 s30, s30, s22
	ds_read_b128 v[200:203], v220
	ds_read_b128 v[204:207], v220 offset:1024
	ds_read_b128 v[208:211], v220 offset:2048
	ds_read_b128 v[232:235], v220 offset:3072
	v_lshl_add_u64 v[220:221], s[50:51], 0, v[178:179]
	s_mov_b32 m0, s30
	v_lshl_add_u64 v[222:223], s[50:51], 0, v[194:195]
	global_load_lds_dwordx4 v[220:221], off
	s_add_i32 m0, s30, 0x2000
	s_nop 0
	global_load_lds_dwordx4 v[222:223], off
	s_barrier
	s_waitcnt lgkmcnt(0)
	v_mfma_f32_16x16x32_bf16 v[116:119], v[200:203], v[144:147], 0
	v_mfma_f32_16x16x32_bf16 v[108:111], v[208:211], v[144:147], 0
	v_mfma_f32_16x16x32_bf16 v[100:103], v[200:203], v[152:155], 0
	v_mfma_f32_16x16x32_bf16 v[96:99], v[208:211], v[152:155], 0
	v_mfma_f32_16x16x32_bf16 v[84:87], v[200:203], v[160:163], 0
	v_mfma_f32_16x16x32_bf16 v[76:79], v[208:211], v[160:163], 0
	v_mfma_f32_16x16x32_bf16 v[68:71], v[200:203], v[168:171], 0
	v_mfma_f32_16x16x32_bf16 v[64:67], v[208:211], v[168:171], 0
	v_mfma_f32_16x16x32_bf16 v[116:119], v[204:207], v[148:151], v[116:119]
	v_mfma_f32_16x16x32_bf16 v[108:111], v[232:235], v[148:151], v[108:111]
	v_mfma_f32_16x16x32_bf16 v[100:103], v[204:207], v[156:159], v[100:103]
	v_mfma_f32_16x16x32_bf16 v[96:99], v[232:235], v[156:159], v[96:99]
	v_mfma_f32_16x16x32_bf16 v[84:87], v[204:207], v[164:167], v[84:87]
	v_mfma_f32_16x16x32_bf16 v[76:79], v[232:235], v[164:167], v[76:79]
	v_mfma_f32_16x16x32_bf16 v[68:71], v[204:207], v[172:175], v[68:71]
	v_mfma_f32_16x16x32_bf16 v[64:67], v[232:235], v[172:175], v[64:67]
	s_barrier
	s_mov_b32 m0, s23
	v_lshl_add_u64 v[236:237], s[52:53], 0, v[178:179]
	ds_read_b128 v[144:147], v230 offset:16384
	ds_read_b128 v[148:151], v230 offset:17408
	ds_read_b128 v[152:155], v230 offset:18432
	ds_read_b128 v[156:159], v230 offset:19456
	ds_read_b128 v[160:163], v230 offset:20480
	ds_read_b128 v[164:167], v230 offset:21504
	ds_read_b128 v[168:171], v230 offset:22528
	ds_read_b128 v[172:175], v230 offset:23552
	global_load_lds_dwordx4 v[236:237], off
	v_lshl_add_u64 v[238:239], s[52:53], 0, v[194:195]
	s_mov_b32 m0, s24
	s_nop 0
	global_load_lds_dwordx4 v[238:239], off
	s_barrier
	s_waitcnt lgkmcnt(0)
	v_mfma_f32_16x16x32_bf16 v[60:63], v[128:131], v[144:147], 0
	v_mfma_f32_16x16x32_bf16 v[56:59], v[136:139], v[144:147], 0
	v_mfma_f32_16x16x32_bf16 v[48:51], v[128:131], v[152:155], 0
	v_mfma_f32_16x16x32_bf16 v[40:43], v[136:139], v[152:155], 0
	v_mfma_f32_16x16x32_bf16 v[28:31], v[128:131], v[160:163], 0
	v_mfma_f32_16x16x32_bf16 v[24:27], v[136:139], v[160:163], 0
	v_mfma_f32_16x16x32_bf16 v[16:19], v[128:131], v[168:171], 0
	v_mfma_f32_16x16x32_bf16 v[8:11], v[136:139], v[168:171], 0
	v_mfma_f32_16x16x32_bf16 v[60:63], v[132:135], v[148:151], v[60:63]
	v_mfma_f32_16x16x32_bf16 v[56:59], v[140:143], v[148:151], v[56:59]
	v_mfma_f32_16x16x32_bf16 v[48:51], v[132:135], v[156:159], v[48:51]
	v_mfma_f32_16x16x32_bf16 v[40:43], v[140:143], v[156:159], v[40:43]
	v_mfma_f32_16x16x32_bf16 v[28:31], v[132:135], v[164:167], v[28:31]
	v_mfma_f32_16x16x32_bf16 v[24:27], v[140:143], v[164:167], v[24:27]
	v_mfma_f32_16x16x32_bf16 v[16:19], v[132:135], v[172:175], v[16:19]
	v_mfma_f32_16x16x32_bf16 v[8:11], v[140:143], v[172:175], v[8:11]
	s_barrier
; #define PG8_STAGE(bufoff, gbase, voff) do { _Pragma("unroll") for (int _i = 0; _i < 2; ++_i) \
;         __builtin_amdgcn_global_load_lds((const unsigned*)((const char*)(gbase) + (voff)[_i]), (LAS unsigned*)(lds + (bufoff) + ldsw + _i * 8192), 16, 0, 0); } while (0)
; #define PG8_LDA(dst, b, h) do { _Pragma("unroll") for (int m = 0; m < 4; ++m) _Pragma("unroll") for (int k = 0; k < 2; ++k) dst[m][k] = *(const LAS bf16x8*)(lds + PG8_SA(b, h) + aoff + m * 2048 + k * 1024); } while (0)
; #define PG8_LDB(dst, b, h) do { _Pragma("unroll") for (int n = 0; n < 2; ++n) _Pragma("unroll") for (int k = 0; k < 2; ++k) dst[n][k] = *(const LAS bf16x8*)(lds + PG8_SB(b, h) + boff + n * 2048 + k * 1024); } while (0)
; #define PG8_MMA(ai, bj, At, Bt) do { __builtin_amdgcn_s_setprio(1); _Pragma("unroll") for (int m = 0; m < 4; ++m) _Pragma("unroll") for (int n = 0; n < 2; ++n) _Pragma("unroll") for (int k = 0; k < 2; ++k) \
;         acc[ai][bj][m][n] = __builtin_amdgcn_mfma_f32_16x16x32_bf16(Bt[n][k], At[m][k], acc[ai][bj][m][n], 0, 0, 0); __builtin_amdgcn_s_setprio(0); } while (0)
; #define PG8_WAIT_V(n) asm volatile("s_waitcnt vmcnt(" #n ")" ::: "memory")
; #define PG8_WAIT_L(n) asm volatile("s_waitcnt lgkmcnt(" #n ")" ::: "memory")
; #define PG8_BAR __builtin_amdgcn_s_barrier()
; #define PG8_SCHED __builtin_amdgcn_sched_barrier(0)
; template <class Epi>
; __device__ __forceinline__ void gemm_phase(LAS unsigned char* lds, const Gemm g, const StaticOrder S, const Epi E) {
;     ...
;             PG8_STAGE(PG8_SB(0, 1), b2 + hstep, voffA);
;             PG8_WAIT_V(6); PG8_BAR; PG8_MMA(1, 1, At, B1); PG8_BAR;
;             PG8_LDB(B0, 1, 0); PG8_SCHED; PG8_LDA(At, 1, 0); PG8_STAGE(PG8_SA(0, 1), a2 + hstep, voffA);
;             PG8_WAIT_L(8); PG8_BAR; PG8_WAIT_L(0); PG8_MMA(0, 0, At, B0); PG8_BAR; PG8_SCHED;
;             PG8_LDB(B1, 1, 1); PG8_STAGE(PG8_SB(1, 0), b3, voffA);
;             PG8_BAR; PG8_WAIT_L(0); PG8_MMA(0, 1, At, B1); PG8_BAR;
;             PG8_LDA(At, 1, 1); PG8_STAGE(PG8_SA(1, 0), a3, voffA);
	s_add_u32 s30, s50, 0x158000
	s_addc_u32 s31, s51, 0
	s_add_i32 s38, s38, s22
	v_lshl_add_u64 v[128:129], s[30:31], 0, v[178:179]
	s_mov_b32 m0, s38
	s_nop 0
	global_load_lds_dwordx4 v[128:129], off
	v_lshl_add_u64 v[128:129], s[30:31], 0, v[194:195]
	s_add_i32 m0, s38, 0x2000
	s_nop 0
	global_load_lds_dwordx4 v[128:129], off
	s_waitcnt vmcnt(6)
	s_barrier
	v_mfma_f32_16x16x32_bf16 v[52:55], v[200:203], v[144:147], 0
	v_mfma_f32_16x16x32_bf16 v[44:47], v[208:211], v[144:147], 0
	v_mfma_f32_16x16x32_bf16 v[36:39], v[200:203], v[152:155], 0
	v_mfma_f32_16x16x32_bf16 v[32:35], v[208:211], v[152:155], 0
	v_mfma_f32_16x16x32_bf16 v[20:23], v[200:203], v[160:163], 0
	v_mfma_f32_16x16x32_bf16 v[12:15], v[208:211], v[160:163], 0
	v_mfma_f32_16x16x32_bf16 v[4:7], v[200:203], v[168:171], 0
	v_mfma_f32_16x16x32_bf16 v[0:3], v[208:211], v[168:171], 0
	v_mfma_f32_16x16x32_bf16 v[52:55], v[204:207], v[148:151], v[52:55]
	v_mfma_f32_16x16x32_bf16 v[44:47], v[232:235], v[148:151], v[44:47]
	v_mfma_f32_16x16x32_bf16 v[36:39], v[204:207], v[156:159], v[36:39]
	v_mfma_f32_16x16x32_bf16 v[32:35], v[232:235], v[156:159], v[32:35]
	v_mfma_f32_16x16x32_bf16 v[20:23], v[204:207], v[164:167], v[20:23]
	v_mfma_f32_16x16x32_bf16 v[12:15], v[232:235], v[164:167], v[12:15]
	v_mfma_f32_16x16x32_bf16 v[4:7], v[204:207], v[172:175], v[4:7]
	v_mfma_f32_16x16x32_bf16 v[0:3], v[232:235], v[172:175], v[0:3]
	s_barrier
	s_add_i32 s38, 0, 0x18000
	v_add_u32_e32 v140, s38, v228
	ds_read_b128 v[128:131], v140
	ds_read_b128 v[132:135], v140 offset:1024
	ds_read_b128 v[136:139], v140 offset:2048
	ds_read_b128 v[140:143], v140 offset:3072
	s_add_u32 s30, s52, 0x158000
	s_addc_u32 s31, s53, 0
	s_mov_b32 m0, s25
	v_lshl_add_u64 v[200:201], s[30:31], 0, v[178:179]
	ds_read_b128 v[144:147], v230 offset:32768
	ds_read_b128 v[148:151], v230 offset:33792
	ds_read_b128 v[152:155], v230 offset:34816
	ds_read_b128 v[156:159], v230 offset:35840
	ds_read_b128 v[160:163], v230 offset:36864
	ds_read_b128 v[164:167], v230 offset:37888
	ds_read_b128 v[168:171], v230 offset:38912
	ds_read_b128 v[172:175], v230 offset:39936
	global_load_lds_dwordx4 v[200:201], off
	v_lshl_add_u64 v[200:201], s[30:31], 0, v[194:195]
	s_mov_b32 m0, s14
	s_nop 0
	global_load_lds_dwordx4 v[200:201], off
	s_waitcnt lgkmcnt(8)
	s_barrier
	s_waitcnt lgkmcnt(0)
	v_mfma_f32_16x16x32_bf16 v[124:127], v[128:131], v[144:147], v[124:127]
	v_mfma_f32_16x16x32_bf16 v[120:123], v[136:139], v[144:147], v[120:123]
	v_mfma_f32_16x16x32_bf16 v[112:115], v[128:131], v[152:155], v[112:115]
	v_mfma_f32_16x16x32_bf16 v[104:107], v[136:139], v[152:155], v[104:107]
	v_mfma_f32_16x16x32_bf16 v[92:95], v[128:131], v[160:163], v[92:95]
	v_mfma_f32_16x16x32_bf16 v[88:91], v[136:139], v[160:163], v[88:91]
	v_mfma_f32_16x16x32_bf16 v[80:83], v[128:131], v[168:171], v[80:83]
	v_mfma_f32_16x16x32_bf16 v[72:75], v[136:139], v[168:171], v[72:75]
	v_mfma_f32_16x16x32_bf16 v[124:127], v[132:135], v[148:151], v[124:127]
	v_mfma_f32_16x16x32_bf16 v[120:123], v[140:143], v[148:151], v[120:123]
	v_mfma_f32_16x16x32_bf16 v[112:115], v[132:135], v[156:159], v[112:115]
	v_mfma_f32_16x16x32_bf16 v[104:107], v[140:143], v[156:159], v[104:107]
	v_mfma_f32_16x16x32_bf16 v[92:95], v[132:135], v[164:167], v[92:95]
	v_mfma_f32_16x16x32_bf16 v[88:91], v[140:143], v[164:167], v[88:91]
	v_mfma_f32_16x16x32_bf16 v[80:83], v[132:135], v[172:175], v[80:83]
	v_mfma_f32_16x16x32_bf16 v[72:75], v[140:143], v[172:175], v[72:75]
	s_barrier
	s_add_i32 s39, 0, 0x1c000
	s_add_i32 s30, s38, s22
	v_add_u32_e32 v231, s39, v228
	v_lshl_add_u64 v[220:221], v[220:221], 0, s[34:35]
	s_mov_b32 m0, s30
	ds_read_b128 v[200:203], v231
	ds_read_b128 v[204:207], v231 offset:1024
	ds_read_b128 v[208:211], v231 offset:2048
	ds_read_b128 v[232:235], v231 offset:3072
	global_load_lds_dwordx4 v[220:221], off
	v_lshl_add_u64 v[220:221], v[222:223], 0, s[34:35]
	s_add_i32 m0, s30, 0x2000
	s_nop 0
	global_load_lds_dwordx4 v[220:221], off
	s_barrier
	s_waitcnt lgkmcnt(0)
	v_mfma_f32_16x16x32_bf16 v[116:119], v[200:203], v[144:147], v[116:119]
	v_mfma_f32_16x16x32_bf16 v[108:111], v[208:211], v[144:147], v[108:111]
	v_mfma_f32_16x16x32_bf16 v[100:103], v[200:203], v[152:155], v[100:103]
	v_mfma_f32_16x16x32_bf16 v[96:99], v[208:211], v[152:155], v[96:99]
	v_mfma_f32_16x16x32_bf16 v[84:87], v[200:203], v[160:163], v[84:87]
	v_mfma_f32_16x16x32_bf16 v[76:79], v[208:211], v[160:163], v[76:79]
	v_mfma_f32_16x16x32_bf16 v[68:71], v[200:203], v[168:171], v[68:71]
	v_mfma_f32_16x16x32_bf16 v[64:67], v[208:211], v[168:171], v[64:67]
	v_mfma_f32_16x16x32_bf16 v[116:119], v[204:207], v[148:151], v[116:119]
	v_mfma_f32_16x16x32_bf16 v[108:111], v[232:235], v[148:151], v[108:111]
	v_mfma_f32_16x16x32_bf16 v[100:103], v[204:207], v[156:159], v[100:103]
	v_mfma_f32_16x16x32_bf16 v[96:99], v[232:235], v[156:159], v[96:99]
	v_mfma_f32_16x16x32_bf16 v[84:87], v[204:207], v[164:167], v[84:87]
	v_mfma_f32_16x16x32_bf16 v[76:79], v[232:235], v[164:167], v[76:79]
	v_mfma_f32_16x16x32_bf16 v[68:71], v[204:207], v[172:175], v[68:71]
	v_mfma_f32_16x16x32_bf16 v[64:67], v[232:235], v[172:175], v[64:67]
	s_barrier
	s_mov_b32 m0, s57
	v_lshl_add_u64 v[220:221], v[236:237], 0, s[34:35]
	ds_read_b128 v[144:147], v230 offset:49152
	ds_read_b128 v[148:151], v230 offset:50176
	ds_read_b128 v[152:155], v230 offset:51200
	ds_read_b128 v[156:159], v230 offset:52224
	ds_read_b128 v[160:163], v230 offset:53248
	ds_read_b128 v[164:167], v230 offset:54272
	ds_read_b128 v[168:171], v230 offset:55296
	ds_read_b128 v[172:175], v230 offset:56320
	global_load_lds_dwordx4 v[220:221], off
	v_lshl_add_u64 v[220:221], v[238:239], 0, s[34:35]
	s_mov_b32 m0, s58
	s_nop 0
	global_load_lds_dwordx4 v[220:221], off
	s_barrier
; #define PG8_STAGE(bufoff, gbase, voff) do { _Pragma("unroll") for (int _i = 0; _i < 2; ++_i) \
;         __builtin_amdgcn_global_load_lds((const unsigned*)((const char*)(gbase) + (voff)[_i]), (LAS unsigned*)(lds + (bufoff) + ldsw + _i * 8192), 16, 0, 0); } while (0)
; #define PG8_LDA(dst, b, h) do { _Pragma("unroll") for (int m = 0; m < 4; ++m) _Pragma("unroll") for (int k = 0; k < 2; ++k) dst[m][k] = *(const LAS bf16x8*)(lds + PG8_SA(b, h) + aoff + m * 2048 + k * 1024); } while (0)
; #define PG8_LDB(dst, b, h) do { _Pragma("unroll") for (int n = 0; n < 2; ++n) _Pragma("unroll") for (int k = 0; k < 2; ++k) dst[n][k] = *(const LAS bf16x8*)(lds + PG8_SB(b, h) + boff + n * 2048 + k * 1024); } while (0)
; #define PG8_MMA(ai, bj, At, Bt) do { __builtin_amdgcn_s_setprio(1); _Pragma("unroll") for (int m = 0; m < 4; ++m) _Pragma("unroll") for (int n = 0; n < 2; ++n) _Pragma("unroll") for (int k = 0; k < 2; ++k) \
;         acc[ai][bj][m][n] = __builtin_amdgcn_mfma_f32_16x16x32_bf16(Bt[n][k], At[m][k], acc[ai][bj][m][n], 0, 0, 0); __builtin_amdgcn_s_setprio(0); } while (0)
; #define PG8_WAIT_V(n) asm volatile("s_waitcnt vmcnt(" #n ")" ::: "memory")
; #define PG8_WAIT_L(n) asm volatile("s_waitcnt lgkmcnt(" #n ")" ::: "memory")
; #define PG8_BAR __builtin_amdgcn_s_barrier()
; #define PG8_SCHED __builtin_amdgcn_sched_barrier(0)
; template <class Epi>
; __device__ __forceinline__ void gemm_phase(LAS unsigned char* lds, const Gemm g, const StaticOrder S, const Epi E) {
;     ...
;         for (int t = 0; t < nt; t += 2) {
;             const bool last = (t == nt - 2);
;             const char* a1 = cA + (size_t)(t + 1) * kstep;
;             const char* a2 = last ? nA : cA + (size_t)(t + 2) * kstep; const char* b2 = last ? nB : cB + (size_t)(t + 2) * kstep;
;             const char* a3 = a2 + kstep; const char* b3 = b2 + kstep;
;             PG8_LDB(B0, 0, 0); PG8_SCHED; PG8_LDA(At, 0, 0); PG8_STAGE(PG8_SA(1, 1), a1 + hstep, voffA);
;             PG8_WAIT_L(8); PG8_BAR; PG8_WAIT_L(0); PG8_MMA(0, 0, At, B0); PG8_BAR; PG8_SCHED;
;             PG8_LDB(B1, 0, 1); PG8_STAGE(PG8_SB(0, 0), b2, voffA);
;     ...
;             PG8_BAR; PG8_WAIT_L(0); PG8_MMA(1, 0, At, B0); PG8_BAR; PG8_SCHED;
;             PG8_STAGE(PG8_SB(1, 1), b3 + hstep, voffA);
;             PG8_WAIT_V(6); PG8_BAR; PG8_MMA(1, 1, At, B1); PG8_BAR;
	s_waitcnt lgkmcnt(0)
	v_mfma_f32_16x16x32_bf16 v[60:63], v[128:131], v[144:147], v[60:63]
	v_mfma_f32_16x16x32_bf16 v[56:59], v[136:139], v[144:147], v[56:59]
	v_mfma_f32_16x16x32_bf16 v[48:51], v[128:131], v[152:155], v[48:51]
	v_mfma_f32_16x16x32_bf16 v[40:43], v[136:139], v[152:155], v[40:43]
	v_mfma_f32_16x16x32_bf16 v[28:31], v[128:131], v[160:163], v[28:31]
	v_mfma_f32_16x16x32_bf16 v[24:27], v[136:139], v[160:163], v[24:27]
	v_mfma_f32_16x16x32_bf16 v[16:19], v[128:131], v[168:171], v[16:19]
	v_mfma_f32_16x16x32_bf16 v[8:11], v[136:139], v[168:171], v[8:11]
	v_mfma_f32_16x16x32_bf16 v[60:63], v[132:135], v[148:151], v[60:63]
	v_mfma_f32_16x16x32_bf16 v[56:59], v[140:143], v[148:151], v[56:59]
	v_mfma_f32_16x16x32_bf16 v[48:51], v[132:135], v[156:159], v[48:51]
	v_mfma_f32_16x16x32_bf16 v[40:43], v[140:143], v[156:159], v[40:43]
	v_mfma_f32_16x16x32_bf16 v[28:31], v[132:135], v[164:167], v[28:31]
	v_mfma_f32_16x16x32_bf16 v[24:27], v[140:143], v[164:167], v[24:27]
	v_mfma_f32_16x16x32_bf16 v[16:19], v[132:135], v[172:175], v[16:19]
	v_mfma_f32_16x16x32_bf16 v[8:11], v[140:143], v[172:175], v[8:11]
	s_barrier
	s_add_u32 s30, s50, 0x158080
	s_addc_u32 s31, s51, 0
	s_add_i32 s38, s39, s22
	v_lshl_add_u64 v[128:129], s[30:31], 0, v[178:179]
	s_mov_b32 m0, s38
	s_nop 0
	global_load_lds_dwordx4 v[128:129], off
	v_lshl_add_u64 v[128:129], s[30:31], 0, v[194:195]
	s_add_i32 m0, s38, 0x2000
	s_nop 0
	global_load_lds_dwordx4 v[128:129], off
	s_waitcnt vmcnt(6)
	s_barrier
	v_mfma_f32_16x16x32_bf16 v[52:55], v[200:203], v[144:147], v[52:55]
	v_mfma_f32_16x16x32_bf16 v[44:47], v[208:211], v[144:147], v[44:47]
	v_mfma_f32_16x16x32_bf16 v[36:39], v[200:203], v[152:155], v[36:39]
	v_mfma_f32_16x16x32_bf16 v[32:35], v[208:211], v[152:155], v[32:35]
	v_mfma_f32_16x16x32_bf16 v[20:23], v[200:203], v[160:163], v[20:23]
	v_mfma_f32_16x16x32_bf16 v[12:15], v[208:211], v[160:163], v[12:15]
	v_mfma_f32_16x16x32_bf16 v[4:7], v[200:203], v[168:171], v[4:7]
	v_mfma_f32_16x16x32_bf16 v[0:3], v[208:211], v[168:171], v[0:3]
	v_mfma_f32_16x16x32_bf16 v[52:55], v[204:207], v[148:151], v[52:55]
	v_mfma_f32_16x16x32_bf16 v[44:47], v[232:235], v[148:151], v[44:47]
	v_mfma_f32_16x16x32_bf16 v[36:39], v[204:207], v[156:159], v[36:39]
	v_mfma_f32_16x16x32_bf16 v[32:35], v[232:235], v[156:159], v[32:35]
	v_mfma_f32_16x16x32_bf16 v[20:23], v[204:207], v[164:167], v[20:23]
	v_mfma_f32_16x16x32_bf16 v[12:15], v[232:235], v[164:167], v[12:15]
	v_mfma_f32_16x16x32_bf16 v[4:7], v[204:207], v[172:175], v[4:7]
	v_mfma_f32_16x16x32_bf16 v[0:3], v[232:235], v[172:175], v[0:3]
	s_barrier
	s_add_u32 s64, s64, 0x100
	s_addc_u32 s65, s65, 0
	s_cmp_ge_i32 s66, s63
	s_mov_b64 s[38:39], s[48:49]
	s_mov_b32 s50, s66
	s_cbranch_scc0 .LBB0_2573
	s_branch .Lpeel_exit_1
.LBB0_2573:
	s_add_i32 s66, s50, 2
	s_add_u32 s48, s38, 0x100
	s_addc_u32 s49, s39, 0
	s_add_i32 s30, 0, 0x10000
	v_add_u32_e32 v140, s30, v228
	ds_read_b128 v[128:131], v140
	ds_read_b128 v[132:135], v140 offset:1024
	ds_read_b128 v[136:139], v140 offset:2048
	ds_read_b128 v[140:143], v140 offset:3072
	s_cmp_eq_u32 s11, s50
	s_cselect_b32 s50, s46, s64
	s_cselect_b32 s53, s43, s49
	s_cselect_b32 s52, s42, s48
	s_cselect_b32 s51, s47, s65
	v_lshl_add_u64 v[200:201], s[38:39], 0, v[196:197]
	s_add_i32 m0, s23, 0xc000
	ds_read_b128 v[144:147], v230
	ds_read_b128 v[148:151], v230 offset:1024
	ds_read_b128 v[152:155], v230 offset:2048
	ds_read_b128 v[156:159], v230 offset:3072
	ds_read_b128 v[160:163], v230 offset:4096
	ds_read_b128 v[164:167], v230 offset:5120
	ds_read_b128 v[168:171], v230 offset:6144
	ds_read_b128 v[172:175], v230 offset:7168
	global_load_lds_dwordx4 v[200:201], off
	v_lshl_add_u64 v[200:201], s[38:39], 0, v[198:199]
	s_add_i32 m0, s23, 0xe000
	s_nop 0
	global_load_lds_dwordx4 v[200:201], off
	s_waitcnt lgkmcnt(8)
	s_barrier
	s_waitcnt lgkmcnt(0)
	v_mfma_f32_16x16x32_bf16 v[124:127], v[128:131], v[144:147], v[124:127]
	v_mfma_f32_16x16x32_bf16 v[120:123], v[136:139], v[144:147], v[120:123]
	v_mfma_f32_16x16x32_bf16 v[112:115], v[128:131], v[152:155], v[112:115]
	v_mfma_f32_16x16x32_bf16 v[104:107], v[136:139], v[152:155], v[104:107]
	v_mfma_f32_16x16x32_bf16 v[92:95], v[128:131], v[160:163], v[92:95]
	v_mfma_f32_16x16x32_bf16 v[88:91], v[136:139], v[160:163], v[88:91]
	v_mfma_f32_16x16x32_bf16 v[80:83], v[128:131], v[168:171], v[80:83]
	v_mfma_f32_16x16x32_bf16 v[72:75], v[136:139], v[168:171], v[72:75]
	v_mfma_f32_16x16x32_bf16 v[124:127], v[132:135], v[148:151], v[124:127]
	v_mfma_f32_16x16x32_bf16 v[120:123], v[140:143], v[148:151], v[120:123]
	v_mfma_f32_16x16x32_bf16 v[112:115], v[132:135], v[156:159], v[112:115]
	v_mfma_f32_16x16x32_bf16 v[104:107], v[140:143], v[156:159], v[104:107]
	v_mfma_f32_16x16x32_bf16 v[92:95], v[132:135], v[164:167], v[92:95]
	v_mfma_f32_16x16x32_bf16 v[88:91], v[140:143], v[164:167], v[88:91]
	v_mfma_f32_16x16x32_bf16 v[80:83], v[132:135], v[172:175], v[80:83]
	v_mfma_f32_16x16x32_bf16 v[72:75], v[140:143], v[172:175], v[72:75]
	s_barrier
	s_add_i32 s38, 0, 0x14000
	v_add_u32_e32 v220, s38, v228
	s_add_i32 s30, s30, s22
	ds_read_b128 v[200:203], v220
	ds_read_b128 v[204:207], v220 offset:1024
	ds_read_b128 v[208:211], v220 offset:2048
	ds_read_b128 v[232:235], v220 offset:3072
	v_lshl_add_u64 v[220:221], s[50:51], 0, v[178:179]
	s_mov_b32 m0, s30
	v_lshl_add_u64 v[222:223], s[50:51], 0, v[194:195]
	global_load_lds_dwordx4 v[220:221], off
	s_add_i32 m0, s30, 0x2000
	s_nop 0
	global_load_lds_dwordx4 v[222:223], off
	s_barrier
; #define PG8_STAGE(bufoff, gbase, voff) do { _Pragma("unroll") for (int _i = 0; _i < 2; ++_i) \
;         __builtin_amdgcn_global_load_lds((const unsigned*)((const char*)(gbase) + (voff)[_i]), (LAS unsigned*)(lds + (bufoff) + ldsw + _i * 8192), 16, 0, 0); } while (0)
; #define PG8_LDA(dst, b, h) do { _Pragma("unroll") for (int m = 0; m < 4; ++m) _Pragma("unroll") for (int k = 0; k < 2; ++k) dst[m][k] = *(const LAS bf16x8*)(lds + PG8_SA(b, h) + aoff + m * 2048 + k * 1024); } while (0)
; #define PG8_LDB(dst, b, h) do { _Pragma("unroll") for (int n = 0; n < 2; ++n) _Pragma("unroll") for (int k = 0; k < 2; ++k) dst[n][k] = *(const LAS bf16x8*)(lds + PG8_SB(b, h) + boff + n * 2048 + k * 1024); } while (0)
; #define PG8_MMA(ai, bj, At, Bt) do { __builtin_amdgcn_s_setprio(1); _Pragma("unroll") for (int m = 0; m < 4; ++m) _Pragma("unroll") for (int n = 0; n < 2; ++n) _Pragma("unroll") for (int k = 0; k < 2; ++k) \
;         acc[ai][bj][m][n] = __builtin_amdgcn_mfma_f32_16x16x32_bf16(Bt[n][k], At[m][k], acc[ai][bj][m][n], 0, 0, 0); __builtin_amdgcn_s_setprio(0); } while (0)
; #define PG8_WAIT_V(n) asm volatile("s_waitcnt vmcnt(" #n ")" ::: "memory")
; #define PG8_WAIT_L(n) asm volatile("s_waitcnt lgkmcnt(" #n ")" ::: "memory")
; #define PG8_BAR __builtin_amdgcn_s_barrier()
; #define PG8_SCHED __builtin_amdgcn_sched_barrier(0)
; template <class Epi>
; __device__ __forceinline__ void gemm_phase(LAS unsigned char* lds, const Gemm g, const StaticOrder S, const Epi E) {
;     ...
;             PG8_BAR; PG8_WAIT_L(0); PG8_MMA(0, 1, At, B1); PG8_BAR;
;             PG8_LDA(At, 0, 1); PG8_STAGE(PG8_SA(0, 0), a2, voffA);
;             PG8_BAR; PG8_WAIT_L(0); PG8_MMA(1, 0, At, B0); PG8_BAR; PG8_SCHED;
;             PG8_STAGE(PG8_SB(0, 1), b2 + hstep, voffA);
;             PG8_WAIT_V(6); PG8_BAR; PG8_MMA(1, 1, At, B1); PG8_BAR;
;             PG8_LDB(B0, 1, 0); PG8_SCHED; PG8_LDA(At, 1, 0); PG8_STAGE(PG8_SA(0, 1), a2 + hstep, voffA);
;             PG8_WAIT_L(8); PG8_BAR; PG8_WAIT_L(0); PG8_MMA(0, 0, At, B0); PG8_BAR; PG8_SCHED;
	s_waitcnt lgkmcnt(0)
	v_mfma_f32_16x16x32_bf16 v[116:119], v[200:203], v[144:147], v[116:119]
	v_mfma_f32_16x16x32_bf16 v[108:111], v[208:211], v[144:147], v[108:111]
	v_mfma_f32_16x16x32_bf16 v[100:103], v[200:203], v[152:155], v[100:103]
	v_mfma_f32_16x16x32_bf16 v[96:99], v[208:211], v[152:155], v[96:99]
	v_mfma_f32_16x16x32_bf16 v[84:87], v[200:203], v[160:163], v[84:87]
	v_mfma_f32_16x16x32_bf16 v[76:79], v[208:211], v[160:163], v[76:79]
	v_mfma_f32_16x16x32_bf16 v[68:71], v[200:203], v[168:171], v[68:71]
	v_mfma_f32_16x16x32_bf16 v[64:67], v[208:211], v[168:171], v[64:67]
	v_mfma_f32_16x16x32_bf16 v[116:119], v[204:207], v[148:151], v[116:119]
	v_mfma_f32_16x16x32_bf16 v[108:111], v[232:235], v[148:151], v[108:111]
	v_mfma_f32_16x16x32_bf16 v[100:103], v[204:207], v[156:159], v[100:103]
	v_mfma_f32_16x16x32_bf16 v[96:99], v[232:235], v[156:159], v[96:99]
	v_mfma_f32_16x16x32_bf16 v[84:87], v[204:207], v[164:167], v[84:87]
	v_mfma_f32_16x16x32_bf16 v[76:79], v[232:235], v[164:167], v[76:79]
	v_mfma_f32_16x16x32_bf16 v[68:71], v[204:207], v[172:175], v[68:71]
	v_mfma_f32_16x16x32_bf16 v[64:67], v[232:235], v[172:175], v[64:67]
	s_barrier
	s_mov_b32 m0, s23
	v_lshl_add_u64 v[236:237], s[52:53], 0, v[178:179]
	ds_read_b128 v[144:147], v230 offset:16384
	ds_read_b128 v[148:151], v230 offset:17408
	ds_read_b128 v[152:155], v230 offset:18432
	ds_read_b128 v[156:159], v230 offset:19456
	ds_read_b128 v[160:163], v230 offset:20480
	ds_read_b128 v[164:167], v230 offset:21504
	ds_read_b128 v[168:171], v230 offset:22528
	ds_read_b128 v[172:175], v230 offset:23552
	global_load_lds_dwordx4 v[236:237], off
	v_lshl_add_u64 v[238:239], s[52:53], 0, v[194:195]
	s_mov_b32 m0, s24
	s_nop 0
	global_load_lds_dwordx4 v[238:239], off
	s_barrier
	s_waitcnt lgkmcnt(0)
	v_mfma_f32_16x16x32_bf16 v[60:63], v[128:131], v[144:147], v[60:63]
	v_mfma_f32_16x16x32_bf16 v[56:59], v[136:139], v[144:147], v[56:59]
	v_mfma_f32_16x16x32_bf16 v[48:51], v[128:131], v[152:155], v[48:51]
	v_mfma_f32_16x16x32_bf16 v[40:43], v[136:139], v[152:155], v[40:43]
	v_mfma_f32_16x16x32_bf16 v[28:31], v[128:131], v[160:163], v[28:31]
	v_mfma_f32_16x16x32_bf16 v[24:27], v[136:139], v[160:163], v[24:27]
	v_mfma_f32_16x16x32_bf16 v[16:19], v[128:131], v[168:171], v[16:19]
	v_mfma_f32_16x16x32_bf16 v[8:11], v[136:139], v[168:171], v[8:11]
	v_mfma_f32_16x16x32_bf16 v[60:63], v[132:135], v[148:151], v[60:63]
	v_mfma_f32_16x16x32_bf16 v[56:59], v[140:143], v[148:151], v[56:59]
	v_mfma_f32_16x16x32_bf16 v[48:51], v[132:135], v[156:159], v[48:51]
	v_mfma_f32_16x16x32_bf16 v[40:43], v[140:143], v[156:159], v[40:43]
	v_mfma_f32_16x16x32_bf16 v[28:31], v[132:135], v[164:167], v[28:31]
	v_mfma_f32_16x16x32_bf16 v[24:27], v[140:143], v[164:167], v[24:27]
	v_mfma_f32_16x16x32_bf16 v[16:19], v[132:135], v[172:175], v[16:19]
	v_mfma_f32_16x16x32_bf16 v[8:11], v[140:143], v[172:175], v[8:11]
	s_barrier
	s_add_u32 s30, s50, 0x158000
	s_addc_u32 s31, s51, 0
	s_add_i32 s38, s38, s22
	v_lshl_add_u64 v[128:129], s[30:31], 0, v[178:179]
	s_mov_b32 m0, s38
	s_nop 0
	global_load_lds_dwordx4 v[128:129], off
	v_lshl_add_u64 v[128:129], s[30:31], 0, v[194:195]
	s_add_i32 m0, s38, 0x2000
	s_nop 0
	global_load_lds_dwordx4 v[128:129], off
	s_waitcnt vmcnt(6)
	s_barrier
	v_mfma_f32_16x16x32_bf16 v[52:55], v[200:203], v[144:147], v[52:55]
	v_mfma_f32_16x16x32_bf16 v[44:47], v[208:211], v[144:147], v[44:47]
	v_mfma_f32_16x16x32_bf16 v[36:39], v[200:203], v[152:155], v[36:39]
	v_mfma_f32_16x16x32_bf16 v[32:35], v[208:211], v[152:155], v[32:35]
	v_mfma_f32_16x16x32_bf16 v[20:23], v[200:203], v[160:163], v[20:23]
	v_mfma_f32_16x16x32_bf16 v[12:15], v[208:211], v[160:163], v[12:15]
	v_mfma_f32_16x16x32_bf16 v[4:7], v[200:203], v[168:171], v[4:7]
	v_mfma_f32_16x16x32_bf16 v[0:3], v[208:211], v[168:171], v[0:3]
	v_mfma_f32_16x16x32_bf16 v[52:55], v[204:207], v[148:151], v[52:55]
	v_mfma_f32_16x16x32_bf16 v[44:47], v[232:235], v[148:151], v[44:47]
	v_mfma_f32_16x16x32_bf16 v[36:39], v[204:207], v[156:159], v[36:39]
	v_mfma_f32_16x16x32_bf16 v[32:35], v[232:235], v[156:159], v[32:35]
	v_mfma_f32_16x16x32_bf16 v[20:23], v[204:207], v[164:167], v[20:23]
	v_mfma_f32_16x16x32_bf16 v[12:15], v[232:235], v[164:167], v[12:15]
	v_mfma_f32_16x16x32_bf16 v[4:7], v[204:207], v[172:175], v[4:7]
	v_mfma_f32_16x16x32_bf16 v[0:3], v[232:235], v[172:175], v[0:3]
	s_barrier
	s_add_i32 s38, 0, 0x18000
	v_add_u32_e32 v140, s38, v228
	ds_read_b128 v[128:131], v140
	ds_read_b128 v[132:135], v140 offset:1024
	ds_read_b128 v[136:139], v140 offset:2048
	ds_read_b128 v[140:143], v140 offset:3072
	s_add_u32 s30, s52, 0x158000
	s_addc_u32 s31, s53, 0
	s_mov_b32 m0, s25
	v_lshl_add_u64 v[200:201], s[30:31], 0, v[178:179]
	ds_read_b128 v[144:147], v230 offset:32768
	ds_read_b128 v[148:151], v230 offset:33792
	ds_read_b128 v[152:155], v230 offset:34816
	ds_read_b128 v[156:159], v230 offset:35840
	ds_read_b128 v[160:163], v230 offset:36864
	ds_read_b128 v[164:167], v230 offset:37888
	ds_read_b128 v[168:171], v230 offset:38912
	ds_read_b128 v[172:175], v230 offset:39936
	global_load_lds_dwordx4 v[200:201], off
	v_lshl_add_u64 v[200:201], s[30:31], 0, v[194:195]
	s_mov_b32 m0, s14
	s_nop 0
	global_load_lds_dwordx4 v[200:201], off
	s_waitcnt lgkmcnt(8)
	s_barrier
; #define PG8_STAGE(bufoff, gbase, voff) do { _Pragma("unroll") for (int _i = 0; _i < 2; ++_i) \
;         __builtin_amdgcn_global_load_lds((const unsigned*)((const char*)(gbase) + (voff)[_i]), (LAS unsigned*)(lds + (bufoff) + ldsw + _i * 8192), 16, 0, 0); } while (0)
; #define PG8_LDA(dst, b, h) do { _Pragma("unroll") for (int m = 0; m < 4; ++m) _Pragma("unroll") for (int k = 0; k < 2; ++k) dst[m][k] = *(const LAS bf16x8*)(lds + PG8_SA(b, h) + aoff + m * 2048 + k * 1024); } while (0)
; #define PG8_LDB(dst, b, h) do { _Pragma("unroll") for (int n = 0; n < 2; ++n) _Pragma("unroll") for (int k = 0; k < 2; ++k) dst[n][k] = *(const LAS bf16x8*)(lds + PG8_SB(b, h) + boff + n * 2048 + k * 1024); } while (0)
; #define PG8_MMA(ai, bj, At, Bt) do { __builtin_amdgcn_s_setprio(1); _Pragma("unroll") for (int m = 0; m < 4; ++m) _Pragma("unroll") for (int n = 0; n < 2; ++n) _Pragma("unroll") for (int k = 0; k < 2; ++k) \
;         acc[ai][bj][m][n] = __builtin_amdgcn_mfma_f32_16x16x32_bf16(Bt[n][k], At[m][k], acc[ai][bj][m][n], 0, 0, 0); __builtin_amdgcn_s_setprio(0); } while (0)
; #define PG8_WAIT_V(n) asm volatile("s_waitcnt vmcnt(" #n ")" ::: "memory")
; #define PG8_WAIT_L(n) asm volatile("s_waitcnt lgkmcnt(" #n ")" ::: "memory")
; #define PG8_BAR __builtin_amdgcn_s_barrier()
; #define PG8_SCHED __builtin_amdgcn_sched_barrier(0)
; template <class Epi>
; __device__ __forceinline__ void gemm_phase(LAS unsigned char* lds, const Gemm g, const StaticOrder S, const Epi E) {
;     ...
;             PG8_WAIT_L(8); PG8_BAR; PG8_WAIT_L(0); PG8_MMA(0, 0, At, B0); PG8_BAR; PG8_SCHED;
;             PG8_LDB(B1, 1, 1); PG8_STAGE(PG8_SB(1, 0), b3, voffA);
;             PG8_BAR; PG8_WAIT_L(0); PG8_MMA(0, 1, At, B1); PG8_BAR;
;             PG8_LDA(At, 1, 1); PG8_STAGE(PG8_SA(1, 0), a3, voffA);
;             PG8_BAR; PG8_WAIT_L(0); PG8_MMA(1, 0, At, B0); PG8_BAR; PG8_SCHED;
;             PG8_STAGE(PG8_SB(1, 1), b3 + hstep, voffA);
;             PG8_WAIT_V(6); PG8_BAR; PG8_MMA(1, 1, At, B1); PG8_BAR;
;         }
	s_waitcnt lgkmcnt(0)
	v_mfma_f32_16x16x32_bf16 v[124:127], v[128:131], v[144:147], v[124:127]
	v_mfma_f32_16x16x32_bf16 v[120:123], v[136:139], v[144:147], v[120:123]
	v_mfma_f32_16x16x32_bf16 v[112:115], v[128:131], v[152:155], v[112:115]
	v_mfma_f32_16x16x32_bf16 v[104:107], v[136:139], v[152:155], v[104:107]
	v_mfma_f32_16x16x32_bf16 v[92:95], v[128:131], v[160:163], v[92:95]
	v_mfma_f32_16x16x32_bf16 v[88:91], v[136:139], v[160:163], v[88:91]
	v_mfma_f32_16x16x32_bf16 v[80:83], v[128:131], v[168:171], v[80:83]
	v_mfma_f32_16x16x32_bf16 v[72:75], v[136:139], v[168:171], v[72:75]
	v_mfma_f32_16x16x32_bf16 v[124:127], v[132:135], v[148:151], v[124:127]
	v_mfma_f32_16x16x32_bf16 v[120:123], v[140:143], v[148:151], v[120:123]
	v_mfma_f32_16x16x32_bf16 v[112:115], v[132:135], v[156:159], v[112:115]
	v_mfma_f32_16x16x32_bf16 v[104:107], v[140:143], v[156:159], v[104:107]
	v_mfma_f32_16x16x32_bf16 v[92:95], v[132:135], v[164:167], v[92:95]
	v_mfma_f32_16x16x32_bf16 v[88:91], v[140:143], v[164:167], v[88:91]
	v_mfma_f32_16x16x32_bf16 v[80:83], v[132:135], v[172:175], v[80:83]
	v_mfma_f32_16x16x32_bf16 v[72:75], v[140:143], v[172:175], v[72:75]
	s_barrier
	s_add_i32 s39, 0, 0x1c000
	s_add_i32 s30, s38, s22
	v_add_u32_e32 v231, s39, v228
	v_lshl_add_u64 v[220:221], v[220:221], 0, s[34:35]
	s_mov_b32 m0, s30
	ds_read_b128 v[200:203], v231
	ds_read_b128 v[204:207], v231 offset:1024
	ds_read_b128 v[208:211], v231 offset:2048
	ds_read_b128 v[232:235], v231 offset:3072
	global_load_lds_dwordx4 v[220:221], off
	v_lshl_add_u64 v[220:221], v[222:223], 0, s[34:35]
	s_add_i32 m0, s30, 0x2000
	s_nop 0
	global_load_lds_dwordx4 v[220:221], off
	s_barrier
	s_waitcnt lgkmcnt(0)
	v_mfma_f32_16x16x32_bf16 v[116:119], v[200:203], v[144:147], v[116:119]
	v_mfma_f32_16x16x32_bf16 v[108:111], v[208:211], v[144:147], v[108:111]
	v_mfma_f32_16x16x32_bf16 v[100:103], v[200:203], v[152:155], v[100:103]
	v_mfma_f32_16x16x32_bf16 v[96:99], v[208:211], v[152:155], v[96:99]
	v_mfma_f32_16x16x32_bf16 v[84:87], v[200:203], v[160:163], v[84:87]
	v_mfma_f32_16x16x32_bf16 v[76:79], v[208:211], v[160:163], v[76:79]
	v_mfma_f32_16x16x32_bf16 v[68:71], v[200:203], v[168:171], v[68:71]
	v_mfma_f32_16x16x32_bf16 v[64:67], v[208:211], v[168:171], v[64:67]
	v_mfma_f32_16x16x32_bf16 v[116:119], v[204:207], v[148:151], v[116:119]
	v_mfma_f32_16x16x32_bf16 v[108:111], v[232:235], v[148:151], v[108:111]
	v_mfma_f32_16x16x32_bf16 v[100:103], v[204:207], v[156:159], v[100:103]
	v_mfma_f32_16x16x32_bf16 v[96:99], v[232:235], v[156:159], v[96:99]
	v_mfma_f32_16x16x32_bf16 v[84:87], v[204:207], v[164:167], v[84:87]
	v_mfma_f32_16x16x32_bf16 v[76:79], v[232:235], v[164:167], v[76:79]
	v_mfma_f32_16x16x32_bf16 v[68:71], v[204:207], v[172:175], v[68:71]
	v_mfma_f32_16x16x32_bf16 v[64:67], v[232:235], v[172:175], v[64:67]
	s_barrier
	s_mov_b32 m0, s57
	v_lshl_add_u64 v[220:221], v[236:237], 0, s[34:35]
	ds_read_b128 v[144:147], v230 offset:49152
	ds_read_b128 v[148:151], v230 offset:50176
	ds_read_b128 v[152:155], v230 offset:51200
	ds_read_b128 v[156:159], v230 offset:52224
	ds_read_b128 v[160:163], v230 offset:53248
	ds_read_b128 v[164:167], v230 offset:54272
	ds_read_b128 v[168:171], v230 offset:55296
	ds_read_b128 v[172:175], v230 offset:56320
	global_load_lds_dwordx4 v[220:221], off
	v_lshl_add_u64 v[220:221], v[238:239], 0, s[34:35]
	s_mov_b32 m0, s58
	s_nop 0
	global_load_lds_dwordx4 v[220:221], off
	s_barrier
	s_waitcnt lgkmcnt(0)
	v_mfma_f32_16x16x32_bf16 v[60:63], v[128:131], v[144:147], v[60:63]
	v_mfma_f32_16x16x32_bf16 v[56:59], v[136:139], v[144:147], v[56:59]
	v_mfma_f32_16x16x32_bf16 v[48:51], v[128:131], v[152:155], v[48:51]
	v_mfma_f32_16x16x32_bf16 v[40:43], v[136:139], v[152:155], v[40:43]
	v_mfma_f32_16x16x32_bf16 v[28:31], v[128:131], v[160:163], v[28:31]
	v_mfma_f32_16x16x32_bf16 v[24:27], v[136:139], v[160:163], v[24:27]
	v_mfma_f32_16x16x32_bf16 v[16:19], v[128:131], v[168:171], v[16:19]
	v_mfma_f32_16x16x32_bf16 v[8:11], v[136:139], v[168:171], v[8:11]
	v_mfma_f32_16x16x32_bf16 v[60:63], v[132:135], v[148:151], v[60:63]
	v_mfma_f32_16x16x32_bf16 v[56:59], v[140:143], v[148:151], v[56:59]
	v_mfma_f32_16x16x32_bf16 v[48:51], v[132:135], v[156:159], v[48:51]
	v_mfma_f32_16x16x32_bf16 v[40:43], v[140:143], v[156:159], v[40:43]
	v_mfma_f32_16x16x32_bf16 v[28:31], v[132:135], v[164:167], v[28:31]
	v_mfma_f32_16x16x32_bf16 v[24:27], v[140:143], v[164:167], v[24:27]
	v_mfma_f32_16x16x32_bf16 v[16:19], v[132:135], v[172:175], v[16:19]
	v_mfma_f32_16x16x32_bf16 v[8:11], v[140:143], v[172:175], v[8:11]
	s_barrier
	s_add_u32 s30, s50, 0x158080
	s_addc_u32 s31, s51, 0
	s_add_i32 s38, s39, s22
	v_lshl_add_u64 v[128:129], s[30:31], 0, v[178:179]
	s_mov_b32 m0, s38
	s_nop 0
	global_load_lds_dwordx4 v[128:129], off
	v_lshl_add_u64 v[128:129], s[30:31], 0, v[194:195]
	s_add_i32 m0, s38, 0x2000
	s_nop 0
	global_load_lds_dwordx4 v[128:129], off
	s_waitcnt vmcnt(6)
	s_barrier
	v_mfma_f32_16x16x32_bf16 v[52:55], v[200:203], v[144:147], v[52:55]
	v_mfma_f32_16x16x32_bf16 v[44:47], v[208:211], v[144:147], v[44:47]
	v_mfma_f32_16x16x32_bf16 v[36:39], v[200:203], v[152:155], v[36:39]
	v_mfma_f32_16x16x32_bf16 v[32:35], v[208:211], v[152:155], v[32:35]
	v_mfma_f32_16x16x32_bf16 v[20:23], v[200:203], v[160:163], v[20:23]
	v_mfma_f32_16x16x32_bf16 v[12:15], v[208:211], v[160:163], v[12:15]
	v_mfma_f32_16x16x32_bf16 v[4:7], v[200:203], v[168:171], v[4:7]
	v_mfma_f32_16x16x32_bf16 v[0:3], v[208:211], v[168:171], v[0:3]
	v_mfma_f32_16x16x32_bf16 v[52:55], v[204:207], v[148:151], v[52:55]
	v_mfma_f32_16x16x32_bf16 v[44:47], v[232:235], v[148:151], v[44:47]
	v_mfma_f32_16x16x32_bf16 v[36:39], v[204:207], v[156:159], v[36:39]
	v_mfma_f32_16x16x32_bf16 v[32:35], v[232:235], v[156:159], v[32:35]
	v_mfma_f32_16x16x32_bf16 v[20:23], v[204:207], v[164:167], v[20:23]
	v_mfma_f32_16x16x32_bf16 v[12:15], v[232:235], v[164:167], v[12:15]
	v_mfma_f32_16x16x32_bf16 v[4:7], v[204:207], v[172:175], v[4:7]
	v_mfma_f32_16x16x32_bf16 v[0:3], v[232:235], v[172:175], v[0:3]
	s_barrier
	s_add_u32 s64, s64, 0x100
	s_addc_u32 s65, s65, 0
	s_cmp_ge_i32 s66, s63
	s_mov_b64 s[38:39], s[48:49]
	s_mov_b32 s50, s66
	s_cbranch_scc0 .LBB0_2573

; #define PG8_STAGE(bufoff, gbase, voff) do { _Pragma("unroll") for (int _i = 0; _i < 2; ++_i) \
;         __builtin_amdgcn_global_load_lds((const unsigned*)((const char*)(gbase) + (voff)[_i]), (LAS unsigned*)(lds + (bufoff) + ldsw + _i * 8192), 16, 0, 0); } while (0)
; #define PG8_LDA(dst, b, h) do { _Pragma("unroll") for (int m = 0; m < 4; ++m) _Pragma("unroll") for (int k = 0; k < 2; ++k) dst[m][k] = *(const LAS bf16x8*)(lds + PG8_SA(b, h) + aoff + m * 2048 + k * 1024); } while (0)
; #define PG8_LDB(dst, b, h) do { _Pragma("unroll") for (int n = 0; n < 2; ++n) _Pragma("unroll") for (int k = 0; k < 2; ++k) dst[n][k] = *(const LAS bf16x8*)(lds + PG8_SB(b, h) + boff + n * 2048 + k * 1024); } while (0)
; #define PG8_MMA(ai, bj, At, Bt) do { __builtin_amdgcn_s_setprio(1); _Pragma("unroll") for (int m = 0; m < 4; ++m) _Pragma("unroll") for (int n = 0; n < 2; ++n) _Pragma("unroll") for (int k = 0; k < 2; ++k) \
;         acc[ai][bj][m][n] = __builtin_amdgcn_mfma_f32_16x16x32_bf16(Bt[n][k], At[m][k], acc[ai][bj][m][n], 0, 0, 0); __builtin_amdgcn_s_setprio(0); } while (0)
; template <class Epi>
; __device__ __forceinline__ void gemm_phase(LAS unsigned char* lds, const Gemm g, const StaticOrder S, const Epi E) {
;     ...
;         const bool has_next = S.next(ui + 1, nxt);
;         const char* nA = has_next ? (const char*)g.A + (size_t)nxt.pm * tstep + (size_t)nxt.k0 * kstep : cA; const char* nB = has_next ? (const char*)g.Bt + (size_t)nxt.pn * tstep + (size_t)nxt.k0 * kstep : cB;
;         const int nt = cur.nk;
;         for (int t = 0; t < nt; t += 2) {
;             const bool last = (t == nt - 2);
;             const char* a1 = cA + (size_t)(t + 1) * kstep;
;             const char* a2 = last ? nA : cA + (size_t)(t + 2) * kstep; const char* b2 = last ? nB : cB + (size_t)(t + 2) * kstep;
;             const char* a3 = a2 + kstep; const char* b3 = b2 + kstep;
;             PG8_LDB(B0, 0, 0); PG8_SCHED; PG8_LDA(At, 0, 0); PG8_STAGE(PG8_SA(1, 1), a1 + hstep, voffA);
;             PG8_WAIT_L(8); PG8_BAR; PG8_WAIT_L(0); PG8_MMA(0, 0, At, B0); PG8_BAR; PG8_SCHED;
;             PG8_LDB(B1, 0, 1); PG8_STAGE(PG8_SB(0, 0), b2, voffA);
;             PG8_BAR; PG8_WAIT_L(0); PG8_MMA(0, 1, At, B1); PG8_BAR;
;             PG8_LDA(At, 0, 1); PG8_STAGE(PG8_SA(0, 0), a2, voffA);
;             PG8_BAR; PG8_WAIT_L(0); PG8_MMA(1, 0, At, B0); PG8_BAR; PG8_SCHED;
.LBB0_2720:
	s_ashr_i32 s11, s10, 31
	s_lshl_b64 s[30:31], s[10:11], 20
	v_readlane_b32 s3, v255, 1
	s_add_u32 s3, s3, s30
	v_readlane_b32 s11, v255, 2
	v_cmp_lt_i64_e32 vcc, s[44:45], v[184:185]
	s_addc_u32 s11, s11, s31
	s_and_b64 s[30:31], vcc, exec
	s_cselect_b32 s45, s11, s43
	s_cselect_b32 s44, s3, s42
	s_ashr_i32 s3, s2, 31
	s_lshl_b64 s[30:31], s[2:3], 20
	s_add_u32 s3, s6, s30
	s_addc_u32 s11, s7, s31
	s_and_b64 s[30:31], vcc, exec
	s_cselect_b32 s47, s11, s49
	s_cselect_b32 s46, s3, s48
	s_add_u32 s3, s48, 0x100
	s_addc_u32 s11, s49, 0
	s_mov_b32 s57, -2
	s_add_u32 s48, s42, 0x100
	s_addc_u32 s49, s43, 0
	s_add_i32 s30, 0, 0x10000
	v_add_u32_e32 v132, s30, v151
	ds_read_b128 v[128:131], v132
	ds_read_b128 v[142:145], v132 offset:1024
	ds_read_b128 v[146:149], v132 offset:2048
	ds_read_b128 v[158:161], v132 offset:3072
	s_cmp_eq_u32 s57, 28
	s_cselect_b32 s53, s45, s49
	s_cselect_b32 s52, s44, s48
	s_cselect_b32 s51, s47, s11
	s_cselect_b32 s50, s46, s3
	v_lshl_add_u64 v[132:133], s[42:43], 0, v[138:139]
	s_add_i32 m0, s23, 0xc000
	ds_read_b128 v[162:165], v156
	ds_read_b128 v[166:169], v156 offset:1024
	ds_read_b128 v[170:173], v156 offset:2048
	ds_read_b128 v[194:197], v156 offset:3072
	ds_read_b128 v[198:201], v156 offset:4096
	ds_read_b128 v[202:205], v156 offset:5120
	ds_read_b128 v[206:209], v156 offset:6144
	ds_read_b128 v[228:231], v156 offset:7168
	global_load_lds_dwordx4 v[132:133], off
	v_lshl_add_u64 v[132:133], s[42:43], 0, v[140:141]
	s_add_i32 m0, s23, 0xe000
	s_nop 0
	global_load_lds_dwordx4 v[132:133], off
	s_waitcnt lgkmcnt(8)
	s_barrier
	s_waitcnt lgkmcnt(0)
	v_mfma_f32_16x16x32_bf16 v[124:127], v[128:131], v[162:165], 0
	v_mfma_f32_16x16x32_bf16 v[120:123], v[146:149], v[162:165], 0
	v_mfma_f32_16x16x32_bf16 v[108:111], v[128:131], v[170:173], 0
	v_mfma_f32_16x16x32_bf16 v[104:107], v[146:149], v[170:173], 0
	v_mfma_f32_16x16x32_bf16 v[92:95], v[128:131], v[198:201], 0
	v_mfma_f32_16x16x32_bf16 v[88:91], v[146:149], v[198:201], 0
	v_mfma_f32_16x16x32_bf16 v[76:79], v[128:131], v[206:209], 0
	v_mfma_f32_16x16x32_bf16 v[72:75], v[146:149], v[206:209], 0
	v_mfma_f32_16x16x32_bf16 v[124:127], v[142:145], v[166:169], v[124:127]
	v_mfma_f32_16x16x32_bf16 v[120:123], v[158:161], v[166:169], v[120:123]
	v_mfma_f32_16x16x32_bf16 v[108:111], v[142:145], v[194:197], v[108:111]
	v_mfma_f32_16x16x32_bf16 v[104:107], v[158:161], v[194:197], v[104:107]
	v_mfma_f32_16x16x32_bf16 v[92:95], v[142:145], v[202:205], v[92:95]
	v_mfma_f32_16x16x32_bf16 v[88:91], v[158:161], v[202:205], v[88:91]
	v_mfma_f32_16x16x32_bf16 v[76:79], v[142:145], v[228:231], v[76:79]
	v_mfma_f32_16x16x32_bf16 v[72:75], v[158:161], v[228:231], v[72:75]
	s_barrier
	s_add_i32 s42, 0, 0x14000
	v_add_u32_e32 v132, s42, v151
	s_add_i32 s30, s30, s22
	ds_read_b128 v[232:235], v132
	ds_read_b128 v[236:239], v132 offset:1024
	ds_read_b128 v[240:243], v132 offset:2048
	ds_read_b128 v[244:247], v132 offset:3072
	v_lshl_add_u64 v[132:133], s[50:51], 0, v[178:179]
	s_mov_b32 m0, s30
	v_lshl_add_u64 v[174:175], s[50:51], 0, v[134:135]
	global_load_lds_dwordx4 v[132:133], off
	s_add_i32 m0, s30, 0x2000
	s_nop 0
	global_load_lds_dwordx4 v[174:175], off
	s_barrier
	s_waitcnt lgkmcnt(0)
	v_mfma_f32_16x16x32_bf16 v[116:119], v[232:235], v[162:165], 0
	v_mfma_f32_16x16x32_bf16 v[112:115], v[240:243], v[162:165], 0
	v_mfma_f32_16x16x32_bf16 v[100:103], v[232:235], v[170:173], 0
	v_mfma_f32_16x16x32_bf16 v[96:99], v[240:243], v[170:173], 0
	v_mfma_f32_16x16x32_bf16 v[84:87], v[232:235], v[198:201], 0
	v_mfma_f32_16x16x32_bf16 v[80:83], v[240:243], v[198:201], 0
	v_mfma_f32_16x16x32_bf16 v[68:71], v[232:235], v[206:209], 0
	v_mfma_f32_16x16x32_bf16 v[64:67], v[240:243], v[206:209], 0
	v_mfma_f32_16x16x32_bf16 v[116:119], v[236:239], v[166:169], v[116:119]
	v_mfma_f32_16x16x32_bf16 v[112:115], v[244:247], v[166:169], v[112:115]
	v_mfma_f32_16x16x32_bf16 v[100:103], v[236:239], v[194:197], v[100:103]
	v_mfma_f32_16x16x32_bf16 v[96:99], v[244:247], v[194:197], v[96:99]
	v_mfma_f32_16x16x32_bf16 v[84:87], v[236:239], v[202:205], v[84:87]
	v_mfma_f32_16x16x32_bf16 v[80:83], v[244:247], v[202:205], v[80:83]
	v_mfma_f32_16x16x32_bf16 v[68:71], v[236:239], v[228:231], v[68:71]
	v_mfma_f32_16x16x32_bf16 v[64:67], v[244:247], v[228:231], v[64:67]
	s_barrier
	s_mov_b32 m0, s23
	v_lshl_add_u64 v[210:211], s[52:53], 0, v[178:179]
	ds_read_b128 v[162:165], v156 offset:16384
	ds_read_b128 v[166:169], v156 offset:17408
	ds_read_b128 v[170:173], v156 offset:18432
	ds_read_b128 v[194:197], v156 offset:19456
	ds_read_b128 v[198:201], v156 offset:20480
	ds_read_b128 v[202:205], v156 offset:21504
	ds_read_b128 v[206:209], v156 offset:22528
	ds_read_b128 v[228:231], v156 offset:23552
	global_load_lds_dwordx4 v[210:211], off
	v_lshl_add_u64 v[220:221], s[52:53], 0, v[134:135]
	s_mov_b32 m0, s24
	s_nop 0
	global_load_lds_dwordx4 v[220:221], off
	s_barrier
	s_waitcnt lgkmcnt(0)
	v_mfma_f32_16x16x32_bf16 v[60:63], v[128:131], v[162:165], 0
	v_mfma_f32_16x16x32_bf16 v[56:59], v[146:149], v[162:165], 0
	v_mfma_f32_16x16x32_bf16 v[44:47], v[128:131], v[170:173], 0
	v_mfma_f32_16x16x32_bf16 v[40:43], v[146:149], v[170:173], 0
	v_mfma_f32_16x16x32_bf16 v[28:31], v[128:131], v[198:201], 0
	v_mfma_f32_16x16x32_bf16 v[24:27], v[146:149], v[198:201], 0
	v_mfma_f32_16x16x32_bf16 v[12:15], v[128:131], v[206:209], 0
	v_mfma_f32_16x16x32_bf16 v[8:11], v[146:149], v[206:209], 0
	v_mfma_f32_16x16x32_bf16 v[60:63], v[142:145], v[166:169], v[60:63]
	v_mfma_f32_16x16x32_bf16 v[56:59], v[158:161], v[166:169], v[56:59]
	v_mfma_f32_16x16x32_bf16 v[44:47], v[142:145], v[194:197], v[44:47]
	v_mfma_f32_16x16x32_bf16 v[40:43], v[158:161], v[194:197], v[40:43]
	v_mfma_f32_16x16x32_bf16 v[28:31], v[142:145], v[202:205], v[28:31]
	v_mfma_f32_16x16x32_bf16 v[24:27], v[158:161], v[202:205], v[24:27]
	v_mfma_f32_16x16x32_bf16 v[12:15], v[142:145], v[228:231], v[12:15]
	v_mfma_f32_16x16x32_bf16 v[8:11], v[158:161], v[228:231], v[8:11]
	s_barrier
; #define PG8_STAGE(bufoff, gbase, voff) do { _Pragma("unroll") for (int _i = 0; _i < 2; ++_i) \
;         __builtin_amdgcn_global_load_lds((const unsigned*)((const char*)(gbase) + (voff)[_i]), (LAS unsigned*)(lds + (bufoff) + ldsw + _i * 8192), 16, 0, 0); } while (0)
; #define PG8_LDA(dst, b, h) do { _Pragma("unroll") for (int m = 0; m < 4; ++m) _Pragma("unroll") for (int k = 0; k < 2; ++k) dst[m][k] = *(const LAS bf16x8*)(lds + PG8_SA(b, h) + aoff + m * 2048 + k * 1024); } while (0)
; #define PG8_LDB(dst, b, h) do { _Pragma("unroll") for (int n = 0; n < 2; ++n) _Pragma("unroll") for (int k = 0; k < 2; ++k) dst[n][k] = *(const LAS bf16x8*)(lds + PG8_SB(b, h) + boff + n * 2048 + k * 1024); } while (0)
; #define PG8_MMA(ai, bj, At, Bt) do { __builtin_amdgcn_s_setprio(1); _Pragma("unroll") for (int m = 0; m < 4; ++m) _Pragma("unroll") for (int n = 0; n < 2; ++n) _Pragma("unroll") for (int k = 0; k < 2; ++k) \
;         acc[ai][bj][m][n] = __builtin_amdgcn_mfma_f32_16x16x32_bf16(Bt[n][k], At[m][k], acc[ai][bj][m][n], 0, 0, 0); __builtin_amdgcn_s_setprio(0); } while (0)
; #define PG8_WAIT_V(n) asm volatile("s_waitcnt vmcnt(" #n ")" ::: "memory")
; #define PG8_WAIT_L(n) asm volatile("s_waitcnt lgkmcnt(" #n ")" ::: "memory")
; #define PG8_BAR __builtin_amdgcn_s_barrier()
; #define PG8_SCHED __builtin_amdgcn_sched_barrier(0)
; template <class Epi>
; __device__ __forceinline__ void gemm_phase(LAS unsigned char* lds, const Gemm g, const StaticOrder S, const Epi E) {
;     ...
;             PG8_STAGE(PG8_SB(0, 1), b2 + hstep, voffA);
;             PG8_WAIT_V(6); PG8_BAR; PG8_MMA(1, 1, At, B1); PG8_BAR;
;             PG8_LDB(B0, 1, 0); PG8_SCHED; PG8_LDA(At, 1, 0); PG8_STAGE(PG8_SA(0, 1), a2 + hstep, voffA);
;             PG8_WAIT_L(8); PG8_BAR; PG8_WAIT_L(0); PG8_MMA(0, 0, At, B0); PG8_BAR; PG8_SCHED;
;             PG8_LDB(B1, 1, 1); PG8_STAGE(PG8_SB(1, 0), b3, voffA);
;             PG8_BAR; PG8_WAIT_L(0); PG8_MMA(0, 1, At, B1); PG8_BAR;
;             PG8_LDA(At, 1, 1); PG8_STAGE(PG8_SA(1, 0), a3, voffA);
	s_add_u32 s30, s50, 0x80000
	s_addc_u32 s31, s51, 0
	s_add_i32 s42, s42, s22
	v_lshl_add_u64 v[128:129], s[30:31], 0, v[178:179]
	s_mov_b32 m0, s42
	s_nop 0
	global_load_lds_dwordx4 v[128:129], off
	v_lshl_add_u64 v[128:129], s[30:31], 0, v[134:135]
	s_add_i32 m0, s42, 0x2000
	s_nop 0
	global_load_lds_dwordx4 v[128:129], off
	s_waitcnt vmcnt(6)
	s_barrier
	v_mfma_f32_16x16x32_bf16 v[52:55], v[232:235], v[162:165], 0
	v_mfma_f32_16x16x32_bf16 v[48:51], v[240:243], v[162:165], 0
	v_mfma_f32_16x16x32_bf16 v[36:39], v[232:235], v[170:173], 0
	v_mfma_f32_16x16x32_bf16 v[32:35], v[240:243], v[170:173], 0
	v_mfma_f32_16x16x32_bf16 v[20:23], v[232:235], v[198:201], 0
	v_mfma_f32_16x16x32_bf16 v[16:19], v[240:243], v[198:201], 0
	v_mfma_f32_16x16x32_bf16 v[4:7], v[232:235], v[206:209], 0
	v_mfma_f32_16x16x32_bf16 v[0:3], v[240:243], v[206:209], 0
	v_mfma_f32_16x16x32_bf16 v[52:55], v[236:239], v[166:169], v[52:55]
	v_mfma_f32_16x16x32_bf16 v[48:51], v[244:247], v[166:169], v[48:51]
	v_mfma_f32_16x16x32_bf16 v[36:39], v[236:239], v[194:197], v[36:39]
	v_mfma_f32_16x16x32_bf16 v[32:35], v[244:247], v[194:197], v[32:35]
	v_mfma_f32_16x16x32_bf16 v[20:23], v[236:239], v[202:205], v[20:23]
	v_mfma_f32_16x16x32_bf16 v[16:19], v[244:247], v[202:205], v[16:19]
	v_mfma_f32_16x16x32_bf16 v[4:7], v[236:239], v[228:231], v[4:7]
	v_mfma_f32_16x16x32_bf16 v[0:3], v[244:247], v[228:231], v[0:3]
	s_barrier
	s_add_i32 s42, 0, 0x18000
	v_add_u32_e32 v157, s42, v151
	ds_read_b128 v[128:131], v157
	ds_read_b128 v[142:145], v157 offset:1024
	ds_read_b128 v[146:149], v157 offset:2048
	ds_read_b128 v[158:161], v157 offset:3072
	s_add_u32 s30, s52, 0x80000
	s_addc_u32 s31, s53, 0
	s_mov_b32 m0, s25
	v_lshl_add_u64 v[222:223], s[30:31], 0, v[178:179]
	ds_read_b128 v[162:165], v156 offset:32768
	ds_read_b128 v[166:169], v156 offset:33792
	ds_read_b128 v[170:173], v156 offset:34816
	ds_read_b128 v[194:197], v156 offset:35840
	ds_read_b128 v[198:201], v156 offset:36864
	ds_read_b128 v[202:205], v156 offset:37888
	ds_read_b128 v[206:209], v156 offset:38912
	ds_read_b128 v[228:231], v156 offset:39936
	global_load_lds_dwordx4 v[222:223], off
	v_lshl_add_u64 v[222:223], s[30:31], 0, v[134:135]
	s_mov_b32 m0, s26
	s_nop 0
	global_load_lds_dwordx4 v[222:223], off
	s_waitcnt lgkmcnt(8)
	s_barrier
	s_waitcnt lgkmcnt(0)
	v_mfma_f32_16x16x32_bf16 v[124:127], v[128:131], v[162:165], v[124:127]
	v_mfma_f32_16x16x32_bf16 v[120:123], v[146:149], v[162:165], v[120:123]
	v_mfma_f32_16x16x32_bf16 v[108:111], v[128:131], v[170:173], v[108:111]
	v_mfma_f32_16x16x32_bf16 v[104:107], v[146:149], v[170:173], v[104:107]
	v_mfma_f32_16x16x32_bf16 v[92:95], v[128:131], v[198:201], v[92:95]
	v_mfma_f32_16x16x32_bf16 v[88:91], v[146:149], v[198:201], v[88:91]
	v_mfma_f32_16x16x32_bf16 v[76:79], v[128:131], v[206:209], v[76:79]
	v_mfma_f32_16x16x32_bf16 v[72:75], v[146:149], v[206:209], v[72:75]
	v_mfma_f32_16x16x32_bf16 v[124:127], v[142:145], v[166:169], v[124:127]
	v_mfma_f32_16x16x32_bf16 v[120:123], v[158:161], v[166:169], v[120:123]
	v_mfma_f32_16x16x32_bf16 v[108:111], v[142:145], v[194:197], v[108:111]
	v_mfma_f32_16x16x32_bf16 v[104:107], v[158:161], v[194:197], v[104:107]
	v_mfma_f32_16x16x32_bf16 v[92:95], v[142:145], v[202:205], v[92:95]
	v_mfma_f32_16x16x32_bf16 v[88:91], v[158:161], v[202:205], v[88:91]
	v_mfma_f32_16x16x32_bf16 v[76:79], v[142:145], v[228:231], v[76:79]
	v_mfma_f32_16x16x32_bf16 v[72:75], v[158:161], v[228:231], v[72:75]
	s_barrier
	s_add_i32 s43, 0, 0x1c000
	s_add_i32 s30, s42, s22
	v_add_u32_e32 v157, s43, v151
	v_lshl_add_u64 v[132:133], v[132:133], 0, s[34:35]
	s_mov_b32 m0, s30
	ds_read_b128 v[232:235], v157
	ds_read_b128 v[236:239], v157 offset:1024
	ds_read_b128 v[240:243], v157 offset:2048
	ds_read_b128 v[244:247], v157 offset:3072
	global_load_lds_dwordx4 v[132:133], off
	v_lshl_add_u64 v[132:133], v[174:175], 0, s[34:35]
	s_add_i32 m0, s30, 0x2000
	s_nop 0
	global_load_lds_dwordx4 v[132:133], off
	s_barrier
	s_waitcnt lgkmcnt(0)
	v_mfma_f32_16x16x32_bf16 v[116:119], v[232:235], v[162:165], v[116:119]
	v_mfma_f32_16x16x32_bf16 v[112:115], v[240:243], v[162:165], v[112:115]
	v_mfma_f32_16x16x32_bf16 v[100:103], v[232:235], v[170:173], v[100:103]
	v_mfma_f32_16x16x32_bf16 v[96:99], v[240:243], v[170:173], v[96:99]
	v_mfma_f32_16x16x32_bf16 v[84:87], v[232:235], v[198:201], v[84:87]
	v_mfma_f32_16x16x32_bf16 v[80:83], v[240:243], v[198:201], v[80:83]
	v_mfma_f32_16x16x32_bf16 v[68:71], v[232:235], v[206:209], v[68:71]
	v_mfma_f32_16x16x32_bf16 v[64:67], v[240:243], v[206:209], v[64:67]
	v_mfma_f32_16x16x32_bf16 v[116:119], v[236:239], v[166:169], v[116:119]
	v_mfma_f32_16x16x32_bf16 v[112:115], v[244:247], v[166:169], v[112:115]
	v_mfma_f32_16x16x32_bf16 v[100:103], v[236:239], v[194:197], v[100:103]
	v_mfma_f32_16x16x32_bf16 v[96:99], v[244:247], v[194:197], v[96:99]
	v_mfma_f32_16x16x32_bf16 v[84:87], v[236:239], v[202:205], v[84:87]
	v_mfma_f32_16x16x32_bf16 v[80:83], v[244:247], v[202:205], v[80:83]
	v_mfma_f32_16x16x32_bf16 v[68:71], v[236:239], v[228:231], v[68:71]
	v_mfma_f32_16x16x32_bf16 v[64:67], v[244:247], v[228:231], v[64:67]
	s_barrier
	s_mov_b32 m0, s28
	v_lshl_add_u64 v[132:133], v[210:211], 0, s[34:35]
	ds_read_b128 v[162:165], v156 offset:49152
	ds_read_b128 v[166:169], v156 offset:50176
	ds_read_b128 v[170:173], v156 offset:51200
	ds_read_b128 v[194:197], v156 offset:52224
	ds_read_b128 v[198:201], v156 offset:53248
	ds_read_b128 v[202:205], v156 offset:54272
	ds_read_b128 v[206:209], v156 offset:55296
	ds_read_b128 v[228:231], v156 offset:56320
	global_load_lds_dwordx4 v[132:133], off
	v_lshl_add_u64 v[132:133], v[220:221], 0, s[34:35]
	s_mov_b32 m0, s29
	s_nop 0
	global_load_lds_dwordx4 v[132:133], off
	s_barrier
; #define PG8_STAGE(bufoff, gbase, voff) do { _Pragma("unroll") for (int _i = 0; _i < 2; ++_i) \
;         __builtin_amdgcn_global_load_lds((const unsigned*)((const char*)(gbase) + (voff)[_i]), (LAS unsigned*)(lds + (bufoff) + ldsw + _i * 8192), 16, 0, 0); } while (0)
; #define PG8_LDA(dst, b, h) do { _Pragma("unroll") for (int m = 0; m < 4; ++m) _Pragma("unroll") for (int k = 0; k < 2; ++k) dst[m][k] = *(const LAS bf16x8*)(lds + PG8_SA(b, h) + aoff + m * 2048 + k * 1024); } while (0)
; #define PG8_LDB(dst, b, h) do { _Pragma("unroll") for (int n = 0; n < 2; ++n) _Pragma("unroll") for (int k = 0; k < 2; ++k) dst[n][k] = *(const LAS bf16x8*)(lds + PG8_SB(b, h) + boff + n * 2048 + k * 1024); } while (0)
; #define PG8_MMA(ai, bj, At, Bt) do { __builtin_amdgcn_s_setprio(1); _Pragma("unroll") for (int m = 0; m < 4; ++m) _Pragma("unroll") for (int n = 0; n < 2; ++n) _Pragma("unroll") for (int k = 0; k < 2; ++k) \
;         acc[ai][bj][m][n] = __builtin_amdgcn_mfma_f32_16x16x32_bf16(Bt[n][k], At[m][k], acc[ai][bj][m][n], 0, 0, 0); __builtin_amdgcn_s_setprio(0); } while (0)
; #define PG8_WAIT_V(n) asm volatile("s_waitcnt vmcnt(" #n ")" ::: "memory")
; #define PG8_WAIT_L(n) asm volatile("s_waitcnt lgkmcnt(" #n ")" ::: "memory")
; #define PG8_BAR __builtin_amdgcn_s_barrier()
; #define PG8_SCHED __builtin_amdgcn_sched_barrier(0)
; template <class Epi>
; __device__ __forceinline__ void gemm_phase(LAS unsigned char* lds, const Gemm g, const StaticOrder S, const Epi E) {
;     ...
;         for (int t = 0; t < nt; t += 2) {
;             const bool last = (t == nt - 2);
;             const char* a1 = cA + (size_t)(t + 1) * kstep;
;             const char* a2 = last ? nA : cA + (size_t)(t + 2) * kstep; const char* b2 = last ? nB : cB + (size_t)(t + 2) * kstep;
;             const char* a3 = a2 + kstep; const char* b3 = b2 + kstep;
;             PG8_LDB(B0, 0, 0); PG8_SCHED; PG8_LDA(At, 0, 0); PG8_STAGE(PG8_SA(1, 1), a1 + hstep, voffA);
;             PG8_WAIT_L(8); PG8_BAR; PG8_WAIT_L(0); PG8_MMA(0, 0, At, B0); PG8_BAR; PG8_SCHED;
;             PG8_LDB(B1, 0, 1); PG8_STAGE(PG8_SB(0, 0), b2, voffA);
;     ...
;             PG8_BAR; PG8_WAIT_L(0); PG8_MMA(1, 0, At, B0); PG8_BAR; PG8_SCHED;
;             PG8_STAGE(PG8_SB(1, 1), b3 + hstep, voffA);
;             PG8_WAIT_V(6); PG8_BAR; PG8_MMA(1, 1, At, B1); PG8_BAR;
	s_waitcnt lgkmcnt(0)
	v_mfma_f32_16x16x32_bf16 v[60:63], v[128:131], v[162:165], v[60:63]
	v_mfma_f32_16x16x32_bf16 v[56:59], v[146:149], v[162:165], v[56:59]
	v_mfma_f32_16x16x32_bf16 v[44:47], v[128:131], v[170:173], v[44:47]
	v_mfma_f32_16x16x32_bf16 v[40:43], v[146:149], v[170:173], v[40:43]
	v_mfma_f32_16x16x32_bf16 v[28:31], v[128:131], v[198:201], v[28:31]
	v_mfma_f32_16x16x32_bf16 v[24:27], v[146:149], v[198:201], v[24:27]
	v_mfma_f32_16x16x32_bf16 v[12:15], v[128:131], v[206:209], v[12:15]
	v_mfma_f32_16x16x32_bf16 v[8:11], v[146:149], v[206:209], v[8:11]
	v_mfma_f32_16x16x32_bf16 v[60:63], v[142:145], v[166:169], v[60:63]
	v_mfma_f32_16x16x32_bf16 v[56:59], v[158:161], v[166:169], v[56:59]
	v_mfma_f32_16x16x32_bf16 v[44:47], v[142:145], v[194:197], v[44:47]
	v_mfma_f32_16x16x32_bf16 v[40:43], v[158:161], v[194:197], v[40:43]
	v_mfma_f32_16x16x32_bf16 v[28:31], v[142:145], v[202:205], v[28:31]
	v_mfma_f32_16x16x32_bf16 v[24:27], v[158:161], v[202:205], v[24:27]
	v_mfma_f32_16x16x32_bf16 v[12:15], v[142:145], v[228:231], v[12:15]
	v_mfma_f32_16x16x32_bf16 v[8:11], v[158:161], v[228:231], v[8:11]
	s_barrier
	s_add_u32 s30, s50, 0x80080
	s_addc_u32 s31, s51, 0
	s_add_i32 s42, s43, s22
	v_lshl_add_u64 v[128:129], s[30:31], 0, v[178:179]
	s_mov_b32 m0, s42
	s_nop 0
	global_load_lds_dwordx4 v[128:129], off
	v_lshl_add_u64 v[128:129], s[30:31], 0, v[134:135]
	s_add_i32 m0, s42, 0x2000
	s_nop 0
	global_load_lds_dwordx4 v[128:129], off
	s_waitcnt vmcnt(6)
	s_barrier
	v_mfma_f32_16x16x32_bf16 v[52:55], v[232:235], v[162:165], v[52:55]
	v_mfma_f32_16x16x32_bf16 v[48:51], v[240:243], v[162:165], v[48:51]
	v_mfma_f32_16x16x32_bf16 v[36:39], v[232:235], v[170:173], v[36:39]
	v_mfma_f32_16x16x32_bf16 v[32:35], v[240:243], v[170:173], v[32:35]
	v_mfma_f32_16x16x32_bf16 v[20:23], v[232:235], v[198:201], v[20:23]
	v_mfma_f32_16x16x32_bf16 v[16:19], v[240:243], v[198:201], v[16:19]
	v_mfma_f32_16x16x32_bf16 v[4:7], v[232:235], v[206:209], v[4:7]
	v_mfma_f32_16x16x32_bf16 v[0:3], v[240:243], v[206:209], v[0:3]
	v_mfma_f32_16x16x32_bf16 v[52:55], v[236:239], v[166:169], v[52:55]
	v_mfma_f32_16x16x32_bf16 v[48:51], v[244:247], v[166:169], v[48:51]
	v_mfma_f32_16x16x32_bf16 v[36:39], v[236:239], v[194:197], v[36:39]
	v_mfma_f32_16x16x32_bf16 v[32:35], v[244:247], v[194:197], v[32:35]
	v_mfma_f32_16x16x32_bf16 v[20:23], v[236:239], v[202:205], v[20:23]
	v_mfma_f32_16x16x32_bf16 v[16:19], v[244:247], v[202:205], v[16:19]
	v_mfma_f32_16x16x32_bf16 v[4:7], v[236:239], v[228:231], v[4:7]
	v_mfma_f32_16x16x32_bf16 v[0:3], v[244:247], v[228:231], v[0:3]
	s_barrier
	s_add_i32 s57, s57, 2
	s_add_u32 s3, s3, 0x100
	s_addc_u32 s11, s11, 0
	s_cmp_gt_u32 s57, 29
	s_mov_b64 s[42:43], s[48:49]
	s_cbranch_scc0 .LBB0_2721
	s_branch .Lpeel_exit_2
.LBB0_2721:
	s_add_u32 s48, s42, 0x100
	s_addc_u32 s49, s43, 0
	s_add_i32 s30, 0, 0x10000
	v_add_u32_e32 v132, s30, v151
	ds_read_b128 v[128:131], v132
	ds_read_b128 v[142:145], v132 offset:1024
	ds_read_b128 v[146:149], v132 offset:2048
	ds_read_b128 v[158:161], v132 offset:3072
	s_cmp_eq_u32 s57, 28
	s_cselect_b32 s53, s45, s49
	s_cselect_b32 s52, s44, s48
	s_cselect_b32 s51, s47, s11
	s_cselect_b32 s50, s46, s3
	v_lshl_add_u64 v[132:133], s[42:43], 0, v[138:139]
	s_add_i32 m0, s23, 0xc000
	ds_read_b128 v[162:165], v156
	ds_read_b128 v[166:169], v156 offset:1024
	ds_read_b128 v[170:173], v156 offset:2048
	ds_read_b128 v[194:197], v156 offset:3072
	ds_read_b128 v[198:201], v156 offset:4096
	ds_read_b128 v[202:205], v156 offset:5120
	ds_read_b128 v[206:209], v156 offset:6144
	ds_read_b128 v[228:231], v156 offset:7168
	global_load_lds_dwordx4 v[132:133], off
	v_lshl_add_u64 v[132:133], s[42:43], 0, v[140:141]
	s_add_i32 m0, s23, 0xe000
	s_nop 0
	global_load_lds_dwordx4 v[132:133], off
	s_waitcnt lgkmcnt(8)
	s_barrier
	s_waitcnt lgkmcnt(0)
	v_mfma_f32_16x16x32_bf16 v[124:127], v[128:131], v[162:165], v[124:127]
	v_mfma_f32_16x16x32_bf16 v[120:123], v[146:149], v[162:165], v[120:123]
	v_mfma_f32_16x16x32_bf16 v[108:111], v[128:131], v[170:173], v[108:111]
	v_mfma_f32_16x16x32_bf16 v[104:107], v[146:149], v[170:173], v[104:107]
	v_mfma_f32_16x16x32_bf16 v[92:95], v[128:131], v[198:201], v[92:95]
	v_mfma_f32_16x16x32_bf16 v[88:91], v[146:149], v[198:201], v[88:91]
	v_mfma_f32_16x16x32_bf16 v[76:79], v[128:131], v[206:209], v[76:79]
	v_mfma_f32_16x16x32_bf16 v[72:75], v[146:149], v[206:209], v[72:75]
	v_mfma_f32_16x16x32_bf16 v[124:127], v[142:145], v[166:169], v[124:127]
	v_mfma_f32_16x16x32_bf16 v[120:123], v[158:161], v[166:169], v[120:123]
	v_mfma_f32_16x16x32_bf16 v[108:111], v[142:145], v[194:197], v[108:111]
	v_mfma_f32_16x16x32_bf16 v[104:107], v[158:161], v[194:197], v[104:107]
	v_mfma_f32_16x16x32_bf16 v[92:95], v[142:145], v[202:205], v[92:95]
	v_mfma_f32_16x16x32_bf16 v[88:91], v[158:161], v[202:205], v[88:91]
	v_mfma_f32_16x16x32_bf16 v[76:79], v[142:145], v[228:231], v[76:79]
	v_mfma_f32_16x16x32_bf16 v[72:75], v[158:161], v[228:231], v[72:75]
	s_barrier
	s_add_i32 s42, 0, 0x14000
	v_add_u32_e32 v132, s42, v151
	s_add_i32 s30, s30, s22
	ds_read_b128 v[232:235], v132
	ds_read_b128 v[236:239], v132 offset:1024
	ds_read_b128 v[240:243], v132 offset:2048
	ds_read_b128 v[244:247], v132 offset:3072
	v_lshl_add_u64 v[132:133], s[50:51], 0, v[178:179]
	s_mov_b32 m0, s30
	v_lshl_add_u64 v[174:175], s[50:51], 0, v[134:135]
	global_load_lds_dwordx4 v[132:133], off
	s_add_i32 m0, s30, 0x2000
	s_nop 0
	global_load_lds_dwordx4 v[174:175], off
	s_barrier
; #define PG8_STAGE(bufoff, gbase, voff) do { _Pragma("unroll") for (int _i = 0; _i < 2; ++_i) \
;         __builtin_amdgcn_global_load_lds((const unsigned*)((const char*)(gbase) + (voff)[_i]), (LAS unsigned*)(lds + (bufoff) + ldsw + _i * 8192), 16, 0, 0); } while (0)
; #define PG8_LDA(dst, b, h) do { _Pragma("unroll") for (int m = 0; m < 4; ++m) _Pragma("unroll") for (int k = 0; k < 2; ++k) dst[m][k] = *(const LAS bf16x8*)(lds + PG8_SA(b, h) + aoff + m * 2048 + k * 1024); } while (0)
; #define PG8_LDB(dst, b, h) do { _Pragma("unroll") for (int n = 0; n < 2; ++n) _Pragma("unroll") for (int k = 0; k < 2; ++k) dst[n][k] = *(const LAS bf16x8*)(lds + PG8_SB(b, h) + boff + n * 2048 + k * 1024); } while (0)
; #define PG8_MMA(ai, bj, At, Bt) do { __builtin_amdgcn_s_setprio(1); _Pragma("unroll") for (int m = 0; m < 4; ++m) _Pragma("unroll") for (int n = 0; n < 2; ++n) _Pragma("unroll") for (int k = 0; k < 2; ++k) \
;         acc[ai][bj][m][n] = __builtin_amdgcn_mfma_f32_16x16x32_bf16(Bt[n][k], At[m][k], acc[ai][bj][m][n], 0, 0, 0); __builtin_amdgcn_s_setprio(0); } while (0)
; #define PG8_WAIT_V(n) asm volatile("s_waitcnt vmcnt(" #n ")" ::: "memory")
; #define PG8_WAIT_L(n) asm volatile("s_waitcnt lgkmcnt(" #n ")" ::: "memory")
; #define PG8_BAR __builtin_amdgcn_s_barrier()
; #define PG8_SCHED __builtin_amdgcn_sched_barrier(0)
; template <class Epi>
; __device__ __forceinline__ void gemm_phase(LAS unsigned char* lds, const Gemm g, const StaticOrder S, const Epi E) {
;     ...
;             PG8_BAR; PG8_WAIT_L(0); PG8_MMA(0, 1, At, B1); PG8_BAR;
;             PG8_LDA(At, 0, 1); PG8_STAGE(PG8_SA(0, 0), a2, voffA);
;             PG8_BAR; PG8_WAIT_L(0); PG8_MMA(1, 0, At, B0); PG8_BAR; PG8_SCHED;
;             PG8_STAGE(PG8_SB(0, 1), b2 + hstep, voffA);
;             PG8_WAIT_V(6); PG8_BAR; PG8_MMA(1, 1, At, B1); PG8_BAR;
;             PG8_LDB(B0, 1, 0); PG8_SCHED; PG8_LDA(At, 1, 0); PG8_STAGE(PG8_SA(0, 1), a2 + hstep, voffA);
;             PG8_WAIT_L(8); PG8_BAR; PG8_WAIT_L(0); PG8_MMA(0, 0, At, B0); PG8_BAR; PG8_SCHED;
	s_waitcnt lgkmcnt(0)
	v_mfma_f32_16x16x32_bf16 v[116:119], v[232:235], v[162:165], v[116:119]
	v_mfma_f32_16x16x32_bf16 v[112:115], v[240:243], v[162:165], v[112:115]
	v_mfma_f32_16x16x32_bf16 v[100:103], v[232:235], v[170:173], v[100:103]
	v_mfma_f32_16x16x32_bf16 v[96:99], v[240:243], v[170:173], v[96:99]
	v_mfma_f32_16x16x32_bf16 v[84:87], v[232:235], v[198:201], v[84:87]
	v_mfma_f32_16x16x32_bf16 v[80:83], v[240:243], v[198:201], v[80:83]
	v_mfma_f32_16x16x32_bf16 v[68:71], v[232:235], v[206:209], v[68:71]
	v_mfma_f32_16x16x32_bf16 v[64:67], v[240:243], v[206:209], v[64:67]
	v_mfma_f32_16x16x32_bf16 v[116:119], v[236:239], v[166:169], v[116:119]
	v_mfma_f32_16x16x32_bf16 v[112:115], v[244:247], v[166:169], v[112:115]
	v_mfma_f32_16x16x32_bf16 v[100:103], v[236:239], v[194:197], v[100:103]
	v_mfma_f32_16x16x32_bf16 v[96:99], v[244:247], v[194:197], v[96:99]
	v_mfma_f32_16x16x32_bf16 v[84:87], v[236:239], v[202:205], v[84:87]
	v_mfma_f32_16x16x32_bf16 v[80:83], v[244:247], v[202:205], v[80:83]
	v_mfma_f32_16x16x32_bf16 v[68:71], v[236:239], v[228:231], v[68:71]
	v_mfma_f32_16x16x32_bf16 v[64:67], v[244:247], v[228:231], v[64:67]
	s_barrier
	s_mov_b32 m0, s23
	v_lshl_add_u64 v[210:211], s[52:53], 0, v[178:179]
	ds_read_b128 v[162:165], v156 offset:16384
	ds_read_b128 v[166:169], v156 offset:17408
	ds_read_b128 v[170:173], v156 offset:18432
	ds_read_b128 v[194:197], v156 offset:19456
	ds_read_b128 v[198:201], v156 offset:20480
	ds_read_b128 v[202:205], v156 offset:21504
	ds_read_b128 v[206:209], v156 offset:22528
	ds_read_b128 v[228:231], v156 offset:23552
	global_load_lds_dwordx4 v[210:211], off
	v_lshl_add_u64 v[220:221], s[52:53], 0, v[134:135]
	s_mov_b32 m0, s24
	s_nop 0
	global_load_lds_dwordx4 v[220:221], off
	s_barrier
	s_waitcnt lgkmcnt(0)
	v_mfma_f32_16x16x32_bf16 v[60:63], v[128:131], v[162:165], v[60:63]
	v_mfma_f32_16x16x32_bf16 v[56:59], v[146:149], v[162:165], v[56:59]
	v_mfma_f32_16x16x32_bf16 v[44:47], v[128:131], v[170:173], v[44:47]
	v_mfma_f32_16x16x32_bf16 v[40:43], v[146:149], v[170:173], v[40:43]
	v_mfma_f32_16x16x32_bf16 v[28:31], v[128:131], v[198:201], v[28:31]
	v_mfma_f32_16x16x32_bf16 v[24:27], v[146:149], v[198:201], v[24:27]
	v_mfma_f32_16x16x32_bf16 v[12:15], v[128:131], v[206:209], v[12:15]
	v_mfma_f32_16x16x32_bf16 v[8:11], v[146:149], v[206:209], v[8:11]
	v_mfma_f32_16x16x32_bf16 v[60:63], v[142:145], v[166:169], v[60:63]
	v_mfma_f32_16x16x32_bf16 v[56:59], v[158:161], v[166:169], v[56:59]
	v_mfma_f32_16x16x32_bf16 v[44:47], v[142:145], v[194:197], v[44:47]
	v_mfma_f32_16x16x32_bf16 v[40:43], v[158:161], v[194:197], v[40:43]
	v_mfma_f32_16x16x32_bf16 v[28:31], v[142:145], v[202:205], v[28:31]
	v_mfma_f32_16x16x32_bf16 v[24:27], v[158:161], v[202:205], v[24:27]
	v_mfma_f32_16x16x32_bf16 v[12:15], v[142:145], v[228:231], v[12:15]
	v_mfma_f32_16x16x32_bf16 v[8:11], v[158:161], v[228:231], v[8:11]
	s_barrier
	s_add_u32 s30, s50, 0x80000
	s_addc_u32 s31, s51, 0
	s_add_i32 s42, s42, s22
	v_lshl_add_u64 v[128:129], s[30:31], 0, v[178:179]
	s_mov_b32 m0, s42
	s_nop 0
	global_load_lds_dwordx4 v[128:129], off
	v_lshl_add_u64 v[128:129], s[30:31], 0, v[134:135]
	s_add_i32 m0, s42, 0x2000
	s_nop 0
	global_load_lds_dwordx4 v[128:129], off
	s_waitcnt vmcnt(6)
	s_barrier
	v_mfma_f32_16x16x32_bf16 v[52:55], v[232:235], v[162:165], v[52:55]
	v_mfma_f32_16x16x32_bf16 v[48:51], v[240:243], v[162:165], v[48:51]
	v_mfma_f32_16x16x32_bf16 v[36:39], v[232:235], v[170:173], v[36:39]
	v_mfma_f32_16x16x32_bf16 v[32:35], v[240:243], v[170:173], v[32:35]
	v_mfma_f32_16x16x32_bf16 v[20:23], v[232:235], v[198:201], v[20:23]
	v_mfma_f32_16x16x32_bf16 v[16:19], v[240:243], v[198:201], v[16:19]
	v_mfma_f32_16x16x32_bf16 v[4:7], v[232:235], v[206:209], v[4:7]
	v_mfma_f32_16x16x32_bf16 v[0:3], v[240:243], v[206:209], v[0:3]
	v_mfma_f32_16x16x32_bf16 v[52:55], v[236:239], v[166:169], v[52:55]
	v_mfma_f32_16x16x32_bf16 v[48:51], v[244:247], v[166:169], v[48:51]
	v_mfma_f32_16x16x32_bf16 v[36:39], v[236:239], v[194:197], v[36:39]
	v_mfma_f32_16x16x32_bf16 v[32:35], v[244:247], v[194:197], v[32:35]
	v_mfma_f32_16x16x32_bf16 v[20:23], v[236:239], v[202:205], v[20:23]
	v_mfma_f32_16x16x32_bf16 v[16:19], v[244:247], v[202:205], v[16:19]
	v_mfma_f32_16x16x32_bf16 v[4:7], v[236:239], v[228:231], v[4:7]
	v_mfma_f32_16x16x32_bf16 v[0:3], v[244:247], v[228:231], v[0:3]
	s_barrier
	s_add_i32 s42, 0, 0x18000
	v_add_u32_e32 v157, s42, v151
	ds_read_b128 v[128:131], v157
	ds_read_b128 v[142:145], v157 offset:1024
	ds_read_b128 v[146:149], v157 offset:2048
	ds_read_b128 v[158:161], v157 offset:3072
	s_add_u32 s30, s52, 0x80000
	s_addc_u32 s31, s53, 0
	s_mov_b32 m0, s25
	v_lshl_add_u64 v[222:223], s[30:31], 0, v[178:179]
	ds_read_b128 v[162:165], v156 offset:32768
	ds_read_b128 v[166:169], v156 offset:33792
	ds_read_b128 v[170:173], v156 offset:34816
	ds_read_b128 v[194:197], v156 offset:35840
	ds_read_b128 v[198:201], v156 offset:36864
	ds_read_b128 v[202:205], v156 offset:37888
	ds_read_b128 v[206:209], v156 offset:38912
	ds_read_b128 v[228:231], v156 offset:39936
	global_load_lds_dwordx4 v[222:223], off
	v_lshl_add_u64 v[222:223], s[30:31], 0, v[134:135]
	s_mov_b32 m0, s26
	s_nop 0
	global_load_lds_dwordx4 v[222:223], off
	s_waitcnt lgkmcnt(8)
	s_barrier
; #define PG8_STAGE(bufoff, gbase, voff) do { _Pragma("unroll") for (int _i = 0; _i < 2; ++_i) \
;         __builtin_amdgcn_global_load_lds((const unsigned*)((const char*)(gbase) + (voff)[_i]), (LAS unsigned*)(lds + (bufoff) + ldsw + _i * 8192), 16, 0, 0); } while (0)
; #define PG8_LDA(dst, b, h) do { _Pragma("unroll") for (int m = 0; m < 4; ++m) _Pragma("unroll") for (int k = 0; k < 2; ++k) dst[m][k] = *(const LAS bf16x8*)(lds + PG8_SA(b, h) + aoff + m * 2048 + k * 1024); } while (0)
; #define PG8_LDB(dst, b, h) do { _Pragma("unroll") for (int n = 0; n < 2; ++n) _Pragma("unroll") for (int k = 0; k < 2; ++k) dst[n][k] = *(const LAS bf16x8*)(lds + PG8_SB(b, h) + boff + n * 2048 + k * 1024); } while (0)
; #define PG8_MMA(ai, bj, At, Bt) do { __builtin_amdgcn_s_setprio(1); _Pragma("unroll") for (int m = 0; m < 4; ++m) _Pragma("unroll") for (int n = 0; n < 2; ++n) _Pragma("unroll") for (int k = 0; k < 2; ++k) \
;         acc[ai][bj][m][n] = __builtin_amdgcn_mfma_f32_16x16x32_bf16(Bt[n][k], At[m][k], acc[ai][bj][m][n], 0, 0, 0); __builtin_amdgcn_s_setprio(0); } while (0)
; #define PG8_WAIT_V(n) asm volatile("s_waitcnt vmcnt(" #n ")" ::: "memory")
; #define PG8_WAIT_L(n) asm volatile("s_waitcnt lgkmcnt(" #n ")" ::: "memory")
; #define PG8_BAR __builtin_amdgcn_s_barrier()
; #define PG8_SCHED __builtin_amdgcn_sched_barrier(0)
; template <class Epi>
; __device__ __forceinline__ void gemm_phase(LAS unsigned char* lds, const Gemm g, const StaticOrder S, const Epi E) {
;     ...
;             PG8_WAIT_L(8); PG8_BAR; PG8_WAIT_L(0); PG8_MMA(0, 0, At, B0); PG8_BAR; PG8_SCHED;
;             PG8_LDB(B1, 1, 1); PG8_STAGE(PG8_SB(1, 0), b3, voffA);
;             PG8_BAR; PG8_WAIT_L(0); PG8_MMA(0, 1, At, B1); PG8_BAR;
;             PG8_LDA(At, 1, 1); PG8_STAGE(PG8_SA(1, 0), a3, voffA);
;             PG8_BAR; PG8_WAIT_L(0); PG8_MMA(1, 0, At, B0); PG8_BAR; PG8_SCHED;
;             PG8_STAGE(PG8_SB(1, 1), b3 + hstep, voffA);
;             PG8_WAIT_V(6); PG8_BAR; PG8_MMA(1, 1, At, B1); PG8_BAR;
;         }
	s_waitcnt lgkmcnt(0)
	v_mfma_f32_16x16x32_bf16 v[124:127], v[128:131], v[162:165], v[124:127]
	v_mfma_f32_16x16x32_bf16 v[120:123], v[146:149], v[162:165], v[120:123]
	v_mfma_f32_16x16x32_bf16 v[108:111], v[128:131], v[170:173], v[108:111]
	v_mfma_f32_16x16x32_bf16 v[104:107], v[146:149], v[170:173], v[104:107]
	v_mfma_f32_16x16x32_bf16 v[92:95], v[128:131], v[198:201], v[92:95]
	v_mfma_f32_16x16x32_bf16 v[88:91], v[146:149], v[198:201], v[88:91]
	v_mfma_f32_16x16x32_bf16 v[76:79], v[128:131], v[206:209], v[76:79]
	v_mfma_f32_16x16x32_bf16 v[72:75], v[146:149], v[206:209], v[72:75]
	v_mfma_f32_16x16x32_bf16 v[124:127], v[142:145], v[166:169], v[124:127]
	v_mfma_f32_16x16x32_bf16 v[120:123], v[158:161], v[166:169], v[120:123]
	v_mfma_f32_16x16x32_bf16 v[108:111], v[142:145], v[194:197], v[108:111]
	v_mfma_f32_16x16x32_bf16 v[104:107], v[158:161], v[194:197], v[104:107]
	v_mfma_f32_16x16x32_bf16 v[92:95], v[142:145], v[202:205], v[92:95]
	v_mfma_f32_16x16x32_bf16 v[88:91], v[158:161], v[202:205], v[88:91]
	v_mfma_f32_16x16x32_bf16 v[76:79], v[142:145], v[228:231], v[76:79]
	v_mfma_f32_16x16x32_bf16 v[72:75], v[158:161], v[228:231], v[72:75]
	s_barrier
	s_add_i32 s43, 0, 0x1c000
	s_add_i32 s30, s42, s22
	v_add_u32_e32 v157, s43, v151
	v_lshl_add_u64 v[132:133], v[132:133], 0, s[34:35]
	s_mov_b32 m0, s30
	ds_read_b128 v[232:235], v157
	ds_read_b128 v[236:239], v157 offset:1024
	ds_read_b128 v[240:243], v157 offset:2048
	ds_read_b128 v[244:247], v157 offset:3072
	global_load_lds_dwordx4 v[132:133], off
	v_lshl_add_u64 v[132:133], v[174:175], 0, s[34:35]
	s_add_i32 m0, s30, 0x2000
	s_nop 0
	global_load_lds_dwordx4 v[132:133], off
	s_barrier
	s_waitcnt lgkmcnt(0)
	v_mfma_f32_16x16x32_bf16 v[116:119], v[232:235], v[162:165], v[116:119]
	v_mfma_f32_16x16x32_bf16 v[112:115], v[240:243], v[162:165], v[112:115]
	v_mfma_f32_16x16x32_bf16 v[100:103], v[232:235], v[170:173], v[100:103]
	v_mfma_f32_16x16x32_bf16 v[96:99], v[240:243], v[170:173], v[96:99]
	v_mfma_f32_16x16x32_bf16 v[84:87], v[232:235], v[198:201], v[84:87]
	v_mfma_f32_16x16x32_bf16 v[80:83], v[240:243], v[198:201], v[80:83]
	v_mfma_f32_16x16x32_bf16 v[68:71], v[232:235], v[206:209], v[68:71]
	v_mfma_f32_16x16x32_bf16 v[64:67], v[240:243], v[206:209], v[64:67]
	v_mfma_f32_16x16x32_bf16 v[116:119], v[236:239], v[166:169], v[116:119]
	v_mfma_f32_16x16x32_bf16 v[112:115], v[244:247], v[166:169], v[112:115]
	v_mfma_f32_16x16x32_bf16 v[100:103], v[236:239], v[194:197], v[100:103]
	v_mfma_f32_16x16x32_bf16 v[96:99], v[244:247], v[194:197], v[96:99]
	v_mfma_f32_16x16x32_bf16 v[84:87], v[236:239], v[202:205], v[84:87]
	v_mfma_f32_16x16x32_bf16 v[80:83], v[244:247], v[202:205], v[80:83]
	v_mfma_f32_16x16x32_bf16 v[68:71], v[236:239], v[228:231], v[68:71]
	v_mfma_f32_16x16x32_bf16 v[64:67], v[244:247], v[228:231], v[64:67]
	s_barrier
	s_mov_b32 m0, s28
	v_lshl_add_u64 v[132:133], v[210:211], 0, s[34:35]
	ds_read_b128 v[162:165], v156 offset:49152
	ds_read_b128 v[166:169], v156 offset:50176
	ds_read_b128 v[170:173], v156 offset:51200
	ds_read_b128 v[194:197], v156 offset:52224
	ds_read_b128 v[198:201], v156 offset:53248
	ds_read_b128 v[202:205], v156 offset:54272
	ds_read_b128 v[206:209], v156 offset:55296
	ds_read_b128 v[228:231], v156 offset:56320
	global_load_lds_dwordx4 v[132:133], off
	v_lshl_add_u64 v[132:133], v[220:221], 0, s[34:35]
	s_mov_b32 m0, s29
	s_nop 0
	global_load_lds_dwordx4 v[132:133], off
	s_barrier
	s_waitcnt lgkmcnt(0)
	v_mfma_f32_16x16x32_bf16 v[60:63], v[128:131], v[162:165], v[60:63]
	v_mfma_f32_16x16x32_bf16 v[56:59], v[146:149], v[162:165], v[56:59]
	v_mfma_f32_16x16x32_bf16 v[44:47], v[128:131], v[170:173], v[44:47]
	v_mfma_f32_16x16x32_bf16 v[40:43], v[146:149], v[170:173], v[40:43]
	v_mfma_f32_16x16x32_bf16 v[28:31], v[128:131], v[198:201], v[28:31]
	v_mfma_f32_16x16x32_bf16 v[24:27], v[146:149], v[198:201], v[24:27]
	v_mfma_f32_16x16x32_bf16 v[12:15], v[128:131], v[206:209], v[12:15]
	v_mfma_f32_16x16x32_bf16 v[8:11], v[146:149], v[206:209], v[8:11]
	v_mfma_f32_16x16x32_bf16 v[60:63], v[142:145], v[166:169], v[60:63]
	v_mfma_f32_16x16x32_bf16 v[56:59], v[158:161], v[166:169], v[56:59]
	v_mfma_f32_16x16x32_bf16 v[44:47], v[142:145], v[194:197], v[44:47]
	v_mfma_f32_16x16x32_bf16 v[40:43], v[158:161], v[194:197], v[40:43]
	v_mfma_f32_16x16x32_bf16 v[28:31], v[142:145], v[202:205], v[28:31]
	v_mfma_f32_16x16x32_bf16 v[24:27], v[158:161], v[202:205], v[24:27]
	v_mfma_f32_16x16x32_bf16 v[12:15], v[142:145], v[228:231], v[12:15]
	v_mfma_f32_16x16x32_bf16 v[8:11], v[158:161], v[228:231], v[8:11]
	s_barrier
	s_add_u32 s30, s50, 0x80080
	s_addc_u32 s31, s51, 0
	s_add_i32 s42, s43, s22
	v_lshl_add_u64 v[128:129], s[30:31], 0, v[178:179]
	s_mov_b32 m0, s42
	s_nop 0
	global_load_lds_dwordx4 v[128:129], off
	v_lshl_add_u64 v[128:129], s[30:31], 0, v[134:135]
	s_add_i32 m0, s42, 0x2000
	s_nop 0
	global_load_lds_dwordx4 v[128:129], off
	s_waitcnt vmcnt(6)
	s_barrier
	v_mfma_f32_16x16x32_bf16 v[52:55], v[232:235], v[162:165], v[52:55]
	v_mfma_f32_16x16x32_bf16 v[48:51], v[240:243], v[162:165], v[48:51]
	v_mfma_f32_16x16x32_bf16 v[36:39], v[232:235], v[170:173], v[36:39]
	v_mfma_f32_16x16x32_bf16 v[32:35], v[240:243], v[170:173], v[32:35]
	v_mfma_f32_16x16x32_bf16 v[20:23], v[232:235], v[198:201], v[20:23]
	v_mfma_f32_16x16x32_bf16 v[16:19], v[240:243], v[198:201], v[16:19]
	v_mfma_f32_16x16x32_bf16 v[4:7], v[232:235], v[206:209], v[4:7]
	v_mfma_f32_16x16x32_bf16 v[0:3], v[240:243], v[206:209], v[0:3]
	v_mfma_f32_16x16x32_bf16 v[52:55], v[236:239], v[166:169], v[52:55]
	v_mfma_f32_16x16x32_bf16 v[48:51], v[244:247], v[166:169], v[48:51]
	v_mfma_f32_16x16x32_bf16 v[36:39], v[236:239], v[194:197], v[36:39]
	v_mfma_f32_16x16x32_bf16 v[32:35], v[244:247], v[194:197], v[32:35]
	v_mfma_f32_16x16x32_bf16 v[20:23], v[236:239], v[202:205], v[20:23]
	v_mfma_f32_16x16x32_bf16 v[16:19], v[244:247], v[202:205], v[16:19]
	v_mfma_f32_16x16x32_bf16 v[4:7], v[236:239], v[228:231], v[4:7]
	v_mfma_f32_16x16x32_bf16 v[0:3], v[244:247], v[228:231], v[0:3]
	s_barrier
	s_add_i32 s57, s57, 2
	s_add_u32 s3, s3, 0x100
	s_addc_u32 s11, s11, 0
	s_cmp_gt_u32 s57, 29
	s_mov_b64 s[42:43], s[48:49]
	s_cbranch_scc0 .LBB0_2721

; #define PG8_STAGE(bufoff, gbase, voff) do { _Pragma("unroll") for (int _i = 0; _i < 2; ++_i) \
;         __builtin_amdgcn_global_load_lds((const unsigned*)((const char*)(gbase) + (voff)[_i]), (LAS unsigned*)(lds + (bufoff) + ldsw + _i * 8192), 16, 0, 0); } while (0)
; #define PG8_LDA(dst, b, h) do { _Pragma("unroll") for (int m = 0; m < 4; ++m) _Pragma("unroll") for (int k = 0; k < 2; ++k) dst[m][k] = *(const LAS bf16x8*)(lds + PG8_SA(b, h) + aoff + m * 2048 + k * 1024); } while (0)
; #define PG8_LDB(dst, b, h) do { _Pragma("unroll") for (int n = 0; n < 2; ++n) _Pragma("unroll") for (int k = 0; k < 2; ++k) dst[n][k] = *(const LAS bf16x8*)(lds + PG8_SB(b, h) + boff + n * 2048 + k * 1024); } while (0)
; #define PG8_MMA(ai, bj, At, Bt) do { __builtin_amdgcn_s_setprio(1); _Pragma("unroll") for (int m = 0; m < 4; ++m) _Pragma("unroll") for (int n = 0; n < 2; ++n) _Pragma("unroll") for (int k = 0; k < 2; ++k) \
;         acc[ai][bj][m][n] = __builtin_amdgcn_mfma_f32_16x16x32_bf16(Bt[n][k], At[m][k], acc[ai][bj][m][n], 0, 0, 0); __builtin_amdgcn_s_setprio(0); } while (0)
; template <class Epi>
; __device__ __forceinline__ void gemm_phase(LAS unsigned char* lds, const Gemm g, const StaticOrder S, const Epi E) {
;     ...
;         const bool has_next = S.next(ui + 1, nxt);
;         const char* nA = has_next ? (const char*)g.A + (size_t)nxt.pm * tstep + (size_t)nxt.k0 * kstep : cA; const char* nB = has_next ? (const char*)g.Bt + (size_t)nxt.pn * tstep + (size_t)nxt.k0 * kstep : cB;
;         const int nt = cur.nk;
;         for (int t = 0; t < nt; t += 2) {
;             const bool last = (t == nt - 2);
;             const char* a1 = cA + (size_t)(t + 1) * kstep;
;             const char* a2 = last ? nA : cA + (size_t)(t + 2) * kstep; const char* b2 = last ? nB : cB + (size_t)(t + 2) * kstep;
;             const char* a3 = a2 + kstep; const char* b3 = b2 + kstep;
;             PG8_LDB(B0, 0, 0); PG8_SCHED; PG8_LDA(At, 0, 0); PG8_STAGE(PG8_SA(1, 1), a1 + hstep, voffA);
;             PG8_WAIT_L(8); PG8_BAR; PG8_WAIT_L(0); PG8_MMA(0, 0, At, B0); PG8_BAR; PG8_SCHED;
;             PG8_LDB(B1, 0, 1); PG8_STAGE(PG8_SB(0, 0), b2, voffA);
;             PG8_BAR; PG8_WAIT_L(0); PG8_MMA(0, 1, At, B1); PG8_BAR;
;             PG8_LDA(At, 0, 1); PG8_STAGE(PG8_SA(0, 0), a2, voffA);
;             PG8_BAR; PG8_WAIT_L(0); PG8_MMA(1, 0, At, B0); PG8_BAR; PG8_SCHED;
.LBB0_3277:
	s_ashr_i32 s3, s2, 31
	s_lshl_b64 s[28:29], s[2:3], 18
	v_readlane_b32 s1, v253, 48
	s_add_u32 s1, s1, s28
	v_cmp_lt_i64_e32 vcc, s[46:47], v[188:189]
	s_addc_u32 s3, s14, s29
	s_and_b64 s[28:29], vcc, exec
	s_cselect_b32 s47, s3, s53
	s_cselect_b32 s46, s1, s52
	s_ashr_i32 s1, s0, 31
	s_lshl_b64 s[28:29], s[0:1], 18
	s_add_u32 s1, s6, s28
	s_addc_u32 s3, s7, s29
	s_and_b64 s[28:29], vcc, exec
	s_cselect_b32 s49, s3, s55
	s_cselect_b32 s48, s1, s54
	s_add_u32 s1, s54, 0x100
	s_addc_u32 s3, s55, 0
	s_mov_b32 s27, -2
	s_add_u32 s54, s52, 0x100
	s_addc_u32 s55, s53, 0
	s_add_i32 s28, 0, 0x10000
	v_add_u32_e32 v140, s28, v157
	ds_read_b128 v[128:131], v140
	ds_read_b128 v[132:135], v140 offset:1024
	ds_read_b128 v[136:139], v140 offset:2048
	ds_read_b128 v[164:167], v140 offset:3072
	s_cmp_eq_u32 s27, 4
	s_cselect_b32 s59, s47, s55
	s_cselect_b32 s58, s46, s54
	s_cselect_b32 s57, s49, s3
	s_cselect_b32 s56, s48, s1
	v_lshl_add_u64 v[140:141], s[52:53], 0, v[150:151]
	s_add_i32 m0, s23, 0xc000
	ds_read_b128 v[168:171], v162
	ds_read_b128 v[172:175], v162 offset:1024
	ds_read_b128 v[194:197], v162 offset:2048
	ds_read_b128 v[198:201], v162 offset:3072
	ds_read_b128 v[202:205], v162 offset:4096
	ds_read_b128 v[206:209], v162 offset:5120
	ds_read_b128 v[228:231], v162 offset:6144
	ds_read_b128 v[232:235], v162 offset:7168
	global_load_lds_dwordx4 v[140:141], off
	v_lshl_add_u64 v[140:141], s[52:53], 0, v[152:153]
	s_add_i32 m0, s23, 0xe000
	s_nop 0
	global_load_lds_dwordx4 v[140:141], off
	s_waitcnt lgkmcnt(8)
	s_barrier
	s_waitcnt lgkmcnt(0)
	v_mfma_f32_16x16x32_bf16 v[124:127], v[128:131], v[168:171], 0
	v_mfma_f32_16x16x32_bf16 v[120:123], v[136:139], v[168:171], 0
	v_mfma_f32_16x16x32_bf16 v[108:111], v[128:131], v[194:197], 0
	v_mfma_f32_16x16x32_bf16 v[104:107], v[136:139], v[194:197], 0
	v_mfma_f32_16x16x32_bf16 v[92:95], v[128:131], v[202:205], 0
	v_mfma_f32_16x16x32_bf16 v[88:91], v[136:139], v[202:205], 0
	v_mfma_f32_16x16x32_bf16 v[76:79], v[128:131], v[228:231], 0
	v_mfma_f32_16x16x32_bf16 v[72:75], v[136:139], v[228:231], 0
	v_mfma_f32_16x16x32_bf16 v[124:127], v[132:135], v[172:175], v[124:127]
	v_mfma_f32_16x16x32_bf16 v[120:123], v[164:167], v[172:175], v[120:123]
	v_mfma_f32_16x16x32_bf16 v[108:111], v[132:135], v[198:201], v[108:111]
	v_mfma_f32_16x16x32_bf16 v[104:107], v[164:167], v[198:201], v[104:107]
	v_mfma_f32_16x16x32_bf16 v[92:95], v[132:135], v[206:209], v[92:95]
	v_mfma_f32_16x16x32_bf16 v[88:91], v[164:167], v[206:209], v[88:91]
	v_mfma_f32_16x16x32_bf16 v[76:79], v[132:135], v[232:235], v[76:79]
	v_mfma_f32_16x16x32_bf16 v[72:75], v[164:167], v[232:235], v[72:75]
	s_barrier
	s_add_i32 s30, 0, 0x14000
	v_add_u32_e32 v140, s30, v157
	s_add_i32 s28, s28, s22
	ds_read_b128 v[236:239], v140
	ds_read_b128 v[240:243], v140 offset:1024
	ds_read_b128 v[244:247], v140 offset:2048
	ds_read_b128 v[220:223], v140 offset:3072
	v_lshl_add_u64 v[140:141], s[56:57], 0, v[142:143]
	s_mov_b32 m0, s28
	v_lshl_add_u64 v[154:155], s[56:57], 0, v[144:145]
	global_load_lds_dwordx4 v[140:141], off
	s_add_i32 m0, s28, 0x2000
	s_nop 0
	global_load_lds_dwordx4 v[154:155], off
	s_barrier
	s_waitcnt lgkmcnt(0)
	v_mfma_f32_16x16x32_bf16 v[116:119], v[236:239], v[168:171], 0
	v_mfma_f32_16x16x32_bf16 v[112:115], v[244:247], v[168:171], 0
	v_mfma_f32_16x16x32_bf16 v[100:103], v[236:239], v[194:197], 0
	v_mfma_f32_16x16x32_bf16 v[96:99], v[244:247], v[194:197], 0
	v_mfma_f32_16x16x32_bf16 v[84:87], v[236:239], v[202:205], 0
	v_mfma_f32_16x16x32_bf16 v[80:83], v[244:247], v[202:205], 0
	v_mfma_f32_16x16x32_bf16 v[68:71], v[236:239], v[228:231], 0
	v_mfma_f32_16x16x32_bf16 v[64:67], v[244:247], v[228:231], 0
	v_mfma_f32_16x16x32_bf16 v[116:119], v[240:243], v[172:175], v[116:119]
	v_mfma_f32_16x16x32_bf16 v[112:115], v[220:223], v[172:175], v[112:115]
	v_mfma_f32_16x16x32_bf16 v[100:103], v[240:243], v[198:201], v[100:103]
	v_mfma_f32_16x16x32_bf16 v[96:99], v[220:223], v[198:201], v[96:99]
	v_mfma_f32_16x16x32_bf16 v[84:87], v[240:243], v[206:209], v[84:87]
	v_mfma_f32_16x16x32_bf16 v[80:83], v[220:223], v[206:209], v[80:83]
	v_mfma_f32_16x16x32_bf16 v[68:71], v[240:243], v[232:235], v[68:71]
	v_mfma_f32_16x16x32_bf16 v[64:67], v[220:223], v[232:235], v[64:67]
	s_barrier
	s_mov_b32 m0, s23
	v_lshl_add_u64 v[210:211], s[58:59], 0, v[142:143]
	ds_read_b128 v[168:171], v162 offset:16384
	ds_read_b128 v[172:175], v162 offset:17408
	ds_read_b128 v[194:197], v162 offset:18432
	ds_read_b128 v[198:201], v162 offset:19456
	ds_read_b128 v[202:205], v162 offset:20480
	ds_read_b128 v[206:209], v162 offset:21504
	ds_read_b128 v[228:231], v162 offset:22528
	ds_read_b128 v[232:235], v162 offset:23552
	global_load_lds_dwordx4 v[210:211], off
	v_lshl_add_u64 v[248:249], s[58:59], 0, v[144:145]
	s_mov_b32 m0, s24
	s_nop 0
	global_load_lds_dwordx4 v[248:249], off
	s_barrier
	s_waitcnt lgkmcnt(0)
	v_mfma_f32_16x16x32_bf16 v[60:63], v[128:131], v[168:171], 0
	v_mfma_f32_16x16x32_bf16 v[56:59], v[136:139], v[168:171], 0
	v_mfma_f32_16x16x32_bf16 v[44:47], v[128:131], v[194:197], 0
	v_mfma_f32_16x16x32_bf16 v[40:43], v[136:139], v[194:197], 0
	v_mfma_f32_16x16x32_bf16 v[28:31], v[128:131], v[202:205], 0
	v_mfma_f32_16x16x32_bf16 v[24:27], v[136:139], v[202:205], 0
	v_mfma_f32_16x16x32_bf16 v[12:15], v[128:131], v[228:231], 0
	v_mfma_f32_16x16x32_bf16 v[8:11], v[136:139], v[228:231], 0
	v_mfma_f32_16x16x32_bf16 v[60:63], v[132:135], v[172:175], v[60:63]
	v_mfma_f32_16x16x32_bf16 v[56:59], v[164:167], v[172:175], v[56:59]
	v_mfma_f32_16x16x32_bf16 v[44:47], v[132:135], v[198:201], v[44:47]
	v_mfma_f32_16x16x32_bf16 v[40:43], v[164:167], v[198:201], v[40:43]
	v_mfma_f32_16x16x32_bf16 v[28:31], v[132:135], v[206:209], v[28:31]
	v_mfma_f32_16x16x32_bf16 v[24:27], v[164:167], v[206:209], v[24:27]
	v_mfma_f32_16x16x32_bf16 v[12:15], v[132:135], v[232:235], v[12:15]
	v_mfma_f32_16x16x32_bf16 v[8:11], v[164:167], v[232:235], v[8:11]
	s_barrier
; #define PG8_STAGE(bufoff, gbase, voff) do { _Pragma("unroll") for (int _i = 0; _i < 2; ++_i) \
;         __builtin_amdgcn_global_load_lds((const unsigned*)((const char*)(gbase) + (voff)[_i]), (LAS unsigned*)(lds + (bufoff) + ldsw + _i * 8192), 16, 0, 0); } while (0)
; #define PG8_LDA(dst, b, h) do { _Pragma("unroll") for (int m = 0; m < 4; ++m) _Pragma("unroll") for (int k = 0; k < 2; ++k) dst[m][k] = *(const LAS bf16x8*)(lds + PG8_SA(b, h) + aoff + m * 2048 + k * 1024); } while (0)
; #define PG8_LDB(dst, b, h) do { _Pragma("unroll") for (int n = 0; n < 2; ++n) _Pragma("unroll") for (int k = 0; k < 2; ++k) dst[n][k] = *(const LAS bf16x8*)(lds + PG8_SB(b, h) + boff + n * 2048 + k * 1024); } while (0)
; #define PG8_MMA(ai, bj, At, Bt) do { __builtin_amdgcn_s_setprio(1); _Pragma("unroll") for (int m = 0; m < 4; ++m) _Pragma("unroll") for (int n = 0; n < 2; ++n) _Pragma("unroll") for (int k = 0; k < 2; ++k) \
;         acc[ai][bj][m][n] = __builtin_amdgcn_mfma_f32_16x16x32_bf16(Bt[n][k], At[m][k], acc[ai][bj][m][n], 0, 0, 0); __builtin_amdgcn_s_setprio(0); } while (0)
; #define PG8_WAIT_V(n) asm volatile("s_waitcnt vmcnt(" #n ")" ::: "memory")
; #define PG8_WAIT_L(n) asm volatile("s_waitcnt lgkmcnt(" #n ")" ::: "memory")
; #define PG8_BAR __builtin_amdgcn_s_barrier()
; #define PG8_SCHED __builtin_amdgcn_sched_barrier(0)
; template <class Epi>
; __device__ __forceinline__ void gemm_phase(LAS unsigned char* lds, const Gemm g, const StaticOrder S, const Epi E) {
;     ...
;             PG8_STAGE(PG8_SB(0, 1), b2 + hstep, voffA);
;             PG8_WAIT_V(6); PG8_BAR; PG8_MMA(1, 1, At, B1); PG8_BAR;
;             PG8_LDB(B0, 1, 0); PG8_SCHED; PG8_LDA(At, 1, 0); PG8_STAGE(PG8_SA(0, 1), a2 + hstep, voffA);
;             PG8_WAIT_L(8); PG8_BAR; PG8_WAIT_L(0); PG8_MMA(0, 0, At, B0); PG8_BAR; PG8_SCHED;
;             PG8_LDB(B1, 1, 1); PG8_STAGE(PG8_SB(1, 0), b3, voffA);
;             PG8_BAR; PG8_WAIT_L(0); PG8_MMA(0, 1, At, B1); PG8_BAR;
;             PG8_LDA(At, 1, 1); PG8_STAGE(PG8_SA(1, 0), a3, voffA);
	s_add_u32 s28, s56, 0x20000
	s_addc_u32 s29, s57, 0
	s_add_i32 s30, s30, s22
	v_lshl_add_u64 v[128:129], s[28:29], 0, v[142:143]
	s_mov_b32 m0, s30
	s_nop 0
	global_load_lds_dwordx4 v[128:129], off
	v_lshl_add_u64 v[128:129], s[28:29], 0, v[144:145]
	s_add_i32 m0, s30, 0x2000
	s_nop 0
	global_load_lds_dwordx4 v[128:129], off
	s_waitcnt vmcnt(6)
	s_barrier
	v_mfma_f32_16x16x32_bf16 v[52:55], v[236:239], v[168:171], 0
	v_mfma_f32_16x16x32_bf16 v[48:51], v[244:247], v[168:171], 0
	v_mfma_f32_16x16x32_bf16 v[36:39], v[236:239], v[194:197], 0
	v_mfma_f32_16x16x32_bf16 v[32:35], v[244:247], v[194:197], 0
	v_mfma_f32_16x16x32_bf16 v[20:23], v[236:239], v[202:205], 0
	v_mfma_f32_16x16x32_bf16 v[16:19], v[244:247], v[202:205], 0
	v_mfma_f32_16x16x32_bf16 v[4:7], v[236:239], v[228:231], 0
	v_mfma_f32_16x16x32_bf16 v[0:3], v[244:247], v[228:231], 0
	v_mfma_f32_16x16x32_bf16 v[52:55], v[240:243], v[172:175], v[52:55]
	v_mfma_f32_16x16x32_bf16 v[48:51], v[220:223], v[172:175], v[48:51]
	v_mfma_f32_16x16x32_bf16 v[36:39], v[240:243], v[198:201], v[36:39]
	v_mfma_f32_16x16x32_bf16 v[32:35], v[220:223], v[198:201], v[32:35]
	v_mfma_f32_16x16x32_bf16 v[20:23], v[240:243], v[206:209], v[20:23]
	v_mfma_f32_16x16x32_bf16 v[16:19], v[220:223], v[206:209], v[16:19]
	v_mfma_f32_16x16x32_bf16 v[4:7], v[240:243], v[232:235], v[4:7]
	v_mfma_f32_16x16x32_bf16 v[0:3], v[220:223], v[232:235], v[0:3]
	s_barrier
	s_add_i32 s30, 0, 0x18000
	v_add_u32_e32 v163, s30, v157
	ds_read_b128 v[128:131], v163
	ds_read_b128 v[132:135], v163 offset:1024
	ds_read_b128 v[136:139], v163 offset:2048
	ds_read_b128 v[164:167], v163 offset:3072
	s_add_u32 s28, s58, 0x20000
	s_addc_u32 s29, s59, 0
	s_mov_b32 m0, s25
	v_lshl_add_u64 v[232:233], s[28:29], 0, v[142:143]
	ds_read_b128 v[168:171], v162 offset:32768
	ds_read_b128 v[172:175], v162 offset:33792
	ds_read_b128 v[194:197], v162 offset:34816
	ds_read_b128 v[198:201], v162 offset:35840
	ds_read_b128 v[202:205], v162 offset:36864
	ds_read_b128 v[206:209], v162 offset:37888
	ds_read_b128 v[220:223], v162 offset:38912
	ds_read_b128 v[228:231], v162 offset:39936
	global_load_lds_dwordx4 v[232:233], off
	v_lshl_add_u64 v[232:233], s[28:29], 0, v[144:145]
	s_mov_b32 m0, s51
	s_nop 0
	global_load_lds_dwordx4 v[232:233], off
	s_waitcnt lgkmcnt(8)
	s_barrier
	s_waitcnt lgkmcnt(0)
	v_mfma_f32_16x16x32_bf16 v[124:127], v[128:131], v[168:171], v[124:127]
	v_mfma_f32_16x16x32_bf16 v[120:123], v[136:139], v[168:171], v[120:123]
	v_mfma_f32_16x16x32_bf16 v[108:111], v[128:131], v[194:197], v[108:111]
	v_mfma_f32_16x16x32_bf16 v[104:107], v[136:139], v[194:197], v[104:107]
	v_mfma_f32_16x16x32_bf16 v[92:95], v[128:131], v[202:205], v[92:95]
	v_mfma_f32_16x16x32_bf16 v[88:91], v[136:139], v[202:205], v[88:91]
	v_mfma_f32_16x16x32_bf16 v[76:79], v[128:131], v[220:223], v[76:79]
	v_mfma_f32_16x16x32_bf16 v[72:75], v[136:139], v[220:223], v[72:75]
	v_mfma_f32_16x16x32_bf16 v[124:127], v[132:135], v[172:175], v[124:127]
	v_mfma_f32_16x16x32_bf16 v[120:123], v[164:167], v[172:175], v[120:123]
	v_mfma_f32_16x16x32_bf16 v[108:111], v[132:135], v[198:201], v[108:111]
	v_mfma_f32_16x16x32_bf16 v[104:107], v[164:167], v[198:201], v[104:107]
	v_mfma_f32_16x16x32_bf16 v[92:95], v[132:135], v[206:209], v[92:95]
	v_mfma_f32_16x16x32_bf16 v[88:91], v[164:167], v[206:209], v[88:91]
	v_mfma_f32_16x16x32_bf16 v[76:79], v[132:135], v[228:231], v[76:79]
	v_mfma_f32_16x16x32_bf16 v[72:75], v[164:167], v[228:231], v[72:75]
	s_barrier
	s_add_i32 s31, 0, 0x1c000
	s_add_i32 s28, s30, s22
	v_add_u32_e32 v163, s31, v157
	v_lshl_add_u64 v[140:141], v[140:141], 0, s[34:35]
	s_mov_b32 m0, s28
	ds_read_b128 v[232:235], v163
	ds_read_b128 v[236:239], v163 offset:1024
	ds_read_b128 v[240:243], v163 offset:2048
	ds_read_b128 v[244:247], v163 offset:3072
	global_load_lds_dwordx4 v[140:141], off
	v_lshl_add_u64 v[140:141], v[154:155], 0, s[34:35]
	s_add_i32 m0, s28, 0x2000
	s_nop 0
	global_load_lds_dwordx4 v[140:141], off
	s_barrier
	s_waitcnt lgkmcnt(0)
	v_mfma_f32_16x16x32_bf16 v[116:119], v[232:235], v[168:171], v[116:119]
	v_mfma_f32_16x16x32_bf16 v[112:115], v[240:243], v[168:171], v[112:115]
	v_mfma_f32_16x16x32_bf16 v[100:103], v[232:235], v[194:197], v[100:103]
	v_mfma_f32_16x16x32_bf16 v[96:99], v[240:243], v[194:197], v[96:99]
	v_mfma_f32_16x16x32_bf16 v[84:87], v[232:235], v[202:205], v[84:87]
	v_mfma_f32_16x16x32_bf16 v[80:83], v[240:243], v[202:205], v[80:83]
	v_mfma_f32_16x16x32_bf16 v[68:71], v[232:235], v[220:223], v[68:71]
	v_mfma_f32_16x16x32_bf16 v[64:67], v[240:243], v[220:223], v[64:67]
	v_mfma_f32_16x16x32_bf16 v[116:119], v[236:239], v[172:175], v[116:119]
	v_mfma_f32_16x16x32_bf16 v[112:115], v[244:247], v[172:175], v[112:115]
	v_mfma_f32_16x16x32_bf16 v[100:103], v[236:239], v[198:201], v[100:103]
	v_mfma_f32_16x16x32_bf16 v[96:99], v[244:247], v[198:201], v[96:99]
	v_mfma_f32_16x16x32_bf16 v[84:87], v[236:239], v[206:209], v[84:87]
	v_mfma_f32_16x16x32_bf16 v[80:83], v[244:247], v[206:209], v[80:83]
	v_mfma_f32_16x16x32_bf16 v[68:71], v[236:239], v[228:231], v[68:71]
	v_mfma_f32_16x16x32_bf16 v[64:67], v[244:247], v[228:231], v[64:67]
	s_barrier
	s_mov_b32 m0, s61
	v_lshl_add_u64 v[140:141], v[210:211], 0, s[34:35]
	ds_read_b128 v[168:171], v162 offset:49152
	ds_read_b128 v[172:175], v162 offset:50176
	ds_read_b128 v[194:197], v162 offset:51200
	ds_read_b128 v[198:201], v162 offset:52224
	ds_read_b128 v[202:205], v162 offset:53248
	ds_read_b128 v[206:209], v162 offset:54272
	ds_read_b128 v[220:223], v162 offset:55296
	ds_read_b128 v[228:231], v162 offset:56320
	global_load_lds_dwordx4 v[140:141], off
	v_lshl_add_u64 v[140:141], v[248:249], 0, s[34:35]
	s_mov_b32 m0, s62
	s_nop 0
	global_load_lds_dwordx4 v[140:141], off
	s_barrier
; #define PG8_STAGE(bufoff, gbase, voff) do { _Pragma("unroll") for (int _i = 0; _i < 2; ++_i) \
;         __builtin_amdgcn_global_load_lds((const unsigned*)((const char*)(gbase) + (voff)[_i]), (LAS unsigned*)(lds + (bufoff) + ldsw + _i * 8192), 16, 0, 0); } while (0)
; #define PG8_LDA(dst, b, h) do { _Pragma("unroll") for (int m = 0; m < 4; ++m) _Pragma("unroll") for (int k = 0; k < 2; ++k) dst[m][k] = *(const LAS bf16x8*)(lds + PG8_SA(b, h) + aoff + m * 2048 + k * 1024); } while (0)
; #define PG8_LDB(dst, b, h) do { _Pragma("unroll") for (int n = 0; n < 2; ++n) _Pragma("unroll") for (int k = 0; k < 2; ++k) dst[n][k] = *(const LAS bf16x8*)(lds + PG8_SB(b, h) + boff + n * 2048 + k * 1024); } while (0)
; #define PG8_MMA(ai, bj, At, Bt) do { __builtin_amdgcn_s_setprio(1); _Pragma("unroll") for (int m = 0; m < 4; ++m) _Pragma("unroll") for (int n = 0; n < 2; ++n) _Pragma("unroll") for (int k = 0; k < 2; ++k) \
;         acc[ai][bj][m][n] = __builtin_amdgcn_mfma_f32_16x16x32_bf16(Bt[n][k], At[m][k], acc[ai][bj][m][n], 0, 0, 0); __builtin_amdgcn_s_setprio(0); } while (0)
; #define PG8_WAIT_V(n) asm volatile("s_waitcnt vmcnt(" #n ")" ::: "memory")
; #define PG8_WAIT_L(n) asm volatile("s_waitcnt lgkmcnt(" #n ")" ::: "memory")
; #define PG8_BAR __builtin_amdgcn_s_barrier()
; #define PG8_SCHED __builtin_amdgcn_sched_barrier(0)
; template <class Epi>
; __device__ __forceinline__ void gemm_phase(LAS unsigned char* lds, const Gemm g, const StaticOrder S, const Epi E) {
;     ...
;         for (int t = 0; t < nt; t += 2) {
;             const bool last = (t == nt - 2);
;             const char* a1 = cA + (size_t)(t + 1) * kstep;
;             const char* a2 = last ? nA : cA + (size_t)(t + 2) * kstep; const char* b2 = last ? nB : cB + (size_t)(t + 2) * kstep;
;             const char* a3 = a2 + kstep; const char* b3 = b2 + kstep;
;             PG8_LDB(B0, 0, 0); PG8_SCHED; PG8_LDA(At, 0, 0); PG8_STAGE(PG8_SA(1, 1), a1 + hstep, voffA);
;             PG8_WAIT_L(8); PG8_BAR; PG8_WAIT_L(0); PG8_MMA(0, 0, At, B0); PG8_BAR; PG8_SCHED;
;             PG8_LDB(B1, 0, 1); PG8_STAGE(PG8_SB(0, 0), b2, voffA);
;     ...
;             PG8_BAR; PG8_WAIT_L(0); PG8_MMA(1, 0, At, B0); PG8_BAR; PG8_SCHED;
;             PG8_STAGE(PG8_SB(1, 1), b3 + hstep, voffA);
;             PG8_WAIT_V(6); PG8_BAR; PG8_MMA(1, 1, At, B1); PG8_BAR;
	s_waitcnt lgkmcnt(0)
	v_mfma_f32_16x16x32_bf16 v[60:63], v[128:131], v[168:171], v[60:63]
	v_mfma_f32_16x16x32_bf16 v[56:59], v[136:139], v[168:171], v[56:59]
	v_mfma_f32_16x16x32_bf16 v[44:47], v[128:131], v[194:197], v[44:47]
	v_mfma_f32_16x16x32_bf16 v[40:43], v[136:139], v[194:197], v[40:43]
	v_mfma_f32_16x16x32_bf16 v[28:31], v[128:131], v[202:205], v[28:31]
	v_mfma_f32_16x16x32_bf16 v[24:27], v[136:139], v[202:205], v[24:27]
	v_mfma_f32_16x16x32_bf16 v[12:15], v[128:131], v[220:223], v[12:15]
	v_mfma_f32_16x16x32_bf16 v[8:11], v[136:139], v[220:223], v[8:11]
	v_mfma_f32_16x16x32_bf16 v[60:63], v[132:135], v[172:175], v[60:63]
	v_mfma_f32_16x16x32_bf16 v[56:59], v[164:167], v[172:175], v[56:59]
	v_mfma_f32_16x16x32_bf16 v[44:47], v[132:135], v[198:201], v[44:47]
	v_mfma_f32_16x16x32_bf16 v[40:43], v[164:167], v[198:201], v[40:43]
	v_mfma_f32_16x16x32_bf16 v[28:31], v[132:135], v[206:209], v[28:31]
	v_mfma_f32_16x16x32_bf16 v[24:27], v[164:167], v[206:209], v[24:27]
	v_mfma_f32_16x16x32_bf16 v[12:15], v[132:135], v[228:231], v[12:15]
	v_mfma_f32_16x16x32_bf16 v[8:11], v[164:167], v[228:231], v[8:11]
	s_barrier
	s_add_u32 s28, s56, 0x20080
	s_addc_u32 s29, s57, 0
	s_add_i32 s30, s31, s22
	v_lshl_add_u64 v[128:129], s[28:29], 0, v[142:143]
	s_mov_b32 m0, s30
	s_nop 0
	global_load_lds_dwordx4 v[128:129], off
	v_lshl_add_u64 v[128:129], s[28:29], 0, v[144:145]
	s_add_i32 m0, s30, 0x2000
	s_nop 0
	global_load_lds_dwordx4 v[128:129], off
	s_waitcnt vmcnt(6)
	s_barrier
	v_mfma_f32_16x16x32_bf16 v[52:55], v[232:235], v[168:171], v[52:55]
	v_mfma_f32_16x16x32_bf16 v[48:51], v[240:243], v[168:171], v[48:51]
	v_mfma_f32_16x16x32_bf16 v[36:39], v[232:235], v[194:197], v[36:39]
	v_mfma_f32_16x16x32_bf16 v[32:35], v[240:243], v[194:197], v[32:35]
	v_mfma_f32_16x16x32_bf16 v[20:23], v[232:235], v[202:205], v[20:23]
	v_mfma_f32_16x16x32_bf16 v[16:19], v[240:243], v[202:205], v[16:19]
	v_mfma_f32_16x16x32_bf16 v[4:7], v[232:235], v[220:223], v[4:7]
	v_mfma_f32_16x16x32_bf16 v[0:3], v[240:243], v[220:223], v[0:3]
	v_mfma_f32_16x16x32_bf16 v[52:55], v[236:239], v[172:175], v[52:55]
	v_mfma_f32_16x16x32_bf16 v[48:51], v[244:247], v[172:175], v[48:51]
	v_mfma_f32_16x16x32_bf16 v[36:39], v[236:239], v[198:201], v[36:39]
	v_mfma_f32_16x16x32_bf16 v[32:35], v[244:247], v[198:201], v[32:35]
	v_mfma_f32_16x16x32_bf16 v[20:23], v[236:239], v[206:209], v[20:23]
	v_mfma_f32_16x16x32_bf16 v[16:19], v[244:247], v[206:209], v[16:19]
	v_mfma_f32_16x16x32_bf16 v[4:7], v[236:239], v[228:231], v[4:7]
	v_mfma_f32_16x16x32_bf16 v[0:3], v[244:247], v[228:231], v[0:3]
	s_barrier
	s_add_i32 s27, s27, 2
	s_add_u32 s1, s1, 0x100
	s_addc_u32 s3, s3, 0
	s_cmp_gt_u32 s27, 5
	s_mov_b64 s[52:53], s[54:55]
	s_cbranch_scc0 .LBB0_3278
	s_branch .Lpeel_exit_3
.LBB0_3278:
	s_add_u32 s54, s52, 0x100
	s_addc_u32 s55, s53, 0
	s_add_i32 s28, 0, 0x10000
	v_add_u32_e32 v140, s28, v157
	ds_read_b128 v[128:131], v140
	ds_read_b128 v[132:135], v140 offset:1024
	ds_read_b128 v[136:139], v140 offset:2048
	ds_read_b128 v[164:167], v140 offset:3072
	s_cmp_eq_u32 s27, 4
	s_cselect_b32 s59, s47, s55
	s_cselect_b32 s58, s46, s54
	s_cselect_b32 s57, s49, s3
	s_cselect_b32 s56, s48, s1
	v_lshl_add_u64 v[140:141], s[52:53], 0, v[150:151]
	s_add_i32 m0, s23, 0xc000
	ds_read_b128 v[168:171], v162
	ds_read_b128 v[172:175], v162 offset:1024
	ds_read_b128 v[194:197], v162 offset:2048
	ds_read_b128 v[198:201], v162 offset:3072
	ds_read_b128 v[202:205], v162 offset:4096
	ds_read_b128 v[206:209], v162 offset:5120
	ds_read_b128 v[228:231], v162 offset:6144
	ds_read_b128 v[232:235], v162 offset:7168
	global_load_lds_dwordx4 v[140:141], off
	v_lshl_add_u64 v[140:141], s[52:53], 0, v[152:153]
	s_add_i32 m0, s23, 0xe000
	s_nop 0
	global_load_lds_dwordx4 v[140:141], off
	s_waitcnt lgkmcnt(8)
	s_barrier
	s_waitcnt lgkmcnt(0)
	v_mfma_f32_16x16x32_bf16 v[124:127], v[128:131], v[168:171], v[124:127]
	v_mfma_f32_16x16x32_bf16 v[120:123], v[136:139], v[168:171], v[120:123]
	v_mfma_f32_16x16x32_bf16 v[108:111], v[128:131], v[194:197], v[108:111]
	v_mfma_f32_16x16x32_bf16 v[104:107], v[136:139], v[194:197], v[104:107]
	v_mfma_f32_16x16x32_bf16 v[92:95], v[128:131], v[202:205], v[92:95]
	v_mfma_f32_16x16x32_bf16 v[88:91], v[136:139], v[202:205], v[88:91]
	v_mfma_f32_16x16x32_bf16 v[76:79], v[128:131], v[228:231], v[76:79]
	v_mfma_f32_16x16x32_bf16 v[72:75], v[136:139], v[228:231], v[72:75]
	v_mfma_f32_16x16x32_bf16 v[124:127], v[132:135], v[172:175], v[124:127]
	v_mfma_f32_16x16x32_bf16 v[120:123], v[164:167], v[172:175], v[120:123]
	v_mfma_f32_16x16x32_bf16 v[108:111], v[132:135], v[198:201], v[108:111]
	v_mfma_f32_16x16x32_bf16 v[104:107], v[164:167], v[198:201], v[104:107]
	v_mfma_f32_16x16x32_bf16 v[92:95], v[132:135], v[206:209], v[92:95]
	v_mfma_f32_16x16x32_bf16 v[88:91], v[164:167], v[206:209], v[88:91]
	v_mfma_f32_16x16x32_bf16 v[76:79], v[132:135], v[232:235], v[76:79]
	v_mfma_f32_16x16x32_bf16 v[72:75], v[164:167], v[232:235], v[72:75]
	s_barrier
	s_add_i32 s30, 0, 0x14000
	v_add_u32_e32 v140, s30, v157
	s_add_i32 s28, s28, s22
	ds_read_b128 v[236:239], v140
	ds_read_b128 v[240:243], v140 offset:1024
	ds_read_b128 v[244:247], v140 offset:2048
	ds_read_b128 v[220:223], v140 offset:3072
	v_lshl_add_u64 v[140:141], s[56:57], 0, v[142:143]
	s_mov_b32 m0, s28
	v_lshl_add_u64 v[154:155], s[56:57], 0, v[144:145]
	global_load_lds_dwordx4 v[140:141], off
	s_add_i32 m0, s28, 0x2000
	s_nop 0
	global_load_lds_dwordx4 v[154:155], off
	s_barrier
; #define PG8_STAGE(bufoff, gbase, voff) do { _Pragma("unroll") for (int _i = 0; _i < 2; ++_i) \
;         __builtin_amdgcn_global_load_lds((const unsigned*)((const char*)(gbase) + (voff)[_i]), (LAS unsigned*)(lds + (bufoff) + ldsw + _i * 8192), 16, 0, 0); } while (0)
; #define PG8_LDA(dst, b, h) do { _Pragma("unroll") for (int m = 0; m < 4; ++m) _Pragma("unroll") for (int k = 0; k < 2; ++k) dst[m][k] = *(const LAS bf16x8*)(lds + PG8_SA(b, h) + aoff + m * 2048 + k * 1024); } while (0)
; #define PG8_LDB(dst, b, h) do { _Pragma("unroll") for (int n = 0; n < 2; ++n) _Pragma("unroll") for (int k = 0; k < 2; ++k) dst[n][k] = *(const LAS bf16x8*)(lds + PG8_SB(b, h) + boff + n * 2048 + k * 1024); } while (0)
; #define PG8_MMA(ai, bj, At, Bt) do { __builtin_amdgcn_s_setprio(1); _Pragma("unroll") for (int m = 0; m < 4; ++m) _Pragma("unroll") for (int n = 0; n < 2; ++n) _Pragma("unroll") for (int k = 0; k < 2; ++k) \
;         acc[ai][bj][m][n] = __builtin_amdgcn_mfma_f32_16x16x32_bf16(Bt[n][k], At[m][k], acc[ai][bj][m][n], 0, 0, 0); __builtin_amdgcn_s_setprio(0); } while (0)
; #define PG8_WAIT_V(n) asm volatile("s_waitcnt vmcnt(" #n ")" ::: "memory")
; #define PG8_WAIT_L(n) asm volatile("s_waitcnt lgkmcnt(" #n ")" ::: "memory")
; #define PG8_BAR __builtin_amdgcn_s_barrier()
; #define PG8_SCHED __builtin_amdgcn_sched_barrier(0)
; template <class Epi>
; __device__ __forceinline__ void gemm_phase(LAS unsigned char* lds, const Gemm g, const StaticOrder S, const Epi E) {
;     ...
;             PG8_BAR; PG8_WAIT_L(0); PG8_MMA(0, 1, At, B1); PG8_BAR;
;             PG8_LDA(At, 0, 1); PG8_STAGE(PG8_SA(0, 0), a2, voffA);
;             PG8_BAR; PG8_WAIT_L(0); PG8_MMA(1, 0, At, B0); PG8_BAR; PG8_SCHED;
;             PG8_STAGE(PG8_SB(0, 1), b2 + hstep, voffA);
;             PG8_WAIT_V(6); PG8_BAR; PG8_MMA(1, 1, At, B1); PG8_BAR;
;             PG8_LDB(B0, 1, 0); PG8_SCHED; PG8_LDA(At, 1, 0); PG8_STAGE(PG8_SA(0, 1), a2 + hstep, voffA);
;             PG8_WAIT_L(8); PG8_BAR; PG8_WAIT_L(0); PG8_MMA(0, 0, At, B0); PG8_BAR; PG8_SCHED;
	s_waitcnt lgkmcnt(0)
	v_mfma_f32_16x16x32_bf16 v[116:119], v[236:239], v[168:171], v[116:119]
	v_mfma_f32_16x16x32_bf16 v[112:115], v[244:247], v[168:171], v[112:115]
	v_mfma_f32_16x16x32_bf16 v[100:103], v[236:239], v[194:197], v[100:103]
	v_mfma_f32_16x16x32_bf16 v[96:99], v[244:247], v[194:197], v[96:99]
	v_mfma_f32_16x16x32_bf16 v[84:87], v[236:239], v[202:205], v[84:87]
	v_mfma_f32_16x16x32_bf16 v[80:83], v[244:247], v[202:205], v[80:83]
	v_mfma_f32_16x16x32_bf16 v[68:71], v[236:239], v[228:231], v[68:71]
	v_mfma_f32_16x16x32_bf16 v[64:67], v[244:247], v[228:231], v[64:67]
	v_mfma_f32_16x16x32_bf16 v[116:119], v[240:243], v[172:175], v[116:119]
	v_mfma_f32_16x16x32_bf16 v[112:115], v[220:223], v[172:175], v[112:115]
	v_mfma_f32_16x16x32_bf16 v[100:103], v[240:243], v[198:201], v[100:103]
	v_mfma_f32_16x16x32_bf16 v[96:99], v[220:223], v[198:201], v[96:99]
	v_mfma_f32_16x16x32_bf16 v[84:87], v[240:243], v[206:209], v[84:87]
	v_mfma_f32_16x16x32_bf16 v[80:83], v[220:223], v[206:209], v[80:83]
	v_mfma_f32_16x16x32_bf16 v[68:71], v[240:243], v[232:235], v[68:71]
	v_mfma_f32_16x16x32_bf16 v[64:67], v[220:223], v[232:235], v[64:67]
	s_barrier
	s_mov_b32 m0, s23
	v_lshl_add_u64 v[210:211], s[58:59], 0, v[142:143]
	ds_read_b128 v[168:171], v162 offset:16384
	ds_read_b128 v[172:175], v162 offset:17408
	ds_read_b128 v[194:197], v162 offset:18432
	ds_read_b128 v[198:201], v162 offset:19456
	ds_read_b128 v[202:205], v162 offset:20480
	ds_read_b128 v[206:209], v162 offset:21504
	ds_read_b128 v[228:231], v162 offset:22528
	ds_read_b128 v[232:235], v162 offset:23552
	global_load_lds_dwordx4 v[210:211], off
	v_lshl_add_u64 v[248:249], s[58:59], 0, v[144:145]
	s_mov_b32 m0, s24
	s_nop 0
	global_load_lds_dwordx4 v[248:249], off
	s_barrier
	s_waitcnt lgkmcnt(0)
	v_mfma_f32_16x16x32_bf16 v[60:63], v[128:131], v[168:171], v[60:63]
	v_mfma_f32_16x16x32_bf16 v[56:59], v[136:139], v[168:171], v[56:59]
	v_mfma_f32_16x16x32_bf16 v[44:47], v[128:131], v[194:197], v[44:47]
	v_mfma_f32_16x16x32_bf16 v[40:43], v[136:139], v[194:197], v[40:43]
	v_mfma_f32_16x16x32_bf16 v[28:31], v[128:131], v[202:205], v[28:31]
	v_mfma_f32_16x16x32_bf16 v[24:27], v[136:139], v[202:205], v[24:27]
	v_mfma_f32_16x16x32_bf16 v[12:15], v[128:131], v[228:231], v[12:15]
	v_mfma_f32_16x16x32_bf16 v[8:11], v[136:139], v[228:231], v[8:11]
	v_mfma_f32_16x16x32_bf16 v[60:63], v[132:135], v[172:175], v[60:63]
	v_mfma_f32_16x16x32_bf16 v[56:59], v[164:167], v[172:175], v[56:59]
	v_mfma_f32_16x16x32_bf16 v[44:47], v[132:135], v[198:201], v[44:47]
	v_mfma_f32_16x16x32_bf16 v[40:43], v[164:167], v[198:201], v[40:43]
	v_mfma_f32_16x16x32_bf16 v[28:31], v[132:135], v[206:209], v[28:31]
	v_mfma_f32_16x16x32_bf16 v[24:27], v[164:167], v[206:209], v[24:27]
	v_mfma_f32_16x16x32_bf16 v[12:15], v[132:135], v[232:235], v[12:15]
	v_mfma_f32_16x16x32_bf16 v[8:11], v[164:167], v[232:235], v[8:11]
	s_barrier
	s_add_u32 s28, s56, 0x20000
	s_addc_u32 s29, s57, 0
	s_add_i32 s30, s30, s22
	v_lshl_add_u64 v[128:129], s[28:29], 0, v[142:143]
	s_mov_b32 m0, s30
	s_nop 0
	global_load_lds_dwordx4 v[128:129], off
	v_lshl_add_u64 v[128:129], s[28:29], 0, v[144:145]
	s_add_i32 m0, s30, 0x2000
	s_nop 0
	global_load_lds_dwordx4 v[128:129], off
	s_waitcnt vmcnt(6)
	s_barrier
	v_mfma_f32_16x16x32_bf16 v[52:55], v[236:239], v[168:171], v[52:55]
	v_mfma_f32_16x16x32_bf16 v[48:51], v[244:247], v[168:171], v[48:51]
	v_mfma_f32_16x16x32_bf16 v[36:39], v[236:239], v[194:197], v[36:39]
	v_mfma_f32_16x16x32_bf16 v[32:35], v[244:247], v[194:197], v[32:35]
	v_mfma_f32_16x16x32_bf16 v[20:23], v[236:239], v[202:205], v[20:23]
	v_mfma_f32_16x16x32_bf16 v[16:19], v[244:247], v[202:205], v[16:19]
	v_mfma_f32_16x16x32_bf16 v[4:7], v[236:239], v[228:231], v[4:7]
	v_mfma_f32_16x16x32_bf16 v[0:3], v[244:247], v[228:231], v[0:3]
	v_mfma_f32_16x16x32_bf16 v[52:55], v[240:243], v[172:175], v[52:55]
	v_mfma_f32_16x16x32_bf16 v[48:51], v[220:223], v[172:175], v[48:51]
	v_mfma_f32_16x16x32_bf16 v[36:39], v[240:243], v[198:201], v[36:39]
	v_mfma_f32_16x16x32_bf16 v[32:35], v[220:223], v[198:201], v[32:35]
	v_mfma_f32_16x16x32_bf16 v[20:23], v[240:243], v[206:209], v[20:23]
	v_mfma_f32_16x16x32_bf16 v[16:19], v[220:223], v[206:209], v[16:19]
	v_mfma_f32_16x16x32_bf16 v[4:7], v[240:243], v[232:235], v[4:7]
	v_mfma_f32_16x16x32_bf16 v[0:3], v[220:223], v[232:235], v[0:3]
	s_barrier
	s_add_i32 s30, 0, 0x18000
	v_add_u32_e32 v163, s30, v157
	ds_read_b128 v[128:131], v163
	ds_read_b128 v[132:135], v163 offset:1024
	ds_read_b128 v[136:139], v163 offset:2048
	ds_read_b128 v[164:167], v163 offset:3072
	s_add_u32 s28, s58, 0x20000
	s_addc_u32 s29, s59, 0
	s_mov_b32 m0, s25
	v_lshl_add_u64 v[232:233], s[28:29], 0, v[142:143]
	ds_read_b128 v[168:171], v162 offset:32768
	ds_read_b128 v[172:175], v162 offset:33792
	ds_read_b128 v[194:197], v162 offset:34816
	ds_read_b128 v[198:201], v162 offset:35840
	ds_read_b128 v[202:205], v162 offset:36864
	ds_read_b128 v[206:209], v162 offset:37888
	ds_read_b128 v[220:223], v162 offset:38912
	ds_read_b128 v[228:231], v162 offset:39936
	global_load_lds_dwordx4 v[232:233], off
	v_lshl_add_u64 v[232:233], s[28:29], 0, v[144:145]
	s_mov_b32 m0, s51
	s_nop 0
	global_load_lds_dwordx4 v[232:233], off
	s_waitcnt lgkmcnt(8)
	s_barrier
; #define PG8_STAGE(bufoff, gbase, voff) do { _Pragma("unroll") for (int _i = 0; _i < 2; ++_i) \
;         __builtin_amdgcn_global_load_lds((const unsigned*)((const char*)(gbase) + (voff)[_i]), (LAS unsigned*)(lds + (bufoff) + ldsw + _i * 8192), 16, 0, 0); } while (0)
; #define PG8_LDA(dst, b, h) do { _Pragma("unroll") for (int m = 0; m < 4; ++m) _Pragma("unroll") for (int k = 0; k < 2; ++k) dst[m][k] = *(const LAS bf16x8*)(lds + PG8_SA(b, h) + aoff + m * 2048 + k * 1024); } while (0)
; #define PG8_LDB(dst, b, h) do { _Pragma("unroll") for (int n = 0; n < 2; ++n) _Pragma("unroll") for (int k = 0; k < 2; ++k) dst[n][k] = *(const LAS bf16x8*)(lds + PG8_SB(b, h) + boff + n * 2048 + k * 1024); } while (0)
; #define PG8_MMA(ai, bj, At, Bt) do { __builtin_amdgcn_s_setprio(1); _Pragma("unroll") for (int m = 0; m < 4; ++m) _Pragma("unroll") for (int n = 0; n < 2; ++n) _Pragma("unroll") for (int k = 0; k < 2; ++k) \
;         acc[ai][bj][m][n] = __builtin_amdgcn_mfma_f32_16x16x32_bf16(Bt[n][k], At[m][k], acc[ai][bj][m][n], 0, 0, 0); __builtin_amdgcn_s_setprio(0); } while (0)
; #define PG8_WAIT_V(n) asm volatile("s_waitcnt vmcnt(" #n ")" ::: "memory")
; #define PG8_WAIT_L(n) asm volatile("s_waitcnt lgkmcnt(" #n ")" ::: "memory")
; #define PG8_BAR __builtin_amdgcn_s_barrier()
; #define PG8_SCHED __builtin_amdgcn_sched_barrier(0)
; template <class Epi>
; __device__ __forceinline__ void gemm_phase(LAS unsigned char* lds, const Gemm g, const StaticOrder S, const Epi E) {
;     ...
;             PG8_WAIT_L(8); PG8_BAR; PG8_WAIT_L(0); PG8_MMA(0, 0, At, B0); PG8_BAR; PG8_SCHED;
;             PG8_LDB(B1, 1, 1); PG8_STAGE(PG8_SB(1, 0), b3, voffA);
;             PG8_BAR; PG8_WAIT_L(0); PG8_MMA(0, 1, At, B1); PG8_BAR;
;             PG8_LDA(At, 1, 1); PG8_STAGE(PG8_SA(1, 0), a3, voffA);
;             PG8_BAR; PG8_WAIT_L(0); PG8_MMA(1, 0, At, B0); PG8_BAR; PG8_SCHED;
;             PG8_STAGE(PG8_SB(1, 1), b3 + hstep, voffA);
;             PG8_WAIT_V(6); PG8_BAR; PG8_MMA(1, 1, At, B1); PG8_BAR;
;         }
	s_waitcnt lgkmcnt(0)
	v_mfma_f32_16x16x32_bf16 v[124:127], v[128:131], v[168:171], v[124:127]
	v_mfma_f32_16x16x32_bf16 v[120:123], v[136:139], v[168:171], v[120:123]
	v_mfma_f32_16x16x32_bf16 v[108:111], v[128:131], v[194:197], v[108:111]
	v_mfma_f32_16x16x32_bf16 v[104:107], v[136:139], v[194:197], v[104:107]
	v_mfma_f32_16x16x32_bf16 v[92:95], v[128:131], v[202:205], v[92:95]
	v_mfma_f32_16x16x32_bf16 v[88:91], v[136:139], v[202:205], v[88:91]
	v_mfma_f32_16x16x32_bf16 v[76:79], v[128:131], v[220:223], v[76:79]
	v_mfma_f32_16x16x32_bf16 v[72:75], v[136:139], v[220:223], v[72:75]
	v_mfma_f32_16x16x32_bf16 v[124:127], v[132:135], v[172:175], v[124:127]
	v_mfma_f32_16x16x32_bf16 v[120:123], v[164:167], v[172:175], v[120:123]
	v_mfma_f32_16x16x32_bf16 v[108:111], v[132:135], v[198:201], v[108:111]
	v_mfma_f32_16x16x32_bf16 v[104:107], v[164:167], v[198:201], v[104:107]
	v_mfma_f32_16x16x32_bf16 v[92:95], v[132:135], v[206:209], v[92:95]
	v_mfma_f32_16x16x32_bf16 v[88:91], v[164:167], v[206:209], v[88:91]
	v_mfma_f32_16x16x32_bf16 v[76:79], v[132:135], v[228:231], v[76:79]
	v_mfma_f32_16x16x32_bf16 v[72:75], v[164:167], v[228:231], v[72:75]
	s_barrier
	s_add_i32 s31, 0, 0x1c000
	s_add_i32 s28, s30, s22
	v_add_u32_e32 v163, s31, v157
	v_lshl_add_u64 v[140:141], v[140:141], 0, s[34:35]
	s_mov_b32 m0, s28
	ds_read_b128 v[232:235], v163
	ds_read_b128 v[236:239], v163 offset:1024
	ds_read_b128 v[240:243], v163 offset:2048
	ds_read_b128 v[244:247], v163 offset:3072
	global_load_lds_dwordx4 v[140:141], off
	v_lshl_add_u64 v[140:141], v[154:155], 0, s[34:35]
	s_add_i32 m0, s28, 0x2000
	s_nop 0
	global_load_lds_dwordx4 v[140:141], off
	s_barrier
	s_waitcnt lgkmcnt(0)
	v_mfma_f32_16x16x32_bf16 v[116:119], v[232:235], v[168:171], v[116:119]
	v_mfma_f32_16x16x32_bf16 v[112:115], v[240:243], v[168:171], v[112:115]
	v_mfma_f32_16x16x32_bf16 v[100:103], v[232:235], v[194:197], v[100:103]
	v_mfma_f32_16x16x32_bf16 v[96:99], v[240:243], v[194:197], v[96:99]
	v_mfma_f32_16x16x32_bf16 v[84:87], v[232:235], v[202:205], v[84:87]
	v_mfma_f32_16x16x32_bf16 v[80:83], v[240:243], v[202:205], v[80:83]
	v_mfma_f32_16x16x32_bf16 v[68:71], v[232:235], v[220:223], v[68:71]
	v_mfma_f32_16x16x32_bf16 v[64:67], v[240:243], v[220:223], v[64:67]
	v_mfma_f32_16x16x32_bf16 v[116:119], v[236:239], v[172:175], v[116:119]
	v_mfma_f32_16x16x32_bf16 v[112:115], v[244:247], v[172:175], v[112:115]
	v_mfma_f32_16x16x32_bf16 v[100:103], v[236:239], v[198:201], v[100:103]
	v_mfma_f32_16x16x32_bf16 v[96:99], v[244:247], v[198:201], v[96:99]
	v_mfma_f32_16x16x32_bf16 v[84:87], v[236:239], v[206:209], v[84:87]
	v_mfma_f32_16x16x32_bf16 v[80:83], v[244:247], v[206:209], v[80:83]
	v_mfma_f32_16x16x32_bf16 v[68:71], v[236:239], v[228:231], v[68:71]
	v_mfma_f32_16x16x32_bf16 v[64:67], v[244:247], v[228:231], v[64:67]
	s_barrier
	s_mov_b32 m0, s61
	v_lshl_add_u64 v[140:141], v[210:211], 0, s[34:35]
	ds_read_b128 v[168:171], v162 offset:49152
	ds_read_b128 v[172:175], v162 offset:50176
	ds_read_b128 v[194:197], v162 offset:51200
	ds_read_b128 v[198:201], v162 offset:52224
	ds_read_b128 v[202:205], v162 offset:53248
	ds_read_b128 v[206:209], v162 offset:54272
	ds_read_b128 v[220:223], v162 offset:55296
	ds_read_b128 v[228:231], v162 offset:56320
	global_load_lds_dwordx4 v[140:141], off
	v_lshl_add_u64 v[140:141], v[248:249], 0, s[34:35]
	s_mov_b32 m0, s62
	s_nop 0
	global_load_lds_dwordx4 v[140:141], off
	s_barrier
	s_waitcnt lgkmcnt(0)
	v_mfma_f32_16x16x32_bf16 v[60:63], v[128:131], v[168:171], v[60:63]
	v_mfma_f32_16x16x32_bf16 v[56:59], v[136:139], v[168:171], v[56:59]
	v_mfma_f32_16x16x32_bf16 v[44:47], v[128:131], v[194:197], v[44:47]
	v_mfma_f32_16x16x32_bf16 v[40:43], v[136:139], v[194:197], v[40:43]
	v_mfma_f32_16x16x32_bf16 v[28:31], v[128:131], v[202:205], v[28:31]
	v_mfma_f32_16x16x32_bf16 v[24:27], v[136:139], v[202:205], v[24:27]
	v_mfma_f32_16x16x32_bf16 v[12:15], v[128:131], v[220:223], v[12:15]
	v_mfma_f32_16x16x32_bf16 v[8:11], v[136:139], v[220:223], v[8:11]
	v_mfma_f32_16x16x32_bf16 v[60:63], v[132:135], v[172:175], v[60:63]
	v_mfma_f32_16x16x32_bf16 v[56:59], v[164:167], v[172:175], v[56:59]
	v_mfma_f32_16x16x32_bf16 v[44:47], v[132:135], v[198:201], v[44:47]
	v_mfma_f32_16x16x32_bf16 v[40:43], v[164:167], v[198:201], v[40:43]
	v_mfma_f32_16x16x32_bf16 v[28:31], v[132:135], v[206:209], v[28:31]
	v_mfma_f32_16x16x32_bf16 v[24:27], v[164:167], v[206:209], v[24:27]
	v_mfma_f32_16x16x32_bf16 v[12:15], v[132:135], v[228:231], v[12:15]
	v_mfma_f32_16x16x32_bf16 v[8:11], v[164:167], v[228:231], v[8:11]
	s_barrier
	s_add_u32 s28, s56, 0x20080
	s_addc_u32 s29, s57, 0
	s_add_i32 s30, s31, s22
	v_lshl_add_u64 v[128:129], s[28:29], 0, v[142:143]
	s_mov_b32 m0, s30
	s_nop 0
	global_load_lds_dwordx4 v[128:129], off
	v_lshl_add_u64 v[128:129], s[28:29], 0, v[144:145]
	s_add_i32 m0, s30, 0x2000
	s_nop 0
	global_load_lds_dwordx4 v[128:129], off
	s_waitcnt vmcnt(6)
	s_barrier
	v_mfma_f32_16x16x32_bf16 v[52:55], v[232:235], v[168:171], v[52:55]
	v_mfma_f32_16x16x32_bf16 v[48:51], v[240:243], v[168:171], v[48:51]
	v_mfma_f32_16x16x32_bf16 v[36:39], v[232:235], v[194:197], v[36:39]
	v_mfma_f32_16x16x32_bf16 v[32:35], v[240:243], v[194:197], v[32:35]
	v_mfma_f32_16x16x32_bf16 v[20:23], v[232:235], v[202:205], v[20:23]
	v_mfma_f32_16x16x32_bf16 v[16:19], v[240:243], v[202:205], v[16:19]
	v_mfma_f32_16x16x32_bf16 v[4:7], v[232:235], v[220:223], v[4:7]
	v_mfma_f32_16x16x32_bf16 v[0:3], v[240:243], v[220:223], v[0:3]
	v_mfma_f32_16x16x32_bf16 v[52:55], v[236:239], v[172:175], v[52:55]
	v_mfma_f32_16x16x32_bf16 v[48:51], v[244:247], v[172:175], v[48:51]
	v_mfma_f32_16x16x32_bf16 v[36:39], v[236:239], v[198:201], v[36:39]
	v_mfma_f32_16x16x32_bf16 v[32:35], v[244:247], v[198:201], v[32:35]
	v_mfma_f32_16x16x32_bf16 v[20:23], v[236:239], v[206:209], v[20:23]
	v_mfma_f32_16x16x32_bf16 v[16:19], v[244:247], v[206:209], v[16:19]
	v_mfma_f32_16x16x32_bf16 v[4:7], v[236:239], v[228:231], v[4:7]
	v_mfma_f32_16x16x32_bf16 v[0:3], v[244:247], v[228:231], v[0:3]
	s_barrier
	s_add_i32 s27, s27, 2
	s_add_u32 s1, s1, 0x100
	s_addc_u32 s3, s3, 0
	s_cmp_gt_u32 s27, 5
	s_mov_b64 s[52:53], s[54:55]
	s_cbranch_scc0 .LBB0_3278

; #define PG8_STAGE(bufoff, gbase, voff) do { _Pragma("unroll") for (int _i = 0; _i < 2; ++_i) \
;         __builtin_amdgcn_global_load_lds((const unsigned*)((const char*)(gbase) + (voff)[_i]), (LAS unsigned*)(lds + (bufoff) + ldsw + _i * 8192), 16, 0, 0); } while (0)
; #define PG8_WAIT_V(n) asm volatile("s_waitcnt vmcnt(" #n ")" ::: "memory")
; template <class Epi>
; __device__ __forceinline__ void gemm_phase(LAS unsigned char* lds, const Gemm g, const StaticOrder S, const Epi E) {
;     ...
;         const bool has_next = S.next(ui + 1, nxt);
;         const char* nA = has_next ? (const char*)g.A + (size_t)nxt.pm * tstep + (size_t)nxt.k0 * kstep : cA; const char* nB = has_next ? (const char*)g.Bt + (size_t)nxt.pn * tstep + (size_t)nxt.k0 * kstep : cB;
;         const int nt = cur.nk;
;         for (int t = 0; t < nt; t += 2) {
;             const bool last = (t == nt - 2);
;             const char* a1 = cA + (size_t)(t + 1) * kstep;
;             const char* a2 = last ? nA : cA + (size_t)(t + 2) * kstep; const char* b2 = last ? nB : cB + (size_t)(t + 2) * kstep;
;             const char* a3 = a2 + kstep; const char* b3 = b2 + kstep;
;             PG8_LDB(B0, 0, 0); PG8_SCHED; PG8_LDA(At, 0, 0); PG8_STAGE(PG8_SA(1, 1), a1 + hstep, voffA);
;             PG8_WAIT_L(8); PG8_BAR; PG8_WAIT_L(0); PG8_MMA(0, 0, At, B0); PG8_BAR; PG8_SCHED;
;             PG8_LDB(B1, 0, 1); PG8_STAGE(PG8_SB(0, 0), b2, voffA);
;             PG8_BAR; PG8_WAIT_L(0); PG8_MMA(0, 1, At, B1); PG8_BAR;
;             PG8_LDA(At, 0, 1); PG8_STAGE(PG8_SA(0, 0), a2, voffA);
;             PG8_BAR; PG8_WAIT_L(0); PG8_MMA(1, 0, At, B0); PG8_BAR; PG8_SCHED;
;             PG8_STAGE(PG8_SB(0, 1), b2 + hstep, voffA);
;             PG8_WAIT_V(6); PG8_BAR; PG8_MMA(1, 1, At, B1); PG8_BAR;
;             PG8_LDB(B0, 1, 0); PG8_SCHED; PG8_LDA(At, 1, 0); PG8_STAGE(PG8_SA(0, 1), a2 + hstep, voffA);
;             PG8_WAIT_L(8); PG8_BAR; PG8_WAIT_L(0); PG8_MMA(0, 0, At, B0); PG8_BAR; PG8_SCHED;
;             PG8_LDB(B1, 1, 1); PG8_STAGE(PG8_SB(1, 0), b3, voffA);
;             PG8_BAR; PG8_WAIT_L(0); PG8_MMA(0, 1, At, B1); PG8_BAR;
;             PG8_LDA(At, 1, 1); PG8_STAGE(PG8_SA(1, 0), a3, voffA);
;             PG8_BAR; PG8_WAIT_L(0); PG8_MMA(1, 0, At, B0); PG8_BAR; PG8_SCHED;
;             PG8_STAGE(PG8_SB(1, 1), b3 + hstep, voffA);
;             PG8_WAIT_V(6); PG8_BAR; PG8_MMA(1, 1, At, B1); PG8_BAR;
.LBB0_3305:
	s_ashr_i32 s3, s2, 31
	s_lshl_b64 s[30:31], s[2:3], 17
	v_readlane_b32 s1, v255, 16
	s_add_u32 s1, s1, s30
	v_readlane_b32 s3, v255, 17
	v_cmp_lt_i64_e32 vcc, s[46:47], v[192:193]
	s_addc_u32 s3, s3, s31
	s_and_b64 s[30:31], vcc, exec
	s_cselect_b32 s47, s3, s51
	s_cselect_b32 s46, s1, s50
	s_ashr_i32 s1, s0, 31
	s_lshl_b64 s[30:31], s[0:1], 17
	s_add_u32 s1, s6, s30
	s_addc_u32 s3, s7, s31
	s_and_b64 s[30:31], vcc, exec
	s_cselect_b32 s49, s3, s43
	s_cselect_b32 s48, s1, s42
	s_mov_b32 s1, 0
	s_mov_b64 s[52:53], -1
	s_mov_b64 s[54:55], 0
	s_add_u32 s3, s50, s1
	s_addc_u32 s29, s51, 0
	s_add_u32 s44, s3, 0x100
	s_addc_u32 s45, s29, 0
	s_and_b64 s[30:31], s[54:55], exec
	s_cselect_b32 s61, s47, s45
	s_cselect_b32 s60, s46, s44
	s_add_u32 s1, s42, s1
	s_addc_u32 s30, s43, 0
	s_add_u32 s1, s1, 0x100
	s_addc_u32 s44, s30, 0
	s_add_i32 s45, 0, 0x10000
	s_and_b64 s[30:31], s[54:55], exec
	s_cselect_b32 s63, s49, s44
	s_cselect_b32 s62, s48, s1
	s_add_u32 s64, s3, 0x10080
	s_addc_u32 s65, s29, 0
	s_add_i32 s73, s45, s22
	s_add_i32 m0, s14, 0xc000
	s_add_i32 s23, s14, 0xe000
	s_add_i32 vcc_hi, 0, 0x14000
	s_add_i32 s31, s73, 0x2000
	s_add_u32 s58, s62, 0x10000
	v_add_u32_e32 v140, s45, v155
	s_addc_u32 s59, s63, 0
	s_add_i32 s44, vcc_hi, s22
	ds_read_b128 v[128:131], v140
	ds_read_b128 v[132:135], v140 offset:1024
	ds_read_b128 v[136:139], v140 offset:2048
	ds_read_b128 v[150:153], v140 offset:3072
	s_add_i32 s72, s44, 0x2000
	s_add_i32 vcc_lo, 0, 0x18000
	s_add_u32 s56, s60, 0x10000
	s_addc_u32 s57, s61, 0
	s_add_i32 s29, vcc_lo, s22
	s_add_i32 s3, 0, 0x1c000
	s_add_i32 s1, s29, 0x2000
	s_add_u32 s54, s62, 0x10080
	s_addc_u32 s55, s63, 0
	s_add_i32 s45, s3, s22
	s_add_i32 s30, s45, 0x2000
	v_lshl_add_u64 v[140:141], s[64:65], 0, v[144:145]
	ds_read_b128 v[162:165], v160
	ds_read_b128 v[166:169], v160 offset:1024
	ds_read_b128 v[170:173], v160 offset:2048
	ds_read_b128 v[194:197], v160 offset:3072
	ds_read_b128 v[198:201], v160 offset:4096
	ds_read_b128 v[202:205], v160 offset:5120
	ds_read_b128 v[206:209], v160 offset:6144
	ds_read_b128 v[220:223], v160 offset:7168
	global_load_lds_dwordx4 v[140:141], off
	v_lshl_add_u64 v[140:141], s[64:65], 0, v[142:143]
	s_mov_b32 m0, s23
	s_nop 0
	global_load_lds_dwordx4 v[140:141], off
	s_waitcnt lgkmcnt(8)
	s_barrier
	s_waitcnt lgkmcnt(0)
	v_mfma_f32_16x16x32_bf16 v[124:127], v[128:131], v[162:165], 0
	v_mfma_f32_16x16x32_bf16 v[120:123], v[136:139], v[162:165], 0
	v_mfma_f32_16x16x32_bf16 v[108:111], v[128:131], v[170:173], 0
	v_mfma_f32_16x16x32_bf16 v[104:107], v[136:139], v[170:173], 0
	v_mfma_f32_16x16x32_bf16 v[92:95], v[128:131], v[198:201], 0
	v_mfma_f32_16x16x32_bf16 v[88:91], v[136:139], v[198:201], 0
	v_mfma_f32_16x16x32_bf16 v[76:79], v[128:131], v[206:209], 0
	v_mfma_f32_16x16x32_bf16 v[72:75], v[136:139], v[206:209], 0
	v_mfma_f32_16x16x32_bf16 v[124:127], v[132:135], v[166:169], v[124:127]
	v_mfma_f32_16x16x32_bf16 v[120:123], v[150:153], v[166:169], v[120:123]
	v_mfma_f32_16x16x32_bf16 v[108:111], v[132:135], v[194:197], v[108:111]
	v_mfma_f32_16x16x32_bf16 v[104:107], v[150:153], v[194:197], v[104:107]
	v_mfma_f32_16x16x32_bf16 v[92:95], v[132:135], v[202:205], v[92:95]
	v_mfma_f32_16x16x32_bf16 v[88:91], v[150:153], v[202:205], v[88:91]
	v_mfma_f32_16x16x32_bf16 v[76:79], v[132:135], v[220:223], v[76:79]
	v_mfma_f32_16x16x32_bf16 v[72:75], v[150:153], v[220:223], v[72:75]
	s_barrier
	v_add_u32_e32 v140, vcc_hi, v155
	s_mov_b32 m0, s73
	ds_read_b128 v[228:231], v140
	ds_read_b128 v[232:235], v140 offset:1024
	ds_read_b128 v[236:239], v140 offset:2048
	ds_read_b128 v[240:243], v140 offset:3072
	v_lshl_add_u64 v[140:141], s[62:63], 0, v[144:145]
	global_load_lds_dwordx4 v[140:141], off
	v_lshl_add_u64 v[174:175], s[62:63], 0, v[142:143]
	s_mov_b32 m0, s31
	s_nop 0
	global_load_lds_dwordx4 v[174:175], off
	s_barrier
	s_waitcnt lgkmcnt(0)
	v_mfma_f32_16x16x32_bf16 v[116:119], v[228:231], v[162:165], 0
	v_mfma_f32_16x16x32_bf16 v[112:115], v[236:239], v[162:165], 0
	v_mfma_f32_16x16x32_bf16 v[100:103], v[228:231], v[170:173], 0
	v_mfma_f32_16x16x32_bf16 v[96:99], v[236:239], v[170:173], 0
	v_mfma_f32_16x16x32_bf16 v[84:87], v[228:231], v[198:201], 0
	v_mfma_f32_16x16x32_bf16 v[80:83], v[236:239], v[198:201], 0
	v_mfma_f32_16x16x32_bf16 v[68:71], v[228:231], v[206:209], 0
	v_mfma_f32_16x16x32_bf16 v[64:67], v[236:239], v[206:209], 0
	v_mfma_f32_16x16x32_bf16 v[116:119], v[232:235], v[166:169], v[116:119]
	v_mfma_f32_16x16x32_bf16 v[112:115], v[240:243], v[166:169], v[112:115]
	v_mfma_f32_16x16x32_bf16 v[100:103], v[232:235], v[194:197], v[100:103]
	v_mfma_f32_16x16x32_bf16 v[96:99], v[240:243], v[194:197], v[96:99]
	v_mfma_f32_16x16x32_bf16 v[84:87], v[232:235], v[202:205], v[84:87]
	v_mfma_f32_16x16x32_bf16 v[80:83], v[240:243], v[202:205], v[80:83]
	v_mfma_f32_16x16x32_bf16 v[68:71], v[232:235], v[220:223], v[68:71]
	v_mfma_f32_16x16x32_bf16 v[64:67], v[240:243], v[220:223], v[64:67]
	s_barrier
	s_mov_b32 m0, s14
	v_lshl_add_u64 v[210:211], s[60:61], 0, v[144:145]
	ds_read_b128 v[162:165], v160 offset:16384
	ds_read_b128 v[166:169], v160 offset:17408
	ds_read_b128 v[170:173], v160 offset:18432
	ds_read_b128 v[194:197], v160 offset:19456
	ds_read_b128 v[198:201], v160 offset:20480
	ds_read_b128 v[202:205], v160 offset:21504
	ds_read_b128 v[206:209], v160 offset:22528
	ds_read_b128 v[220:223], v160 offset:23552
	global_load_lds_dwordx4 v[210:211], off
	v_lshl_add_u64 v[244:245], s[60:61], 0, v[142:143]
	s_mov_b32 m0, s24
	s_nop 0
	global_load_lds_dwordx4 v[244:245], off
	s_barrier
; #define PG8_STAGE(bufoff, gbase, voff) do { _Pragma("unroll") for (int _i = 0; _i < 2; ++_i) \
;         __builtin_amdgcn_global_load_lds((const unsigned*)((const char*)(gbase) + (voff)[_i]), (LAS unsigned*)(lds + (bufoff) + ldsw + _i * 8192), 16, 0, 0); } while (0)
; #define PG8_LDA(dst, b, h) do { _Pragma("unroll") for (int m = 0; m < 4; ++m) _Pragma("unroll") for (int k = 0; k < 2; ++k) dst[m][k] = *(const LAS bf16x8*)(lds + PG8_SA(b, h) + aoff + m * 2048 + k * 1024); } while (0)
; #define PG8_LDB(dst, b, h) do { _Pragma("unroll") for (int n = 0; n < 2; ++n) _Pragma("unroll") for (int k = 0; k < 2; ++k) dst[n][k] = *(const LAS bf16x8*)(lds + PG8_SB(b, h) + boff + n * 2048 + k * 1024); } while (0)
; #define PG8_WAIT_V(n) asm volatile("s_waitcnt vmcnt(" #n ")" ::: "memory")
; #define PG8_WAIT_L(n) asm volatile("s_waitcnt lgkmcnt(" #n ")" ::: "memory")
; #define PG8_BAR __builtin_amdgcn_s_barrier()
; #define PG8_SCHED __builtin_amdgcn_sched_barrier(0)
; template <class Epi>
; __device__ __forceinline__ void gemm_phase(LAS unsigned char* lds, const Gemm g, const StaticOrder S, const Epi E) {
;     ...
;             PG8_LDB(B0, 0, 0); PG8_SCHED; PG8_LDA(At, 0, 0); PG8_STAGE(PG8_SA(1, 1), a1 + hstep, voffA);
;             PG8_WAIT_L(8); PG8_BAR; PG8_WAIT_L(0); PG8_MMA(0, 0, At, B0); PG8_BAR; PG8_SCHED;
;             PG8_LDB(B1, 0, 1); PG8_STAGE(PG8_SB(0, 0), b2, voffA);
;             PG8_BAR; PG8_WAIT_L(0); PG8_MMA(0, 1, At, B1); PG8_BAR;
;             PG8_LDA(At, 0, 1); PG8_STAGE(PG8_SA(0, 0), a2, voffA);
;             PG8_BAR; PG8_WAIT_L(0); PG8_MMA(1, 0, At, B0); PG8_BAR; PG8_SCHED;
;             PG8_STAGE(PG8_SB(0, 1), b2 + hstep, voffA);
;             PG8_WAIT_V(6); PG8_BAR; PG8_MMA(1, 1, At, B1); PG8_BAR;
;             PG8_LDB(B0, 1, 0); PG8_SCHED; PG8_LDA(At, 1, 0); PG8_STAGE(PG8_SA(0, 1), a2 + hstep, voffA);
;             PG8_WAIT_L(8); PG8_BAR; PG8_WAIT_L(0); PG8_MMA(0, 0, At, B0); PG8_BAR; PG8_SCHED;
;             PG8_LDB(B1, 1, 1); PG8_STAGE(PG8_SB(1, 0), b3, voffA);
;             PG8_BAR; PG8_WAIT_L(0); PG8_MMA(0, 1, At, B1); PG8_BAR;
;             PG8_LDA(At, 1, 1); PG8_STAGE(PG8_SA(1, 0), a3, voffA);
;             PG8_BAR; PG8_WAIT_L(0); PG8_MMA(1, 0, At, B0); PG8_BAR; PG8_SCHED;
;             PG8_STAGE(PG8_SB(1, 1), b3 + hstep, voffA);
;             PG8_WAIT_V(6); PG8_BAR; PG8_MMA(1, 1, At, B1); PG8_BAR;
	s_waitcnt lgkmcnt(0)
	v_mfma_f32_16x16x32_bf16 v[60:63], v[128:131], v[162:165], 0
	v_mfma_f32_16x16x32_bf16 v[56:59], v[136:139], v[162:165], 0
	v_mfma_f32_16x16x32_bf16 v[44:47], v[128:131], v[170:173], 0
	v_mfma_f32_16x16x32_bf16 v[40:43], v[136:139], v[170:173], 0
	v_mfma_f32_16x16x32_bf16 v[28:31], v[128:131], v[198:201], 0
	v_mfma_f32_16x16x32_bf16 v[24:27], v[136:139], v[198:201], 0
	v_mfma_f32_16x16x32_bf16 v[12:15], v[128:131], v[206:209], 0
	v_mfma_f32_16x16x32_bf16 v[8:11], v[136:139], v[206:209], 0
	v_mfma_f32_16x16x32_bf16 v[60:63], v[132:135], v[166:169], v[60:63]
	v_mfma_f32_16x16x32_bf16 v[56:59], v[150:153], v[166:169], v[56:59]
	v_mfma_f32_16x16x32_bf16 v[44:47], v[132:135], v[194:197], v[44:47]
	v_mfma_f32_16x16x32_bf16 v[40:43], v[150:153], v[194:197], v[40:43]
	v_mfma_f32_16x16x32_bf16 v[28:31], v[132:135], v[202:205], v[28:31]
	v_mfma_f32_16x16x32_bf16 v[24:27], v[150:153], v[202:205], v[24:27]
	v_mfma_f32_16x16x32_bf16 v[12:15], v[132:135], v[220:223], v[12:15]
	v_mfma_f32_16x16x32_bf16 v[8:11], v[150:153], v[220:223], v[8:11]
	s_barrier
	s_mov_b32 m0, s44
	v_lshl_add_u64 v[128:129], s[58:59], 0, v[144:145]
	global_load_lds_dwordx4 v[128:129], off
	v_lshl_add_u64 v[128:129], s[58:59], 0, v[142:143]
	s_mov_b32 m0, s72
	s_nop 0
	global_load_lds_dwordx4 v[128:129], off
	s_waitcnt vmcnt(6)
	s_barrier
	v_mfma_f32_16x16x32_bf16 v[52:55], v[228:231], v[162:165], 0
	v_mfma_f32_16x16x32_bf16 v[48:51], v[236:239], v[162:165], 0
	v_mfma_f32_16x16x32_bf16 v[36:39], v[228:231], v[170:173], 0
	v_mfma_f32_16x16x32_bf16 v[32:35], v[236:239], v[170:173], 0
	v_mfma_f32_16x16x32_bf16 v[20:23], v[228:231], v[198:201], 0
	v_mfma_f32_16x16x32_bf16 v[16:19], v[236:239], v[198:201], 0
	v_mfma_f32_16x16x32_bf16 v[4:7], v[228:231], v[206:209], 0
	v_mfma_f32_16x16x32_bf16 v[0:3], v[236:239], v[206:209], 0
	v_mfma_f32_16x16x32_bf16 v[52:55], v[232:235], v[166:169], v[52:55]
	v_mfma_f32_16x16x32_bf16 v[48:51], v[240:243], v[166:169], v[48:51]
	v_mfma_f32_16x16x32_bf16 v[36:39], v[232:235], v[194:197], v[36:39]
	v_mfma_f32_16x16x32_bf16 v[32:35], v[240:243], v[194:197], v[32:35]
	v_mfma_f32_16x16x32_bf16 v[20:23], v[232:235], v[202:205], v[20:23]
	v_mfma_f32_16x16x32_bf16 v[16:19], v[240:243], v[202:205], v[16:19]
	v_mfma_f32_16x16x32_bf16 v[4:7], v[232:235], v[220:223], v[4:7]
	v_mfma_f32_16x16x32_bf16 v[0:3], v[240:243], v[220:223], v[0:3]
	s_barrier
	v_add_u32_e32 v150, vcc_lo, v155
	ds_read_b128 v[128:131], v150
	ds_read_b128 v[132:135], v150 offset:1024
	ds_read_b128 v[136:139], v150 offset:2048
	ds_read_b128 v[150:153], v150 offset:3072
	s_mov_b32 m0, s25
	v_lshl_add_u64 v[228:229], s[56:57], 0, v[144:145]
	ds_read_b128 v[162:165], v160 offset:32768
	ds_read_b128 v[166:169], v160 offset:33792
	ds_read_b128 v[170:173], v160 offset:34816
	ds_read_b128 v[194:197], v160 offset:35840
	ds_read_b128 v[198:201], v160 offset:36864
	ds_read_b128 v[202:205], v160 offset:37888
	ds_read_b128 v[206:209], v160 offset:38912
	ds_read_b128 v[220:223], v160 offset:39936
	global_load_lds_dwordx4 v[228:229], off
	v_lshl_add_u64 v[228:229], s[56:57], 0, v[142:143]
	s_mov_b32 m0, s66
	s_nop 0
	global_load_lds_dwordx4 v[228:229], off
	s_waitcnt lgkmcnt(8)
	s_barrier
	s_waitcnt lgkmcnt(0)
	v_mfma_f32_16x16x32_bf16 v[124:127], v[128:131], v[162:165], v[124:127]
	v_mfma_f32_16x16x32_bf16 v[120:123], v[136:139], v[162:165], v[120:123]
	v_mfma_f32_16x16x32_bf16 v[108:111], v[128:131], v[170:173], v[108:111]
	v_mfma_f32_16x16x32_bf16 v[104:107], v[136:139], v[170:173], v[104:107]
	v_mfma_f32_16x16x32_bf16 v[92:95], v[128:131], v[198:201], v[92:95]
	v_mfma_f32_16x16x32_bf16 v[88:91], v[136:139], v[198:201], v[88:91]
	v_mfma_f32_16x16x32_bf16 v[76:79], v[128:131], v[206:209], v[76:79]
	v_mfma_f32_16x16x32_bf16 v[72:75], v[136:139], v[206:209], v[72:75]
	v_mfma_f32_16x16x32_bf16 v[124:127], v[132:135], v[166:169], v[124:127]
	v_mfma_f32_16x16x32_bf16 v[120:123], v[150:153], v[166:169], v[120:123]
	v_mfma_f32_16x16x32_bf16 v[108:111], v[132:135], v[194:197], v[108:111]
	v_mfma_f32_16x16x32_bf16 v[104:107], v[150:153], v[194:197], v[104:107]
	v_mfma_f32_16x16x32_bf16 v[92:95], v[132:135], v[202:205], v[92:95]
	v_mfma_f32_16x16x32_bf16 v[88:91], v[150:153], v[202:205], v[88:91]
	v_mfma_f32_16x16x32_bf16 v[76:79], v[132:135], v[220:223], v[76:79]
	v_mfma_f32_16x16x32_bf16 v[72:75], v[150:153], v[220:223], v[72:75]
	s_barrier
	s_mov_b32 m0, s29
	v_add_u32_e32 v161, s3, v155
	v_lshl_add_u64 v[140:141], v[140:141], 0, s[34:35]
	ds_read_b128 v[228:231], v161
	ds_read_b128 v[232:235], v161 offset:1024
	ds_read_b128 v[236:239], v161 offset:2048
	ds_read_b128 v[240:243], v161 offset:3072
	global_load_lds_dwordx4 v[140:141], off
	v_lshl_add_u64 v[140:141], v[174:175], 0, s[34:35]
	s_mov_b32 m0, s1
	s_nop 0
	global_load_lds_dwordx4 v[140:141], off
	s_barrier
	s_waitcnt lgkmcnt(0)
	v_mfma_f32_16x16x32_bf16 v[116:119], v[228:231], v[162:165], v[116:119]
	v_mfma_f32_16x16x32_bf16 v[112:115], v[236:239], v[162:165], v[112:115]
	v_mfma_f32_16x16x32_bf16 v[100:103], v[228:231], v[170:173], v[100:103]
	v_mfma_f32_16x16x32_bf16 v[96:99], v[236:239], v[170:173], v[96:99]
	v_mfma_f32_16x16x32_bf16 v[84:87], v[228:231], v[198:201], v[84:87]
	v_mfma_f32_16x16x32_bf16 v[80:83], v[236:239], v[198:201], v[80:83]
	v_mfma_f32_16x16x32_bf16 v[68:71], v[228:231], v[206:209], v[68:71]
	v_mfma_f32_16x16x32_bf16 v[64:67], v[236:239], v[206:209], v[64:67]
	v_mfma_f32_16x16x32_bf16 v[116:119], v[232:235], v[166:169], v[116:119]
	v_mfma_f32_16x16x32_bf16 v[112:115], v[240:243], v[166:169], v[112:115]
	v_mfma_f32_16x16x32_bf16 v[100:103], v[232:235], v[194:197], v[100:103]
	v_mfma_f32_16x16x32_bf16 v[96:99], v[240:243], v[194:197], v[96:99]
	v_mfma_f32_16x16x32_bf16 v[84:87], v[232:235], v[202:205], v[84:87]
	v_mfma_f32_16x16x32_bf16 v[80:83], v[240:243], v[202:205], v[80:83]
	v_mfma_f32_16x16x32_bf16 v[68:71], v[232:235], v[220:223], v[68:71]
	v_mfma_f32_16x16x32_bf16 v[64:67], v[240:243], v[220:223], v[64:67]
	s_barrier
; #define PG8_STAGE(bufoff, gbase, voff) do { _Pragma("unroll") for (int _i = 0; _i < 2; ++_i) \
;         __builtin_amdgcn_global_load_lds((const unsigned*)((const char*)(gbase) + (voff)[_i]), (LAS unsigned*)(lds + (bufoff) + ldsw + _i * 8192), 16, 0, 0); } while (0)
; #define PG8_LDA(dst, b, h) do { _Pragma("unroll") for (int m = 0; m < 4; ++m) _Pragma("unroll") for (int k = 0; k < 2; ++k) dst[m][k] = *(const LAS bf16x8*)(lds + PG8_SA(b, h) + aoff + m * 2048 + k * 1024); } while (0)
; #define PG8_WAIT_V(n) asm volatile("s_waitcnt vmcnt(" #n ")" ::: "memory")
; #define PG8_WAIT_L(n) asm volatile("s_waitcnt lgkmcnt(" #n ")" ::: "memory")
; template <class Epi>
; __device__ __forceinline__ void gemm_phase(LAS unsigned char* lds, const Gemm g, const StaticOrder S, const Epi E) {
;     ...
;         for (int t = 0; t < nt; t += 2) {
;             const bool last = (t == nt - 2);
;             const char* a1 = cA + (size_t)(t + 1) * kstep;
;             const char* a2 = last ? nA : cA + (size_t)(t + 2) * kstep; const char* b2 = last ? nB : cB + (size_t)(t + 2) * kstep;
;             const char* a3 = a2 + kstep; const char* b3 = b2 + kstep;
;             PG8_LDB(B0, 0, 0); PG8_SCHED; PG8_LDA(At, 0, 0); PG8_STAGE(PG8_SA(1, 1), a1 + hstep, voffA);
;             PG8_WAIT_L(8); PG8_BAR; PG8_WAIT_L(0); PG8_MMA(0, 0, At, B0); PG8_BAR; PG8_SCHED;
;             PG8_LDB(B1, 0, 1); PG8_STAGE(PG8_SB(0, 0), b2, voffA);
;             PG8_BAR; PG8_WAIT_L(0); PG8_MMA(0, 1, At, B1); PG8_BAR;
;             PG8_LDA(At, 0, 1); PG8_STAGE(PG8_SA(0, 0), a2, voffA);
;             PG8_BAR; PG8_WAIT_L(0); PG8_MMA(1, 0, At, B0); PG8_BAR; PG8_SCHED;
;             PG8_STAGE(PG8_SB(0, 1), b2 + hstep, voffA);
;             PG8_WAIT_V(6); PG8_BAR; PG8_MMA(1, 1, At, B1); PG8_BAR;
;             PG8_LDB(B0, 1, 0); PG8_SCHED; PG8_LDA(At, 1, 0); PG8_STAGE(PG8_SA(0, 1), a2 + hstep, voffA);
;             PG8_WAIT_L(8); PG8_BAR; PG8_WAIT_L(0); PG8_MMA(0, 0, At, B0); PG8_BAR; PG8_SCHED;
;             PG8_LDB(B1, 1, 1); PG8_STAGE(PG8_SB(1, 0), b3, voffA);
;             PG8_BAR; PG8_WAIT_L(0); PG8_MMA(0, 1, At, B1); PG8_BAR;
;             PG8_LDA(At, 1, 1); PG8_STAGE(PG8_SA(1, 0), a3, voffA);
;             PG8_BAR; PG8_WAIT_L(0); PG8_MMA(1, 0, At, B0); PG8_BAR; PG8_SCHED;
;             PG8_STAGE(PG8_SB(1, 1), b3 + hstep, voffA);
;             PG8_WAIT_V(6); PG8_BAR; PG8_MMA(1, 1, At, B1); PG8_BAR;
	s_mov_b32 m0, s68
	v_lshl_add_u64 v[140:141], v[210:211], 0, s[34:35]
	ds_read_b128 v[162:165], v160 offset:49152
	ds_read_b128 v[166:169], v160 offset:50176
	ds_read_b128 v[170:173], v160 offset:51200
	ds_read_b128 v[194:197], v160 offset:52224
	ds_read_b128 v[198:201], v160 offset:53248
	ds_read_b128 v[202:205], v160 offset:54272
	ds_read_b128 v[206:209], v160 offset:55296
	ds_read_b128 v[220:223], v160 offset:56320
	global_load_lds_dwordx4 v[140:141], off
	v_lshl_add_u64 v[140:141], v[244:245], 0, s[34:35]
	s_mov_b32 m0, s69
	s_nop 0
	global_load_lds_dwordx4 v[140:141], off
	s_barrier
	s_waitcnt lgkmcnt(0)
	v_mfma_f32_16x16x32_bf16 v[60:63], v[128:131], v[162:165], v[60:63]
	v_mfma_f32_16x16x32_bf16 v[56:59], v[136:139], v[162:165], v[56:59]
	v_mfma_f32_16x16x32_bf16 v[44:47], v[128:131], v[170:173], v[44:47]
	v_mfma_f32_16x16x32_bf16 v[40:43], v[136:139], v[170:173], v[40:43]
	v_mfma_f32_16x16x32_bf16 v[28:31], v[128:131], v[198:201], v[28:31]
	v_mfma_f32_16x16x32_bf16 v[24:27], v[136:139], v[198:201], v[24:27]
	v_mfma_f32_16x16x32_bf16 v[12:15], v[128:131], v[206:209], v[12:15]
	v_mfma_f32_16x16x32_bf16 v[8:11], v[136:139], v[206:209], v[8:11]
	v_mfma_f32_16x16x32_bf16 v[60:63], v[132:135], v[166:169], v[60:63]
	v_mfma_f32_16x16x32_bf16 v[56:59], v[150:153], v[166:169], v[56:59]
	v_mfma_f32_16x16x32_bf16 v[44:47], v[132:135], v[194:197], v[44:47]
	v_mfma_f32_16x16x32_bf16 v[40:43], v[150:153], v[194:197], v[40:43]
	v_mfma_f32_16x16x32_bf16 v[28:31], v[132:135], v[202:205], v[28:31]
	v_mfma_f32_16x16x32_bf16 v[24:27], v[150:153], v[202:205], v[24:27]
	v_mfma_f32_16x16x32_bf16 v[12:15], v[132:135], v[220:223], v[12:15]
	v_mfma_f32_16x16x32_bf16 v[8:11], v[150:153], v[220:223], v[8:11]
	s_barrier
	s_mov_b32 m0, s45
	v_lshl_add_u64 v[128:129], s[54:55], 0, v[144:145]
	global_load_lds_dwordx4 v[128:129], off
	v_lshl_add_u64 v[128:129], s[54:55], 0, v[142:143]
	s_mov_b32 m0, s30
	s_nop 0
	global_load_lds_dwordx4 v[128:129], off
	s_waitcnt vmcnt(6)
	s_barrier
	v_mfma_f32_16x16x32_bf16 v[52:55], v[228:231], v[162:165], v[52:55]
	v_mfma_f32_16x16x32_bf16 v[48:51], v[236:239], v[162:165], v[48:51]
	v_mfma_f32_16x16x32_bf16 v[36:39], v[228:231], v[170:173], v[36:39]
	v_mfma_f32_16x16x32_bf16 v[32:35], v[236:239], v[170:173], v[32:35]
	v_mfma_f32_16x16x32_bf16 v[20:23], v[228:231], v[198:201], v[20:23]
	v_mfma_f32_16x16x32_bf16 v[16:19], v[236:239], v[198:201], v[16:19]
	v_mfma_f32_16x16x32_bf16 v[4:7], v[228:231], v[206:209], v[4:7]
	v_mfma_f32_16x16x32_bf16 v[0:3], v[236:239], v[206:209], v[0:3]
	v_mfma_f32_16x16x32_bf16 v[52:55], v[232:235], v[166:169], v[52:55]
	v_mfma_f32_16x16x32_bf16 v[48:51], v[240:243], v[166:169], v[48:51]
	v_mfma_f32_16x16x32_bf16 v[36:39], v[232:235], v[194:197], v[36:39]
	v_mfma_f32_16x16x32_bf16 v[32:35], v[240:243], v[194:197], v[32:35]
	v_mfma_f32_16x16x32_bf16 v[20:23], v[232:235], v[202:205], v[20:23]
	v_mfma_f32_16x16x32_bf16 v[16:19], v[240:243], v[202:205], v[16:19]
	v_mfma_f32_16x16x32_bf16 v[4:7], v[232:235], v[220:223], v[4:7]
	v_mfma_f32_16x16x32_bf16 v[0:3], v[240:243], v[220:223], v[0:3]
	s_barrier
	s_movk_i32 s1, 0x100
	s_andn2_b64 vcc, exec, s[52:53]
	s_mov_b64 s[54:55], -1
	s_mov_b64 s[52:53], 0
	s_cbranch_vccz .LBB0_3306
	s_branch .Lpeel_exit_4
.LBB0_3306:
	s_add_u32 s3, s50, s1
	s_addc_u32 s29, s51, 0
	s_add_u32 s44, s3, 0x100
	s_addc_u32 s45, s29, 0
	s_and_b64 s[30:31], s[54:55], exec
	s_cselect_b32 s61, s47, s45
	s_cselect_b32 s60, s46, s44
	s_add_u32 s1, s42, s1
	s_addc_u32 s30, s43, 0
	s_add_u32 s1, s1, 0x100
	s_addc_u32 s44, s30, 0
	s_add_i32 s45, 0, 0x10000
	s_and_b64 s[30:31], s[54:55], exec
	s_cselect_b32 s63, s49, s44
	s_cselect_b32 s62, s48, s1
	s_add_u32 s64, s3, 0x10080
	s_addc_u32 s65, s29, 0
	s_add_i32 s73, s45, s22
	s_add_i32 m0, s14, 0xc000
	s_add_i32 s23, s14, 0xe000
	s_add_i32 vcc_hi, 0, 0x14000
	s_add_i32 s31, s73, 0x2000
	s_add_u32 s58, s62, 0x10000
	v_add_u32_e32 v140, s45, v155
	s_addc_u32 s59, s63, 0
	s_add_i32 s44, vcc_hi, s22
	ds_read_b128 v[128:131], v140
	ds_read_b128 v[132:135], v140 offset:1024
	ds_read_b128 v[136:139], v140 offset:2048
	ds_read_b128 v[150:153], v140 offset:3072
	s_add_i32 s72, s44, 0x2000
	s_add_i32 vcc_lo, 0, 0x18000
	s_add_u32 s56, s60, 0x10000
	s_addc_u32 s57, s61, 0
	s_add_i32 s29, vcc_lo, s22
	s_add_i32 s3, 0, 0x1c000
	s_add_i32 s1, s29, 0x2000
	s_add_u32 s54, s62, 0x10080
	s_addc_u32 s55, s63, 0
	s_add_i32 s45, s3, s22
	s_add_i32 s30, s45, 0x2000
	v_lshl_add_u64 v[140:141], s[64:65], 0, v[144:145]
	ds_read_b128 v[162:165], v160
	ds_read_b128 v[166:169], v160 offset:1024
	ds_read_b128 v[170:173], v160 offset:2048
	ds_read_b128 v[194:197], v160 offset:3072
	ds_read_b128 v[198:201], v160 offset:4096
	ds_read_b128 v[202:205], v160 offset:5120
	ds_read_b128 v[206:209], v160 offset:6144
	ds_read_b128 v[220:223], v160 offset:7168
	global_load_lds_dwordx4 v[140:141], off
	v_lshl_add_u64 v[140:141], s[64:65], 0, v[142:143]
	s_mov_b32 m0, s23
	s_nop 0
	global_load_lds_dwordx4 v[140:141], off
	s_waitcnt lgkmcnt(8)
	s_barrier
	s_waitcnt lgkmcnt(0)
	v_mfma_f32_16x16x32_bf16 v[124:127], v[128:131], v[162:165], v[124:127]
	v_mfma_f32_16x16x32_bf16 v[120:123], v[136:139], v[162:165], v[120:123]
	v_mfma_f32_16x16x32_bf16 v[108:111], v[128:131], v[170:173], v[108:111]
	v_mfma_f32_16x16x32_bf16 v[104:107], v[136:139], v[170:173], v[104:107]
	v_mfma_f32_16x16x32_bf16 v[92:95], v[128:131], v[198:201], v[92:95]
	v_mfma_f32_16x16x32_bf16 v[88:91], v[136:139], v[198:201], v[88:91]
	v_mfma_f32_16x16x32_bf16 v[76:79], v[128:131], v[206:209], v[76:79]
	v_mfma_f32_16x16x32_bf16 v[72:75], v[136:139], v[206:209], v[72:75]
	v_mfma_f32_16x16x32_bf16 v[124:127], v[132:135], v[166:169], v[124:127]
	v_mfma_f32_16x16x32_bf16 v[120:123], v[150:153], v[166:169], v[120:123]
	v_mfma_f32_16x16x32_bf16 v[108:111], v[132:135], v[194:197], v[108:111]
	v_mfma_f32_16x16x32_bf16 v[104:107], v[150:153], v[194:197], v[104:107]
	v_mfma_f32_16x16x32_bf16 v[92:95], v[132:135], v[202:205], v[92:95]
	v_mfma_f32_16x16x32_bf16 v[88:91], v[150:153], v[202:205], v[88:91]
	v_mfma_f32_16x16x32_bf16 v[76:79], v[132:135], v[220:223], v[76:79]
	v_mfma_f32_16x16x32_bf16 v[72:75], v[150:153], v[220:223], v[72:75]
	s_barrier
; #define PG8_STAGE(bufoff, gbase, voff) do { _Pragma("unroll") for (int _i = 0; _i < 2; ++_i) \
;         __builtin_amdgcn_global_load_lds((const unsigned*)((const char*)(gbase) + (voff)[_i]), (LAS unsigned*)(lds + (bufoff) + ldsw + _i * 8192), 16, 0, 0); } while (0)
; #define PG8_LDA(dst, b, h) do { _Pragma("unroll") for (int m = 0; m < 4; ++m) _Pragma("unroll") for (int k = 0; k < 2; ++k) dst[m][k] = *(const LAS bf16x8*)(lds + PG8_SA(b, h) + aoff + m * 2048 + k * 1024); } while (0)
; #define PG8_LDB(dst, b, h) do { _Pragma("unroll") for (int n = 0; n < 2; ++n) _Pragma("unroll") for (int k = 0; k < 2; ++k) dst[n][k] = *(const LAS bf16x8*)(lds + PG8_SB(b, h) + boff + n * 2048 + k * 1024); } while (0)
; #define PG8_MMA(ai, bj, At, Bt) do { __builtin_amdgcn_s_setprio(1); _Pragma("unroll") for (int m = 0; m < 4; ++m) _Pragma("unroll") for (int n = 0; n < 2; ++n) _Pragma("unroll") for (int k = 0; k < 2; ++k) \
;         acc[ai][bj][m][n] = __builtin_amdgcn_mfma_f32_16x16x32_bf16(Bt[n][k], At[m][k], acc[ai][bj][m][n], 0, 0, 0); __builtin_amdgcn_s_setprio(0); } while (0)
; #define PG8_WAIT_V(n) asm volatile("s_waitcnt vmcnt(" #n ")" ::: "memory")
; #define PG8_BAR __builtin_amdgcn_s_barrier()
; template <class Epi>
; __device__ __forceinline__ void gemm_phase(LAS unsigned char* lds, const Gemm g, const StaticOrder S, const Epi E) {
;     ...
;             PG8_LDB(B0, 0, 0); PG8_SCHED; PG8_LDA(At, 0, 0); PG8_STAGE(PG8_SA(1, 1), a1 + hstep, voffA);
;             PG8_WAIT_L(8); PG8_BAR; PG8_WAIT_L(0); PG8_MMA(0, 0, At, B0); PG8_BAR; PG8_SCHED;
;             PG8_LDB(B1, 0, 1); PG8_STAGE(PG8_SB(0, 0), b2, voffA);
;             PG8_BAR; PG8_WAIT_L(0); PG8_MMA(0, 1, At, B1); PG8_BAR;
;             PG8_LDA(At, 0, 1); PG8_STAGE(PG8_SA(0, 0), a2, voffA);
;             PG8_BAR; PG8_WAIT_L(0); PG8_MMA(1, 0, At, B0); PG8_BAR; PG8_SCHED;
;             PG8_STAGE(PG8_SB(0, 1), b2 + hstep, voffA);
;             PG8_WAIT_V(6); PG8_BAR; PG8_MMA(1, 1, At, B1); PG8_BAR;
;             PG8_LDB(B0, 1, 0); PG8_SCHED; PG8_LDA(At, 1, 0); PG8_STAGE(PG8_SA(0, 1), a2 + hstep, voffA);
;             PG8_WAIT_L(8); PG8_BAR; PG8_WAIT_L(0); PG8_MMA(0, 0, At, B0); PG8_BAR; PG8_SCHED;
;             PG8_LDB(B1, 1, 1); PG8_STAGE(PG8_SB(1, 0), b3, voffA);
;             PG8_BAR; PG8_WAIT_L(0); PG8_MMA(0, 1, At, B1); PG8_BAR;
;             PG8_LDA(At, 1, 1); PG8_STAGE(PG8_SA(1, 0), a3, voffA);
	v_add_u32_e32 v140, vcc_hi, v155
	s_mov_b32 m0, s73
	ds_read_b128 v[228:231], v140
	ds_read_b128 v[232:235], v140 offset:1024
	ds_read_b128 v[236:239], v140 offset:2048
	ds_read_b128 v[240:243], v140 offset:3072
	v_lshl_add_u64 v[140:141], s[62:63], 0, v[144:145]
	global_load_lds_dwordx4 v[140:141], off
	v_lshl_add_u64 v[174:175], s[62:63], 0, v[142:143]
	s_mov_b32 m0, s31
	s_nop 0
	global_load_lds_dwordx4 v[174:175], off
	s_barrier
	s_waitcnt lgkmcnt(0)
	v_mfma_f32_16x16x32_bf16 v[116:119], v[228:231], v[162:165], v[116:119]
	v_mfma_f32_16x16x32_bf16 v[112:115], v[236:239], v[162:165], v[112:115]
	v_mfma_f32_16x16x32_bf16 v[100:103], v[228:231], v[170:173], v[100:103]
	v_mfma_f32_16x16x32_bf16 v[96:99], v[236:239], v[170:173], v[96:99]
	v_mfma_f32_16x16x32_bf16 v[84:87], v[228:231], v[198:201], v[84:87]
	v_mfma_f32_16x16x32_bf16 v[80:83], v[236:239], v[198:201], v[80:83]
	v_mfma_f32_16x16x32_bf16 v[68:71], v[228:231], v[206:209], v[68:71]
	v_mfma_f32_16x16x32_bf16 v[64:67], v[236:239], v[206:209], v[64:67]
	v_mfma_f32_16x16x32_bf16 v[116:119], v[232:235], v[166:169], v[116:119]
	v_mfma_f32_16x16x32_bf16 v[112:115], v[240:243], v[166:169], v[112:115]
	v_mfma_f32_16x16x32_bf16 v[100:103], v[232:235], v[194:197], v[100:103]
	v_mfma_f32_16x16x32_bf16 v[96:99], v[240:243], v[194:197], v[96:99]
	v_mfma_f32_16x16x32_bf16 v[84:87], v[232:235], v[202:205], v[84:87]
	v_mfma_f32_16x16x32_bf16 v[80:83], v[240:243], v[202:205], v[80:83]
	v_mfma_f32_16x16x32_bf16 v[68:71], v[232:235], v[220:223], v[68:71]
	v_mfma_f32_16x16x32_bf16 v[64:67], v[240:243], v[220:223], v[64:67]
	s_barrier
	s_mov_b32 m0, s14
	v_lshl_add_u64 v[210:211], s[60:61], 0, v[144:145]
	ds_read_b128 v[162:165], v160 offset:16384
	ds_read_b128 v[166:169], v160 offset:17408
	ds_read_b128 v[170:173], v160 offset:18432
	ds_read_b128 v[194:197], v160 offset:19456
	ds_read_b128 v[198:201], v160 offset:20480
	ds_read_b128 v[202:205], v160 offset:21504
	ds_read_b128 v[206:209], v160 offset:22528
	ds_read_b128 v[220:223], v160 offset:23552
	global_load_lds_dwordx4 v[210:211], off
	v_lshl_add_u64 v[244:245], s[60:61], 0, v[142:143]
	s_mov_b32 m0, s24
	s_nop 0
	global_load_lds_dwordx4 v[244:245], off
	s_barrier
	s_waitcnt lgkmcnt(0)
	v_mfma_f32_16x16x32_bf16 v[60:63], v[128:131], v[162:165], v[60:63]
	v_mfma_f32_16x16x32_bf16 v[56:59], v[136:139], v[162:165], v[56:59]
	v_mfma_f32_16x16x32_bf16 v[44:47], v[128:131], v[170:173], v[44:47]
	v_mfma_f32_16x16x32_bf16 v[40:43], v[136:139], v[170:173], v[40:43]
	v_mfma_f32_16x16x32_bf16 v[28:31], v[128:131], v[198:201], v[28:31]
	v_mfma_f32_16x16x32_bf16 v[24:27], v[136:139], v[198:201], v[24:27]
	v_mfma_f32_16x16x32_bf16 v[12:15], v[128:131], v[206:209], v[12:15]
	v_mfma_f32_16x16x32_bf16 v[8:11], v[136:139], v[206:209], v[8:11]
	v_mfma_f32_16x16x32_bf16 v[60:63], v[132:135], v[166:169], v[60:63]
	v_mfma_f32_16x16x32_bf16 v[56:59], v[150:153], v[166:169], v[56:59]
	v_mfma_f32_16x16x32_bf16 v[44:47], v[132:135], v[194:197], v[44:47]
	v_mfma_f32_16x16x32_bf16 v[40:43], v[150:153], v[194:197], v[40:43]
	v_mfma_f32_16x16x32_bf16 v[28:31], v[132:135], v[202:205], v[28:31]
	v_mfma_f32_16x16x32_bf16 v[24:27], v[150:153], v[202:205], v[24:27]
	v_mfma_f32_16x16x32_bf16 v[12:15], v[132:135], v[220:223], v[12:15]
	v_mfma_f32_16x16x32_bf16 v[8:11], v[150:153], v[220:223], v[8:11]
	s_barrier
	s_mov_b32 m0, s44
	v_lshl_add_u64 v[128:129], s[58:59], 0, v[144:145]
	global_load_lds_dwordx4 v[128:129], off
	v_lshl_add_u64 v[128:129], s[58:59], 0, v[142:143]
	s_mov_b32 m0, s72
	s_nop 0
	global_load_lds_dwordx4 v[128:129], off
	s_waitcnt vmcnt(6)
	s_barrier
	v_mfma_f32_16x16x32_bf16 v[52:55], v[228:231], v[162:165], v[52:55]
	v_mfma_f32_16x16x32_bf16 v[48:51], v[236:239], v[162:165], v[48:51]
	v_mfma_f32_16x16x32_bf16 v[36:39], v[228:231], v[170:173], v[36:39]
	v_mfma_f32_16x16x32_bf16 v[32:35], v[236:239], v[170:173], v[32:35]
	v_mfma_f32_16x16x32_bf16 v[20:23], v[228:231], v[198:201], v[20:23]
	v_mfma_f32_16x16x32_bf16 v[16:19], v[236:239], v[198:201], v[16:19]
	v_mfma_f32_16x16x32_bf16 v[4:7], v[228:231], v[206:209], v[4:7]
	v_mfma_f32_16x16x32_bf16 v[0:3], v[236:239], v[206:209], v[0:3]
	v_mfma_f32_16x16x32_bf16 v[52:55], v[232:235], v[166:169], v[52:55]
	v_mfma_f32_16x16x32_bf16 v[48:51], v[240:243], v[166:169], v[48:51]
	v_mfma_f32_16x16x32_bf16 v[36:39], v[232:235], v[194:197], v[36:39]
	v_mfma_f32_16x16x32_bf16 v[32:35], v[240:243], v[194:197], v[32:35]
	v_mfma_f32_16x16x32_bf16 v[20:23], v[232:235], v[202:205], v[20:23]
	v_mfma_f32_16x16x32_bf16 v[16:19], v[240:243], v[202:205], v[16:19]
	v_mfma_f32_16x16x32_bf16 v[4:7], v[232:235], v[220:223], v[4:7]
	v_mfma_f32_16x16x32_bf16 v[0:3], v[240:243], v[220:223], v[0:3]
	s_barrier
	v_add_u32_e32 v150, vcc_lo, v155
	ds_read_b128 v[128:131], v150
	ds_read_b128 v[132:135], v150 offset:1024
	ds_read_b128 v[136:139], v150 offset:2048
	ds_read_b128 v[150:153], v150 offset:3072
	s_mov_b32 m0, s25
	v_lshl_add_u64 v[228:229], s[56:57], 0, v[144:145]
	ds_read_b128 v[162:165], v160 offset:32768
	ds_read_b128 v[166:169], v160 offset:33792
	ds_read_b128 v[170:173], v160 offset:34816
	ds_read_b128 v[194:197], v160 offset:35840
	ds_read_b128 v[198:201], v160 offset:36864
	ds_read_b128 v[202:205], v160 offset:37888
	ds_read_b128 v[206:209], v160 offset:38912
	ds_read_b128 v[220:223], v160 offset:39936
	global_load_lds_dwordx4 v[228:229], off
	v_lshl_add_u64 v[228:229], s[56:57], 0, v[142:143]
	s_mov_b32 m0, s66
	s_nop 0
	global_load_lds_dwordx4 v[228:229], off
	s_waitcnt lgkmcnt(8)
	s_barrier
; #define PG8_STAGE(bufoff, gbase, voff) do { _Pragma("unroll") for (int _i = 0; _i < 2; ++_i) \
;         __builtin_amdgcn_global_load_lds((const unsigned*)((const char*)(gbase) + (voff)[_i]), (LAS unsigned*)(lds + (bufoff) + ldsw + _i * 8192), 16, 0, 0); } while (0)
; #define PG8_LDA(dst, b, h) do { _Pragma("unroll") for (int m = 0; m < 4; ++m) _Pragma("unroll") for (int k = 0; k < 2; ++k) dst[m][k] = *(const LAS bf16x8*)(lds + PG8_SA(b, h) + aoff + m * 2048 + k * 1024); } while (0)
; #define PG8_LDB(dst, b, h) do { _Pragma("unroll") for (int n = 0; n < 2; ++n) _Pragma("unroll") for (int k = 0; k < 2; ++k) dst[n][k] = *(const LAS bf16x8*)(lds + PG8_SB(b, h) + boff + n * 2048 + k * 1024); } while (0)
; #define PG8_MMA(ai, bj, At, Bt) do { __builtin_amdgcn_s_setprio(1); _Pragma("unroll") for (int m = 0; m < 4; ++m) _Pragma("unroll") for (int n = 0; n < 2; ++n) _Pragma("unroll") for (int k = 0; k < 2; ++k) \
;         acc[ai][bj][m][n] = __builtin_amdgcn_mfma_f32_16x16x32_bf16(Bt[n][k], At[m][k], acc[ai][bj][m][n], 0, 0, 0); __builtin_amdgcn_s_setprio(0); } while (0)
; #define PG8_WAIT_V(n) asm volatile("s_waitcnt vmcnt(" #n ")" ::: "memory")
; #define PG8_WAIT_L(n) asm volatile("s_waitcnt lgkmcnt(" #n ")" ::: "memory")
; #define PG8_BAR __builtin_amdgcn_s_barrier()
; #define PG8_SCHED __builtin_amdgcn_sched_barrier(0)
; template <class Epi>
; __device__ __forceinline__ void gemm_phase(LAS unsigned char* lds, const Gemm g, const StaticOrder S, const Epi E) {
;     ...
;             PG8_LDB(B0, 1, 0); PG8_SCHED; PG8_LDA(At, 1, 0); PG8_STAGE(PG8_SA(0, 1), a2 + hstep, voffA);
;             PG8_WAIT_L(8); PG8_BAR; PG8_WAIT_L(0); PG8_MMA(0, 0, At, B0); PG8_BAR; PG8_SCHED;
;             PG8_LDB(B1, 1, 1); PG8_STAGE(PG8_SB(1, 0), b3, voffA);
;             PG8_BAR; PG8_WAIT_L(0); PG8_MMA(0, 1, At, B1); PG8_BAR;
;             PG8_LDA(At, 1, 1); PG8_STAGE(PG8_SA(1, 0), a3, voffA);
;             PG8_BAR; PG8_WAIT_L(0); PG8_MMA(1, 0, At, B0); PG8_BAR; PG8_SCHED;
;             PG8_STAGE(PG8_SB(1, 1), b3 + hstep, voffA);
;             PG8_WAIT_V(6); PG8_BAR; PG8_MMA(1, 1, At, B1); PG8_BAR;
;         }
	s_waitcnt lgkmcnt(0)
	v_mfma_f32_16x16x32_bf16 v[124:127], v[128:131], v[162:165], v[124:127]
	v_mfma_f32_16x16x32_bf16 v[120:123], v[136:139], v[162:165], v[120:123]
	v_mfma_f32_16x16x32_bf16 v[108:111], v[128:131], v[170:173], v[108:111]
	v_mfma_f32_16x16x32_bf16 v[104:107], v[136:139], v[170:173], v[104:107]
	v_mfma_f32_16x16x32_bf16 v[92:95], v[128:131], v[198:201], v[92:95]
	v_mfma_f32_16x16x32_bf16 v[88:91], v[136:139], v[198:201], v[88:91]
	v_mfma_f32_16x16x32_bf16 v[76:79], v[128:131], v[206:209], v[76:79]
	v_mfma_f32_16x16x32_bf16 v[72:75], v[136:139], v[206:209], v[72:75]
	v_mfma_f32_16x16x32_bf16 v[124:127], v[132:135], v[166:169], v[124:127]
	v_mfma_f32_16x16x32_bf16 v[120:123], v[150:153], v[166:169], v[120:123]
	v_mfma_f32_16x16x32_bf16 v[108:111], v[132:135], v[194:197], v[108:111]
	v_mfma_f32_16x16x32_bf16 v[104:107], v[150:153], v[194:197], v[104:107]
	v_mfma_f32_16x16x32_bf16 v[92:95], v[132:135], v[202:205], v[92:95]
	v_mfma_f32_16x16x32_bf16 v[88:91], v[150:153], v[202:205], v[88:91]
	v_mfma_f32_16x16x32_bf16 v[76:79], v[132:135], v[220:223], v[76:79]
	v_mfma_f32_16x16x32_bf16 v[72:75], v[150:153], v[220:223], v[72:75]
	s_barrier
	s_mov_b32 m0, s29
	v_add_u32_e32 v161, s3, v155
	v_lshl_add_u64 v[140:141], v[140:141], 0, s[34:35]
	ds_read_b128 v[228:231], v161
	ds_read_b128 v[232:235], v161 offset:1024
	ds_read_b128 v[236:239], v161 offset:2048
	ds_read_b128 v[240:243], v161 offset:3072
	global_load_lds_dwordx4 v[140:141], off
	v_lshl_add_u64 v[140:141], v[174:175], 0, s[34:35]
	s_mov_b32 m0, s1
	s_nop 0
	global_load_lds_dwordx4 v[140:141], off
	s_barrier
	s_waitcnt lgkmcnt(0)
	v_mfma_f32_16x16x32_bf16 v[116:119], v[228:231], v[162:165], v[116:119]
	v_mfma_f32_16x16x32_bf16 v[112:115], v[236:239], v[162:165], v[112:115]
	v_mfma_f32_16x16x32_bf16 v[100:103], v[228:231], v[170:173], v[100:103]
	v_mfma_f32_16x16x32_bf16 v[96:99], v[236:239], v[170:173], v[96:99]
	v_mfma_f32_16x16x32_bf16 v[84:87], v[228:231], v[198:201], v[84:87]
	v_mfma_f32_16x16x32_bf16 v[80:83], v[236:239], v[198:201], v[80:83]
	v_mfma_f32_16x16x32_bf16 v[68:71], v[228:231], v[206:209], v[68:71]
	v_mfma_f32_16x16x32_bf16 v[64:67], v[236:239], v[206:209], v[64:67]
	v_mfma_f32_16x16x32_bf16 v[116:119], v[232:235], v[166:169], v[116:119]
	v_mfma_f32_16x16x32_bf16 v[112:115], v[240:243], v[166:169], v[112:115]
	v_mfma_f32_16x16x32_bf16 v[100:103], v[232:235], v[194:197], v[100:103]
	v_mfma_f32_16x16x32_bf16 v[96:99], v[240:243], v[194:197], v[96:99]
	v_mfma_f32_16x16x32_bf16 v[84:87], v[232:235], v[202:205], v[84:87]
	v_mfma_f32_16x16x32_bf16 v[80:83], v[240:243], v[202:205], v[80:83]
	v_mfma_f32_16x16x32_bf16 v[68:71], v[232:235], v[220:223], v[68:71]
	v_mfma_f32_16x16x32_bf16 v[64:67], v[240:243], v[220:223], v[64:67]
	s_barrier
	s_mov_b32 m0, s68
	v_lshl_add_u64 v[140:141], v[210:211], 0, s[34:35]
	ds_read_b128 v[162:165], v160 offset:49152
	ds_read_b128 v[166:169], v160 offset:50176
	ds_read_b128 v[170:173], v160 offset:51200
	ds_read_b128 v[194:197], v160 offset:52224
	ds_read_b128 v[198:201], v160 offset:53248
	ds_read_b128 v[202:205], v160 offset:54272
	ds_read_b128 v[206:209], v160 offset:55296
	ds_read_b128 v[220:223], v160 offset:56320
	global_load_lds_dwordx4 v[140:141], off
	v_lshl_add_u64 v[140:141], v[244:245], 0, s[34:35]
	s_mov_b32 m0, s69
	s_nop 0
	global_load_lds_dwordx4 v[140:141], off
	s_barrier
	s_waitcnt lgkmcnt(0)
	v_mfma_f32_16x16x32_bf16 v[60:63], v[128:131], v[162:165], v[60:63]
	v_mfma_f32_16x16x32_bf16 v[56:59], v[136:139], v[162:165], v[56:59]
	v_mfma_f32_16x16x32_bf16 v[44:47], v[128:131], v[170:173], v[44:47]
	v_mfma_f32_16x16x32_bf16 v[40:43], v[136:139], v[170:173], v[40:43]
	v_mfma_f32_16x16x32_bf16 v[28:31], v[128:131], v[198:201], v[28:31]
	v_mfma_f32_16x16x32_bf16 v[24:27], v[136:139], v[198:201], v[24:27]
	v_mfma_f32_16x16x32_bf16 v[12:15], v[128:131], v[206:209], v[12:15]
	v_mfma_f32_16x16x32_bf16 v[8:11], v[136:139], v[206:209], v[8:11]
	v_mfma_f32_16x16x32_bf16 v[60:63], v[132:135], v[166:169], v[60:63]
	v_mfma_f32_16x16x32_bf16 v[56:59], v[150:153], v[166:169], v[56:59]
	v_mfma_f32_16x16x32_bf16 v[44:47], v[132:135], v[194:197], v[44:47]
	v_mfma_f32_16x16x32_bf16 v[40:43], v[150:153], v[194:197], v[40:43]
	v_mfma_f32_16x16x32_bf16 v[28:31], v[132:135], v[202:205], v[28:31]
	v_mfma_f32_16x16x32_bf16 v[24:27], v[150:153], v[202:205], v[24:27]
	v_mfma_f32_16x16x32_bf16 v[12:15], v[132:135], v[220:223], v[12:15]
	v_mfma_f32_16x16x32_bf16 v[8:11], v[150:153], v[220:223], v[8:11]
	s_barrier
	s_mov_b32 m0, s45
	v_lshl_add_u64 v[128:129], s[54:55], 0, v[144:145]
	global_load_lds_dwordx4 v[128:129], off
	v_lshl_add_u64 v[128:129], s[54:55], 0, v[142:143]
	s_mov_b32 m0, s30
	s_nop 0
	global_load_lds_dwordx4 v[128:129], off
	s_waitcnt vmcnt(6)
	s_barrier
	v_mfma_f32_16x16x32_bf16 v[52:55], v[228:231], v[162:165], v[52:55]
	v_mfma_f32_16x16x32_bf16 v[48:51], v[236:239], v[162:165], v[48:51]
	v_mfma_f32_16x16x32_bf16 v[36:39], v[228:231], v[170:173], v[36:39]
	v_mfma_f32_16x16x32_bf16 v[32:35], v[236:239], v[170:173], v[32:35]
	v_mfma_f32_16x16x32_bf16 v[20:23], v[228:231], v[198:201], v[20:23]
	v_mfma_f32_16x16x32_bf16 v[16:19], v[236:239], v[198:201], v[16:19]
	v_mfma_f32_16x16x32_bf16 v[4:7], v[228:231], v[206:209], v[4:7]
	v_mfma_f32_16x16x32_bf16 v[0:3], v[236:239], v[206:209], v[0:3]
	v_mfma_f32_16x16x32_bf16 v[52:55], v[232:235], v[166:169], v[52:55]
	v_mfma_f32_16x16x32_bf16 v[48:51], v[240:243], v[166:169], v[48:51]
	v_mfma_f32_16x16x32_bf16 v[36:39], v[232:235], v[194:197], v[36:39]
	v_mfma_f32_16x16x32_bf16 v[32:35], v[240:243], v[194:197], v[32:35]
	v_mfma_f32_16x16x32_bf16 v[20:23], v[232:235], v[202:205], v[20:23]
	v_mfma_f32_16x16x32_bf16 v[16:19], v[240:243], v[202:205], v[16:19]
	v_mfma_f32_16x16x32_bf16 v[4:7], v[232:235], v[220:223], v[4:7]
	v_mfma_f32_16x16x32_bf16 v[0:3], v[240:243], v[220:223], v[0:3]
	s_barrier
	s_movk_i32 s1, 0x100
	s_andn2_b64 vcc, exec, s[52:53]
	s_mov_b64 s[54:55], -1
	s_mov_b64 s[52:53], 0
	s_cbranch_vccz .LBB0_3306

; #define PG8_STAGE(bufoff, gbase, voff) do { _Pragma("unroll") for (int _i = 0; _i < 2; ++_i) \
;         __builtin_amdgcn_global_load_lds((const unsigned*)((const char*)(gbase) + (voff)[_i]), (LAS unsigned*)(lds + (bufoff) + ldsw + _i * 8192), 16, 0, 0); } while (0)
; #define PG8_LDA(dst, b, h) do { _Pragma("unroll") for (int m = 0; m < 4; ++m) _Pragma("unroll") for (int k = 0; k < 2; ++k) dst[m][k] = *(const LAS bf16x8*)(lds + PG8_SA(b, h) + aoff + m * 2048 + k * 1024); } while (0)
; #define PG8_LDB(dst, b, h) do { _Pragma("unroll") for (int n = 0; n < 2; ++n) _Pragma("unroll") for (int k = 0; k < 2; ++k) dst[n][k] = *(const LAS bf16x8*)(lds + PG8_SB(b, h) + boff + n * 2048 + k * 1024); } while (0)
; #define PG8_WAIT_V(n) asm volatile("s_waitcnt vmcnt(" #n ")" ::: "memory")
; #define PG8_WAIT_L(n) asm volatile("s_waitcnt lgkmcnt(" #n ")" ::: "memory")
; #define PG8_BAR __builtin_amdgcn_s_barrier()
; #define PG8_SCHED __builtin_amdgcn_sched_barrier(0)
; template <class Epi>
; __device__ __forceinline__ void gemm_phase(LAS unsigned char* lds, const Gemm g, const StaticOrder S, const Epi E) {
;     ...
;         const bool has_next = S.next(ui + 1, nxt);
;         const char* nA = has_next ? (const char*)g.A + (size_t)nxt.pm * tstep + (size_t)nxt.k0 * kstep : cA; const char* nB = has_next ? (const char*)g.Bt + (size_t)nxt.pn * tstep + (size_t)nxt.k0 * kstep : cB;
;         const int nt = cur.nk;
;         for (int t = 0; t < nt; t += 2) {
;             const bool last = (t == nt - 2);
;             const char* a1 = cA + (size_t)(t + 1) * kstep;
;             const char* a2 = last ? nA : cA + (size_t)(t + 2) * kstep; const char* b2 = last ? nB : cB + (size_t)(t + 2) * kstep;
;             const char* a3 = a2 + kstep; const char* b3 = b2 + kstep;
;             PG8_LDB(B0, 0, 0); PG8_SCHED; PG8_LDA(At, 0, 0); PG8_STAGE(PG8_SA(1, 1), a1 + hstep, voffA);
;             PG8_WAIT_L(8); PG8_BAR; PG8_WAIT_L(0); PG8_MMA(0, 0, At, B0); PG8_BAR; PG8_SCHED;
;             PG8_LDB(B1, 0, 1); PG8_STAGE(PG8_SB(0, 0), b2, voffA);
;             PG8_BAR; PG8_WAIT_L(0); PG8_MMA(0, 1, At, B1); PG8_BAR;
;             PG8_LDA(At, 0, 1); PG8_STAGE(PG8_SA(0, 0), a2, voffA);
;             PG8_BAR; PG8_WAIT_L(0); PG8_MMA(1, 0, At, B0); PG8_BAR; PG8_SCHED;
;             PG8_STAGE(PG8_SB(0, 1), b2 + hstep, voffA);
;             PG8_WAIT_V(6); PG8_BAR; PG8_MMA(1, 1, At, B1); PG8_BAR;
.LBB0_3567:
	s_add_i32 s43, s39, -2
	s_add_u32 s45, s58, 0x100
	s_addc_u32 s47, s59, 0
	s_mov_b32 s55, 0
	s_add_i32 vcc_lo, s55, 2
	s_add_u32 s58, s56, 0x100
	s_addc_u32 s59, s57, 0
	s_add_i32 s14, 0, 0x10000
	v_add_u32_e32 v132, s14, v228
	ds_read_b128 v[116:119], v132
	ds_read_b128 v[124:127], v132 offset:1024
	ds_read_b128 v[128:131], v132 offset:2048
	ds_read_b128 v[132:135], v132 offset:3072
	s_cmp_eq_u32 s43, s55
	s_cselect_b32 s63, s51, s59
	s_cselect_b32 s62, s50, s58
	s_cselect_b32 s61, s53, s47
	s_cselect_b32 s60, s52, s45
	v_lshl_add_u64 v[200:201], s[56:57], 0, v[196:197]
	s_add_i32 m0, s25, 0xc000
	ds_read_b128 v[144:147], v230
	ds_read_b128 v[148:151], v230 offset:1024
	ds_read_b128 v[152:155], v230 offset:2048
	ds_read_b128 v[156:159], v230 offset:3072
	ds_read_b128 v[160:163], v230 offset:4096
	ds_read_b128 v[164:167], v230 offset:5120
	ds_read_b128 v[168:171], v230 offset:6144
	ds_read_b128 v[172:175], v230 offset:7168
	global_load_lds_dwordx4 v[200:201], off
	v_lshl_add_u64 v[200:201], s[56:57], 0, v[198:199]
	s_add_i32 m0, s25, 0xe000
	s_nop 0
	global_load_lds_dwordx4 v[200:201], off
	s_waitcnt lgkmcnt(8)
	s_barrier
	s_waitcnt lgkmcnt(0)
	v_mfma_f32_16x16x32_bf16 v[140:143], v[116:119], v[144:147], 0
	v_mfma_f32_16x16x32_bf16 v[136:139], v[128:131], v[144:147], 0
	v_mfma_f32_16x16x32_bf16 v[112:115], v[116:119], v[152:155], 0
	v_mfma_f32_16x16x32_bf16 v[104:107], v[128:131], v[152:155], 0
	v_mfma_f32_16x16x32_bf16 v[92:95], v[116:119], v[160:163], 0
	v_mfma_f32_16x16x32_bf16 v[88:91], v[128:131], v[160:163], 0
	v_mfma_f32_16x16x32_bf16 v[80:83], v[116:119], v[168:171], 0
	v_mfma_f32_16x16x32_bf16 v[72:75], v[128:131], v[168:171], 0
	v_mfma_f32_16x16x32_bf16 v[140:143], v[124:127], v[148:151], v[140:143]
	v_mfma_f32_16x16x32_bf16 v[136:139], v[132:135], v[148:151], v[136:139]
	v_mfma_f32_16x16x32_bf16 v[112:115], v[124:127], v[156:159], v[112:115]
	v_mfma_f32_16x16x32_bf16 v[104:107], v[132:135], v[156:159], v[104:107]
	v_mfma_f32_16x16x32_bf16 v[92:95], v[124:127], v[164:167], v[92:95]
	v_mfma_f32_16x16x32_bf16 v[88:91], v[132:135], v[164:167], v[88:91]
	v_mfma_f32_16x16x32_bf16 v[80:83], v[124:127], v[172:175], v[80:83]
	v_mfma_f32_16x16x32_bf16 v[72:75], v[132:135], v[172:175], v[72:75]
	s_barrier
	s_add_i32 s55, 0, 0x14000
	s_add_i32 s14, s14, s24
	v_add_u32_e32 v220, s55, v228
	v_lshl_add_u64 v[232:233], s[60:61], 0, v[178:179]
	s_mov_b32 m0, s14
	ds_read_b128 v[200:203], v220
	ds_read_b128 v[204:207], v220 offset:1024
	ds_read_b128 v[208:211], v220 offset:2048
	ds_read_b128 v[220:223], v220 offset:3072
	global_load_lds_dwordx4 v[232:233], off
	v_lshl_add_u64 v[234:235], s[60:61], 0, v[194:195]
	s_add_i32 m0, s14, 0x2000
	s_nop 0
	global_load_lds_dwordx4 v[234:235], off
	s_barrier
	s_waitcnt lgkmcnt(0)
	v_mfma_f32_16x16x32_bf16 v[120:123], v[200:203], v[144:147], 0
	v_mfma_f32_16x16x32_bf16 v[108:111], v[208:211], v[144:147], 0
	v_mfma_f32_16x16x32_bf16 v[100:103], v[200:203], v[152:155], 0
	v_mfma_f32_16x16x32_bf16 v[96:99], v[208:211], v[152:155], 0
	v_mfma_f32_16x16x32_bf16 v[84:87], v[200:203], v[160:163], 0
	v_mfma_f32_16x16x32_bf16 v[76:79], v[208:211], v[160:163], 0
	v_mfma_f32_16x16x32_bf16 v[68:71], v[200:203], v[168:171], 0
	v_mfma_f32_16x16x32_bf16 v[64:67], v[208:211], v[168:171], 0
	v_mfma_f32_16x16x32_bf16 v[120:123], v[204:207], v[148:151], v[120:123]
	v_mfma_f32_16x16x32_bf16 v[108:111], v[220:223], v[148:151], v[108:111]
	v_mfma_f32_16x16x32_bf16 v[100:103], v[204:207], v[156:159], v[100:103]
	v_mfma_f32_16x16x32_bf16 v[96:99], v[220:223], v[156:159], v[96:99]
	v_mfma_f32_16x16x32_bf16 v[84:87], v[204:207], v[164:167], v[84:87]
	v_mfma_f32_16x16x32_bf16 v[76:79], v[220:223], v[164:167], v[76:79]
	v_mfma_f32_16x16x32_bf16 v[68:71], v[204:207], v[172:175], v[68:71]
	v_mfma_f32_16x16x32_bf16 v[64:67], v[220:223], v[172:175], v[64:67]
	s_barrier
	s_mov_b32 m0, s25
	v_lshl_add_u64 v[236:237], s[62:63], 0, v[178:179]
	ds_read_b128 v[144:147], v230 offset:16384
	ds_read_b128 v[148:151], v230 offset:17408
	ds_read_b128 v[152:155], v230 offset:18432
	ds_read_b128 v[156:159], v230 offset:19456
	ds_read_b128 v[160:163], v230 offset:20480
	ds_read_b128 v[164:167], v230 offset:21504
	ds_read_b128 v[168:171], v230 offset:22528
	ds_read_b128 v[172:175], v230 offset:23552
	global_load_lds_dwordx4 v[236:237], off
	v_lshl_add_u64 v[238:239], s[62:63], 0, v[194:195]
	s_mov_b32 m0, s64
	s_nop 0
	global_load_lds_dwordx4 v[238:239], off
	s_barrier
	s_waitcnt lgkmcnt(0)
	v_mfma_f32_16x16x32_bf16 v[60:63], v[116:119], v[144:147], 0
	v_mfma_f32_16x16x32_bf16 v[56:59], v[128:131], v[144:147], 0
	v_mfma_f32_16x16x32_bf16 v[48:51], v[116:119], v[152:155], 0
	v_mfma_f32_16x16x32_bf16 v[40:43], v[128:131], v[152:155], 0
	v_mfma_f32_16x16x32_bf16 v[28:31], v[116:119], v[160:163], 0
	v_mfma_f32_16x16x32_bf16 v[24:27], v[128:131], v[160:163], 0
	v_mfma_f32_16x16x32_bf16 v[16:19], v[116:119], v[168:171], 0
	v_mfma_f32_16x16x32_bf16 v[8:11], v[128:131], v[168:171], 0
	v_mfma_f32_16x16x32_bf16 v[60:63], v[124:127], v[148:151], v[60:63]
	v_mfma_f32_16x16x32_bf16 v[56:59], v[132:135], v[148:151], v[56:59]
	v_mfma_f32_16x16x32_bf16 v[48:51], v[124:127], v[156:159], v[48:51]
	v_mfma_f32_16x16x32_bf16 v[40:43], v[132:135], v[156:159], v[40:43]
	v_mfma_f32_16x16x32_bf16 v[28:31], v[124:127], v[164:167], v[28:31]
	v_mfma_f32_16x16x32_bf16 v[24:27], v[132:135], v[164:167], v[24:27]
	v_mfma_f32_16x16x32_bf16 v[16:19], v[124:127], v[172:175], v[16:19]
	v_mfma_f32_16x16x32_bf16 v[8:11], v[132:135], v[172:175], v[8:11]
	s_barrier
; #define PG8_STAGE(bufoff, gbase, voff) do { _Pragma("unroll") for (int _i = 0; _i < 2; ++_i) \
;         __builtin_amdgcn_global_load_lds((const unsigned*)((const char*)(gbase) + (voff)[_i]), (LAS unsigned*)(lds + (bufoff) + ldsw + _i * 8192), 16, 0, 0); } while (0)
; #define PG8_LDA(dst, b, h) do { _Pragma("unroll") for (int m = 0; m < 4; ++m) _Pragma("unroll") for (int k = 0; k < 2; ++k) dst[m][k] = *(const LAS bf16x8*)(lds + PG8_SA(b, h) + aoff + m * 2048 + k * 1024); } while (0)
; #define PG8_LDB(dst, b, h) do { _Pragma("unroll") for (int n = 0; n < 2; ++n) _Pragma("unroll") for (int k = 0; k < 2; ++k) dst[n][k] = *(const LAS bf16x8*)(lds + PG8_SB(b, h) + boff + n * 2048 + k * 1024); } while (0)
; #define PG8_MMA(ai, bj, At, Bt) do { __builtin_amdgcn_s_setprio(1); _Pragma("unroll") for (int m = 0; m < 4; ++m) _Pragma("unroll") for (int n = 0; n < 2; ++n) _Pragma("unroll") for (int k = 0; k < 2; ++k) \
;         acc[ai][bj][m][n] = __builtin_amdgcn_mfma_f32_16x16x32_bf16(Bt[n][k], At[m][k], acc[ai][bj][m][n], 0, 0, 0); __builtin_amdgcn_s_setprio(0); } while (0)
; #define PG8_WAIT_V(n) asm volatile("s_waitcnt vmcnt(" #n ")" ::: "memory")
; #define PG8_WAIT_L(n) asm volatile("s_waitcnt lgkmcnt(" #n ")" ::: "memory")
; #define PG8_BAR __builtin_amdgcn_s_barrier()
; #define PG8_SCHED __builtin_amdgcn_sched_barrier(0)
; template <class Epi>
; __device__ __forceinline__ void gemm_phase(LAS unsigned char* lds, const Gemm g, const StaticOrder S, const Epi E) {
;     ...
;             PG8_STAGE(PG8_SB(0, 1), b2 + hstep, voffA);
;             PG8_WAIT_V(6); PG8_BAR; PG8_MMA(1, 1, At, B1); PG8_BAR;
;             PG8_LDB(B0, 1, 0); PG8_SCHED; PG8_LDA(At, 1, 0); PG8_STAGE(PG8_SA(0, 1), a2 + hstep, voffA);
;             PG8_WAIT_L(8); PG8_BAR; PG8_WAIT_L(0); PG8_MMA(0, 0, At, B0); PG8_BAR; PG8_SCHED;
;             PG8_LDB(B1, 1, 1); PG8_STAGE(PG8_SB(1, 0), b3, voffA);
;             PG8_BAR; PG8_WAIT_L(0); PG8_MMA(0, 1, At, B1); PG8_BAR;
;             PG8_LDA(At, 1, 1); PG8_STAGE(PG8_SA(1, 0), a3, voffA);
;             PG8_BAR; PG8_WAIT_L(0); PG8_MMA(1, 0, At, B0); PG8_BAR; PG8_SCHED;
;             PG8_STAGE(PG8_SB(1, 1), b3 + hstep, voffA);
;             PG8_WAIT_V(6); PG8_BAR; PG8_MMA(1, 1, At, B1); PG8_BAR;
	s_add_u32 s30, s60, 0x80000
	s_addc_u32 s31, s61, 0
	s_add_i32 s14, s55, s24
	v_lshl_add_u64 v[116:117], s[30:31], 0, v[178:179]
	s_mov_b32 m0, s14
	s_nop 0
	global_load_lds_dwordx4 v[116:117], off
	v_lshl_add_u64 v[116:117], s[30:31], 0, v[194:195]
	s_add_i32 m0, s14, 0x2000
	s_nop 0
	global_load_lds_dwordx4 v[116:117], off
	s_waitcnt vmcnt(6)
	s_barrier
	v_mfma_f32_16x16x32_bf16 v[52:55], v[200:203], v[144:147], 0
	v_mfma_f32_16x16x32_bf16 v[44:47], v[208:211], v[144:147], 0
	v_mfma_f32_16x16x32_bf16 v[36:39], v[200:203], v[152:155], 0
	v_mfma_f32_16x16x32_bf16 v[32:35], v[208:211], v[152:155], 0
	v_mfma_f32_16x16x32_bf16 v[20:23], v[200:203], v[160:163], 0
	v_mfma_f32_16x16x32_bf16 v[12:15], v[208:211], v[160:163], 0
	v_mfma_f32_16x16x32_bf16 v[4:7], v[200:203], v[168:171], 0
	v_mfma_f32_16x16x32_bf16 v[0:3], v[208:211], v[168:171], 0
	v_mfma_f32_16x16x32_bf16 v[52:55], v[204:207], v[148:151], v[52:55]
	v_mfma_f32_16x16x32_bf16 v[44:47], v[220:223], v[148:151], v[44:47]
	v_mfma_f32_16x16x32_bf16 v[36:39], v[204:207], v[156:159], v[36:39]
	v_mfma_f32_16x16x32_bf16 v[32:35], v[220:223], v[156:159], v[32:35]
	v_mfma_f32_16x16x32_bf16 v[20:23], v[204:207], v[164:167], v[20:23]
	v_mfma_f32_16x16x32_bf16 v[12:15], v[220:223], v[164:167], v[12:15]
	v_mfma_f32_16x16x32_bf16 v[4:7], v[204:207], v[172:175], v[4:7]
	v_mfma_f32_16x16x32_bf16 v[0:3], v[220:223], v[172:175], v[0:3]
	s_barrier
	s_add_i32 s14, 0, 0x18000
	v_add_u32_e32 v132, s14, v228
	ds_read_b128 v[116:119], v132
	ds_read_b128 v[124:127], v132 offset:1024
	ds_read_b128 v[128:131], v132 offset:2048
	ds_read_b128 v[132:135], v132 offset:3072
	s_add_u32 s30, s62, 0x80000
	s_addc_u32 s31, s63, 0
	s_mov_b32 m0, s65
	v_lshl_add_u64 v[200:201], s[30:31], 0, v[178:179]
	ds_read_b128 v[144:147], v230 offset:32768
	ds_read_b128 v[148:151], v230 offset:33792
	ds_read_b128 v[152:155], v230 offset:34816
	ds_read_b128 v[156:159], v230 offset:35840
	ds_read_b128 v[160:163], v230 offset:36864
	ds_read_b128 v[164:167], v230 offset:37888
	ds_read_b128 v[168:171], v230 offset:38912
	ds_read_b128 v[172:175], v230 offset:39936
	global_load_lds_dwordx4 v[200:201], off
	v_lshl_add_u64 v[200:201], s[30:31], 0, v[194:195]
	s_mov_b32 m0, s66
	s_nop 0
	global_load_lds_dwordx4 v[200:201], off
	s_waitcnt lgkmcnt(8)
	s_barrier
	s_waitcnt lgkmcnt(0)
	v_mfma_f32_16x16x32_bf16 v[140:143], v[116:119], v[144:147], v[140:143]
	v_mfma_f32_16x16x32_bf16 v[136:139], v[128:131], v[144:147], v[136:139]
	v_mfma_f32_16x16x32_bf16 v[112:115], v[116:119], v[152:155], v[112:115]
	v_mfma_f32_16x16x32_bf16 v[104:107], v[128:131], v[152:155], v[104:107]
	v_mfma_f32_16x16x32_bf16 v[92:95], v[116:119], v[160:163], v[92:95]
	v_mfma_f32_16x16x32_bf16 v[88:91], v[128:131], v[160:163], v[88:91]
	v_mfma_f32_16x16x32_bf16 v[80:83], v[116:119], v[168:171], v[80:83]
	v_mfma_f32_16x16x32_bf16 v[72:75], v[128:131], v[168:171], v[72:75]
	v_mfma_f32_16x16x32_bf16 v[140:143], v[124:127], v[148:151], v[140:143]
	v_mfma_f32_16x16x32_bf16 v[136:139], v[132:135], v[148:151], v[136:139]
	v_mfma_f32_16x16x32_bf16 v[112:115], v[124:127], v[156:159], v[112:115]
	v_mfma_f32_16x16x32_bf16 v[104:107], v[132:135], v[156:159], v[104:107]
	v_mfma_f32_16x16x32_bf16 v[92:95], v[124:127], v[164:167], v[92:95]
	v_mfma_f32_16x16x32_bf16 v[88:91], v[132:135], v[164:167], v[88:91]
	v_mfma_f32_16x16x32_bf16 v[80:83], v[124:127], v[172:175], v[80:83]
	v_mfma_f32_16x16x32_bf16 v[72:75], v[132:135], v[172:175], v[72:75]
	s_barrier
	s_add_i32 s55, 0, 0x1c000
	s_add_i32 s14, s14, s24
	v_add_u32_e32 v220, s55, v228
	v_lshl_add_u64 v[232:233], v[232:233], 0, s[34:35]
	s_mov_b32 m0, s14
	ds_read_b128 v[200:203], v220
	ds_read_b128 v[204:207], v220 offset:1024
	ds_read_b128 v[208:211], v220 offset:2048
	ds_read_b128 v[220:223], v220 offset:3072
	global_load_lds_dwordx4 v[232:233], off
	v_lshl_add_u64 v[232:233], v[234:235], 0, s[34:35]
	s_add_i32 m0, s14, 0x2000
	s_nop 0
	global_load_lds_dwordx4 v[232:233], off
	s_barrier
	s_waitcnt lgkmcnt(0)
	v_mfma_f32_16x16x32_bf16 v[120:123], v[200:203], v[144:147], v[120:123]
	v_mfma_f32_16x16x32_bf16 v[108:111], v[208:211], v[144:147], v[108:111]
	v_mfma_f32_16x16x32_bf16 v[100:103], v[200:203], v[152:155], v[100:103]
	v_mfma_f32_16x16x32_bf16 v[96:99], v[208:211], v[152:155], v[96:99]
	v_mfma_f32_16x16x32_bf16 v[84:87], v[200:203], v[160:163], v[84:87]
	v_mfma_f32_16x16x32_bf16 v[76:79], v[208:211], v[160:163], v[76:79]
	v_mfma_f32_16x16x32_bf16 v[68:71], v[200:203], v[168:171], v[68:71]
	v_mfma_f32_16x16x32_bf16 v[64:67], v[208:211], v[168:171], v[64:67]
	v_mfma_f32_16x16x32_bf16 v[120:123], v[204:207], v[148:151], v[120:123]
	v_mfma_f32_16x16x32_bf16 v[108:111], v[220:223], v[148:151], v[108:111]
	v_mfma_f32_16x16x32_bf16 v[100:103], v[204:207], v[156:159], v[100:103]
	v_mfma_f32_16x16x32_bf16 v[96:99], v[220:223], v[156:159], v[96:99]
	v_mfma_f32_16x16x32_bf16 v[84:87], v[204:207], v[164:167], v[84:87]
	v_mfma_f32_16x16x32_bf16 v[76:79], v[220:223], v[164:167], v[76:79]
	v_mfma_f32_16x16x32_bf16 v[68:71], v[204:207], v[172:175], v[68:71]
	v_mfma_f32_16x16x32_bf16 v[64:67], v[220:223], v[172:175], v[64:67]
	s_barrier
	s_mov_b32 m0, s69
	v_lshl_add_u64 v[232:233], v[236:237], 0, s[34:35]
	ds_read_b128 v[144:147], v230 offset:49152
	ds_read_b128 v[148:151], v230 offset:50176
	ds_read_b128 v[152:155], v230 offset:51200
	ds_read_b128 v[156:159], v230 offset:52224
	ds_read_b128 v[160:163], v230 offset:53248
	ds_read_b128 v[164:167], v230 offset:54272
	ds_read_b128 v[168:171], v230 offset:55296
	ds_read_b128 v[172:175], v230 offset:56320
	global_load_lds_dwordx4 v[232:233], off
	v_lshl_add_u64 v[232:233], v[238:239], 0, s[34:35]
	s_mov_b32 m0, s7
	s_nop 0
	global_load_lds_dwordx4 v[232:233], off
	s_barrier
; #define PG8_STAGE(bufoff, gbase, voff) do { _Pragma("unroll") for (int _i = 0; _i < 2; ++_i) \
;         __builtin_amdgcn_global_load_lds((const unsigned*)((const char*)(gbase) + (voff)[_i]), (LAS unsigned*)(lds + (bufoff) + ldsw + _i * 8192), 16, 0, 0); } while (0)
; #define PG8_LDA(dst, b, h) do { _Pragma("unroll") for (int m = 0; m < 4; ++m) _Pragma("unroll") for (int k = 0; k < 2; ++k) dst[m][k] = *(const LAS bf16x8*)(lds + PG8_SA(b, h) + aoff + m * 2048 + k * 1024); } while (0)
; #define PG8_LDB(dst, b, h) do { _Pragma("unroll") for (int n = 0; n < 2; ++n) _Pragma("unroll") for (int k = 0; k < 2; ++k) dst[n][k] = *(const LAS bf16x8*)(lds + PG8_SB(b, h) + boff + n * 2048 + k * 1024); } while (0)
; #define PG8_WAIT_V(n) asm volatile("s_waitcnt vmcnt(" #n ")" ::: "memory")
; #define PG8_WAIT_L(n) asm volatile("s_waitcnt lgkmcnt(" #n ")" ::: "memory")
; #define PG8_BAR __builtin_amdgcn_s_barrier()
; #define PG8_SCHED __builtin_amdgcn_sched_barrier(0)
; template <class Epi>
; __device__ __forceinline__ void gemm_phase(LAS unsigned char* lds, const Gemm g, const StaticOrder S, const Epi E) {
;     ...
;         for (int t = 0; t < nt; t += 2) {
;             const bool last = (t == nt - 2);
;             const char* a1 = cA + (size_t)(t + 1) * kstep;
;             const char* a2 = last ? nA : cA + (size_t)(t + 2) * kstep; const char* b2 = last ? nB : cB + (size_t)(t + 2) * kstep;
;             const char* a3 = a2 + kstep; const char* b3 = b2 + kstep;
;             PG8_LDB(B0, 0, 0); PG8_SCHED; PG8_LDA(At, 0, 0); PG8_STAGE(PG8_SA(1, 1), a1 + hstep, voffA);
;             PG8_WAIT_L(8); PG8_BAR; PG8_WAIT_L(0); PG8_MMA(0, 0, At, B0); PG8_BAR; PG8_SCHED;
;             PG8_LDB(B1, 0, 1); PG8_STAGE(PG8_SB(0, 0), b2, voffA);
;             PG8_BAR; PG8_WAIT_L(0); PG8_MMA(0, 1, At, B1); PG8_BAR;
;             PG8_LDA(At, 0, 1); PG8_STAGE(PG8_SA(0, 0), a2, voffA);
;             PG8_BAR; PG8_WAIT_L(0); PG8_MMA(1, 0, At, B0); PG8_BAR; PG8_SCHED;
;             PG8_STAGE(PG8_SB(0, 1), b2 + hstep, voffA);
;             PG8_WAIT_V(6); PG8_BAR; PG8_MMA(1, 1, At, B1); PG8_BAR;
;     ...
;             PG8_LDA(At, 1, 1); PG8_STAGE(PG8_SA(1, 0), a3, voffA);
;             PG8_BAR; PG8_WAIT_L(0); PG8_MMA(1, 0, At, B0); PG8_BAR; PG8_SCHED;
;             PG8_STAGE(PG8_SB(1, 1), b3 + hstep, voffA);
;             PG8_WAIT_V(6); PG8_BAR; PG8_MMA(1, 1, At, B1); PG8_BAR;
	s_waitcnt lgkmcnt(0)
	v_mfma_f32_16x16x32_bf16 v[60:63], v[116:119], v[144:147], v[60:63]
	v_mfma_f32_16x16x32_bf16 v[56:59], v[128:131], v[144:147], v[56:59]
	v_mfma_f32_16x16x32_bf16 v[48:51], v[116:119], v[152:155], v[48:51]
	v_mfma_f32_16x16x32_bf16 v[40:43], v[128:131], v[152:155], v[40:43]
	v_mfma_f32_16x16x32_bf16 v[28:31], v[116:119], v[160:163], v[28:31]
	v_mfma_f32_16x16x32_bf16 v[24:27], v[128:131], v[160:163], v[24:27]
	v_mfma_f32_16x16x32_bf16 v[16:19], v[116:119], v[168:171], v[16:19]
	v_mfma_f32_16x16x32_bf16 v[8:11], v[128:131], v[168:171], v[8:11]
	v_mfma_f32_16x16x32_bf16 v[60:63], v[124:127], v[148:151], v[60:63]
	v_mfma_f32_16x16x32_bf16 v[56:59], v[132:135], v[148:151], v[56:59]
	v_mfma_f32_16x16x32_bf16 v[48:51], v[124:127], v[156:159], v[48:51]
	v_mfma_f32_16x16x32_bf16 v[40:43], v[132:135], v[156:159], v[40:43]
	v_mfma_f32_16x16x32_bf16 v[28:31], v[124:127], v[164:167], v[28:31]
	v_mfma_f32_16x16x32_bf16 v[24:27], v[132:135], v[164:167], v[24:27]
	v_mfma_f32_16x16x32_bf16 v[16:19], v[124:127], v[172:175], v[16:19]
	v_mfma_f32_16x16x32_bf16 v[8:11], v[132:135], v[172:175], v[8:11]
	s_barrier
	s_add_u32 s30, s60, 0x80080
	s_addc_u32 s31, s61, 0
	s_add_i32 s14, s55, s24
	v_lshl_add_u64 v[116:117], s[30:31], 0, v[178:179]
	s_mov_b32 m0, s14
	s_nop 0
	global_load_lds_dwordx4 v[116:117], off
	v_lshl_add_u64 v[116:117], s[30:31], 0, v[194:195]
	s_add_i32 m0, s14, 0x2000
	s_nop 0
	global_load_lds_dwordx4 v[116:117], off
	s_waitcnt vmcnt(6)
	s_barrier
	v_mfma_f32_16x16x32_bf16 v[52:55], v[200:203], v[144:147], v[52:55]
	v_mfma_f32_16x16x32_bf16 v[44:47], v[208:211], v[144:147], v[44:47]
	v_mfma_f32_16x16x32_bf16 v[36:39], v[200:203], v[152:155], v[36:39]
	v_mfma_f32_16x16x32_bf16 v[32:35], v[208:211], v[152:155], v[32:35]
	v_mfma_f32_16x16x32_bf16 v[20:23], v[200:203], v[160:163], v[20:23]
	v_mfma_f32_16x16x32_bf16 v[12:15], v[208:211], v[160:163], v[12:15]
	v_mfma_f32_16x16x32_bf16 v[4:7], v[200:203], v[168:171], v[4:7]
	v_mfma_f32_16x16x32_bf16 v[0:3], v[208:211], v[168:171], v[0:3]
	v_mfma_f32_16x16x32_bf16 v[52:55], v[204:207], v[148:151], v[52:55]
	v_mfma_f32_16x16x32_bf16 v[44:47], v[220:223], v[148:151], v[44:47]
	v_mfma_f32_16x16x32_bf16 v[36:39], v[204:207], v[156:159], v[36:39]
	v_mfma_f32_16x16x32_bf16 v[32:35], v[220:223], v[156:159], v[32:35]
	v_mfma_f32_16x16x32_bf16 v[20:23], v[204:207], v[164:167], v[20:23]
	v_mfma_f32_16x16x32_bf16 v[12:15], v[220:223], v[164:167], v[12:15]
	v_mfma_f32_16x16x32_bf16 v[4:7], v[204:207], v[172:175], v[4:7]
	v_mfma_f32_16x16x32_bf16 v[0:3], v[220:223], v[172:175], v[0:3]
	s_barrier
	s_add_u32 s45, s45, 0x100
	s_addc_u32 s47, s47, 0
	s_cmp_ge_i32 vcc_lo, s39
	s_mov_b64 s[56:57], s[58:59]
	s_mov_b32 s55, vcc_lo
	s_cbranch_scc0 .LBB0_3568
	s_branch .Lpeel_exit_5
.LBB0_3568:
	s_add_i32 vcc_lo, s55, 2
	s_add_u32 s58, s56, 0x100
	s_addc_u32 s59, s57, 0
	s_add_i32 s14, 0, 0x10000
	v_add_u32_e32 v132, s14, v228
	ds_read_b128 v[116:119], v132
	ds_read_b128 v[124:127], v132 offset:1024
	ds_read_b128 v[128:131], v132 offset:2048
	ds_read_b128 v[132:135], v132 offset:3072
	s_cmp_eq_u32 s43, s55
	s_cselect_b32 s63, s51, s59
	s_cselect_b32 s62, s50, s58
	s_cselect_b32 s61, s53, s47
	s_cselect_b32 s60, s52, s45
	v_lshl_add_u64 v[200:201], s[56:57], 0, v[196:197]
	s_add_i32 m0, s25, 0xc000
	ds_read_b128 v[144:147], v230
	ds_read_b128 v[148:151], v230 offset:1024
	ds_read_b128 v[152:155], v230 offset:2048
	ds_read_b128 v[156:159], v230 offset:3072
	ds_read_b128 v[160:163], v230 offset:4096
	ds_read_b128 v[164:167], v230 offset:5120
	ds_read_b128 v[168:171], v230 offset:6144
	ds_read_b128 v[172:175], v230 offset:7168
	global_load_lds_dwordx4 v[200:201], off
	v_lshl_add_u64 v[200:201], s[56:57], 0, v[198:199]
	s_add_i32 m0, s25, 0xe000
	s_nop 0
	global_load_lds_dwordx4 v[200:201], off
	s_waitcnt lgkmcnt(8)
	s_barrier
	s_waitcnt lgkmcnt(0)
	v_mfma_f32_16x16x32_bf16 v[140:143], v[116:119], v[144:147], v[140:143]
	v_mfma_f32_16x16x32_bf16 v[136:139], v[128:131], v[144:147], v[136:139]
	v_mfma_f32_16x16x32_bf16 v[112:115], v[116:119], v[152:155], v[112:115]
	v_mfma_f32_16x16x32_bf16 v[104:107], v[128:131], v[152:155], v[104:107]
	v_mfma_f32_16x16x32_bf16 v[92:95], v[116:119], v[160:163], v[92:95]
	v_mfma_f32_16x16x32_bf16 v[88:91], v[128:131], v[160:163], v[88:91]
	v_mfma_f32_16x16x32_bf16 v[80:83], v[116:119], v[168:171], v[80:83]
	v_mfma_f32_16x16x32_bf16 v[72:75], v[128:131], v[168:171], v[72:75]
	v_mfma_f32_16x16x32_bf16 v[140:143], v[124:127], v[148:151], v[140:143]
	v_mfma_f32_16x16x32_bf16 v[136:139], v[132:135], v[148:151], v[136:139]
	v_mfma_f32_16x16x32_bf16 v[112:115], v[124:127], v[156:159], v[112:115]
	v_mfma_f32_16x16x32_bf16 v[104:107], v[132:135], v[156:159], v[104:107]
	v_mfma_f32_16x16x32_bf16 v[92:95], v[124:127], v[164:167], v[92:95]
	v_mfma_f32_16x16x32_bf16 v[88:91], v[132:135], v[164:167], v[88:91]
	v_mfma_f32_16x16x32_bf16 v[80:83], v[124:127], v[172:175], v[80:83]
	v_mfma_f32_16x16x32_bf16 v[72:75], v[132:135], v[172:175], v[72:75]
	s_barrier
	s_add_i32 s55, 0, 0x14000
	s_add_i32 s14, s14, s24
	v_add_u32_e32 v220, s55, v228
	v_lshl_add_u64 v[232:233], s[60:61], 0, v[178:179]
	s_mov_b32 m0, s14
	ds_read_b128 v[200:203], v220
	ds_read_b128 v[204:207], v220 offset:1024
	ds_read_b128 v[208:211], v220 offset:2048
	ds_read_b128 v[220:223], v220 offset:3072
	global_load_lds_dwordx4 v[232:233], off
	v_lshl_add_u64 v[234:235], s[60:61], 0, v[194:195]
	s_add_i32 m0, s14, 0x2000
	s_nop 0
	global_load_lds_dwordx4 v[234:235], off
	s_barrier
; #define PG8_STAGE(bufoff, gbase, voff) do { _Pragma("unroll") for (int _i = 0; _i < 2; ++_i) \
;         __builtin_amdgcn_global_load_lds((const unsigned*)((const char*)(gbase) + (voff)[_i]), (LAS unsigned*)(lds + (bufoff) + ldsw + _i * 8192), 16, 0, 0); } while (0)
; #define PG8_LDA(dst, b, h) do { _Pragma("unroll") for (int m = 0; m < 4; ++m) _Pragma("unroll") for (int k = 0; k < 2; ++k) dst[m][k] = *(const LAS bf16x8*)(lds + PG8_SA(b, h) + aoff + m * 2048 + k * 1024); } while (0)
; #define PG8_LDB(dst, b, h) do { _Pragma("unroll") for (int n = 0; n < 2; ++n) _Pragma("unroll") for (int k = 0; k < 2; ++k) dst[n][k] = *(const LAS bf16x8*)(lds + PG8_SB(b, h) + boff + n * 2048 + k * 1024); } while (0)
; #define PG8_MMA(ai, bj, At, Bt) do { __builtin_amdgcn_s_setprio(1); _Pragma("unroll") for (int m = 0; m < 4; ++m) _Pragma("unroll") for (int n = 0; n < 2; ++n) _Pragma("unroll") for (int k = 0; k < 2; ++k) \
;         acc[ai][bj][m][n] = __builtin_amdgcn_mfma_f32_16x16x32_bf16(Bt[n][k], At[m][k], acc[ai][bj][m][n], 0, 0, 0); __builtin_amdgcn_s_setprio(0); } while (0)
; #define PG8_WAIT_V(n) asm volatile("s_waitcnt vmcnt(" #n ")" ::: "memory")
; #define PG8_WAIT_L(n) asm volatile("s_waitcnt lgkmcnt(" #n ")" ::: "memory")
; #define PG8_BAR __builtin_amdgcn_s_barrier()
; #define PG8_SCHED __builtin_amdgcn_sched_barrier(0)
; template <class Epi>
; __device__ __forceinline__ void gemm_phase(LAS unsigned char* lds, const Gemm g, const StaticOrder S, const Epi E) {
;     ...
;             PG8_LDB(B1, 0, 1); PG8_STAGE(PG8_SB(0, 0), b2, voffA);
;             PG8_BAR; PG8_WAIT_L(0); PG8_MMA(0, 1, At, B1); PG8_BAR;
;             PG8_LDA(At, 0, 1); PG8_STAGE(PG8_SA(0, 0), a2, voffA);
;             PG8_BAR; PG8_WAIT_L(0); PG8_MMA(1, 0, At, B0); PG8_BAR; PG8_SCHED;
;             PG8_STAGE(PG8_SB(0, 1), b2 + hstep, voffA);
;             PG8_WAIT_V(6); PG8_BAR; PG8_MMA(1, 1, At, B1); PG8_BAR;
;             PG8_LDB(B0, 1, 0); PG8_SCHED; PG8_LDA(At, 1, 0); PG8_STAGE(PG8_SA(0, 1), a2 + hstep, voffA);
;             PG8_WAIT_L(8); PG8_BAR; PG8_WAIT_L(0); PG8_MMA(0, 0, At, B0); PG8_BAR; PG8_SCHED;
;             PG8_LDB(B1, 1, 1); PG8_STAGE(PG8_SB(1, 0), b3, voffA);
	s_waitcnt lgkmcnt(0)
	v_mfma_f32_16x16x32_bf16 v[120:123], v[200:203], v[144:147], v[120:123]
	v_mfma_f32_16x16x32_bf16 v[108:111], v[208:211], v[144:147], v[108:111]
	v_mfma_f32_16x16x32_bf16 v[100:103], v[200:203], v[152:155], v[100:103]
	v_mfma_f32_16x16x32_bf16 v[96:99], v[208:211], v[152:155], v[96:99]
	v_mfma_f32_16x16x32_bf16 v[84:87], v[200:203], v[160:163], v[84:87]
	v_mfma_f32_16x16x32_bf16 v[76:79], v[208:211], v[160:163], v[76:79]
	v_mfma_f32_16x16x32_bf16 v[68:71], v[200:203], v[168:171], v[68:71]
	v_mfma_f32_16x16x32_bf16 v[64:67], v[208:211], v[168:171], v[64:67]
	v_mfma_f32_16x16x32_bf16 v[120:123], v[204:207], v[148:151], v[120:123]
	v_mfma_f32_16x16x32_bf16 v[108:111], v[220:223], v[148:151], v[108:111]
	v_mfma_f32_16x16x32_bf16 v[100:103], v[204:207], v[156:159], v[100:103]
	v_mfma_f32_16x16x32_bf16 v[96:99], v[220:223], v[156:159], v[96:99]
	v_mfma_f32_16x16x32_bf16 v[84:87], v[204:207], v[164:167], v[84:87]
	v_mfma_f32_16x16x32_bf16 v[76:79], v[220:223], v[164:167], v[76:79]
	v_mfma_f32_16x16x32_bf16 v[68:71], v[204:207], v[172:175], v[68:71]
	v_mfma_f32_16x16x32_bf16 v[64:67], v[220:223], v[172:175], v[64:67]
	s_barrier
	s_mov_b32 m0, s25
	v_lshl_add_u64 v[236:237], s[62:63], 0, v[178:179]
	ds_read_b128 v[144:147], v230 offset:16384
	ds_read_b128 v[148:151], v230 offset:17408
	ds_read_b128 v[152:155], v230 offset:18432
	ds_read_b128 v[156:159], v230 offset:19456
	ds_read_b128 v[160:163], v230 offset:20480
	ds_read_b128 v[164:167], v230 offset:21504
	ds_read_b128 v[168:171], v230 offset:22528
	ds_read_b128 v[172:175], v230 offset:23552
	global_load_lds_dwordx4 v[236:237], off
	v_lshl_add_u64 v[238:239], s[62:63], 0, v[194:195]
	s_mov_b32 m0, s64
	s_nop 0
	global_load_lds_dwordx4 v[238:239], off
	s_barrier
	s_waitcnt lgkmcnt(0)
	v_mfma_f32_16x16x32_bf16 v[60:63], v[116:119], v[144:147], v[60:63]
	v_mfma_f32_16x16x32_bf16 v[56:59], v[128:131], v[144:147], v[56:59]
	v_mfma_f32_16x16x32_bf16 v[48:51], v[116:119], v[152:155], v[48:51]
	v_mfma_f32_16x16x32_bf16 v[40:43], v[128:131], v[152:155], v[40:43]
	v_mfma_f32_16x16x32_bf16 v[28:31], v[116:119], v[160:163], v[28:31]
	v_mfma_f32_16x16x32_bf16 v[24:27], v[128:131], v[160:163], v[24:27]
	v_mfma_f32_16x16x32_bf16 v[16:19], v[116:119], v[168:171], v[16:19]
	v_mfma_f32_16x16x32_bf16 v[8:11], v[128:131], v[168:171], v[8:11]
	v_mfma_f32_16x16x32_bf16 v[60:63], v[124:127], v[148:151], v[60:63]
	v_mfma_f32_16x16x32_bf16 v[56:59], v[132:135], v[148:151], v[56:59]
	v_mfma_f32_16x16x32_bf16 v[48:51], v[124:127], v[156:159], v[48:51]
	v_mfma_f32_16x16x32_bf16 v[40:43], v[132:135], v[156:159], v[40:43]
	v_mfma_f32_16x16x32_bf16 v[28:31], v[124:127], v[164:167], v[28:31]
	v_mfma_f32_16x16x32_bf16 v[24:27], v[132:135], v[164:167], v[24:27]
	v_mfma_f32_16x16x32_bf16 v[16:19], v[124:127], v[172:175], v[16:19]
	v_mfma_f32_16x16x32_bf16 v[8:11], v[132:135], v[172:175], v[8:11]
	s_barrier
	s_add_u32 s30, s60, 0x80000
	s_addc_u32 s31, s61, 0
	s_add_i32 s14, s55, s24
	v_lshl_add_u64 v[116:117], s[30:31], 0, v[178:179]
	s_mov_b32 m0, s14
	s_nop 0
	global_load_lds_dwordx4 v[116:117], off
	v_lshl_add_u64 v[116:117], s[30:31], 0, v[194:195]
	s_add_i32 m0, s14, 0x2000
	s_nop 0
	global_load_lds_dwordx4 v[116:117], off
	s_waitcnt vmcnt(6)
	s_barrier
	v_mfma_f32_16x16x32_bf16 v[52:55], v[200:203], v[144:147], v[52:55]
	v_mfma_f32_16x16x32_bf16 v[44:47], v[208:211], v[144:147], v[44:47]
	v_mfma_f32_16x16x32_bf16 v[36:39], v[200:203], v[152:155], v[36:39]
	v_mfma_f32_16x16x32_bf16 v[32:35], v[208:211], v[152:155], v[32:35]
	v_mfma_f32_16x16x32_bf16 v[20:23], v[200:203], v[160:163], v[20:23]
	v_mfma_f32_16x16x32_bf16 v[12:15], v[208:211], v[160:163], v[12:15]
	v_mfma_f32_16x16x32_bf16 v[4:7], v[200:203], v[168:171], v[4:7]
	v_mfma_f32_16x16x32_bf16 v[0:3], v[208:211], v[168:171], v[0:3]
	v_mfma_f32_16x16x32_bf16 v[52:55], v[204:207], v[148:151], v[52:55]
	v_mfma_f32_16x16x32_bf16 v[44:47], v[220:223], v[148:151], v[44:47]
	v_mfma_f32_16x16x32_bf16 v[36:39], v[204:207], v[156:159], v[36:39]
	v_mfma_f32_16x16x32_bf16 v[32:35], v[220:223], v[156:159], v[32:35]
	v_mfma_f32_16x16x32_bf16 v[20:23], v[204:207], v[164:167], v[20:23]
	v_mfma_f32_16x16x32_bf16 v[12:15], v[220:223], v[164:167], v[12:15]
	v_mfma_f32_16x16x32_bf16 v[4:7], v[204:207], v[172:175], v[4:7]
	v_mfma_f32_16x16x32_bf16 v[0:3], v[220:223], v[172:175], v[0:3]
	s_barrier
	s_add_i32 s14, 0, 0x18000
	v_add_u32_e32 v132, s14, v228
	ds_read_b128 v[116:119], v132
	ds_read_b128 v[124:127], v132 offset:1024
	ds_read_b128 v[128:131], v132 offset:2048
	ds_read_b128 v[132:135], v132 offset:3072
	s_add_u32 s30, s62, 0x80000
	s_addc_u32 s31, s63, 0
	s_mov_b32 m0, s65
	v_lshl_add_u64 v[200:201], s[30:31], 0, v[178:179]
	ds_read_b128 v[144:147], v230 offset:32768
	ds_read_b128 v[148:151], v230 offset:33792
	ds_read_b128 v[152:155], v230 offset:34816
	ds_read_b128 v[156:159], v230 offset:35840
	ds_read_b128 v[160:163], v230 offset:36864
	ds_read_b128 v[164:167], v230 offset:37888
	ds_read_b128 v[168:171], v230 offset:38912
	ds_read_b128 v[172:175], v230 offset:39936
	global_load_lds_dwordx4 v[200:201], off
	v_lshl_add_u64 v[200:201], s[30:31], 0, v[194:195]
	s_mov_b32 m0, s66
	s_nop 0
	global_load_lds_dwordx4 v[200:201], off
	s_waitcnt lgkmcnt(8)
	s_barrier
; #define PG8_STAGE(bufoff, gbase, voff) do { _Pragma("unroll") for (int _i = 0; _i < 2; ++_i) \
;         __builtin_amdgcn_global_load_lds((const unsigned*)((const char*)(gbase) + (voff)[_i]), (LAS unsigned*)(lds + (bufoff) + ldsw + _i * 8192), 16, 0, 0); } while (0)
; #define PG8_LDA(dst, b, h) do { _Pragma("unroll") for (int m = 0; m < 4; ++m) _Pragma("unroll") for (int k = 0; k < 2; ++k) dst[m][k] = *(const LAS bf16x8*)(lds + PG8_SA(b, h) + aoff + m * 2048 + k * 1024); } while (0)
; #define PG8_MMA(ai, bj, At, Bt) do { __builtin_amdgcn_s_setprio(1); _Pragma("unroll") for (int m = 0; m < 4; ++m) _Pragma("unroll") for (int n = 0; n < 2; ++n) _Pragma("unroll") for (int k = 0; k < 2; ++k) \
;         acc[ai][bj][m][n] = __builtin_amdgcn_mfma_f32_16x16x32_bf16(Bt[n][k], At[m][k], acc[ai][bj][m][n], 0, 0, 0); __builtin_amdgcn_s_setprio(0); } while (0)
; #define PG8_WAIT_V(n) asm volatile("s_waitcnt vmcnt(" #n ")" ::: "memory")
; #define PG8_WAIT_L(n) asm volatile("s_waitcnt lgkmcnt(" #n ")" ::: "memory")
; #define PG8_BAR __builtin_amdgcn_s_barrier()
; #define PG8_SCHED __builtin_amdgcn_sched_barrier(0)
; template <class Epi>
; __device__ __forceinline__ void gemm_phase(LAS unsigned char* lds, const Gemm g, const StaticOrder S, const Epi E) {
;     ...
;             PG8_LDA(At, 1, 1); PG8_STAGE(PG8_SA(1, 0), a3, voffA);
;             PG8_BAR; PG8_WAIT_L(0); PG8_MMA(1, 0, At, B0); PG8_BAR; PG8_SCHED;
;             PG8_STAGE(PG8_SB(1, 1), b3 + hstep, voffA);
;             PG8_WAIT_V(6); PG8_BAR; PG8_MMA(1, 1, At, B1); PG8_BAR;
	s_waitcnt lgkmcnt(0)
	v_mfma_f32_16x16x32_bf16 v[140:143], v[116:119], v[144:147], v[140:143]
	v_mfma_f32_16x16x32_bf16 v[136:139], v[128:131], v[144:147], v[136:139]
	v_mfma_f32_16x16x32_bf16 v[112:115], v[116:119], v[152:155], v[112:115]
	v_mfma_f32_16x16x32_bf16 v[104:107], v[128:131], v[152:155], v[104:107]
	v_mfma_f32_16x16x32_bf16 v[92:95], v[116:119], v[160:163], v[92:95]
	v_mfma_f32_16x16x32_bf16 v[88:91], v[128:131], v[160:163], v[88:91]
	v_mfma_f32_16x16x32_bf16 v[80:83], v[116:119], v[168:171], v[80:83]
	v_mfma_f32_16x16x32_bf16 v[72:75], v[128:131], v[168:171], v[72:75]
	v_mfma_f32_16x16x32_bf16 v[140:143], v[124:127], v[148:151], v[140:143]
	v_mfma_f32_16x16x32_bf16 v[136:139], v[132:135], v[148:151], v[136:139]
	v_mfma_f32_16x16x32_bf16 v[112:115], v[124:127], v[156:159], v[112:115]
	v_mfma_f32_16x16x32_bf16 v[104:107], v[132:135], v[156:159], v[104:107]
	v_mfma_f32_16x16x32_bf16 v[92:95], v[124:127], v[164:167], v[92:95]
	v_mfma_f32_16x16x32_bf16 v[88:91], v[132:135], v[164:167], v[88:91]
	v_mfma_f32_16x16x32_bf16 v[80:83], v[124:127], v[172:175], v[80:83]
	v_mfma_f32_16x16x32_bf16 v[72:75], v[132:135], v[172:175], v[72:75]
	s_barrier
	s_add_i32 s55, 0, 0x1c000
	s_add_i32 s14, s14, s24
	v_add_u32_e32 v220, s55, v228
	v_lshl_add_u64 v[232:233], v[232:233], 0, s[34:35]
	s_mov_b32 m0, s14
	ds_read_b128 v[200:203], v220
	ds_read_b128 v[204:207], v220 offset:1024
	ds_read_b128 v[208:211], v220 offset:2048
	ds_read_b128 v[220:223], v220 offset:3072
	global_load_lds_dwordx4 v[232:233], off
	v_lshl_add_u64 v[232:233], v[234:235], 0, s[34:35]
	s_add_i32 m0, s14, 0x2000
	s_nop 0
	global_load_lds_dwordx4 v[232:233], off
	s_barrier
	s_waitcnt lgkmcnt(0)
	v_mfma_f32_16x16x32_bf16 v[120:123], v[200:203], v[144:147], v[120:123]
	v_mfma_f32_16x16x32_bf16 v[108:111], v[208:211], v[144:147], v[108:111]
	v_mfma_f32_16x16x32_bf16 v[100:103], v[200:203], v[152:155], v[100:103]
	v_mfma_f32_16x16x32_bf16 v[96:99], v[208:211], v[152:155], v[96:99]
	v_mfma_f32_16x16x32_bf16 v[84:87], v[200:203], v[160:163], v[84:87]
	v_mfma_f32_16x16x32_bf16 v[76:79], v[208:211], v[160:163], v[76:79]
	v_mfma_f32_16x16x32_bf16 v[68:71], v[200:203], v[168:171], v[68:71]
	v_mfma_f32_16x16x32_bf16 v[64:67], v[208:211], v[168:171], v[64:67]
	v_mfma_f32_16x16x32_bf16 v[120:123], v[204:207], v[148:151], v[120:123]
	v_mfma_f32_16x16x32_bf16 v[108:111], v[220:223], v[148:151], v[108:111]
	v_mfma_f32_16x16x32_bf16 v[100:103], v[204:207], v[156:159], v[100:103]
	v_mfma_f32_16x16x32_bf16 v[96:99], v[220:223], v[156:159], v[96:99]
	v_mfma_f32_16x16x32_bf16 v[84:87], v[204:207], v[164:167], v[84:87]
	v_mfma_f32_16x16x32_bf16 v[76:79], v[220:223], v[164:167], v[76:79]
	v_mfma_f32_16x16x32_bf16 v[68:71], v[204:207], v[172:175], v[68:71]
	v_mfma_f32_16x16x32_bf16 v[64:67], v[220:223], v[172:175], v[64:67]
	s_barrier
	s_mov_b32 m0, s69
	v_lshl_add_u64 v[232:233], v[236:237], 0, s[34:35]
	ds_read_b128 v[144:147], v230 offset:49152
	ds_read_b128 v[148:151], v230 offset:50176
	ds_read_b128 v[152:155], v230 offset:51200
	ds_read_b128 v[156:159], v230 offset:52224
	ds_read_b128 v[160:163], v230 offset:53248
	ds_read_b128 v[164:167], v230 offset:54272
	ds_read_b128 v[168:171], v230 offset:55296
	ds_read_b128 v[172:175], v230 offset:56320
	global_load_lds_dwordx4 v[232:233], off
	v_lshl_add_u64 v[232:233], v[238:239], 0, s[34:35]
	s_mov_b32 m0, s7
	s_nop 0
	global_load_lds_dwordx4 v[232:233], off
	s_barrier
	s_waitcnt lgkmcnt(0)
	v_mfma_f32_16x16x32_bf16 v[60:63], v[116:119], v[144:147], v[60:63]
	v_mfma_f32_16x16x32_bf16 v[56:59], v[128:131], v[144:147], v[56:59]
	v_mfma_f32_16x16x32_bf16 v[48:51], v[116:119], v[152:155], v[48:51]
	v_mfma_f32_16x16x32_bf16 v[40:43], v[128:131], v[152:155], v[40:43]
	v_mfma_f32_16x16x32_bf16 v[28:31], v[116:119], v[160:163], v[28:31]
	v_mfma_f32_16x16x32_bf16 v[24:27], v[128:131], v[160:163], v[24:27]
	v_mfma_f32_16x16x32_bf16 v[16:19], v[116:119], v[168:171], v[16:19]
	v_mfma_f32_16x16x32_bf16 v[8:11], v[128:131], v[168:171], v[8:11]
	v_mfma_f32_16x16x32_bf16 v[60:63], v[124:127], v[148:151], v[60:63]
	v_mfma_f32_16x16x32_bf16 v[56:59], v[132:135], v[148:151], v[56:59]
	v_mfma_f32_16x16x32_bf16 v[48:51], v[124:127], v[156:159], v[48:51]
	v_mfma_f32_16x16x32_bf16 v[40:43], v[132:135], v[156:159], v[40:43]
	v_mfma_f32_16x16x32_bf16 v[28:31], v[124:127], v[164:167], v[28:31]
	v_mfma_f32_16x16x32_bf16 v[24:27], v[132:135], v[164:167], v[24:27]
	v_mfma_f32_16x16x32_bf16 v[16:19], v[124:127], v[172:175], v[16:19]
	v_mfma_f32_16x16x32_bf16 v[8:11], v[132:135], v[172:175], v[8:11]
	s_barrier
	s_add_u32 s30, s60, 0x80080
	s_addc_u32 s31, s61, 0
	s_add_i32 s14, s55, s24
	v_lshl_add_u64 v[116:117], s[30:31], 0, v[178:179]
	s_mov_b32 m0, s14
	s_nop 0
	global_load_lds_dwordx4 v[116:117], off
	v_lshl_add_u64 v[116:117], s[30:31], 0, v[194:195]
	s_add_i32 m0, s14, 0x2000
	s_nop 0
	global_load_lds_dwordx4 v[116:117], off
	s_waitcnt vmcnt(6)
	s_barrier
	v_mfma_f32_16x16x32_bf16 v[52:55], v[200:203], v[144:147], v[52:55]
	v_mfma_f32_16x16x32_bf16 v[44:47], v[208:211], v[144:147], v[44:47]
	v_mfma_f32_16x16x32_bf16 v[36:39], v[200:203], v[152:155], v[36:39]
	v_mfma_f32_16x16x32_bf16 v[32:35], v[208:211], v[152:155], v[32:35]
	v_mfma_f32_16x16x32_bf16 v[20:23], v[200:203], v[160:163], v[20:23]
	v_mfma_f32_16x16x32_bf16 v[12:15], v[208:211], v[160:163], v[12:15]
	v_mfma_f32_16x16x32_bf16 v[4:7], v[200:203], v[168:171], v[4:7]
	v_mfma_f32_16x16x32_bf16 v[0:3], v[208:211], v[168:171], v[0:3]
	v_mfma_f32_16x16x32_bf16 v[52:55], v[204:207], v[148:151], v[52:55]
	v_mfma_f32_16x16x32_bf16 v[44:47], v[220:223], v[148:151], v[44:47]
	v_mfma_f32_16x16x32_bf16 v[36:39], v[204:207], v[156:159], v[36:39]
	v_mfma_f32_16x16x32_bf16 v[32:35], v[220:223], v[156:159], v[32:35]
	v_mfma_f32_16x16x32_bf16 v[20:23], v[204:207], v[164:167], v[20:23]
	v_mfma_f32_16x16x32_bf16 v[12:15], v[220:223], v[164:167], v[12:15]
	v_mfma_f32_16x16x32_bf16 v[4:7], v[204:207], v[172:175], v[4:7]
	v_mfma_f32_16x16x32_bf16 v[0:3], v[220:223], v[172:175], v[0:3]
	s_barrier
	s_add_u32 s45, s45, 0x100
	s_addc_u32 s47, s47, 0
	s_cmp_ge_i32 vcc_lo, s39
	s_mov_b64 s[56:57], s[58:59]
	s_mov_b32 s55, vcc_lo
	s_cbranch_scc0 .LBB0_3568

; #define PG8_STAGE(bufoff, gbase, voff) do { _Pragma("unroll") for (int _i = 0; _i < 2; ++_i) \
;         __builtin_amdgcn_global_load_lds((const unsigned*)((const char*)(gbase) + (voff)[_i]), (LAS unsigned*)(lds + (bufoff) + ldsw + _i * 8192), 16, 0, 0); } while (0)
; #define PG8_LDA(dst, b, h) do { _Pragma("unroll") for (int m = 0; m < 4; ++m) _Pragma("unroll") for (int k = 0; k < 2; ++k) dst[m][k] = *(const LAS bf16x8*)(lds + PG8_SA(b, h) + aoff + m * 2048 + k * 1024); } while (0)
; #define PG8_LDB(dst, b, h) do { _Pragma("unroll") for (int n = 0; n < 2; ++n) _Pragma("unroll") for (int k = 0; k < 2; ++k) dst[n][k] = *(const LAS bf16x8*)(lds + PG8_SB(b, h) + boff + n * 2048 + k * 1024); } while (0)
; #define PG8_BAR __builtin_amdgcn_s_barrier()
; template <class Epi>
; __device__ __forceinline__ void gemm_phase(LAS unsigned char* lds, const Gemm g, const StaticOrder S, const Epi E) {
;     ...
;         const bool has_next = S.next(ui + 1, nxt);
;         const char* nA = has_next ? (const char*)g.A + (size_t)nxt.pm * tstep + (size_t)nxt.k0 * kstep : cA; const char* nB = has_next ? (const char*)g.Bt + (size_t)nxt.pn * tstep + (size_t)nxt.k0 * kstep : cB;
;         const int nt = cur.nk;
;         for (int t = 0; t < nt; t += 2) {
;             const bool last = (t == nt - 2);
;             const char* a1 = cA + (size_t)(t + 1) * kstep;
;             const char* a2 = last ? nA : cA + (size_t)(t + 2) * kstep; const char* b2 = last ? nB : cB + (size_t)(t + 2) * kstep;
;             const char* a3 = a2 + kstep; const char* b3 = b2 + kstep;
;             PG8_LDB(B0, 0, 0); PG8_SCHED; PG8_LDA(At, 0, 0); PG8_STAGE(PG8_SA(1, 1), a1 + hstep, voffA);
;             PG8_WAIT_L(8); PG8_BAR; PG8_WAIT_L(0); PG8_MMA(0, 0, At, B0); PG8_BAR; PG8_SCHED;
;             PG8_LDB(B1, 0, 1); PG8_STAGE(PG8_SB(0, 0), b2, voffA);
;             PG8_BAR; PG8_WAIT_L(0); PG8_MMA(0, 1, At, B1); PG8_BAR;
;             PG8_LDA(At, 0, 1); PG8_STAGE(PG8_SA(0, 0), a2, voffA);
;             PG8_BAR; PG8_WAIT_L(0); PG8_MMA(1, 0, At, B0); PG8_BAR; PG8_SCHED;
;             PG8_STAGE(PG8_SB(0, 1), b2 + hstep, voffA);
;             PG8_WAIT_V(6); PG8_BAR; PG8_MMA(1, 1, At, B1); PG8_BAR;
;             PG8_LDB(B0, 1, 0); PG8_SCHED; PG8_LDA(At, 1, 0); PG8_STAGE(PG8_SA(0, 1), a2 + hstep, voffA);
;             PG8_WAIT_L(8); PG8_BAR; PG8_WAIT_L(0); PG8_MMA(0, 0, At, B0); PG8_BAR; PG8_SCHED;
.LBB0_3722:
	s_ashr_i32 s3, s2, 31
	v_mov_b64_e32 v[0:1], s[4:5]
	s_lshl_b64 s[26:27], s[2:3], 20
	v_readlane_b32 s1, v255, 1
	v_cmp_lt_i64_e32 vcc, s[42:43], v[0:1]
	s_add_u32 s42, s1, s26
	v_readlane_b32 s1, v255, 2
	s_addc_u32 s43, s1, s27
	s_and_b64 s[26:27], vcc, exec
	s_cselect_b32 s3, s43, s51
	s_cselect_b32 s26, s42, s50
	s_ashr_i32 s1, s0, 31
	s_lshl_b64 s[28:29], s[0:1], 20
	s_add_u32 s44, s56, s28
	s_addc_u32 s45, s57, s29
	s_and_b64 s[28:29], vcc, exec
	s_cselect_b32 s1, s45, s53
	s_cselect_b32 s27, s44, s52
	s_add_u32 s50, s50, 0x80080
	s_addc_u32 s51, s51, 0
	s_add_u32 s28, s52, 0x100
	s_addc_u32 s29, s53, 0
	s_mov_b32 s64, -2
	s_add_u32 s14, s50, 0xfff80080
	s_addc_u32 s30, s51, -1
	s_add_i32 s31, 0, 0x10000
	v_add_u32_e32 v134, s31, v137
	ds_read_b128 v[140:143], v134
	ds_read_b128 v[144:147], v134 offset:1024
	ds_read_b128 v[148:151], v134 offset:2048
	ds_read_b128 v[152:155], v134 offset:3072
	s_cmp_eq_u32 s64, 28
	s_cselect_b32 s55, s3, s30
	s_cselect_b32 s54, s26, s14
	s_cselect_b32 s53, s1, s29
	s_cselect_b32 s52, s27, s28
	v_lshl_add_u64 v[134:135], s[50:51], 0, v[130:131]
	s_add_i32 m0, s47, 0xc000
	ds_read_b128 v[156:159], v139
	ds_read_b128 v[160:163], v139 offset:1024
	ds_read_b128 v[164:167], v139 offset:2048
	ds_read_b128 v[168:171], v139 offset:3072
	ds_read_b128 v[172:175], v139 offset:4096
	ds_read_b128 v[194:197], v139 offset:5120
	ds_read_b128 v[198:201], v139 offset:6144
	ds_read_b128 v[202:205], v139 offset:7168
	global_load_lds_dwordx4 v[134:135], off
	v_lshl_add_u64 v[134:135], s[50:51], 0, v[132:133]
	s_add_i32 m0, s47, 0xe000
	s_nop 0
	global_load_lds_dwordx4 v[134:135], off
	s_waitcnt lgkmcnt(8)
	s_barrier
	s_waitcnt lgkmcnt(0)
	v_mfma_f32_16x16x32_bf16 v[120:123], v[140:143], v[156:159], 0
	v_mfma_f32_16x16x32_bf16 v[124:127], v[148:151], v[156:159], 0
	v_mfma_f32_16x16x32_bf16 v[104:107], v[140:143], v[164:167], 0
	v_mfma_f32_16x16x32_bf16 v[108:111], v[148:151], v[164:167], 0
	v_mfma_f32_16x16x32_bf16 v[88:91], v[140:143], v[172:175], 0
	v_mfma_f32_16x16x32_bf16 v[92:95], v[148:151], v[172:175], 0
	v_mfma_f32_16x16x32_bf16 v[72:75], v[140:143], v[198:201], 0
	v_mfma_f32_16x16x32_bf16 v[76:79], v[148:151], v[198:201], 0
	v_mfma_f32_16x16x32_bf16 v[120:123], v[144:147], v[160:163], v[120:123]
	v_mfma_f32_16x16x32_bf16 v[124:127], v[152:155], v[160:163], v[124:127]
	v_mfma_f32_16x16x32_bf16 v[104:107], v[144:147], v[168:171], v[104:107]
	v_mfma_f32_16x16x32_bf16 v[108:111], v[152:155], v[168:171], v[108:111]
	v_mfma_f32_16x16x32_bf16 v[88:91], v[144:147], v[194:197], v[88:91]
	v_mfma_f32_16x16x32_bf16 v[92:95], v[152:155], v[194:197], v[92:95]
	v_mfma_f32_16x16x32_bf16 v[72:75], v[144:147], v[202:205], v[72:75]
	v_mfma_f32_16x16x32_bf16 v[76:79], v[152:155], v[202:205], v[76:79]
	s_barrier
	s_add_i32 s14, 0, 0x14000
	v_add_u32_e32 v134, s14, v137
	s_add_i32 s30, s31, s58
	ds_read_b128 v[206:209], v134
	ds_read_b128 v[220:223], v134 offset:1024
	ds_read_b128 v[228:231], v134 offset:2048
	ds_read_b128 v[232:235], v134 offset:3072
	v_lshl_add_u64 v[134:135], s[52:53], 0, v[178:179]
	s_mov_b32 m0, s30
	v_lshl_add_u64 v[210:211], s[52:53], 0, v[128:129]
	global_load_lds_dwordx4 v[134:135], off
	s_add_i32 m0, s30, 0x2000
	s_nop 0
	global_load_lds_dwordx4 v[210:211], off
	s_barrier
	s_waitcnt lgkmcnt(0)
	v_mfma_f32_16x16x32_bf16 v[112:115], v[206:209], v[156:159], 0
	v_mfma_f32_16x16x32_bf16 v[116:119], v[228:231], v[156:159], 0
	v_mfma_f32_16x16x32_bf16 v[96:99], v[206:209], v[164:167], 0
	v_mfma_f32_16x16x32_bf16 v[100:103], v[228:231], v[164:167], 0
	v_mfma_f32_16x16x32_bf16 v[80:83], v[206:209], v[172:175], 0
	v_mfma_f32_16x16x32_bf16 v[84:87], v[228:231], v[172:175], 0
	v_mfma_f32_16x16x32_bf16 v[64:67], v[206:209], v[198:201], 0
	v_mfma_f32_16x16x32_bf16 v[68:71], v[228:231], v[198:201], 0
	v_mfma_f32_16x16x32_bf16 v[112:115], v[220:223], v[160:163], v[112:115]
	v_mfma_f32_16x16x32_bf16 v[116:119], v[232:235], v[160:163], v[116:119]
	v_mfma_f32_16x16x32_bf16 v[96:99], v[220:223], v[168:171], v[96:99]
	v_mfma_f32_16x16x32_bf16 v[100:103], v[232:235], v[168:171], v[100:103]
	v_mfma_f32_16x16x32_bf16 v[80:83], v[220:223], v[194:197], v[80:83]
	v_mfma_f32_16x16x32_bf16 v[84:87], v[232:235], v[194:197], v[84:87]
	v_mfma_f32_16x16x32_bf16 v[64:67], v[220:223], v[202:205], v[64:67]
	v_mfma_f32_16x16x32_bf16 v[68:71], v[232:235], v[202:205], v[68:71]
	s_barrier
	s_mov_b32 m0, s47
	v_lshl_add_u64 v[236:237], s[54:55], 0, v[178:179]
	ds_read_b128 v[156:159], v139 offset:16384
	ds_read_b128 v[160:163], v139 offset:17408
	ds_read_b128 v[164:167], v139 offset:18432
	ds_read_b128 v[168:171], v139 offset:19456
	ds_read_b128 v[172:175], v139 offset:20480
	ds_read_b128 v[194:197], v139 offset:21504
	ds_read_b128 v[198:201], v139 offset:22528
	ds_read_b128 v[202:205], v139 offset:23552
	global_load_lds_dwordx4 v[236:237], off
	v_lshl_add_u64 v[238:239], s[54:55], 0, v[128:129]
	s_mov_b32 m0, s49
	s_nop 0
	global_load_lds_dwordx4 v[238:239], off
	s_barrier
	s_waitcnt lgkmcnt(0)
	v_mfma_f32_16x16x32_bf16 v[56:59], v[140:143], v[156:159], 0
	v_mfma_f32_16x16x32_bf16 v[60:63], v[148:151], v[156:159], 0
	v_mfma_f32_16x16x32_bf16 v[40:43], v[140:143], v[164:167], 0
	v_mfma_f32_16x16x32_bf16 v[44:47], v[148:151], v[164:167], 0
	v_mfma_f32_16x16x32_bf16 v[24:27], v[140:143], v[172:175], 0
	v_mfma_f32_16x16x32_bf16 v[28:31], v[148:151], v[172:175], 0
	v_mfma_f32_16x16x32_bf16 v[8:11], v[140:143], v[198:201], 0
	v_mfma_f32_16x16x32_bf16 v[12:15], v[148:151], v[198:201], 0
	v_mfma_f32_16x16x32_bf16 v[56:59], v[144:147], v[160:163], v[56:59]
	v_mfma_f32_16x16x32_bf16 v[60:63], v[152:155], v[160:163], v[60:63]
	v_mfma_f32_16x16x32_bf16 v[40:43], v[144:147], v[168:171], v[40:43]
	v_mfma_f32_16x16x32_bf16 v[44:47], v[152:155], v[168:171], v[44:47]
	v_mfma_f32_16x16x32_bf16 v[24:27], v[144:147], v[194:197], v[24:27]
	v_mfma_f32_16x16x32_bf16 v[28:31], v[152:155], v[194:197], v[28:31]
	v_mfma_f32_16x16x32_bf16 v[8:11], v[144:147], v[202:205], v[8:11]
	v_mfma_f32_16x16x32_bf16 v[12:15], v[152:155], v[202:205], v[12:15]
	s_barrier
; #define PG8_STAGE(bufoff, gbase, voff) do { _Pragma("unroll") for (int _i = 0; _i < 2; ++_i) \
;         __builtin_amdgcn_global_load_lds((const unsigned*)((const char*)(gbase) + (voff)[_i]), (LAS unsigned*)(lds + (bufoff) + ldsw + _i * 8192), 16, 0, 0); } while (0)
; #define PG8_LDA(dst, b, h) do { _Pragma("unroll") for (int m = 0; m < 4; ++m) _Pragma("unroll") for (int k = 0; k < 2; ++k) dst[m][k] = *(const LAS bf16x8*)(lds + PG8_SA(b, h) + aoff + m * 2048 + k * 1024); } while (0)
; #define PG8_LDB(dst, b, h) do { _Pragma("unroll") for (int n = 0; n < 2; ++n) _Pragma("unroll") for (int k = 0; k < 2; ++k) dst[n][k] = *(const LAS bf16x8*)(lds + PG8_SB(b, h) + boff + n * 2048 + k * 1024); } while (0)
; #define PG8_MMA(ai, bj, At, Bt) do { __builtin_amdgcn_s_setprio(1); _Pragma("unroll") for (int m = 0; m < 4; ++m) _Pragma("unroll") for (int n = 0; n < 2; ++n) _Pragma("unroll") for (int k = 0; k < 2; ++k) \
;         acc[ai][bj][m][n] = __builtin_amdgcn_mfma_f32_16x16x32_bf16(Bt[n][k], At[m][k], acc[ai][bj][m][n], 0, 0, 0); __builtin_amdgcn_s_setprio(0); } while (0)
; #define PG8_WAIT_V(n) asm volatile("s_waitcnt vmcnt(" #n ")" ::: "memory")
; #define PG8_WAIT_L(n) asm volatile("s_waitcnt lgkmcnt(" #n ")" ::: "memory")
; #define PG8_BAR __builtin_amdgcn_s_barrier()
; #define PG8_SCHED __builtin_amdgcn_sched_barrier(0)
; template <class Epi>
; __device__ __forceinline__ void gemm_phase(LAS unsigned char* lds, const Gemm g, const StaticOrder S, const Epi E) {
;     ...
;             PG8_STAGE(PG8_SB(0, 1), b2 + hstep, voffA);
;             PG8_WAIT_V(6); PG8_BAR; PG8_MMA(1, 1, At, B1); PG8_BAR;
;             PG8_LDB(B0, 1, 0); PG8_SCHED; PG8_LDA(At, 1, 0); PG8_STAGE(PG8_SA(0, 1), a2 + hstep, voffA);
;             PG8_WAIT_L(8); PG8_BAR; PG8_WAIT_L(0); PG8_MMA(0, 0, At, B0); PG8_BAR; PG8_SCHED;
;             PG8_LDB(B1, 1, 1); PG8_STAGE(PG8_SB(1, 0), b3, voffA);
;             PG8_BAR; PG8_WAIT_L(0); PG8_MMA(0, 1, At, B1); PG8_BAR;
;             PG8_LDA(At, 1, 1); PG8_STAGE(PG8_SA(1, 0), a3, voffA);
;             PG8_BAR; PG8_WAIT_L(0); PG8_MMA(1, 0, At, B0); PG8_BAR; PG8_SCHED;
;             PG8_STAGE(PG8_SB(1, 1), b3 + hstep, voffA);
;             PG8_WAIT_V(6); PG8_BAR; PG8_MMA(1, 1, At, B1); PG8_BAR;
	s_add_u32 s30, s52, 0x80000
	s_addc_u32 s31, s53, 0
	s_add_i32 s14, s14, s58
	v_lshl_add_u64 v[140:141], s[30:31], 0, v[178:179]
	s_mov_b32 m0, s14
	s_nop 0
	global_load_lds_dwordx4 v[140:141], off
	v_lshl_add_u64 v[140:141], s[30:31], 0, v[128:129]
	s_add_i32 m0, s14, 0x2000
	s_nop 0
	global_load_lds_dwordx4 v[140:141], off
	s_waitcnt vmcnt(6)
	s_barrier
	v_mfma_f32_16x16x32_bf16 v[48:51], v[206:209], v[156:159], 0
	v_mfma_f32_16x16x32_bf16 v[52:55], v[228:231], v[156:159], 0
	v_mfma_f32_16x16x32_bf16 v[32:35], v[206:209], v[164:167], 0
	v_mfma_f32_16x16x32_bf16 v[36:39], v[228:231], v[164:167], 0
	v_mfma_f32_16x16x32_bf16 v[16:19], v[206:209], v[172:175], 0
	v_mfma_f32_16x16x32_bf16 v[20:23], v[228:231], v[172:175], 0
	v_mfma_f32_16x16x32_bf16 v[0:3], v[206:209], v[198:201], 0
	v_mfma_f32_16x16x32_bf16 v[4:7], v[228:231], v[198:201], 0
	v_mfma_f32_16x16x32_bf16 v[48:51], v[220:223], v[160:163], v[48:51]
	v_mfma_f32_16x16x32_bf16 v[52:55], v[232:235], v[160:163], v[52:55]
	v_mfma_f32_16x16x32_bf16 v[32:35], v[220:223], v[168:171], v[32:35]
	v_mfma_f32_16x16x32_bf16 v[36:39], v[232:235], v[168:171], v[36:39]
	v_mfma_f32_16x16x32_bf16 v[16:19], v[220:223], v[194:197], v[16:19]
	v_mfma_f32_16x16x32_bf16 v[20:23], v[232:235], v[194:197], v[20:23]
	v_mfma_f32_16x16x32_bf16 v[0:3], v[220:223], v[202:205], v[0:3]
	v_mfma_f32_16x16x32_bf16 v[4:7], v[232:235], v[202:205], v[4:7]
	s_barrier
	s_add_i32 s14, 0, 0x18000
	v_add_u32_e32 v152, s14, v137
	ds_read_b128 v[140:143], v152
	ds_read_b128 v[144:147], v152 offset:1024
	ds_read_b128 v[148:151], v152 offset:2048
	ds_read_b128 v[152:155], v152 offset:3072
	s_add_u32 s30, s54, 0x80000
	s_addc_u32 s31, s55, 0
	s_mov_b32 m0, s59
	v_lshl_add_u64 v[206:207], s[30:31], 0, v[178:179]
	ds_read_b128 v[156:159], v139 offset:32768
	ds_read_b128 v[160:163], v139 offset:33792
	ds_read_b128 v[164:167], v139 offset:34816
	ds_read_b128 v[168:171], v139 offset:35840
	ds_read_b128 v[172:175], v139 offset:36864
	ds_read_b128 v[194:197], v139 offset:37888
	ds_read_b128 v[198:201], v139 offset:38912
	ds_read_b128 v[202:205], v139 offset:39936
	global_load_lds_dwordx4 v[206:207], off
	v_lshl_add_u64 v[206:207], s[30:31], 0, v[128:129]
	s_mov_b32 m0, s60
	s_nop 0
	global_load_lds_dwordx4 v[206:207], off
	s_waitcnt lgkmcnt(8)
	s_barrier
	s_waitcnt lgkmcnt(0)
	v_mfma_f32_16x16x32_bf16 v[120:123], v[140:143], v[156:159], v[120:123]
	v_mfma_f32_16x16x32_bf16 v[124:127], v[148:151], v[156:159], v[124:127]
	v_mfma_f32_16x16x32_bf16 v[104:107], v[140:143], v[164:167], v[104:107]
	v_mfma_f32_16x16x32_bf16 v[108:111], v[148:151], v[164:167], v[108:111]
	v_mfma_f32_16x16x32_bf16 v[88:91], v[140:143], v[172:175], v[88:91]
	v_mfma_f32_16x16x32_bf16 v[92:95], v[148:151], v[172:175], v[92:95]
	v_mfma_f32_16x16x32_bf16 v[72:75], v[140:143], v[198:201], v[72:75]
	v_mfma_f32_16x16x32_bf16 v[76:79], v[148:151], v[198:201], v[76:79]
	v_mfma_f32_16x16x32_bf16 v[120:123], v[144:147], v[160:163], v[120:123]
	v_mfma_f32_16x16x32_bf16 v[124:127], v[152:155], v[160:163], v[124:127]
	v_mfma_f32_16x16x32_bf16 v[104:107], v[144:147], v[168:171], v[104:107]
	v_mfma_f32_16x16x32_bf16 v[108:111], v[152:155], v[168:171], v[108:111]
	v_mfma_f32_16x16x32_bf16 v[88:91], v[144:147], v[194:197], v[88:91]
	v_mfma_f32_16x16x32_bf16 v[92:95], v[152:155], v[194:197], v[92:95]
	v_mfma_f32_16x16x32_bf16 v[72:75], v[144:147], v[202:205], v[72:75]
	v_mfma_f32_16x16x32_bf16 v[76:79], v[152:155], v[202:205], v[76:79]
	s_barrier
	s_add_i32 s54, 0, 0x1c000
	s_add_i32 s14, s14, s58
	v_add_u32_e32 v227, s54, v137
	v_lshl_add_u64 v[134:135], v[134:135], 0, s[34:35]
	s_mov_b32 m0, s14
	ds_read_b128 v[206:209], v227
	ds_read_b128 v[220:223], v227 offset:1024
	ds_read_b128 v[228:231], v227 offset:2048
	ds_read_b128 v[232:235], v227 offset:3072
	global_load_lds_dwordx4 v[134:135], off
	v_lshl_add_u64 v[134:135], v[210:211], 0, s[34:35]
	s_add_i32 m0, s14, 0x2000
	s_nop 0
	global_load_lds_dwordx4 v[134:135], off
	s_barrier
	s_waitcnt lgkmcnt(0)
	v_mfma_f32_16x16x32_bf16 v[112:115], v[206:209], v[156:159], v[112:115]
	v_mfma_f32_16x16x32_bf16 v[116:119], v[228:231], v[156:159], v[116:119]
	v_mfma_f32_16x16x32_bf16 v[96:99], v[206:209], v[164:167], v[96:99]
	v_mfma_f32_16x16x32_bf16 v[100:103], v[228:231], v[164:167], v[100:103]
	v_mfma_f32_16x16x32_bf16 v[80:83], v[206:209], v[172:175], v[80:83]
	v_mfma_f32_16x16x32_bf16 v[84:87], v[228:231], v[172:175], v[84:87]
	v_mfma_f32_16x16x32_bf16 v[64:67], v[206:209], v[198:201], v[64:67]
	v_mfma_f32_16x16x32_bf16 v[68:71], v[228:231], v[198:201], v[68:71]
	v_mfma_f32_16x16x32_bf16 v[112:115], v[220:223], v[160:163], v[112:115]
	v_mfma_f32_16x16x32_bf16 v[116:119], v[232:235], v[160:163], v[116:119]
	v_mfma_f32_16x16x32_bf16 v[96:99], v[220:223], v[168:171], v[96:99]
	v_mfma_f32_16x16x32_bf16 v[100:103], v[232:235], v[168:171], v[100:103]
	v_mfma_f32_16x16x32_bf16 v[80:83], v[220:223], v[194:197], v[80:83]
	v_mfma_f32_16x16x32_bf16 v[84:87], v[232:235], v[194:197], v[84:87]
	v_mfma_f32_16x16x32_bf16 v[64:67], v[220:223], v[202:205], v[64:67]
	v_mfma_f32_16x16x32_bf16 v[68:71], v[232:235], v[202:205], v[68:71]
	s_barrier
	s_mov_b32 m0, s61
	v_lshl_add_u64 v[134:135], v[236:237], 0, s[34:35]
	ds_read_b128 v[156:159], v139 offset:49152
	ds_read_b128 v[160:163], v139 offset:50176
	ds_read_b128 v[164:167], v139 offset:51200
	ds_read_b128 v[168:171], v139 offset:52224
	ds_read_b128 v[172:175], v139 offset:53248
	ds_read_b128 v[194:197], v139 offset:54272
	ds_read_b128 v[198:201], v139 offset:55296
	ds_read_b128 v[202:205], v139 offset:56320
	global_load_lds_dwordx4 v[134:135], off
	v_lshl_add_u64 v[134:135], v[238:239], 0, s[34:35]
	s_mov_b32 m0, s62
	s_nop 0
	global_load_lds_dwordx4 v[134:135], off
	s_barrier
; #define PG8_STAGE(bufoff, gbase, voff) do { _Pragma("unroll") for (int _i = 0; _i < 2; ++_i) \
;         __builtin_amdgcn_global_load_lds((const unsigned*)((const char*)(gbase) + (voff)[_i]), (LAS unsigned*)(lds + (bufoff) + ldsw + _i * 8192), 16, 0, 0); } while (0)
; #define PG8_LDA(dst, b, h) do { _Pragma("unroll") for (int m = 0; m < 4; ++m) _Pragma("unroll") for (int k = 0; k < 2; ++k) dst[m][k] = *(const LAS bf16x8*)(lds + PG8_SA(b, h) + aoff + m * 2048 + k * 1024); } while (0)
; #define PG8_LDB(dst, b, h) do { _Pragma("unroll") for (int n = 0; n < 2; ++n) _Pragma("unroll") for (int k = 0; k < 2; ++k) dst[n][k] = *(const LAS bf16x8*)(lds + PG8_SB(b, h) + boff + n * 2048 + k * 1024); } while (0)
; #define PG8_WAIT_V(n) asm volatile("s_waitcnt vmcnt(" #n ")" ::: "memory")
; #define PG8_WAIT_L(n) asm volatile("s_waitcnt lgkmcnt(" #n ")" ::: "memory")
; #define PG8_BAR __builtin_amdgcn_s_barrier()
; #define PG8_SCHED __builtin_amdgcn_sched_barrier(0)
; template <class Epi>
; __device__ __forceinline__ void gemm_phase(LAS unsigned char* lds, const Gemm g, const StaticOrder S, const Epi E) {
;     ...
;         for (int t = 0; t < nt; t += 2) {
;             const bool last = (t == nt - 2);
;             const char* a1 = cA + (size_t)(t + 1) * kstep;
;             const char* a2 = last ? nA : cA + (size_t)(t + 2) * kstep; const char* b2 = last ? nB : cB + (size_t)(t + 2) * kstep;
;             const char* a3 = a2 + kstep; const char* b3 = b2 + kstep;
;             PG8_LDB(B0, 0, 0); PG8_SCHED; PG8_LDA(At, 0, 0); PG8_STAGE(PG8_SA(1, 1), a1 + hstep, voffA);
;             PG8_WAIT_L(8); PG8_BAR; PG8_WAIT_L(0); PG8_MMA(0, 0, At, B0); PG8_BAR; PG8_SCHED;
;             PG8_LDB(B1, 0, 1); PG8_STAGE(PG8_SB(0, 0), b2, voffA);
;             PG8_BAR; PG8_WAIT_L(0); PG8_MMA(0, 1, At, B1); PG8_BAR;
;             PG8_LDA(At, 0, 1); PG8_STAGE(PG8_SA(0, 0), a2, voffA);
;             PG8_BAR; PG8_WAIT_L(0); PG8_MMA(1, 0, At, B0); PG8_BAR; PG8_SCHED;
;             PG8_STAGE(PG8_SB(0, 1), b2 + hstep, voffA);
;             PG8_WAIT_V(6); PG8_BAR; PG8_MMA(1, 1, At, B1); PG8_BAR;
;     ...
;             PG8_LDA(At, 1, 1); PG8_STAGE(PG8_SA(1, 0), a3, voffA);
;             PG8_BAR; PG8_WAIT_L(0); PG8_MMA(1, 0, At, B0); PG8_BAR; PG8_SCHED;
;             PG8_STAGE(PG8_SB(1, 1), b3 + hstep, voffA);
;             PG8_WAIT_V(6); PG8_BAR; PG8_MMA(1, 1, At, B1); PG8_BAR;
	s_waitcnt lgkmcnt(0)
	v_mfma_f32_16x16x32_bf16 v[56:59], v[140:143], v[156:159], v[56:59]
	v_mfma_f32_16x16x32_bf16 v[60:63], v[148:151], v[156:159], v[60:63]
	v_mfma_f32_16x16x32_bf16 v[40:43], v[140:143], v[164:167], v[40:43]
	v_mfma_f32_16x16x32_bf16 v[44:47], v[148:151], v[164:167], v[44:47]
	v_mfma_f32_16x16x32_bf16 v[24:27], v[140:143], v[172:175], v[24:27]
	v_mfma_f32_16x16x32_bf16 v[28:31], v[148:151], v[172:175], v[28:31]
	v_mfma_f32_16x16x32_bf16 v[8:11], v[140:143], v[198:201], v[8:11]
	v_mfma_f32_16x16x32_bf16 v[12:15], v[148:151], v[198:201], v[12:15]
	v_mfma_f32_16x16x32_bf16 v[56:59], v[144:147], v[160:163], v[56:59]
	v_mfma_f32_16x16x32_bf16 v[60:63], v[152:155], v[160:163], v[60:63]
	v_mfma_f32_16x16x32_bf16 v[40:43], v[144:147], v[168:171], v[40:43]
	v_mfma_f32_16x16x32_bf16 v[44:47], v[152:155], v[168:171], v[44:47]
	v_mfma_f32_16x16x32_bf16 v[24:27], v[144:147], v[194:197], v[24:27]
	v_mfma_f32_16x16x32_bf16 v[28:31], v[152:155], v[194:197], v[28:31]
	v_mfma_f32_16x16x32_bf16 v[8:11], v[144:147], v[202:205], v[8:11]
	v_mfma_f32_16x16x32_bf16 v[12:15], v[152:155], v[202:205], v[12:15]
	s_barrier
	s_add_u32 s30, s52, 0x80080
	s_addc_u32 s31, s53, 0
	s_add_i32 s14, s54, s58
	v_lshl_add_u64 v[134:135], s[30:31], 0, v[178:179]
	s_mov_b32 m0, s14
	s_nop 0
	global_load_lds_dwordx4 v[134:135], off
	v_lshl_add_u64 v[134:135], s[30:31], 0, v[128:129]
	s_add_i32 m0, s14, 0x2000
	s_nop 0
	global_load_lds_dwordx4 v[134:135], off
	s_waitcnt vmcnt(6)
	s_barrier
	v_mfma_f32_16x16x32_bf16 v[48:51], v[206:209], v[156:159], v[48:51]
	v_mfma_f32_16x16x32_bf16 v[52:55], v[228:231], v[156:159], v[52:55]
	v_mfma_f32_16x16x32_bf16 v[32:35], v[206:209], v[164:167], v[32:35]
	v_mfma_f32_16x16x32_bf16 v[36:39], v[228:231], v[164:167], v[36:39]
	v_mfma_f32_16x16x32_bf16 v[16:19], v[206:209], v[172:175], v[16:19]
	v_mfma_f32_16x16x32_bf16 v[20:23], v[228:231], v[172:175], v[20:23]
	v_mfma_f32_16x16x32_bf16 v[0:3], v[206:209], v[198:201], v[0:3]
	v_mfma_f32_16x16x32_bf16 v[4:7], v[228:231], v[198:201], v[4:7]
	v_mfma_f32_16x16x32_bf16 v[48:51], v[220:223], v[160:163], v[48:51]
	v_mfma_f32_16x16x32_bf16 v[52:55], v[232:235], v[160:163], v[52:55]
	v_mfma_f32_16x16x32_bf16 v[32:35], v[220:223], v[168:171], v[32:35]
	v_mfma_f32_16x16x32_bf16 v[36:39], v[232:235], v[168:171], v[36:39]
	v_mfma_f32_16x16x32_bf16 v[16:19], v[220:223], v[194:197], v[16:19]
	v_mfma_f32_16x16x32_bf16 v[20:23], v[232:235], v[194:197], v[20:23]
	v_mfma_f32_16x16x32_bf16 v[0:3], v[220:223], v[202:205], v[0:3]
	v_mfma_f32_16x16x32_bf16 v[4:7], v[232:235], v[202:205], v[4:7]
	s_barrier
	s_add_i32 s64, s64, 2
	s_add_u32 s50, s50, 0x100
	s_addc_u32 s51, s51, 0
	s_add_u32 s28, s28, 0x100
	s_addc_u32 s29, s29, 0
	s_cmp_gt_u32 s64, 29
	s_cbranch_scc0 .LBB0_3723
	s_branch .Lpeel_exit_6
.LBB0_3723:
	s_add_u32 s14, s50, 0xfff80080
	s_addc_u32 s30, s51, -1
	s_add_i32 s31, 0, 0x10000
	v_add_u32_e32 v134, s31, v137
	ds_read_b128 v[140:143], v134
	ds_read_b128 v[144:147], v134 offset:1024
	ds_read_b128 v[148:151], v134 offset:2048
	ds_read_b128 v[152:155], v134 offset:3072
	s_cmp_eq_u32 s64, 28
	s_cselect_b32 s55, s3, s30
	s_cselect_b32 s54, s26, s14
	s_cselect_b32 s53, s1, s29
	s_cselect_b32 s52, s27, s28
	v_lshl_add_u64 v[134:135], s[50:51], 0, v[130:131]
	s_add_i32 m0, s47, 0xc000
	ds_read_b128 v[156:159], v139
	ds_read_b128 v[160:163], v139 offset:1024
	ds_read_b128 v[164:167], v139 offset:2048
	ds_read_b128 v[168:171], v139 offset:3072
	ds_read_b128 v[172:175], v139 offset:4096
	ds_read_b128 v[194:197], v139 offset:5120
	ds_read_b128 v[198:201], v139 offset:6144
	ds_read_b128 v[202:205], v139 offset:7168
	global_load_lds_dwordx4 v[134:135], off
	v_lshl_add_u64 v[134:135], s[50:51], 0, v[132:133]
	s_add_i32 m0, s47, 0xe000
	s_nop 0
	global_load_lds_dwordx4 v[134:135], off
	s_waitcnt lgkmcnt(8)
	s_barrier
	s_waitcnt lgkmcnt(0)
	v_mfma_f32_16x16x32_bf16 v[120:123], v[140:143], v[156:159], v[120:123]
	v_mfma_f32_16x16x32_bf16 v[124:127], v[148:151], v[156:159], v[124:127]
	v_mfma_f32_16x16x32_bf16 v[104:107], v[140:143], v[164:167], v[104:107]
	v_mfma_f32_16x16x32_bf16 v[108:111], v[148:151], v[164:167], v[108:111]
	v_mfma_f32_16x16x32_bf16 v[88:91], v[140:143], v[172:175], v[88:91]
	v_mfma_f32_16x16x32_bf16 v[92:95], v[148:151], v[172:175], v[92:95]
	v_mfma_f32_16x16x32_bf16 v[72:75], v[140:143], v[198:201], v[72:75]
	v_mfma_f32_16x16x32_bf16 v[76:79], v[148:151], v[198:201], v[76:79]
	v_mfma_f32_16x16x32_bf16 v[120:123], v[144:147], v[160:163], v[120:123]
	v_mfma_f32_16x16x32_bf16 v[124:127], v[152:155], v[160:163], v[124:127]
	v_mfma_f32_16x16x32_bf16 v[104:107], v[144:147], v[168:171], v[104:107]
	v_mfma_f32_16x16x32_bf16 v[108:111], v[152:155], v[168:171], v[108:111]
	v_mfma_f32_16x16x32_bf16 v[88:91], v[144:147], v[194:197], v[88:91]
	v_mfma_f32_16x16x32_bf16 v[92:95], v[152:155], v[194:197], v[92:95]
	v_mfma_f32_16x16x32_bf16 v[72:75], v[144:147], v[202:205], v[72:75]
	v_mfma_f32_16x16x32_bf16 v[76:79], v[152:155], v[202:205], v[76:79]
	s_barrier
	s_add_i32 s14, 0, 0x14000
	v_add_u32_e32 v134, s14, v137
	s_add_i32 s30, s31, s58
	ds_read_b128 v[206:209], v134
	ds_read_b128 v[220:223], v134 offset:1024
	ds_read_b128 v[228:231], v134 offset:2048
	ds_read_b128 v[232:235], v134 offset:3072
	v_lshl_add_u64 v[134:135], s[52:53], 0, v[178:179]
	s_mov_b32 m0, s30
	v_lshl_add_u64 v[210:211], s[52:53], 0, v[128:129]
	global_load_lds_dwordx4 v[134:135], off
	s_add_i32 m0, s30, 0x2000
	s_nop 0
	global_load_lds_dwordx4 v[210:211], off
	s_barrier
; #define PG8_STAGE(bufoff, gbase, voff) do { _Pragma("unroll") for (int _i = 0; _i < 2; ++_i) \
;         __builtin_amdgcn_global_load_lds((const unsigned*)((const char*)(gbase) + (voff)[_i]), (LAS unsigned*)(lds + (bufoff) + ldsw + _i * 8192), 16, 0, 0); } while (0)
; #define PG8_LDA(dst, b, h) do { _Pragma("unroll") for (int m = 0; m < 4; ++m) _Pragma("unroll") for (int k = 0; k < 2; ++k) dst[m][k] = *(const LAS bf16x8*)(lds + PG8_SA(b, h) + aoff + m * 2048 + k * 1024); } while (0)
; #define PG8_LDB(dst, b, h) do { _Pragma("unroll") for (int n = 0; n < 2; ++n) _Pragma("unroll") for (int k = 0; k < 2; ++k) dst[n][k] = *(const LAS bf16x8*)(lds + PG8_SB(b, h) + boff + n * 2048 + k * 1024); } while (0)
; #define PG8_MMA(ai, bj, At, Bt) do { __builtin_amdgcn_s_setprio(1); _Pragma("unroll") for (int m = 0; m < 4; ++m) _Pragma("unroll") for (int n = 0; n < 2; ++n) _Pragma("unroll") for (int k = 0; k < 2; ++k) \
;         acc[ai][bj][m][n] = __builtin_amdgcn_mfma_f32_16x16x32_bf16(Bt[n][k], At[m][k], acc[ai][bj][m][n], 0, 0, 0); __builtin_amdgcn_s_setprio(0); } while (0)
; #define PG8_WAIT_V(n) asm volatile("s_waitcnt vmcnt(" #n ")" ::: "memory")
; #define PG8_WAIT_L(n) asm volatile("s_waitcnt lgkmcnt(" #n ")" ::: "memory")
; #define PG8_BAR __builtin_amdgcn_s_barrier()
; #define PG8_SCHED __builtin_amdgcn_sched_barrier(0)
; template <class Epi>
; __device__ __forceinline__ void gemm_phase(LAS unsigned char* lds, const Gemm g, const StaticOrder S, const Epi E) {
;     ...
;             PG8_LDB(B1, 0, 1); PG8_STAGE(PG8_SB(0, 0), b2, voffA);
;             PG8_BAR; PG8_WAIT_L(0); PG8_MMA(0, 1, At, B1); PG8_BAR;
;             PG8_LDA(At, 0, 1); PG8_STAGE(PG8_SA(0, 0), a2, voffA);
;             PG8_BAR; PG8_WAIT_L(0); PG8_MMA(1, 0, At, B0); PG8_BAR; PG8_SCHED;
;             PG8_STAGE(PG8_SB(0, 1), b2 + hstep, voffA);
;             PG8_WAIT_V(6); PG8_BAR; PG8_MMA(1, 1, At, B1); PG8_BAR;
;             PG8_LDB(B0, 1, 0); PG8_SCHED; PG8_LDA(At, 1, 0); PG8_STAGE(PG8_SA(0, 1), a2 + hstep, voffA);
;             PG8_WAIT_L(8); PG8_BAR; PG8_WAIT_L(0); PG8_MMA(0, 0, At, B0); PG8_BAR; PG8_SCHED;
;             PG8_LDB(B1, 1, 1); PG8_STAGE(PG8_SB(1, 0), b3, voffA);
	s_waitcnt lgkmcnt(0)
	v_mfma_f32_16x16x32_bf16 v[112:115], v[206:209], v[156:159], v[112:115]
	v_mfma_f32_16x16x32_bf16 v[116:119], v[228:231], v[156:159], v[116:119]
	v_mfma_f32_16x16x32_bf16 v[96:99], v[206:209], v[164:167], v[96:99]
	v_mfma_f32_16x16x32_bf16 v[100:103], v[228:231], v[164:167], v[100:103]
	v_mfma_f32_16x16x32_bf16 v[80:83], v[206:209], v[172:175], v[80:83]
	v_mfma_f32_16x16x32_bf16 v[84:87], v[228:231], v[172:175], v[84:87]
	v_mfma_f32_16x16x32_bf16 v[64:67], v[206:209], v[198:201], v[64:67]
	v_mfma_f32_16x16x32_bf16 v[68:71], v[228:231], v[198:201], v[68:71]
	v_mfma_f32_16x16x32_bf16 v[112:115], v[220:223], v[160:163], v[112:115]
	v_mfma_f32_16x16x32_bf16 v[116:119], v[232:235], v[160:163], v[116:119]
	v_mfma_f32_16x16x32_bf16 v[96:99], v[220:223], v[168:171], v[96:99]
	v_mfma_f32_16x16x32_bf16 v[100:103], v[232:235], v[168:171], v[100:103]
	v_mfma_f32_16x16x32_bf16 v[80:83], v[220:223], v[194:197], v[80:83]
	v_mfma_f32_16x16x32_bf16 v[84:87], v[232:235], v[194:197], v[84:87]
	v_mfma_f32_16x16x32_bf16 v[64:67], v[220:223], v[202:205], v[64:67]
	v_mfma_f32_16x16x32_bf16 v[68:71], v[232:235], v[202:205], v[68:71]
	s_barrier
	s_mov_b32 m0, s47
	v_lshl_add_u64 v[236:237], s[54:55], 0, v[178:179]
	ds_read_b128 v[156:159], v139 offset:16384
	ds_read_b128 v[160:163], v139 offset:17408
	ds_read_b128 v[164:167], v139 offset:18432
	ds_read_b128 v[168:171], v139 offset:19456
	ds_read_b128 v[172:175], v139 offset:20480
	ds_read_b128 v[194:197], v139 offset:21504
	ds_read_b128 v[198:201], v139 offset:22528
	ds_read_b128 v[202:205], v139 offset:23552
	global_load_lds_dwordx4 v[236:237], off
	v_lshl_add_u64 v[238:239], s[54:55], 0, v[128:129]
	s_mov_b32 m0, s49
	s_nop 0
	global_load_lds_dwordx4 v[238:239], off
	s_barrier
	s_waitcnt lgkmcnt(0)
	v_mfma_f32_16x16x32_bf16 v[56:59], v[140:143], v[156:159], v[56:59]
	v_mfma_f32_16x16x32_bf16 v[60:63], v[148:151], v[156:159], v[60:63]
	v_mfma_f32_16x16x32_bf16 v[40:43], v[140:143], v[164:167], v[40:43]
	v_mfma_f32_16x16x32_bf16 v[44:47], v[148:151], v[164:167], v[44:47]
	v_mfma_f32_16x16x32_bf16 v[24:27], v[140:143], v[172:175], v[24:27]
	v_mfma_f32_16x16x32_bf16 v[28:31], v[148:151], v[172:175], v[28:31]
	v_mfma_f32_16x16x32_bf16 v[8:11], v[140:143], v[198:201], v[8:11]
	v_mfma_f32_16x16x32_bf16 v[12:15], v[148:151], v[198:201], v[12:15]
	v_mfma_f32_16x16x32_bf16 v[56:59], v[144:147], v[160:163], v[56:59]
	v_mfma_f32_16x16x32_bf16 v[60:63], v[152:155], v[160:163], v[60:63]
	v_mfma_f32_16x16x32_bf16 v[40:43], v[144:147], v[168:171], v[40:43]
	v_mfma_f32_16x16x32_bf16 v[44:47], v[152:155], v[168:171], v[44:47]
	v_mfma_f32_16x16x32_bf16 v[24:27], v[144:147], v[194:197], v[24:27]
	v_mfma_f32_16x16x32_bf16 v[28:31], v[152:155], v[194:197], v[28:31]
	v_mfma_f32_16x16x32_bf16 v[8:11], v[144:147], v[202:205], v[8:11]
	v_mfma_f32_16x16x32_bf16 v[12:15], v[152:155], v[202:205], v[12:15]
	s_barrier
	s_add_u32 s30, s52, 0x80000
	s_addc_u32 s31, s53, 0
	s_add_i32 s14, s14, s58
	v_lshl_add_u64 v[140:141], s[30:31], 0, v[178:179]
	s_mov_b32 m0, s14
	s_nop 0
	global_load_lds_dwordx4 v[140:141], off
	v_lshl_add_u64 v[140:141], s[30:31], 0, v[128:129]
	s_add_i32 m0, s14, 0x2000
	s_nop 0
	global_load_lds_dwordx4 v[140:141], off
	s_waitcnt vmcnt(6)
	s_barrier
	v_mfma_f32_16x16x32_bf16 v[48:51], v[206:209], v[156:159], v[48:51]
	v_mfma_f32_16x16x32_bf16 v[52:55], v[228:231], v[156:159], v[52:55]
	v_mfma_f32_16x16x32_bf16 v[32:35], v[206:209], v[164:167], v[32:35]
	v_mfma_f32_16x16x32_bf16 v[36:39], v[228:231], v[164:167], v[36:39]
	v_mfma_f32_16x16x32_bf16 v[16:19], v[206:209], v[172:175], v[16:19]
	v_mfma_f32_16x16x32_bf16 v[20:23], v[228:231], v[172:175], v[20:23]
	v_mfma_f32_16x16x32_bf16 v[0:3], v[206:209], v[198:201], v[0:3]
	v_mfma_f32_16x16x32_bf16 v[4:7], v[228:231], v[198:201], v[4:7]
	v_mfma_f32_16x16x32_bf16 v[48:51], v[220:223], v[160:163], v[48:51]
	v_mfma_f32_16x16x32_bf16 v[52:55], v[232:235], v[160:163], v[52:55]
	v_mfma_f32_16x16x32_bf16 v[32:35], v[220:223], v[168:171], v[32:35]
	v_mfma_f32_16x16x32_bf16 v[36:39], v[232:235], v[168:171], v[36:39]
	v_mfma_f32_16x16x32_bf16 v[16:19], v[220:223], v[194:197], v[16:19]
	v_mfma_f32_16x16x32_bf16 v[20:23], v[232:235], v[194:197], v[20:23]
	v_mfma_f32_16x16x32_bf16 v[0:3], v[220:223], v[202:205], v[0:3]
	v_mfma_f32_16x16x32_bf16 v[4:7], v[232:235], v[202:205], v[4:7]
	s_barrier
	s_add_i32 s14, 0, 0x18000
	v_add_u32_e32 v152, s14, v137
	ds_read_b128 v[140:143], v152
	ds_read_b128 v[144:147], v152 offset:1024
	ds_read_b128 v[148:151], v152 offset:2048
	ds_read_b128 v[152:155], v152 offset:3072
	s_add_u32 s30, s54, 0x80000
	s_addc_u32 s31, s55, 0
	s_mov_b32 m0, s59
	v_lshl_add_u64 v[206:207], s[30:31], 0, v[178:179]
	ds_read_b128 v[156:159], v139 offset:32768
	ds_read_b128 v[160:163], v139 offset:33792
	ds_read_b128 v[164:167], v139 offset:34816
	ds_read_b128 v[168:171], v139 offset:35840
	ds_read_b128 v[172:175], v139 offset:36864
	ds_read_b128 v[194:197], v139 offset:37888
	ds_read_b128 v[198:201], v139 offset:38912
	ds_read_b128 v[202:205], v139 offset:39936
	global_load_lds_dwordx4 v[206:207], off
	v_lshl_add_u64 v[206:207], s[30:31], 0, v[128:129]
	s_mov_b32 m0, s60
	s_nop 0
	global_load_lds_dwordx4 v[206:207], off
	s_waitcnt lgkmcnt(8)
	s_barrier
; #define PG8_STAGE(bufoff, gbase, voff) do { _Pragma("unroll") for (int _i = 0; _i < 2; ++_i) \
;         __builtin_amdgcn_global_load_lds((const unsigned*)((const char*)(gbase) + (voff)[_i]), (LAS unsigned*)(lds + (bufoff) + ldsw + _i * 8192), 16, 0, 0); } while (0)
; #define PG8_LDA(dst, b, h) do { _Pragma("unroll") for (int m = 0; m < 4; ++m) _Pragma("unroll") for (int k = 0; k < 2; ++k) dst[m][k] = *(const LAS bf16x8*)(lds + PG8_SA(b, h) + aoff + m * 2048 + k * 1024); } while (0)
; #define PG8_MMA(ai, bj, At, Bt) do { __builtin_amdgcn_s_setprio(1); _Pragma("unroll") for (int m = 0; m < 4; ++m) _Pragma("unroll") for (int n = 0; n < 2; ++n) _Pragma("unroll") for (int k = 0; k < 2; ++k) \
;         acc[ai][bj][m][n] = __builtin_amdgcn_mfma_f32_16x16x32_bf16(Bt[n][k], At[m][k], acc[ai][bj][m][n], 0, 0, 0); __builtin_amdgcn_s_setprio(0); } while (0)
; #define PG8_WAIT_V(n) asm volatile("s_waitcnt vmcnt(" #n ")" ::: "memory")
; #define PG8_WAIT_L(n) asm volatile("s_waitcnt lgkmcnt(" #n ")" ::: "memory")
; #define PG8_BAR __builtin_amdgcn_s_barrier()
; #define PG8_SCHED __builtin_amdgcn_sched_barrier(0)
; template <class Epi>
; __device__ __forceinline__ void gemm_phase(LAS unsigned char* lds, const Gemm g, const StaticOrder S, const Epi E) {
;     ...
;             PG8_LDA(At, 1, 1); PG8_STAGE(PG8_SA(1, 0), a3, voffA);
;             PG8_BAR; PG8_WAIT_L(0); PG8_MMA(1, 0, At, B0); PG8_BAR; PG8_SCHED;
;             PG8_STAGE(PG8_SB(1, 1), b3 + hstep, voffA);
;             PG8_WAIT_V(6); PG8_BAR; PG8_MMA(1, 1, At, B1); PG8_BAR;
	s_waitcnt lgkmcnt(0)
	v_mfma_f32_16x16x32_bf16 v[120:123], v[140:143], v[156:159], v[120:123]
	v_mfma_f32_16x16x32_bf16 v[124:127], v[148:151], v[156:159], v[124:127]
	v_mfma_f32_16x16x32_bf16 v[104:107], v[140:143], v[164:167], v[104:107]
	v_mfma_f32_16x16x32_bf16 v[108:111], v[148:151], v[164:167], v[108:111]
	v_mfma_f32_16x16x32_bf16 v[88:91], v[140:143], v[172:175], v[88:91]
	v_mfma_f32_16x16x32_bf16 v[92:95], v[148:151], v[172:175], v[92:95]
	v_mfma_f32_16x16x32_bf16 v[72:75], v[140:143], v[198:201], v[72:75]
	v_mfma_f32_16x16x32_bf16 v[76:79], v[148:151], v[198:201], v[76:79]
	v_mfma_f32_16x16x32_bf16 v[120:123], v[144:147], v[160:163], v[120:123]
	v_mfma_f32_16x16x32_bf16 v[124:127], v[152:155], v[160:163], v[124:127]
	v_mfma_f32_16x16x32_bf16 v[104:107], v[144:147], v[168:171], v[104:107]
	v_mfma_f32_16x16x32_bf16 v[108:111], v[152:155], v[168:171], v[108:111]
	v_mfma_f32_16x16x32_bf16 v[88:91], v[144:147], v[194:197], v[88:91]
	v_mfma_f32_16x16x32_bf16 v[92:95], v[152:155], v[194:197], v[92:95]
	v_mfma_f32_16x16x32_bf16 v[72:75], v[144:147], v[202:205], v[72:75]
	v_mfma_f32_16x16x32_bf16 v[76:79], v[152:155], v[202:205], v[76:79]
	s_barrier
	s_add_i32 s54, 0, 0x1c000
	s_add_i32 s14, s14, s58
	v_add_u32_e32 v227, s54, v137
	v_lshl_add_u64 v[134:135], v[134:135], 0, s[34:35]
	s_mov_b32 m0, s14
	ds_read_b128 v[206:209], v227
	ds_read_b128 v[220:223], v227 offset:1024
	ds_read_b128 v[228:231], v227 offset:2048
	ds_read_b128 v[232:235], v227 offset:3072
	global_load_lds_dwordx4 v[134:135], off
	v_lshl_add_u64 v[134:135], v[210:211], 0, s[34:35]
	s_add_i32 m0, s14, 0x2000
	s_nop 0
	global_load_lds_dwordx4 v[134:135], off
	s_barrier
	s_waitcnt lgkmcnt(0)
	v_mfma_f32_16x16x32_bf16 v[112:115], v[206:209], v[156:159], v[112:115]
	v_mfma_f32_16x16x32_bf16 v[116:119], v[228:231], v[156:159], v[116:119]
	v_mfma_f32_16x16x32_bf16 v[96:99], v[206:209], v[164:167], v[96:99]
	v_mfma_f32_16x16x32_bf16 v[100:103], v[228:231], v[164:167], v[100:103]
	v_mfma_f32_16x16x32_bf16 v[80:83], v[206:209], v[172:175], v[80:83]
	v_mfma_f32_16x16x32_bf16 v[84:87], v[228:231], v[172:175], v[84:87]
	v_mfma_f32_16x16x32_bf16 v[64:67], v[206:209], v[198:201], v[64:67]
	v_mfma_f32_16x16x32_bf16 v[68:71], v[228:231], v[198:201], v[68:71]
	v_mfma_f32_16x16x32_bf16 v[112:115], v[220:223], v[160:163], v[112:115]
	v_mfma_f32_16x16x32_bf16 v[116:119], v[232:235], v[160:163], v[116:119]
	v_mfma_f32_16x16x32_bf16 v[96:99], v[220:223], v[168:171], v[96:99]
	v_mfma_f32_16x16x32_bf16 v[100:103], v[232:235], v[168:171], v[100:103]
	v_mfma_f32_16x16x32_bf16 v[80:83], v[220:223], v[194:197], v[80:83]
	v_mfma_f32_16x16x32_bf16 v[84:87], v[232:235], v[194:197], v[84:87]
	v_mfma_f32_16x16x32_bf16 v[64:67], v[220:223], v[202:205], v[64:67]
	v_mfma_f32_16x16x32_bf16 v[68:71], v[232:235], v[202:205], v[68:71]
	s_barrier
	s_mov_b32 m0, s61
	v_lshl_add_u64 v[134:135], v[236:237], 0, s[34:35]
	ds_read_b128 v[156:159], v139 offset:49152
	ds_read_b128 v[160:163], v139 offset:50176
	ds_read_b128 v[164:167], v139 offset:51200
	ds_read_b128 v[168:171], v139 offset:52224
	ds_read_b128 v[172:175], v139 offset:53248
	ds_read_b128 v[194:197], v139 offset:54272
	ds_read_b128 v[198:201], v139 offset:55296
	ds_read_b128 v[202:205], v139 offset:56320
	global_load_lds_dwordx4 v[134:135], off
	v_lshl_add_u64 v[134:135], v[238:239], 0, s[34:35]
	s_mov_b32 m0, s62
	s_nop 0
	global_load_lds_dwordx4 v[134:135], off
	s_barrier
	s_waitcnt lgkmcnt(0)
	v_mfma_f32_16x16x32_bf16 v[56:59], v[140:143], v[156:159], v[56:59]
	v_mfma_f32_16x16x32_bf16 v[60:63], v[148:151], v[156:159], v[60:63]
	v_mfma_f32_16x16x32_bf16 v[40:43], v[140:143], v[164:167], v[40:43]
	v_mfma_f32_16x16x32_bf16 v[44:47], v[148:151], v[164:167], v[44:47]
	v_mfma_f32_16x16x32_bf16 v[24:27], v[140:143], v[172:175], v[24:27]
	v_mfma_f32_16x16x32_bf16 v[28:31], v[148:151], v[172:175], v[28:31]
	v_mfma_f32_16x16x32_bf16 v[8:11], v[140:143], v[198:201], v[8:11]
	v_mfma_f32_16x16x32_bf16 v[12:15], v[148:151], v[198:201], v[12:15]
	v_mfma_f32_16x16x32_bf16 v[56:59], v[144:147], v[160:163], v[56:59]
	v_mfma_f32_16x16x32_bf16 v[60:63], v[152:155], v[160:163], v[60:63]
	v_mfma_f32_16x16x32_bf16 v[40:43], v[144:147], v[168:171], v[40:43]
	v_mfma_f32_16x16x32_bf16 v[44:47], v[152:155], v[168:171], v[44:47]
	v_mfma_f32_16x16x32_bf16 v[24:27], v[144:147], v[194:197], v[24:27]
	v_mfma_f32_16x16x32_bf16 v[28:31], v[152:155], v[194:197], v[28:31]
	v_mfma_f32_16x16x32_bf16 v[8:11], v[144:147], v[202:205], v[8:11]
	v_mfma_f32_16x16x32_bf16 v[12:15], v[152:155], v[202:205], v[12:15]
	s_barrier
	s_add_u32 s30, s52, 0x80080
	s_addc_u32 s31, s53, 0
	s_add_i32 s14, s54, s58
	v_lshl_add_u64 v[134:135], s[30:31], 0, v[178:179]
	s_mov_b32 m0, s14
	s_nop 0
	global_load_lds_dwordx4 v[134:135], off
	v_lshl_add_u64 v[134:135], s[30:31], 0, v[128:129]
	s_add_i32 m0, s14, 0x2000
	s_nop 0
	global_load_lds_dwordx4 v[134:135], off
	s_waitcnt vmcnt(6)
	s_barrier
	v_mfma_f32_16x16x32_bf16 v[48:51], v[206:209], v[156:159], v[48:51]
	v_mfma_f32_16x16x32_bf16 v[52:55], v[228:231], v[156:159], v[52:55]
	v_mfma_f32_16x16x32_bf16 v[32:35], v[206:209], v[164:167], v[32:35]
	v_mfma_f32_16x16x32_bf16 v[36:39], v[228:231], v[164:167], v[36:39]
	v_mfma_f32_16x16x32_bf16 v[16:19], v[206:209], v[172:175], v[16:19]
	v_mfma_f32_16x16x32_bf16 v[20:23], v[228:231], v[172:175], v[20:23]
	v_mfma_f32_16x16x32_bf16 v[0:3], v[206:209], v[198:201], v[0:3]
	v_mfma_f32_16x16x32_bf16 v[4:7], v[228:231], v[198:201], v[4:7]
	v_mfma_f32_16x16x32_bf16 v[48:51], v[220:223], v[160:163], v[48:51]
	v_mfma_f32_16x16x32_bf16 v[52:55], v[232:235], v[160:163], v[52:55]
	v_mfma_f32_16x16x32_bf16 v[32:35], v[220:223], v[168:171], v[32:35]
	v_mfma_f32_16x16x32_bf16 v[36:39], v[232:235], v[168:171], v[36:39]
	v_mfma_f32_16x16x32_bf16 v[16:19], v[220:223], v[194:197], v[16:19]
	v_mfma_f32_16x16x32_bf16 v[20:23], v[232:235], v[194:197], v[20:23]
	v_mfma_f32_16x16x32_bf16 v[0:3], v[220:223], v[202:205], v[0:3]
	v_mfma_f32_16x16x32_bf16 v[4:7], v[232:235], v[202:205], v[4:7]
	s_barrier
	s_add_i32 s64, s64, 2
	s_add_u32 s50, s50, 0x100
	s_addc_u32 s51, s51, 0
	s_add_u32 s28, s28, 0x100
	s_addc_u32 s29, s29, 0
	s_cmp_gt_u32 s64, 29
	s_cbranch_scc0 .LBB0_3723

; #define PG8_STAGE(bufoff, gbase, voff) do { _Pragma("unroll") for (int _i = 0; _i < 2; ++_i) \
;         __builtin_amdgcn_global_load_lds((const unsigned*)((const char*)(gbase) + (voff)[_i]), (LAS unsigned*)(lds + (bufoff) + ldsw + _i * 8192), 16, 0, 0); } while (0)
; #define PG8_LDA(dst, b, h) do { _Pragma("unroll") for (int m = 0; m < 4; ++m) _Pragma("unroll") for (int k = 0; k < 2; ++k) dst[m][k] = *(const LAS bf16x8*)(lds + PG8_SA(b, h) + aoff + m * 2048 + k * 1024); } while (0)
; #define PG8_LDB(dst, b, h) do { _Pragma("unroll") for (int n = 0; n < 2; ++n) _Pragma("unroll") for (int k = 0; k < 2; ++k) dst[n][k] = *(const LAS bf16x8*)(lds + PG8_SB(b, h) + boff + n * 2048 + k * 1024); } while (0)
; #define PG8_WAIT_V(n) asm volatile("s_waitcnt vmcnt(" #n ")" ::: "memory")
; #define PG8_WAIT_L(n) asm volatile("s_waitcnt lgkmcnt(" #n ")" ::: "memory")
; #define PG8_BAR __builtin_amdgcn_s_barrier()
; #define PG8_SCHED __builtin_amdgcn_sched_barrier(0)
; template <class Epi>
; __device__ __forceinline__ void gemm_phase(LAS unsigned char* lds, const Gemm g, const StaticOrder S, const Epi E) {
;     ...
;         const bool has_next = S.next(ui + 1, nxt);
;         const char* nA = has_next ? (const char*)g.A + (size_t)nxt.pm * tstep + (size_t)nxt.k0 * kstep : cA; const char* nB = has_next ? (const char*)g.Bt + (size_t)nxt.pn * tstep + (size_t)nxt.k0 * kstep : cB;
;         const int nt = cur.nk;
;         for (int t = 0; t < nt; t += 2) {
;             const bool last = (t == nt - 2);
;             const char* a1 = cA + (size_t)(t + 1) * kstep;
;             const char* a2 = last ? nA : cA + (size_t)(t + 2) * kstep; const char* b2 = last ? nB : cB + (size_t)(t + 2) * kstep;
;             const char* a3 = a2 + kstep; const char* b3 = b2 + kstep;
;             PG8_LDB(B0, 0, 0); PG8_SCHED; PG8_LDA(At, 0, 0); PG8_STAGE(PG8_SA(1, 1), a1 + hstep, voffA);
;             PG8_WAIT_L(8); PG8_BAR; PG8_WAIT_L(0); PG8_MMA(0, 0, At, B0); PG8_BAR; PG8_SCHED;
;             PG8_LDB(B1, 0, 1); PG8_STAGE(PG8_SB(0, 0), b2, voffA);
;             PG8_BAR; PG8_WAIT_L(0); PG8_MMA(0, 1, At, B1); PG8_BAR;
;             PG8_LDA(At, 0, 1); PG8_STAGE(PG8_SA(0, 0), a2, voffA);
;             PG8_BAR; PG8_WAIT_L(0); PG8_MMA(1, 0, At, B0); PG8_BAR; PG8_SCHED;
;             PG8_STAGE(PG8_SB(0, 1), b2 + hstep, voffA);
;             PG8_WAIT_V(6); PG8_BAR; PG8_MMA(1, 1, At, B1); PG8_BAR;
.LBB0_3918:
	s_add_i32 s43, s67, -2
	s_add_u32 s68, s50, 0x100
	s_addc_u32 s69, s51, 0
	s_mov_b32 s52, 0
	s_add_i32 vcc_lo, s52, 2
	s_add_u32 s50, s38, 0x100
	s_addc_u32 s51, s39, 0
	s_add_i32 s14, 0, 0x10000
	v_add_u32_e32 v140, s14, v228
	ds_read_b128 v[128:131], v140
	ds_read_b128 v[132:135], v140 offset:1024
	ds_read_b128 v[136:139], v140 offset:2048
	ds_read_b128 v[140:143], v140 offset:3072
	s_cmp_eq_u32 s43, s52
	s_cselect_b32 s52, s48, s68
	s_cselect_b32 s55, s45, s51
	s_cselect_b32 s54, s44, s50
	s_cselect_b32 s53, s49, s69
	v_lshl_add_u64 v[200:201], s[38:39], 0, v[196:197]
	s_add_i32 m0, s25, 0xc000
	ds_read_b128 v[144:147], v230
	ds_read_b128 v[148:151], v230 offset:1024
	ds_read_b128 v[152:155], v230 offset:2048
	ds_read_b128 v[156:159], v230 offset:3072
	ds_read_b128 v[160:163], v230 offset:4096
	ds_read_b128 v[164:167], v230 offset:5120
	ds_read_b128 v[168:171], v230 offset:6144
	ds_read_b128 v[172:175], v230 offset:7168
	global_load_lds_dwordx4 v[200:201], off
	v_lshl_add_u64 v[200:201], s[38:39], 0, v[198:199]
	s_add_i32 m0, s25, 0xe000
	s_nop 0
	global_load_lds_dwordx4 v[200:201], off
	s_waitcnt lgkmcnt(8)
	s_barrier
	s_waitcnt lgkmcnt(0)
	v_mfma_f32_16x16x32_bf16 v[124:127], v[128:131], v[144:147], 0
	v_mfma_f32_16x16x32_bf16 v[120:123], v[136:139], v[144:147], 0
	v_mfma_f32_16x16x32_bf16 v[112:115], v[128:131], v[152:155], 0
	v_mfma_f32_16x16x32_bf16 v[104:107], v[136:139], v[152:155], 0
	v_mfma_f32_16x16x32_bf16 v[92:95], v[128:131], v[160:163], 0
	v_mfma_f32_16x16x32_bf16 v[88:91], v[136:139], v[160:163], 0
	v_mfma_f32_16x16x32_bf16 v[80:83], v[128:131], v[168:171], 0
	v_mfma_f32_16x16x32_bf16 v[72:75], v[136:139], v[168:171], 0
	v_mfma_f32_16x16x32_bf16 v[124:127], v[132:135], v[148:151], v[124:127]
	v_mfma_f32_16x16x32_bf16 v[120:123], v[140:143], v[148:151], v[120:123]
	v_mfma_f32_16x16x32_bf16 v[112:115], v[132:135], v[156:159], v[112:115]
	v_mfma_f32_16x16x32_bf16 v[104:107], v[140:143], v[156:159], v[104:107]
	v_mfma_f32_16x16x32_bf16 v[92:95], v[132:135], v[164:167], v[92:95]
	v_mfma_f32_16x16x32_bf16 v[88:91], v[140:143], v[164:167], v[88:91]
	v_mfma_f32_16x16x32_bf16 v[80:83], v[132:135], v[172:175], v[80:83]
	v_mfma_f32_16x16x32_bf16 v[72:75], v[140:143], v[172:175], v[72:75]
	s_barrier
	s_add_i32 s38, 0, 0x14000
	s_add_i32 s14, s14, s24
	v_add_u32_e32 v220, s38, v228
	v_lshl_add_u64 v[232:233], s[52:53], 0, v[178:179]
	s_mov_b32 m0, s14
	ds_read_b128 v[200:203], v220
	ds_read_b128 v[204:207], v220 offset:1024
	ds_read_b128 v[208:211], v220 offset:2048
	ds_read_b128 v[220:223], v220 offset:3072
	global_load_lds_dwordx4 v[232:233], off
	v_lshl_add_u64 v[234:235], s[52:53], 0, v[194:195]
	s_add_i32 m0, s14, 0x2000
	s_nop 0
	global_load_lds_dwordx4 v[234:235], off
	s_barrier
	s_waitcnt lgkmcnt(0)
	v_mfma_f32_16x16x32_bf16 v[116:119], v[200:203], v[144:147], 0
	v_mfma_f32_16x16x32_bf16 v[108:111], v[208:211], v[144:147], 0
	v_mfma_f32_16x16x32_bf16 v[100:103], v[200:203], v[152:155], 0
	v_mfma_f32_16x16x32_bf16 v[96:99], v[208:211], v[152:155], 0
	v_mfma_f32_16x16x32_bf16 v[84:87], v[200:203], v[160:163], 0
	v_mfma_f32_16x16x32_bf16 v[76:79], v[208:211], v[160:163], 0
	v_mfma_f32_16x16x32_bf16 v[68:71], v[200:203], v[168:171], 0
	v_mfma_f32_16x16x32_bf16 v[64:67], v[208:211], v[168:171], 0
	v_mfma_f32_16x16x32_bf16 v[116:119], v[204:207], v[148:151], v[116:119]
	v_mfma_f32_16x16x32_bf16 v[108:111], v[220:223], v[148:151], v[108:111]
	v_mfma_f32_16x16x32_bf16 v[100:103], v[204:207], v[156:159], v[100:103]
	v_mfma_f32_16x16x32_bf16 v[96:99], v[220:223], v[156:159], v[96:99]
	v_mfma_f32_16x16x32_bf16 v[84:87], v[204:207], v[164:167], v[84:87]
	v_mfma_f32_16x16x32_bf16 v[76:79], v[220:223], v[164:167], v[76:79]
	v_mfma_f32_16x16x32_bf16 v[68:71], v[204:207], v[172:175], v[68:71]
	v_mfma_f32_16x16x32_bf16 v[64:67], v[220:223], v[172:175], v[64:67]
	s_barrier
	s_mov_b32 m0, s25
	v_lshl_add_u64 v[236:237], s[54:55], 0, v[178:179]
	ds_read_b128 v[144:147], v230 offset:16384
	ds_read_b128 v[148:151], v230 offset:17408
	ds_read_b128 v[152:155], v230 offset:18432
	ds_read_b128 v[156:159], v230 offset:19456
	ds_read_b128 v[160:163], v230 offset:20480
	ds_read_b128 v[164:167], v230 offset:21504
	ds_read_b128 v[168:171], v230 offset:22528
	ds_read_b128 v[172:175], v230 offset:23552
	global_load_lds_dwordx4 v[236:237], off
	v_lshl_add_u64 v[238:239], s[54:55], 0, v[194:195]
	s_mov_b32 m0, s56
	s_nop 0
	global_load_lds_dwordx4 v[238:239], off
	s_barrier
	s_waitcnt lgkmcnt(0)
	v_mfma_f32_16x16x32_bf16 v[60:63], v[128:131], v[144:147], 0
	v_mfma_f32_16x16x32_bf16 v[56:59], v[136:139], v[144:147], 0
	v_mfma_f32_16x16x32_bf16 v[48:51], v[128:131], v[152:155], 0
	v_mfma_f32_16x16x32_bf16 v[40:43], v[136:139], v[152:155], 0
	v_mfma_f32_16x16x32_bf16 v[28:31], v[128:131], v[160:163], 0
	v_mfma_f32_16x16x32_bf16 v[24:27], v[136:139], v[160:163], 0
	v_mfma_f32_16x16x32_bf16 v[16:19], v[128:131], v[168:171], 0
	v_mfma_f32_16x16x32_bf16 v[8:11], v[136:139], v[168:171], 0
	v_mfma_f32_16x16x32_bf16 v[60:63], v[132:135], v[148:151], v[60:63]
	v_mfma_f32_16x16x32_bf16 v[56:59], v[140:143], v[148:151], v[56:59]
	v_mfma_f32_16x16x32_bf16 v[48:51], v[132:135], v[156:159], v[48:51]
	v_mfma_f32_16x16x32_bf16 v[40:43], v[140:143], v[156:159], v[40:43]
	v_mfma_f32_16x16x32_bf16 v[28:31], v[132:135], v[164:167], v[28:31]
	v_mfma_f32_16x16x32_bf16 v[24:27], v[140:143], v[164:167], v[24:27]
	v_mfma_f32_16x16x32_bf16 v[16:19], v[132:135], v[172:175], v[16:19]
	v_mfma_f32_16x16x32_bf16 v[8:11], v[140:143], v[172:175], v[8:11]
	s_barrier
; #define PG8_STAGE(bufoff, gbase, voff) do { _Pragma("unroll") for (int _i = 0; _i < 2; ++_i) \
;         __builtin_amdgcn_global_load_lds((const unsigned*)((const char*)(gbase) + (voff)[_i]), (LAS unsigned*)(lds + (bufoff) + ldsw + _i * 8192), 16, 0, 0); } while (0)
; #define PG8_LDA(dst, b, h) do { _Pragma("unroll") for (int m = 0; m < 4; ++m) _Pragma("unroll") for (int k = 0; k < 2; ++k) dst[m][k] = *(const LAS bf16x8*)(lds + PG8_SA(b, h) + aoff + m * 2048 + k * 1024); } while (0)
; #define PG8_LDB(dst, b, h) do { _Pragma("unroll") for (int n = 0; n < 2; ++n) _Pragma("unroll") for (int k = 0; k < 2; ++k) dst[n][k] = *(const LAS bf16x8*)(lds + PG8_SB(b, h) + boff + n * 2048 + k * 1024); } while (0)
; #define PG8_MMA(ai, bj, At, Bt) do { __builtin_amdgcn_s_setprio(1); _Pragma("unroll") for (int m = 0; m < 4; ++m) _Pragma("unroll") for (int n = 0; n < 2; ++n) _Pragma("unroll") for (int k = 0; k < 2; ++k) \
;         acc[ai][bj][m][n] = __builtin_amdgcn_mfma_f32_16x16x32_bf16(Bt[n][k], At[m][k], acc[ai][bj][m][n], 0, 0, 0); __builtin_amdgcn_s_setprio(0); } while (0)
; #define PG8_WAIT_V(n) asm volatile("s_waitcnt vmcnt(" #n ")" ::: "memory")
; #define PG8_WAIT_L(n) asm volatile("s_waitcnt lgkmcnt(" #n ")" ::: "memory")
; #define PG8_BAR __builtin_amdgcn_s_barrier()
; #define PG8_SCHED __builtin_amdgcn_sched_barrier(0)
; template <class Epi>
; __device__ __forceinline__ void gemm_phase(LAS unsigned char* lds, const Gemm g, const StaticOrder S, const Epi E) {
;     ...
;             PG8_STAGE(PG8_SB(0, 1), b2 + hstep, voffA);
;             PG8_WAIT_V(6); PG8_BAR; PG8_MMA(1, 1, At, B1); PG8_BAR;
;             PG8_LDB(B0, 1, 0); PG8_SCHED; PG8_LDA(At, 1, 0); PG8_STAGE(PG8_SA(0, 1), a2 + hstep, voffA);
;             PG8_WAIT_L(8); PG8_BAR; PG8_WAIT_L(0); PG8_MMA(0, 0, At, B0); PG8_BAR; PG8_SCHED;
;             PG8_LDB(B1, 1, 1); PG8_STAGE(PG8_SB(1, 0), b3, voffA);
;             PG8_BAR; PG8_WAIT_L(0); PG8_MMA(0, 1, At, B1); PG8_BAR;
;             PG8_LDA(At, 1, 1); PG8_STAGE(PG8_SA(1, 0), a3, voffA);
;             PG8_BAR; PG8_WAIT_L(0); PG8_MMA(1, 0, At, B0); PG8_BAR; PG8_SCHED;
;             PG8_STAGE(PG8_SB(1, 1), b3 + hstep, voffA);
;             PG8_WAIT_V(6); PG8_BAR; PG8_MMA(1, 1, At, B1); PG8_BAR;
	s_add_u32 s30, s52, 0x158000
	s_addc_u32 s31, s53, 0
	s_add_i32 s14, s38, s24
	v_lshl_add_u64 v[128:129], s[30:31], 0, v[178:179]
	s_mov_b32 m0, s14
	s_nop 0
	global_load_lds_dwordx4 v[128:129], off
	v_lshl_add_u64 v[128:129], s[30:31], 0, v[194:195]
	s_add_i32 m0, s14, 0x2000
	s_nop 0
	global_load_lds_dwordx4 v[128:129], off
	s_waitcnt vmcnt(6)
	s_barrier
	v_mfma_f32_16x16x32_bf16 v[52:55], v[200:203], v[144:147], 0
	v_mfma_f32_16x16x32_bf16 v[44:47], v[208:211], v[144:147], 0
	v_mfma_f32_16x16x32_bf16 v[36:39], v[200:203], v[152:155], 0
	v_mfma_f32_16x16x32_bf16 v[32:35], v[208:211], v[152:155], 0
	v_mfma_f32_16x16x32_bf16 v[20:23], v[200:203], v[160:163], 0
	v_mfma_f32_16x16x32_bf16 v[12:15], v[208:211], v[160:163], 0
	v_mfma_f32_16x16x32_bf16 v[4:7], v[200:203], v[168:171], 0
	v_mfma_f32_16x16x32_bf16 v[0:3], v[208:211], v[168:171], 0
	v_mfma_f32_16x16x32_bf16 v[52:55], v[204:207], v[148:151], v[52:55]
	v_mfma_f32_16x16x32_bf16 v[44:47], v[220:223], v[148:151], v[44:47]
	v_mfma_f32_16x16x32_bf16 v[36:39], v[204:207], v[156:159], v[36:39]
	v_mfma_f32_16x16x32_bf16 v[32:35], v[220:223], v[156:159], v[32:35]
	v_mfma_f32_16x16x32_bf16 v[20:23], v[204:207], v[164:167], v[20:23]
	v_mfma_f32_16x16x32_bf16 v[12:15], v[220:223], v[164:167], v[12:15]
	v_mfma_f32_16x16x32_bf16 v[4:7], v[204:207], v[172:175], v[4:7]
	v_mfma_f32_16x16x32_bf16 v[0:3], v[220:223], v[172:175], v[0:3]
	s_barrier
	s_add_i32 s14, 0, 0x18000
	v_add_u32_e32 v140, s14, v228
	ds_read_b128 v[128:131], v140
	ds_read_b128 v[132:135], v140 offset:1024
	ds_read_b128 v[136:139], v140 offset:2048
	ds_read_b128 v[140:143], v140 offset:3072
	s_add_u32 s30, s54, 0x158000
	s_addc_u32 s31, s55, 0
	s_mov_b32 m0, s57
	v_lshl_add_u64 v[200:201], s[30:31], 0, v[178:179]
	ds_read_b128 v[144:147], v230 offset:32768
	ds_read_b128 v[148:151], v230 offset:33792
	ds_read_b128 v[152:155], v230 offset:34816
	ds_read_b128 v[156:159], v230 offset:35840
	ds_read_b128 v[160:163], v230 offset:36864
	ds_read_b128 v[164:167], v230 offset:37888
	ds_read_b128 v[168:171], v230 offset:38912
	ds_read_b128 v[172:175], v230 offset:39936
	global_load_lds_dwordx4 v[200:201], off
	v_lshl_add_u64 v[200:201], s[30:31], 0, v[194:195]
	s_mov_b32 m0, s58
	s_nop 0
	global_load_lds_dwordx4 v[200:201], off
	s_waitcnt lgkmcnt(8)
	s_barrier
	s_waitcnt lgkmcnt(0)
	v_mfma_f32_16x16x32_bf16 v[124:127], v[128:131], v[144:147], v[124:127]
	v_mfma_f32_16x16x32_bf16 v[120:123], v[136:139], v[144:147], v[120:123]
	v_mfma_f32_16x16x32_bf16 v[112:115], v[128:131], v[152:155], v[112:115]
	v_mfma_f32_16x16x32_bf16 v[104:107], v[136:139], v[152:155], v[104:107]
	v_mfma_f32_16x16x32_bf16 v[92:95], v[128:131], v[160:163], v[92:95]
	v_mfma_f32_16x16x32_bf16 v[88:91], v[136:139], v[160:163], v[88:91]
	v_mfma_f32_16x16x32_bf16 v[80:83], v[128:131], v[168:171], v[80:83]
	v_mfma_f32_16x16x32_bf16 v[72:75], v[136:139], v[168:171], v[72:75]
	v_mfma_f32_16x16x32_bf16 v[124:127], v[132:135], v[148:151], v[124:127]
	v_mfma_f32_16x16x32_bf16 v[120:123], v[140:143], v[148:151], v[120:123]
	v_mfma_f32_16x16x32_bf16 v[112:115], v[132:135], v[156:159], v[112:115]
	v_mfma_f32_16x16x32_bf16 v[104:107], v[140:143], v[156:159], v[104:107]
	v_mfma_f32_16x16x32_bf16 v[92:95], v[132:135], v[164:167], v[92:95]
	v_mfma_f32_16x16x32_bf16 v[88:91], v[140:143], v[164:167], v[88:91]
	v_mfma_f32_16x16x32_bf16 v[80:83], v[132:135], v[172:175], v[80:83]
	v_mfma_f32_16x16x32_bf16 v[72:75], v[140:143], v[172:175], v[72:75]
	s_barrier
	s_add_i32 s38, 0, 0x1c000
	s_add_i32 s14, s14, s24
	v_add_u32_e32 v220, s38, v228
	v_lshl_add_u64 v[232:233], v[232:233], 0, s[34:35]
	s_mov_b32 m0, s14
	ds_read_b128 v[200:203], v220
	ds_read_b128 v[204:207], v220 offset:1024
	ds_read_b128 v[208:211], v220 offset:2048
	ds_read_b128 v[220:223], v220 offset:3072
	global_load_lds_dwordx4 v[232:233], off
	v_lshl_add_u64 v[232:233], v[234:235], 0, s[34:35]
	s_add_i32 m0, s14, 0x2000
	s_nop 0
	global_load_lds_dwordx4 v[232:233], off
	s_barrier
	s_waitcnt lgkmcnt(0)
	v_mfma_f32_16x16x32_bf16 v[116:119], v[200:203], v[144:147], v[116:119]
	v_mfma_f32_16x16x32_bf16 v[108:111], v[208:211], v[144:147], v[108:111]
	v_mfma_f32_16x16x32_bf16 v[100:103], v[200:203], v[152:155], v[100:103]
	v_mfma_f32_16x16x32_bf16 v[96:99], v[208:211], v[152:155], v[96:99]
	v_mfma_f32_16x16x32_bf16 v[84:87], v[200:203], v[160:163], v[84:87]
	v_mfma_f32_16x16x32_bf16 v[76:79], v[208:211], v[160:163], v[76:79]
	v_mfma_f32_16x16x32_bf16 v[68:71], v[200:203], v[168:171], v[68:71]
	v_mfma_f32_16x16x32_bf16 v[64:67], v[208:211], v[168:171], v[64:67]
	v_mfma_f32_16x16x32_bf16 v[116:119], v[204:207], v[148:151], v[116:119]
	v_mfma_f32_16x16x32_bf16 v[108:111], v[220:223], v[148:151], v[108:111]
	v_mfma_f32_16x16x32_bf16 v[100:103], v[204:207], v[156:159], v[100:103]
	v_mfma_f32_16x16x32_bf16 v[96:99], v[220:223], v[156:159], v[96:99]
	v_mfma_f32_16x16x32_bf16 v[84:87], v[204:207], v[164:167], v[84:87]
	v_mfma_f32_16x16x32_bf16 v[76:79], v[220:223], v[164:167], v[76:79]
	v_mfma_f32_16x16x32_bf16 v[68:71], v[204:207], v[172:175], v[68:71]
	v_mfma_f32_16x16x32_bf16 v[64:67], v[220:223], v[172:175], v[64:67]
	s_barrier
	s_mov_b32 m0, s61
	v_lshl_add_u64 v[232:233], v[236:237], 0, s[34:35]
	ds_read_b128 v[144:147], v230 offset:49152
	ds_read_b128 v[148:151], v230 offset:50176
	ds_read_b128 v[152:155], v230 offset:51200
	ds_read_b128 v[156:159], v230 offset:52224
	ds_read_b128 v[160:163], v230 offset:53248
	ds_read_b128 v[164:167], v230 offset:54272
	ds_read_b128 v[168:171], v230 offset:55296
	ds_read_b128 v[172:175], v230 offset:56320
	global_load_lds_dwordx4 v[232:233], off
	v_lshl_add_u64 v[232:233], v[238:239], 0, s[34:35]
	s_mov_b32 m0, s62
	s_nop 0
	global_load_lds_dwordx4 v[232:233], off
	s_barrier
; #define PG8_STAGE(bufoff, gbase, voff) do { _Pragma("unroll") for (int _i = 0; _i < 2; ++_i) \
;         __builtin_amdgcn_global_load_lds((const unsigned*)((const char*)(gbase) + (voff)[_i]), (LAS unsigned*)(lds + (bufoff) + ldsw + _i * 8192), 16, 0, 0); } while (0)
; #define PG8_LDA(dst, b, h) do { _Pragma("unroll") for (int m = 0; m < 4; ++m) _Pragma("unroll") for (int k = 0; k < 2; ++k) dst[m][k] = *(const LAS bf16x8*)(lds + PG8_SA(b, h) + aoff + m * 2048 + k * 1024); } while (0)
; #define PG8_LDB(dst, b, h) do { _Pragma("unroll") for (int n = 0; n < 2; ++n) _Pragma("unroll") for (int k = 0; k < 2; ++k) dst[n][k] = *(const LAS bf16x8*)(lds + PG8_SB(b, h) + boff + n * 2048 + k * 1024); } while (0)
; #define PG8_WAIT_V(n) asm volatile("s_waitcnt vmcnt(" #n ")" ::: "memory")
; #define PG8_WAIT_L(n) asm volatile("s_waitcnt lgkmcnt(" #n ")" ::: "memory")
; #define PG8_BAR __builtin_amdgcn_s_barrier()
; #define PG8_SCHED __builtin_amdgcn_sched_barrier(0)
; template <class Epi>
; __device__ __forceinline__ void gemm_phase(LAS unsigned char* lds, const Gemm g, const StaticOrder S, const Epi E) {
;     ...
;         for (int t = 0; t < nt; t += 2) {
;             const bool last = (t == nt - 2);
;             const char* a1 = cA + (size_t)(t + 1) * kstep;
;             const char* a2 = last ? nA : cA + (size_t)(t + 2) * kstep; const char* b2 = last ? nB : cB + (size_t)(t + 2) * kstep;
;             const char* a3 = a2 + kstep; const char* b3 = b2 + kstep;
;             PG8_LDB(B0, 0, 0); PG8_SCHED; PG8_LDA(At, 0, 0); PG8_STAGE(PG8_SA(1, 1), a1 + hstep, voffA);
;             PG8_WAIT_L(8); PG8_BAR; PG8_WAIT_L(0); PG8_MMA(0, 0, At, B0); PG8_BAR; PG8_SCHED;
;             PG8_LDB(B1, 0, 1); PG8_STAGE(PG8_SB(0, 0), b2, voffA);
;             PG8_BAR; PG8_WAIT_L(0); PG8_MMA(0, 1, At, B1); PG8_BAR;
;             PG8_LDA(At, 0, 1); PG8_STAGE(PG8_SA(0, 0), a2, voffA);
;             PG8_BAR; PG8_WAIT_L(0); PG8_MMA(1, 0, At, B0); PG8_BAR; PG8_SCHED;
;             PG8_STAGE(PG8_SB(0, 1), b2 + hstep, voffA);
;             PG8_WAIT_V(6); PG8_BAR; PG8_MMA(1, 1, At, B1); PG8_BAR;
;     ...
;             PG8_LDA(At, 1, 1); PG8_STAGE(PG8_SA(1, 0), a3, voffA);
;             PG8_BAR; PG8_WAIT_L(0); PG8_MMA(1, 0, At, B0); PG8_BAR; PG8_SCHED;
;             PG8_STAGE(PG8_SB(1, 1), b3 + hstep, voffA);
;             PG8_WAIT_V(6); PG8_BAR; PG8_MMA(1, 1, At, B1); PG8_BAR;
	s_waitcnt lgkmcnt(0)
	v_mfma_f32_16x16x32_bf16 v[60:63], v[128:131], v[144:147], v[60:63]
	v_mfma_f32_16x16x32_bf16 v[56:59], v[136:139], v[144:147], v[56:59]
	v_mfma_f32_16x16x32_bf16 v[48:51], v[128:131], v[152:155], v[48:51]
	v_mfma_f32_16x16x32_bf16 v[40:43], v[136:139], v[152:155], v[40:43]
	v_mfma_f32_16x16x32_bf16 v[28:31], v[128:131], v[160:163], v[28:31]
	v_mfma_f32_16x16x32_bf16 v[24:27], v[136:139], v[160:163], v[24:27]
	v_mfma_f32_16x16x32_bf16 v[16:19], v[128:131], v[168:171], v[16:19]
	v_mfma_f32_16x16x32_bf16 v[8:11], v[136:139], v[168:171], v[8:11]
	v_mfma_f32_16x16x32_bf16 v[60:63], v[132:135], v[148:151], v[60:63]
	v_mfma_f32_16x16x32_bf16 v[56:59], v[140:143], v[148:151], v[56:59]
	v_mfma_f32_16x16x32_bf16 v[48:51], v[132:135], v[156:159], v[48:51]
	v_mfma_f32_16x16x32_bf16 v[40:43], v[140:143], v[156:159], v[40:43]
	v_mfma_f32_16x16x32_bf16 v[28:31], v[132:135], v[164:167], v[28:31]
	v_mfma_f32_16x16x32_bf16 v[24:27], v[140:143], v[164:167], v[24:27]
	v_mfma_f32_16x16x32_bf16 v[16:19], v[132:135], v[172:175], v[16:19]
	v_mfma_f32_16x16x32_bf16 v[8:11], v[140:143], v[172:175], v[8:11]
	s_barrier
	s_add_u32 s30, s52, 0x158080
	s_addc_u32 s31, s53, 0
	s_add_i32 s14, s38, s24
	v_lshl_add_u64 v[128:129], s[30:31], 0, v[178:179]
	s_mov_b32 m0, s14
	s_nop 0
	global_load_lds_dwordx4 v[128:129], off
	v_lshl_add_u64 v[128:129], s[30:31], 0, v[194:195]
	s_add_i32 m0, s14, 0x2000
	s_nop 0
	global_load_lds_dwordx4 v[128:129], off
	s_waitcnt vmcnt(6)
	s_barrier
	v_mfma_f32_16x16x32_bf16 v[52:55], v[200:203], v[144:147], v[52:55]
	v_mfma_f32_16x16x32_bf16 v[44:47], v[208:211], v[144:147], v[44:47]
	v_mfma_f32_16x16x32_bf16 v[36:39], v[200:203], v[152:155], v[36:39]
	v_mfma_f32_16x16x32_bf16 v[32:35], v[208:211], v[152:155], v[32:35]
	v_mfma_f32_16x16x32_bf16 v[20:23], v[200:203], v[160:163], v[20:23]
	v_mfma_f32_16x16x32_bf16 v[12:15], v[208:211], v[160:163], v[12:15]
	v_mfma_f32_16x16x32_bf16 v[4:7], v[200:203], v[168:171], v[4:7]
	v_mfma_f32_16x16x32_bf16 v[0:3], v[208:211], v[168:171], v[0:3]
	v_mfma_f32_16x16x32_bf16 v[52:55], v[204:207], v[148:151], v[52:55]
	v_mfma_f32_16x16x32_bf16 v[44:47], v[220:223], v[148:151], v[44:47]
	v_mfma_f32_16x16x32_bf16 v[36:39], v[204:207], v[156:159], v[36:39]
	v_mfma_f32_16x16x32_bf16 v[32:35], v[220:223], v[156:159], v[32:35]
	v_mfma_f32_16x16x32_bf16 v[20:23], v[204:207], v[164:167], v[20:23]
	v_mfma_f32_16x16x32_bf16 v[12:15], v[220:223], v[164:167], v[12:15]
	v_mfma_f32_16x16x32_bf16 v[4:7], v[204:207], v[172:175], v[4:7]
	v_mfma_f32_16x16x32_bf16 v[0:3], v[220:223], v[172:175], v[0:3]
	s_barrier
	s_add_u32 s68, s68, 0x100
	s_addc_u32 s69, s69, 0
	s_cmp_ge_i32 vcc_lo, s67
	s_mov_b64 s[38:39], s[50:51]
	s_mov_b32 s52, vcc_lo
	s_cbranch_scc0 .LBB0_3919
	s_branch .Lpeel_exit_7
.LBB0_3919:
	s_add_i32 vcc_lo, s52, 2
	s_add_u32 s50, s38, 0x100
	s_addc_u32 s51, s39, 0
	s_add_i32 s14, 0, 0x10000
	v_add_u32_e32 v140, s14, v228
	ds_read_b128 v[128:131], v140
	ds_read_b128 v[132:135], v140 offset:1024
	ds_read_b128 v[136:139], v140 offset:2048
	ds_read_b128 v[140:143], v140 offset:3072
	s_cmp_eq_u32 s43, s52
	s_cselect_b32 s52, s48, s68
	s_cselect_b32 s55, s45, s51
	s_cselect_b32 s54, s44, s50
	s_cselect_b32 s53, s49, s69
	v_lshl_add_u64 v[200:201], s[38:39], 0, v[196:197]
	s_add_i32 m0, s25, 0xc000
	ds_read_b128 v[144:147], v230
	ds_read_b128 v[148:151], v230 offset:1024
	ds_read_b128 v[152:155], v230 offset:2048
	ds_read_b128 v[156:159], v230 offset:3072
	ds_read_b128 v[160:163], v230 offset:4096
	ds_read_b128 v[164:167], v230 offset:5120
	ds_read_b128 v[168:171], v230 offset:6144
	ds_read_b128 v[172:175], v230 offset:7168
	global_load_lds_dwordx4 v[200:201], off
	v_lshl_add_u64 v[200:201], s[38:39], 0, v[198:199]
	s_add_i32 m0, s25, 0xe000
	s_nop 0
	global_load_lds_dwordx4 v[200:201], off
	s_waitcnt lgkmcnt(8)
	s_barrier
	s_waitcnt lgkmcnt(0)
	v_mfma_f32_16x16x32_bf16 v[124:127], v[128:131], v[144:147], v[124:127]
	v_mfma_f32_16x16x32_bf16 v[120:123], v[136:139], v[144:147], v[120:123]
	v_mfma_f32_16x16x32_bf16 v[112:115], v[128:131], v[152:155], v[112:115]
	v_mfma_f32_16x16x32_bf16 v[104:107], v[136:139], v[152:155], v[104:107]
	v_mfma_f32_16x16x32_bf16 v[92:95], v[128:131], v[160:163], v[92:95]
	v_mfma_f32_16x16x32_bf16 v[88:91], v[136:139], v[160:163], v[88:91]
	v_mfma_f32_16x16x32_bf16 v[80:83], v[128:131], v[168:171], v[80:83]
	v_mfma_f32_16x16x32_bf16 v[72:75], v[136:139], v[168:171], v[72:75]
	v_mfma_f32_16x16x32_bf16 v[124:127], v[132:135], v[148:151], v[124:127]
	v_mfma_f32_16x16x32_bf16 v[120:123], v[140:143], v[148:151], v[120:123]
	v_mfma_f32_16x16x32_bf16 v[112:115], v[132:135], v[156:159], v[112:115]
	v_mfma_f32_16x16x32_bf16 v[104:107], v[140:143], v[156:159], v[104:107]
	v_mfma_f32_16x16x32_bf16 v[92:95], v[132:135], v[164:167], v[92:95]
	v_mfma_f32_16x16x32_bf16 v[88:91], v[140:143], v[164:167], v[88:91]
	v_mfma_f32_16x16x32_bf16 v[80:83], v[132:135], v[172:175], v[80:83]
	v_mfma_f32_16x16x32_bf16 v[72:75], v[140:143], v[172:175], v[72:75]
	s_barrier
	s_add_i32 s38, 0, 0x14000
	s_add_i32 s14, s14, s24
	v_add_u32_e32 v220, s38, v228
	v_lshl_add_u64 v[232:233], s[52:53], 0, v[178:179]
	s_mov_b32 m0, s14
	ds_read_b128 v[200:203], v220
	ds_read_b128 v[204:207], v220 offset:1024
	ds_read_b128 v[208:211], v220 offset:2048
	ds_read_b128 v[220:223], v220 offset:3072
	global_load_lds_dwordx4 v[232:233], off
	v_lshl_add_u64 v[234:235], s[52:53], 0, v[194:195]
	s_add_i32 m0, s14, 0x2000
	s_nop 0
	global_load_lds_dwordx4 v[234:235], off
	s_barrier
; #define PG8_STAGE(bufoff, gbase, voff) do { _Pragma("unroll") for (int _i = 0; _i < 2; ++_i) \
;         __builtin_amdgcn_global_load_lds((const unsigned*)((const char*)(gbase) + (voff)[_i]), (LAS unsigned*)(lds + (bufoff) + ldsw + _i * 8192), 16, 0, 0); } while (0)
; #define PG8_LDA(dst, b, h) do { _Pragma("unroll") for (int m = 0; m < 4; ++m) _Pragma("unroll") for (int k = 0; k < 2; ++k) dst[m][k] = *(const LAS bf16x8*)(lds + PG8_SA(b, h) + aoff + m * 2048 + k * 1024); } while (0)
; #define PG8_LDB(dst, b, h) do { _Pragma("unroll") for (int n = 0; n < 2; ++n) _Pragma("unroll") for (int k = 0; k < 2; ++k) dst[n][k] = *(const LAS bf16x8*)(lds + PG8_SB(b, h) + boff + n * 2048 + k * 1024); } while (0)
; #define PG8_MMA(ai, bj, At, Bt) do { __builtin_amdgcn_s_setprio(1); _Pragma("unroll") for (int m = 0; m < 4; ++m) _Pragma("unroll") for (int n = 0; n < 2; ++n) _Pragma("unroll") for (int k = 0; k < 2; ++k) \
;         acc[ai][bj][m][n] = __builtin_amdgcn_mfma_f32_16x16x32_bf16(Bt[n][k], At[m][k], acc[ai][bj][m][n], 0, 0, 0); __builtin_amdgcn_s_setprio(0); } while (0)
; #define PG8_WAIT_V(n) asm volatile("s_waitcnt vmcnt(" #n ")" ::: "memory")
; #define PG8_WAIT_L(n) asm volatile("s_waitcnt lgkmcnt(" #n ")" ::: "memory")
; #define PG8_BAR __builtin_amdgcn_s_barrier()
; #define PG8_SCHED __builtin_amdgcn_sched_barrier(0)
; template <class Epi>
; __device__ __forceinline__ void gemm_phase(LAS unsigned char* lds, const Gemm g, const StaticOrder S, const Epi E) {
;     ...
;             PG8_LDB(B1, 0, 1); PG8_STAGE(PG8_SB(0, 0), b2, voffA);
;             PG8_BAR; PG8_WAIT_L(0); PG8_MMA(0, 1, At, B1); PG8_BAR;
;             PG8_LDA(At, 0, 1); PG8_STAGE(PG8_SA(0, 0), a2, voffA);
;             PG8_BAR; PG8_WAIT_L(0); PG8_MMA(1, 0, At, B0); PG8_BAR; PG8_SCHED;
;             PG8_STAGE(PG8_SB(0, 1), b2 + hstep, voffA);
;             PG8_WAIT_V(6); PG8_BAR; PG8_MMA(1, 1, At, B1); PG8_BAR;
;             PG8_LDB(B0, 1, 0); PG8_SCHED; PG8_LDA(At, 1, 0); PG8_STAGE(PG8_SA(0, 1), a2 + hstep, voffA);
;             PG8_WAIT_L(8); PG8_BAR; PG8_WAIT_L(0); PG8_MMA(0, 0, At, B0); PG8_BAR; PG8_SCHED;
;             PG8_LDB(B1, 1, 1); PG8_STAGE(PG8_SB(1, 0), b3, voffA);
	s_waitcnt lgkmcnt(0)
	v_mfma_f32_16x16x32_bf16 v[116:119], v[200:203], v[144:147], v[116:119]
	v_mfma_f32_16x16x32_bf16 v[108:111], v[208:211], v[144:147], v[108:111]
	v_mfma_f32_16x16x32_bf16 v[100:103], v[200:203], v[152:155], v[100:103]
	v_mfma_f32_16x16x32_bf16 v[96:99], v[208:211], v[152:155], v[96:99]
	v_mfma_f32_16x16x32_bf16 v[84:87], v[200:203], v[160:163], v[84:87]
	v_mfma_f32_16x16x32_bf16 v[76:79], v[208:211], v[160:163], v[76:79]
	v_mfma_f32_16x16x32_bf16 v[68:71], v[200:203], v[168:171], v[68:71]
	v_mfma_f32_16x16x32_bf16 v[64:67], v[208:211], v[168:171], v[64:67]
	v_mfma_f32_16x16x32_bf16 v[116:119], v[204:207], v[148:151], v[116:119]
	v_mfma_f32_16x16x32_bf16 v[108:111], v[220:223], v[148:151], v[108:111]
	v_mfma_f32_16x16x32_bf16 v[100:103], v[204:207], v[156:159], v[100:103]
	v_mfma_f32_16x16x32_bf16 v[96:99], v[220:223], v[156:159], v[96:99]
	v_mfma_f32_16x16x32_bf16 v[84:87], v[204:207], v[164:167], v[84:87]
	v_mfma_f32_16x16x32_bf16 v[76:79], v[220:223], v[164:167], v[76:79]
	v_mfma_f32_16x16x32_bf16 v[68:71], v[204:207], v[172:175], v[68:71]
	v_mfma_f32_16x16x32_bf16 v[64:67], v[220:223], v[172:175], v[64:67]
	s_barrier
	s_mov_b32 m0, s25
	v_lshl_add_u64 v[236:237], s[54:55], 0, v[178:179]
	ds_read_b128 v[144:147], v230 offset:16384
	ds_read_b128 v[148:151], v230 offset:17408
	ds_read_b128 v[152:155], v230 offset:18432
	ds_read_b128 v[156:159], v230 offset:19456
	ds_read_b128 v[160:163], v230 offset:20480
	ds_read_b128 v[164:167], v230 offset:21504
	ds_read_b128 v[168:171], v230 offset:22528
	ds_read_b128 v[172:175], v230 offset:23552
	global_load_lds_dwordx4 v[236:237], off
	v_lshl_add_u64 v[238:239], s[54:55], 0, v[194:195]
	s_mov_b32 m0, s56
	s_nop 0
	global_load_lds_dwordx4 v[238:239], off
	s_barrier
	s_waitcnt lgkmcnt(0)
	v_mfma_f32_16x16x32_bf16 v[60:63], v[128:131], v[144:147], v[60:63]
	v_mfma_f32_16x16x32_bf16 v[56:59], v[136:139], v[144:147], v[56:59]
	v_mfma_f32_16x16x32_bf16 v[48:51], v[128:131], v[152:155], v[48:51]
	v_mfma_f32_16x16x32_bf16 v[40:43], v[136:139], v[152:155], v[40:43]
	v_mfma_f32_16x16x32_bf16 v[28:31], v[128:131], v[160:163], v[28:31]
	v_mfma_f32_16x16x32_bf16 v[24:27], v[136:139], v[160:163], v[24:27]
	v_mfma_f32_16x16x32_bf16 v[16:19], v[128:131], v[168:171], v[16:19]
	v_mfma_f32_16x16x32_bf16 v[8:11], v[136:139], v[168:171], v[8:11]
	v_mfma_f32_16x16x32_bf16 v[60:63], v[132:135], v[148:151], v[60:63]
	v_mfma_f32_16x16x32_bf16 v[56:59], v[140:143], v[148:151], v[56:59]
	v_mfma_f32_16x16x32_bf16 v[48:51], v[132:135], v[156:159], v[48:51]
	v_mfma_f32_16x16x32_bf16 v[40:43], v[140:143], v[156:159], v[40:43]
	v_mfma_f32_16x16x32_bf16 v[28:31], v[132:135], v[164:167], v[28:31]
	v_mfma_f32_16x16x32_bf16 v[24:27], v[140:143], v[164:167], v[24:27]
	v_mfma_f32_16x16x32_bf16 v[16:19], v[132:135], v[172:175], v[16:19]
	v_mfma_f32_16x16x32_bf16 v[8:11], v[140:143], v[172:175], v[8:11]
	s_barrier
	s_add_u32 s30, s52, 0x158000
	s_addc_u32 s31, s53, 0
	s_add_i32 s14, s38, s24
	v_lshl_add_u64 v[128:129], s[30:31], 0, v[178:179]
	s_mov_b32 m0, s14
	s_nop 0
	global_load_lds_dwordx4 v[128:129], off
	v_lshl_add_u64 v[128:129], s[30:31], 0, v[194:195]
	s_add_i32 m0, s14, 0x2000
	s_nop 0
	global_load_lds_dwordx4 v[128:129], off
	s_waitcnt vmcnt(6)
	s_barrier
	v_mfma_f32_16x16x32_bf16 v[52:55], v[200:203], v[144:147], v[52:55]
	v_mfma_f32_16x16x32_bf16 v[44:47], v[208:211], v[144:147], v[44:47]
	v_mfma_f32_16x16x32_bf16 v[36:39], v[200:203], v[152:155], v[36:39]
	v_mfma_f32_16x16x32_bf16 v[32:35], v[208:211], v[152:155], v[32:35]
	v_mfma_f32_16x16x32_bf16 v[20:23], v[200:203], v[160:163], v[20:23]
	v_mfma_f32_16x16x32_bf16 v[12:15], v[208:211], v[160:163], v[12:15]
	v_mfma_f32_16x16x32_bf16 v[4:7], v[200:203], v[168:171], v[4:7]
	v_mfma_f32_16x16x32_bf16 v[0:3], v[208:211], v[168:171], v[0:3]
	v_mfma_f32_16x16x32_bf16 v[52:55], v[204:207], v[148:151], v[52:55]
	v_mfma_f32_16x16x32_bf16 v[44:47], v[220:223], v[148:151], v[44:47]
	v_mfma_f32_16x16x32_bf16 v[36:39], v[204:207], v[156:159], v[36:39]
	v_mfma_f32_16x16x32_bf16 v[32:35], v[220:223], v[156:159], v[32:35]
	v_mfma_f32_16x16x32_bf16 v[20:23], v[204:207], v[164:167], v[20:23]
	v_mfma_f32_16x16x32_bf16 v[12:15], v[220:223], v[164:167], v[12:15]
	v_mfma_f32_16x16x32_bf16 v[4:7], v[204:207], v[172:175], v[4:7]
	v_mfma_f32_16x16x32_bf16 v[0:3], v[220:223], v[172:175], v[0:3]
	s_barrier
	s_add_i32 s14, 0, 0x18000
	v_add_u32_e32 v140, s14, v228
	ds_read_b128 v[128:131], v140
	ds_read_b128 v[132:135], v140 offset:1024
	ds_read_b128 v[136:139], v140 offset:2048
	ds_read_b128 v[140:143], v140 offset:3072
	s_add_u32 s30, s54, 0x158000
	s_addc_u32 s31, s55, 0
	s_mov_b32 m0, s57
	v_lshl_add_u64 v[200:201], s[30:31], 0, v[178:179]
	ds_read_b128 v[144:147], v230 offset:32768
	ds_read_b128 v[148:151], v230 offset:33792
	ds_read_b128 v[152:155], v230 offset:34816
	ds_read_b128 v[156:159], v230 offset:35840
	ds_read_b128 v[160:163], v230 offset:36864
	ds_read_b128 v[164:167], v230 offset:37888
	ds_read_b128 v[168:171], v230 offset:38912
	ds_read_b128 v[172:175], v230 offset:39936
	global_load_lds_dwordx4 v[200:201], off
	v_lshl_add_u64 v[200:201], s[30:31], 0, v[194:195]
	s_mov_b32 m0, s58
	s_nop 0
	global_load_lds_dwordx4 v[200:201], off
	s_waitcnt lgkmcnt(8)
	s_barrier
; #define PG8_STAGE(bufoff, gbase, voff) do { _Pragma("unroll") for (int _i = 0; _i < 2; ++_i) \
;         __builtin_amdgcn_global_load_lds((const unsigned*)((const char*)(gbase) + (voff)[_i]), (LAS unsigned*)(lds + (bufoff) + ldsw + _i * 8192), 16, 0, 0); } while (0)
; #define PG8_LDA(dst, b, h) do { _Pragma("unroll") for (int m = 0; m < 4; ++m) _Pragma("unroll") for (int k = 0; k < 2; ++k) dst[m][k] = *(const LAS bf16x8*)(lds + PG8_SA(b, h) + aoff + m * 2048 + k * 1024); } while (0)
; #define PG8_MMA(ai, bj, At, Bt) do { __builtin_amdgcn_s_setprio(1); _Pragma("unroll") for (int m = 0; m < 4; ++m) _Pragma("unroll") for (int n = 0; n < 2; ++n) _Pragma("unroll") for (int k = 0; k < 2; ++k) \
;         acc[ai][bj][m][n] = __builtin_amdgcn_mfma_f32_16x16x32_bf16(Bt[n][k], At[m][k], acc[ai][bj][m][n], 0, 0, 0); __builtin_amdgcn_s_setprio(0); } while (0)
; #define PG8_WAIT_V(n) asm volatile("s_waitcnt vmcnt(" #n ")" ::: "memory")
; #define PG8_WAIT_L(n) asm volatile("s_waitcnt lgkmcnt(" #n ")" ::: "memory")
; #define PG8_BAR __builtin_amdgcn_s_barrier()
; #define PG8_SCHED __builtin_amdgcn_sched_barrier(0)
; template <class Epi>
; __device__ __forceinline__ void gemm_phase(LAS unsigned char* lds, const Gemm g, const StaticOrder S, const Epi E) {
;     ...
;             PG8_LDA(At, 1, 1); PG8_STAGE(PG8_SA(1, 0), a3, voffA);
;             PG8_BAR; PG8_WAIT_L(0); PG8_MMA(1, 0, At, B0); PG8_BAR; PG8_SCHED;
;             PG8_STAGE(PG8_SB(1, 1), b3 + hstep, voffA);
;             PG8_WAIT_V(6); PG8_BAR; PG8_MMA(1, 1, At, B1); PG8_BAR;
	s_waitcnt lgkmcnt(0)
	v_mfma_f32_16x16x32_bf16 v[124:127], v[128:131], v[144:147], v[124:127]
	v_mfma_f32_16x16x32_bf16 v[120:123], v[136:139], v[144:147], v[120:123]
	v_mfma_f32_16x16x32_bf16 v[112:115], v[128:131], v[152:155], v[112:115]
	v_mfma_f32_16x16x32_bf16 v[104:107], v[136:139], v[152:155], v[104:107]
	v_mfma_f32_16x16x32_bf16 v[92:95], v[128:131], v[160:163], v[92:95]
	v_mfma_f32_16x16x32_bf16 v[88:91], v[136:139], v[160:163], v[88:91]
	v_mfma_f32_16x16x32_bf16 v[80:83], v[128:131], v[168:171], v[80:83]
	v_mfma_f32_16x16x32_bf16 v[72:75], v[136:139], v[168:171], v[72:75]
	v_mfma_f32_16x16x32_bf16 v[124:127], v[132:135], v[148:151], v[124:127]
	v_mfma_f32_16x16x32_bf16 v[120:123], v[140:143], v[148:151], v[120:123]
	v_mfma_f32_16x16x32_bf16 v[112:115], v[132:135], v[156:159], v[112:115]
	v_mfma_f32_16x16x32_bf16 v[104:107], v[140:143], v[156:159], v[104:107]
	v_mfma_f32_16x16x32_bf16 v[92:95], v[132:135], v[164:167], v[92:95]
	v_mfma_f32_16x16x32_bf16 v[88:91], v[140:143], v[164:167], v[88:91]
	v_mfma_f32_16x16x32_bf16 v[80:83], v[132:135], v[172:175], v[80:83]
	v_mfma_f32_16x16x32_bf16 v[72:75], v[140:143], v[172:175], v[72:75]
	s_barrier
	s_add_i32 s38, 0, 0x1c000
	s_add_i32 s14, s14, s24
	v_add_u32_e32 v220, s38, v228
	v_lshl_add_u64 v[232:233], v[232:233], 0, s[34:35]
	s_mov_b32 m0, s14
	ds_read_b128 v[200:203], v220
	ds_read_b128 v[204:207], v220 offset:1024
	ds_read_b128 v[208:211], v220 offset:2048
	ds_read_b128 v[220:223], v220 offset:3072
	global_load_lds_dwordx4 v[232:233], off
	v_lshl_add_u64 v[232:233], v[234:235], 0, s[34:35]
	s_add_i32 m0, s14, 0x2000
	s_nop 0
	global_load_lds_dwordx4 v[232:233], off
	s_barrier
	s_waitcnt lgkmcnt(0)
	v_mfma_f32_16x16x32_bf16 v[116:119], v[200:203], v[144:147], v[116:119]
	v_mfma_f32_16x16x32_bf16 v[108:111], v[208:211], v[144:147], v[108:111]
	v_mfma_f32_16x16x32_bf16 v[100:103], v[200:203], v[152:155], v[100:103]
	v_mfma_f32_16x16x32_bf16 v[96:99], v[208:211], v[152:155], v[96:99]
	v_mfma_f32_16x16x32_bf16 v[84:87], v[200:203], v[160:163], v[84:87]
	v_mfma_f32_16x16x32_bf16 v[76:79], v[208:211], v[160:163], v[76:79]
	v_mfma_f32_16x16x32_bf16 v[68:71], v[200:203], v[168:171], v[68:71]
	v_mfma_f32_16x16x32_bf16 v[64:67], v[208:211], v[168:171], v[64:67]
	v_mfma_f32_16x16x32_bf16 v[116:119], v[204:207], v[148:151], v[116:119]
	v_mfma_f32_16x16x32_bf16 v[108:111], v[220:223], v[148:151], v[108:111]
	v_mfma_f32_16x16x32_bf16 v[100:103], v[204:207], v[156:159], v[100:103]
	v_mfma_f32_16x16x32_bf16 v[96:99], v[220:223], v[156:159], v[96:99]
	v_mfma_f32_16x16x32_bf16 v[84:87], v[204:207], v[164:167], v[84:87]
	v_mfma_f32_16x16x32_bf16 v[76:79], v[220:223], v[164:167], v[76:79]
	v_mfma_f32_16x16x32_bf16 v[68:71], v[204:207], v[172:175], v[68:71]
	v_mfma_f32_16x16x32_bf16 v[64:67], v[220:223], v[172:175], v[64:67]
	s_barrier
	s_mov_b32 m0, s61
	v_lshl_add_u64 v[232:233], v[236:237], 0, s[34:35]
	ds_read_b128 v[144:147], v230 offset:49152
	ds_read_b128 v[148:151], v230 offset:50176
	ds_read_b128 v[152:155], v230 offset:51200
	ds_read_b128 v[156:159], v230 offset:52224
	ds_read_b128 v[160:163], v230 offset:53248
	ds_read_b128 v[164:167], v230 offset:54272
	ds_read_b128 v[168:171], v230 offset:55296
	ds_read_b128 v[172:175], v230 offset:56320
	global_load_lds_dwordx4 v[232:233], off
	v_lshl_add_u64 v[232:233], v[238:239], 0, s[34:35]
	s_mov_b32 m0, s62
	s_nop 0
	global_load_lds_dwordx4 v[232:233], off
	s_barrier
	s_waitcnt lgkmcnt(0)
	v_mfma_f32_16x16x32_bf16 v[60:63], v[128:131], v[144:147], v[60:63]
	v_mfma_f32_16x16x32_bf16 v[56:59], v[136:139], v[144:147], v[56:59]
	v_mfma_f32_16x16x32_bf16 v[48:51], v[128:131], v[152:155], v[48:51]
	v_mfma_f32_16x16x32_bf16 v[40:43], v[136:139], v[152:155], v[40:43]
	v_mfma_f32_16x16x32_bf16 v[28:31], v[128:131], v[160:163], v[28:31]
	v_mfma_f32_16x16x32_bf16 v[24:27], v[136:139], v[160:163], v[24:27]
	v_mfma_f32_16x16x32_bf16 v[16:19], v[128:131], v[168:171], v[16:19]
	v_mfma_f32_16x16x32_bf16 v[8:11], v[136:139], v[168:171], v[8:11]
	v_mfma_f32_16x16x32_bf16 v[60:63], v[132:135], v[148:151], v[60:63]
	v_mfma_f32_16x16x32_bf16 v[56:59], v[140:143], v[148:151], v[56:59]
	v_mfma_f32_16x16x32_bf16 v[48:51], v[132:135], v[156:159], v[48:51]
	v_mfma_f32_16x16x32_bf16 v[40:43], v[140:143], v[156:159], v[40:43]
	v_mfma_f32_16x16x32_bf16 v[28:31], v[132:135], v[164:167], v[28:31]
	v_mfma_f32_16x16x32_bf16 v[24:27], v[140:143], v[164:167], v[24:27]
	v_mfma_f32_16x16x32_bf16 v[16:19], v[132:135], v[172:175], v[16:19]
	v_mfma_f32_16x16x32_bf16 v[8:11], v[140:143], v[172:175], v[8:11]
	s_barrier
	s_add_u32 s30, s52, 0x158080
	s_addc_u32 s31, s53, 0
	s_add_i32 s14, s38, s24
	v_lshl_add_u64 v[128:129], s[30:31], 0, v[178:179]
	s_mov_b32 m0, s14
	s_nop 0
	global_load_lds_dwordx4 v[128:129], off
	v_lshl_add_u64 v[128:129], s[30:31], 0, v[194:195]
	s_add_i32 m0, s14, 0x2000
	s_nop 0
	global_load_lds_dwordx4 v[128:129], off
	s_waitcnt vmcnt(6)
	s_barrier
	v_mfma_f32_16x16x32_bf16 v[52:55], v[200:203], v[144:147], v[52:55]
	v_mfma_f32_16x16x32_bf16 v[44:47], v[208:211], v[144:147], v[44:47]
	v_mfma_f32_16x16x32_bf16 v[36:39], v[200:203], v[152:155], v[36:39]
	v_mfma_f32_16x16x32_bf16 v[32:35], v[208:211], v[152:155], v[32:35]
	v_mfma_f32_16x16x32_bf16 v[20:23], v[200:203], v[160:163], v[20:23]
	v_mfma_f32_16x16x32_bf16 v[12:15], v[208:211], v[160:163], v[12:15]
	v_mfma_f32_16x16x32_bf16 v[4:7], v[200:203], v[168:171], v[4:7]
	v_mfma_f32_16x16x32_bf16 v[0:3], v[208:211], v[168:171], v[0:3]
	v_mfma_f32_16x16x32_bf16 v[52:55], v[204:207], v[148:151], v[52:55]
	v_mfma_f32_16x16x32_bf16 v[44:47], v[220:223], v[148:151], v[44:47]
	v_mfma_f32_16x16x32_bf16 v[36:39], v[204:207], v[156:159], v[36:39]
	v_mfma_f32_16x16x32_bf16 v[32:35], v[220:223], v[156:159], v[32:35]
	v_mfma_f32_16x16x32_bf16 v[20:23], v[204:207], v[164:167], v[20:23]
	v_mfma_f32_16x16x32_bf16 v[12:15], v[220:223], v[164:167], v[12:15]
	v_mfma_f32_16x16x32_bf16 v[4:7], v[204:207], v[172:175], v[4:7]
	v_mfma_f32_16x16x32_bf16 v[0:3], v[220:223], v[172:175], v[0:3]
	s_barrier
	s_add_u32 s68, s68, 0x100
	s_addc_u32 s69, s69, 0
	s_cmp_ge_i32 vcc_lo, s67
	s_mov_b64 s[38:39], s[50:51]
	s_mov_b32 s52, vcc_lo
	s_cbranch_scc0 .LBB0_3919
